# half-step stagger (s_sleep 8) for WGs >= 256 before each 256x128 GEMM k-loop, on top of NSA static priority
# baseline (speedup 1.0000x reference)
.LBB0_207:
	s_ashr_i32 s0, s64, 3
	s_lshr_b32 s1, s0, 28
	s_add_i32 s1, s0, s1
	s_and_b32 s5, s1, -16
	s_and_b32 s4, s64, 1
	s_sub_i32 s26, s0, s5
	s_lshr_b32 s5, s0, 6
	s_mul_i32 s5, s5, 5
	s_add_i32 s26, s26, s5
	s_and_b32 s26, s26, 15
	s_lshl_b32 s0, s1, 6
	s_lshl_b32 s1, s64, 7
	s_lshl_b32 s26, s26, 1
	s_and_b32 s0, s0, 0xfffffc00
	s_and_b32 s1, s1, 0x300
	s_or_b32 s26, s26, s4
	s_or_b32 s4, s0, s1
	s_ashr_i32 s5, s4, 31
	s_lshl_b32 s0, s26, 7
	s_lshl_b64 s[52:53], s[4:5], 11
	s_add_u32 s52, s3, s52
	s_addc_u32 s53, s34, s53
	s_ashr_i32 s1, s0, 31
	v_mov_b32_e32 v34, v220
	s_lshl_b64 s[54:55], s[0:1], 11
	s_add_u32 s54, s72, s54
	v_ashrrev_i32_e32 v24, 2, v34
	v_ashrrev_i32_e32 v25, 31, v24
	s_addc_u32 s55, s73, s55
	v_lshlrev_b64 v[0:1], 11, v[24:25]
	v_lshlrev_b32_e32 v4, 4, v34
	v_lshl_add_u64 v[2:3], s[54:55], 0, v[0:1]
	v_lshl_add_u64 v[0:1], s[52:53], 0, v[0:1]
	v_and_b32_e32 v152, 48, v4
	v_lshl_add_u64 v[154:155], v[0:1], 0, v[152:153]
	v_add_co_u32_e32 v26, vcc, s35, v154
	v_lshl_add_u64 v[156:157], v[2:3], 0, v[152:153]
	s_nop 0
	v_addc_co_u32_e32 v27, vcc, 0, v155, vcc
	v_add_co_u32_e32 v28, vcc, s36, v154
	global_load_dwordx4 v[0:3], v[154:155], off
	s_nop 0
	v_addc_co_u32_e32 v29, vcc, 0, v155, vcc
	v_add_co_u32_e32 v30, vcc, s37, v154
	global_load_dwordx4 v[4:7], v[26:27], off
	global_load_dwordx4 v[8:11], v[28:29], off
	v_addc_co_u32_e32 v31, vcc, 0, v155, vcc
	v_add_co_u32_e32 v32, vcc, s35, v156
	global_load_dwordx4 v[12:15], v[30:31], off
	global_load_dwordx4 v[16:19], v[156:157], off
	v_addc_co_u32_e32 v33, vcc, 0, v157, vcc
	global_load_dwordx4 v[20:23], v[32:33], off
	global_load_dwordx4 v[128:131], v[154:155], off offset:64
	global_load_dwordx4 v[136:139], v[26:27], off offset:64
	global_load_dwordx4 v[140:143], v[28:29], off offset:64
	global_load_dwordx4 v[144:147], v[30:31], off offset:64
	global_load_dwordx4 v[132:135], v[156:157], off offset:64
	global_load_dwordx4 v[148:151], v[32:33], off offset:64
	v_lshrrev_b32_e32 v35, 4, v34
	v_lshrrev_b32_e32 v36, 2, v34
	v_sub_u32_e32 v39, 0, v35
	v_sub_u32_e32 v36, 0, v36
	v_and_b32_e32 v37, 0x3ffff8f, v34
	v_lshlrev_b32_e32 v38, 6, v34
	v_xor_b32_e32 v34, v34, v39
	v_xor_b32_e32 v35, v35, v36
	v_lshlrev_b32_e32 v34, 4, v34
	v_lshlrev_b32_e32 v35, 4, v35
	v_mov_b32_e32 v25, 0x4000
	v_and_b32_e32 v40, 0x1000, v38
	v_and_b32_e32 v34, 48, v34
	v_and_b32_e32 v35, 48, v35
	v_and_b32_e32 v41, 0x3c0, v38
	v_and_b32_e32 v38, 0xffffe3c0, v38
	v_lshl_add_u32 v25, v37, 6, v25
	v_lshl_or_b32 v152, v24, 6, v34
	v_or_b32_e32 v24, v35, v40
	s_mov_b32 s1, -2
	v_or3_b32 v175, v40, v41, v35
	v_add_u32_e32 v176, v35, v38
	v_add_u32_e32 v177, v35, v25
	v_add_u32_e32 v178, v24, v41
	v_lshl_add_u64 v[158:159], v[154:155], 0, s[22:23]
	v_lshl_add_u64 v[160:161], v[154:155], 0, s[24:25]
	v_lshl_add_u64 v[162:163], v[154:155], 0, s[28:29]
	v_lshl_add_u64 v[164:165], v[156:157], 0, s[22:23]
	s_mov_b32 s5, s31
	v_mov_b32_e32 v64, 0
	v_mov_b32_e32 v65, v153
	v_mov_b32_e32 v66, v153
	v_mov_b32_e32 v67, v153
	v_mov_b32_e32 v68, 0
	v_mov_b32_e32 v69, v153
	v_mov_b32_e32 v70, v153
	v_mov_b32_e32 v71, v153
	v_mov_b32_e32 v72, 0
	v_mov_b32_e32 v73, v153
	v_mov_b32_e32 v74, v153
	v_mov_b32_e32 v75, v153
	v_mov_b32_e32 v76, 0
	v_mov_b32_e32 v77, v153
	v_mov_b32_e32 v78, v153
	v_mov_b32_e32 v79, v153
	v_mov_b32_e32 v80, 0
	s_waitcnt vmcnt(11)
	ds_write_b128 v152, v[0:3]
	s_waitcnt vmcnt(10)
	ds_write_b128 v152, v[4:7] offset:4096
	s_waitcnt vmcnt(9)
	ds_write_b128 v152, v[8:11] offset:8192
	s_waitcnt vmcnt(8)
	ds_write_b128 v152, v[12:15] offset:12288
	s_waitcnt vmcnt(7)
	ds_write_b128 v152, v[16:19] offset:32768
	s_waitcnt vmcnt(6)
	ds_write_b128 v152, v[20:23] offset:36864
	v_mov_b32_e32 v0, 0
	v_mov_b32_e32 v1, v153
	v_mov_b32_e32 v2, v153
	v_mov_b32_e32 v3, v153
	v_mov_b32_e32 v4, 0
	v_mov_b32_e32 v5, v153
	v_mov_b32_e32 v6, v153
	v_mov_b32_e32 v7, v153
	v_mov_b32_e32 v8, 0
	v_mov_b32_e32 v9, v153
	v_mov_b32_e32 v10, v153
	v_mov_b32_e32 v11, v153
	v_mov_b32_e32 v12, 0
	v_mov_b32_e32 v13, v153
	v_mov_b32_e32 v14, v153
	v_mov_b32_e32 v15, v153
	v_mov_b32_e32 v16, 0
	v_mov_b32_e32 v17, v153
	v_mov_b32_e32 v18, v153
	v_mov_b32_e32 v19, v153
	v_mov_b32_e32 v20, 0
	v_mov_b32_e32 v21, v153
	v_mov_b32_e32 v22, v153
	v_mov_b32_e32 v23, v153
	v_mov_b32_e32 v81, v153
	v_mov_b32_e32 v82, v153
	v_mov_b32_e32 v83, v153
	v_mov_b32_e32 v84, 0
	v_mov_b32_e32 v85, v153
	v_mov_b32_e32 v86, v153
	v_mov_b32_e32 v87, v153
	v_mov_b32_e32 v24, 0
	v_mov_b32_e32 v25, v153
	v_mov_b32_e32 v26, v153
	v_mov_b32_e32 v27, v153
	v_mov_b32_e32 v28, 0
	v_mov_b32_e32 v29, v153
	v_mov_b32_e32 v30, v153
	v_mov_b32_e32 v31, v153
	v_mov_b32_e32 v88, 0
	v_mov_b32_e32 v89, v153
	v_mov_b32_e32 v90, v153
	v_mov_b32_e32 v91, v153
	v_mov_b32_e32 v92, 0
	v_mov_b32_e32 v93, v153
	v_mov_b32_e32 v94, v153
	v_mov_b32_e32 v95, v153
	v_mov_b32_e32 v32, 0
	v_mov_b32_e32 v33, v153
	v_mov_b32_e32 v34, v153
	v_mov_b32_e32 v35, v153
	v_mov_b32_e32 v36, 0
	v_mov_b32_e32 v37, v153
	v_mov_b32_e32 v38, v153
	v_mov_b32_e32 v39, v153
	v_mov_b32_e32 v96, 0
	v_mov_b32_e32 v97, v153
	v_mov_b32_e32 v98, v153
	v_mov_b32_e32 v99, v153
	v_mov_b32_e32 v100, 0
	v_mov_b32_e32 v101, v153
	v_mov_b32_e32 v102, v153
	v_mov_b32_e32 v103, v153
	v_mov_b32_e32 v40, 0
	v_mov_b32_e32 v41, v153
	v_mov_b32_e32 v42, v153
	v_mov_b32_e32 v43, v153
	v_mov_b32_e32 v44, 0
	v_mov_b32_e32 v45, v153
	v_mov_b32_e32 v46, v153
	v_mov_b32_e32 v47, v153
	v_mov_b32_e32 v104, 0
	v_mov_b32_e32 v105, v153
	v_mov_b32_e32 v106, v153
	v_mov_b32_e32 v107, v153
	v_mov_b32_e32 v108, 0
	v_mov_b32_e32 v109, v153
	v_mov_b32_e32 v110, v153
	v_mov_b32_e32 v111, v153
	v_mov_b32_e32 v48, 0
	v_mov_b32_e32 v49, v153
	v_mov_b32_e32 v50, v153
	v_mov_b32_e32 v51, v153
	v_mov_b32_e32 v52, 0
	v_mov_b32_e32 v53, v153
	v_mov_b32_e32 v54, v153
	v_mov_b32_e32 v55, v153
	v_mov_b32_e32 v112, 0
	v_mov_b32_e32 v113, v153
	v_mov_b32_e32 v114, v153
	v_mov_b32_e32 v115, v153
	v_mov_b32_e32 v116, 0
	v_mov_b32_e32 v117, v153
	v_mov_b32_e32 v118, v153
	v_mov_b32_e32 v119, v153
	v_mov_b32_e32 v56, 0
	v_mov_b32_e32 v57, v153
	v_mov_b32_e32 v58, v153
	v_mov_b32_e32 v59, v153
	v_mov_b32_e32 v60, 0
	v_mov_b32_e32 v61, v153
	v_mov_b32_e32 v62, v153
	v_mov_b32_e32 v63, v153
	v_mov_b32_e32 v120, 0
	v_mov_b32_e32 v121, v153
	v_mov_b32_e32 v122, v153
	v_mov_b32_e32 v123, v153
	v_mov_b32_e32 v124, 0
	v_mov_b32_e32 v125, v153
	v_mov_b32_e32 v126, v153
	v_mov_b32_e32 v127, v153
	s_waitcnt lgkmcnt(0)
	s_barrier
	s_cmpk_lt_u32 s2, 0x100
	s_cbranch_scc1 .Lstag_0
	s_sleep 8
.Lstag_0:
.LBB0_208:
	s_add_i32 s27, s5, 64
	s_min_u32 s30, s27, 0x3e0
	s_lshl_b32 s30, s30, 1
	v_lshl_add_u64 v[180:181], v[154:155], 0, s[30:31]
	v_lshl_add_u64 v[184:185], v[158:159], 0, s[30:31]
	v_lshl_add_u64 v[188:189], v[160:161], 0, s[30:31]
	v_lshl_add_u64 v[192:193], v[162:163], 0, s[30:31]
	v_lshl_add_u64 v[196:197], v[156:157], 0, s[30:31]
	v_lshl_add_u64 v[200:201], v[164:165], 0, s[30:31]
	global_load_dwordx4 v[180:183], v[180:181], off
	ds_read_b128 v[204:207], v178 offset:32768
	global_load_dwordx4 v[184:187], v[184:185], off
	ds_read_b128 v[208:211], v178 offset:33792
	global_load_dwordx4 v[188:191], v[188:189], off
	ds_read_b128 v[212:215], v178 offset:34816
	global_load_dwordx4 v[192:195], v[192:193], off
	ds_read_b128 v[216:219], v178 offset:35840
	global_load_dwordx4 v[196:199], v[196:197], off
	ds_read_b128 v[222:225], v176
	global_load_dwordx4 v[200:203], v[200:201], off
	ds_read_b128 v[226:229], v176 offset:1024
	ds_read_b128 v[230:233], v176 offset:2048
	ds_read_b128 v[234:237], v176 offset:3072
	ds_read_b128 v[238:241], v176 offset:4096
	ds_read_b128 v[242:245], v176 offset:5120
	ds_read_b128 v[246:249], v176 offset:6144
	ds_read_b128 v[250:253], v176 offset:7168
	s_setprio 1
	s_waitcnt lgkmcnt(7)
	v_mfma_f32_16x16x32_bf16 v[124:127], v[222:225], v[204:207], v[124:127]
	v_mfma_f32_16x16x32_bf16 v[120:123], v[222:225], v[208:211], v[120:123]
	v_mfma_f32_16x16x32_bf16 v[60:63], v[222:225], v[212:215], v[60:63]
	v_mfma_f32_16x16x32_bf16 v[56:59], v[222:225], v[216:219], v[56:59]
	s_waitcnt vmcnt(11)
	ds_write_b128 v152, v[128:131] offset:16384
	s_waitcnt lgkmcnt(7)
	v_mfma_f32_16x16x32_bf16 v[116:119], v[226:229], v[204:207], v[116:119]
	v_mfma_f32_16x16x32_bf16 v[112:115], v[226:229], v[208:211], v[112:115]
	v_mfma_f32_16x16x32_bf16 v[52:55], v[226:229], v[212:215], v[52:55]
	v_mfma_f32_16x16x32_bf16 v[48:51], v[226:229], v[216:219], v[48:51]
	s_waitcnt vmcnt(9)
	ds_write_b128 v152, v[136:139] offset:20480
	s_waitcnt lgkmcnt(7)
	v_mfma_f32_16x16x32_bf16 v[108:111], v[230:233], v[204:207], v[108:111]
	v_mfma_f32_16x16x32_bf16 v[104:107], v[230:233], v[208:211], v[104:107]
	v_mfma_f32_16x16x32_bf16 v[44:47], v[230:233], v[212:215], v[44:47]
	v_mfma_f32_16x16x32_bf16 v[40:43], v[230:233], v[216:219], v[40:43]
	s_waitcnt vmcnt(8)
	ds_write_b128 v152, v[140:143] offset:24576
	s_waitcnt lgkmcnt(7)
	v_mfma_f32_16x16x32_bf16 v[100:103], v[234:237], v[204:207], v[100:103]
	v_mfma_f32_16x16x32_bf16 v[96:99], v[234:237], v[208:211], v[96:99]
	v_mfma_f32_16x16x32_bf16 v[36:39], v[234:237], v[212:215], v[36:39]
	v_mfma_f32_16x16x32_bf16 v[32:35], v[234:237], v[216:219], v[32:35]
	s_waitcnt vmcnt(7)
	ds_write_b128 v152, v[144:147] offset:28672
	s_waitcnt lgkmcnt(7)
	v_mfma_f32_16x16x32_bf16 v[92:95], v[238:241], v[204:207], v[92:95]
	v_mfma_f32_16x16x32_bf16 v[88:91], v[238:241], v[208:211], v[88:91]
	v_mfma_f32_16x16x32_bf16 v[28:31], v[238:241], v[212:215], v[28:31]
	v_mfma_f32_16x16x32_bf16 v[24:27], v[238:241], v[216:219], v[24:27]
	s_waitcnt vmcnt(7)
	ds_write_b128 v152, v[132:135] offset:40960
	s_waitcnt lgkmcnt(7)
	v_mfma_f32_16x16x32_bf16 v[84:87], v[242:245], v[204:207], v[84:87]
	v_mfma_f32_16x16x32_bf16 v[80:83], v[242:245], v[208:211], v[80:83]
	v_mfma_f32_16x16x32_bf16 v[20:23], v[242:245], v[212:215], v[20:23]
	v_mfma_f32_16x16x32_bf16 v[16:19], v[242:245], v[216:219], v[16:19]
	s_waitcnt vmcnt(6)
	ds_write_b128 v152, v[148:151] offset:45056
	s_waitcnt lgkmcnt(7)
	v_mfma_f32_16x16x32_bf16 v[76:79], v[246:249], v[204:207], v[76:79]
	v_mfma_f32_16x16x32_bf16 v[72:75], v[246:249], v[208:211], v[72:75]
	v_mfma_f32_16x16x32_bf16 v[12:15], v[246:249], v[212:215], v[12:15]
	v_mfma_f32_16x16x32_bf16 v[8:11], v[246:249], v[216:219], v[8:11]
	s_waitcnt lgkmcnt(6)
	v_mfma_f32_16x16x32_bf16 v[68:71], v[250:253], v[204:207], v[68:71]
	v_mfma_f32_16x16x32_bf16 v[64:67], v[250:253], v[208:211], v[64:67]
	v_mfma_f32_16x16x32_bf16 v[4:7], v[250:253], v[212:215], v[4:7]
	v_mfma_f32_16x16x32_bf16 v[0:3], v[250:253], v[216:219], v[0:3]
	s_setprio 0
	s_min_u32 s5, s5, 0x380
	s_lshl_b32 s30, s5, 1
	s_mov_b32 s53, s31
	s_add_i32 s52, s30, 0xc0
	v_lshl_add_u64 v[128:129], v[154:155], 0, s[30:31]
	v_lshl_add_u64 v[132:133], v[156:157], 0, s[30:31]
	v_lshl_add_u64 v[136:137], v[158:159], 0, s[52:53]
	v_lshl_add_u64 v[140:141], v[160:161], 0, s[52:53]
	v_lshl_add_u64 v[144:145], v[162:163], 0, s[52:53]
	v_lshl_add_u64 v[148:149], v[164:165], 0, s[52:53]
	s_waitcnt lgkmcnt(0)
	s_barrier
	global_load_dwordx4 v[128:131], v[128:129], off offset:192
	ds_read_b128 v[204:207], v175 offset:40960
	global_load_dwordx4 v[132:135], v[132:133], off offset:192
	ds_read_b128 v[208:211], v175 offset:41984
	global_load_dwordx4 v[136:139], v[136:137], off
	ds_read_b128 v[212:215], v175 offset:43008
	global_load_dwordx4 v[140:143], v[140:141], off
	ds_read_b128 v[216:219], v175 offset:44032
	global_load_dwordx4 v[144:147], v[144:145], off
	ds_read_b128 v[222:225], v177
	global_load_dwordx4 v[148:151], v[148:149], off
	ds_read_b128 v[226:229], v177 offset:1024
	ds_read_b128 v[230:233], v177 offset:2048
	ds_read_b128 v[234:237], v177 offset:3072
	ds_read_b128 v[238:241], v177 offset:4096
	ds_read_b128 v[242:245], v177 offset:5120
	ds_read_b128 v[246:249], v177 offset:6144
	ds_read_b128 v[250:253], v177 offset:7168
	s_setprio 1
	s_waitcnt lgkmcnt(7)
	v_mfma_f32_16x16x32_bf16 v[124:127], v[222:225], v[204:207], v[124:127]
	v_mfma_f32_16x16x32_bf16 v[120:123], v[222:225], v[208:211], v[120:123]
	v_mfma_f32_16x16x32_bf16 v[60:63], v[222:225], v[212:215], v[60:63]
	v_mfma_f32_16x16x32_bf16 v[56:59], v[222:225], v[216:219], v[56:59]
	s_waitcnt vmcnt(11)
	ds_write_b128 v152, v[180:183]
	s_waitcnt lgkmcnt(7)
	v_mfma_f32_16x16x32_bf16 v[116:119], v[226:229], v[204:207], v[116:119]
	v_mfma_f32_16x16x32_bf16 v[112:115], v[226:229], v[208:211], v[112:115]
	v_mfma_f32_16x16x32_bf16 v[52:55], v[226:229], v[212:215], v[52:55]
	v_mfma_f32_16x16x32_bf16 v[48:51], v[226:229], v[216:219], v[48:51]
	s_waitcnt vmcnt(10)
	ds_write_b128 v152, v[184:187] offset:4096
	s_waitcnt lgkmcnt(7)
	v_mfma_f32_16x16x32_bf16 v[108:111], v[230:233], v[204:207], v[108:111]
	v_mfma_f32_16x16x32_bf16 v[104:107], v[230:233], v[208:211], v[104:107]
	v_mfma_f32_16x16x32_bf16 v[44:47], v[230:233], v[212:215], v[44:47]
	v_mfma_f32_16x16x32_bf16 v[40:43], v[230:233], v[216:219], v[40:43]
	s_waitcnt vmcnt(9)
	ds_write_b128 v152, v[188:191] offset:8192
	s_waitcnt lgkmcnt(7)
	v_mfma_f32_16x16x32_bf16 v[100:103], v[234:237], v[204:207], v[100:103]
	v_mfma_f32_16x16x32_bf16 v[96:99], v[234:237], v[208:211], v[96:99]
	v_mfma_f32_16x16x32_bf16 v[36:39], v[234:237], v[212:215], v[36:39]
	v_mfma_f32_16x16x32_bf16 v[32:35], v[234:237], v[216:219], v[32:35]
	s_waitcnt vmcnt(8)
	ds_write_b128 v152, v[192:195] offset:12288
	s_waitcnt lgkmcnt(7)
	v_mfma_f32_16x16x32_bf16 v[92:95], v[238:241], v[204:207], v[92:95]
	v_mfma_f32_16x16x32_bf16 v[88:91], v[238:241], v[208:211], v[88:91]
	v_mfma_f32_16x16x32_bf16 v[28:31], v[238:241], v[212:215], v[28:31]
	v_mfma_f32_16x16x32_bf16 v[24:27], v[238:241], v[216:219], v[24:27]
	s_waitcnt vmcnt(7)
	ds_write_b128 v152, v[196:199] offset:32768
	s_waitcnt lgkmcnt(7)
	v_mfma_f32_16x16x32_bf16 v[84:87], v[242:245], v[204:207], v[84:87]
	v_mfma_f32_16x16x32_bf16 v[80:83], v[242:245], v[208:211], v[80:83]
	v_mfma_f32_16x16x32_bf16 v[20:23], v[242:245], v[212:215], v[20:23]
	v_mfma_f32_16x16x32_bf16 v[16:19], v[242:245], v[216:219], v[16:19]
	s_waitcnt vmcnt(6)
	ds_write_b128 v152, v[200:203] offset:36864
	s_waitcnt lgkmcnt(7)
	v_mfma_f32_16x16x32_bf16 v[76:79], v[246:249], v[204:207], v[76:79]
	v_mfma_f32_16x16x32_bf16 v[72:75], v[246:249], v[208:211], v[72:75]
	v_mfma_f32_16x16x32_bf16 v[12:15], v[246:249], v[212:215], v[12:15]
	v_mfma_f32_16x16x32_bf16 v[8:11], v[246:249], v[216:219], v[8:11]
	s_waitcnt lgkmcnt(6)
	v_mfma_f32_16x16x32_bf16 v[68:71], v[250:253], v[204:207], v[68:71]
	v_mfma_f32_16x16x32_bf16 v[64:67], v[250:253], v[208:211], v[64:67]
	v_mfma_f32_16x16x32_bf16 v[4:7], v[250:253], v[212:215], v[4:7]
	v_mfma_f32_16x16x32_bf16 v[0:3], v[250:253], v[216:219], v[0:3]
	s_setprio 0
	s_add_i32 s1, s1, 2
	s_cmp_lt_u32 s1, 30
	s_mov_b32 s5, s27
	s_waitcnt lgkmcnt(0)
	s_barrier
	s_cbranch_scc1 .LBB0_208
	s_waitcnt vmcnt(5)
	v_mov_b32_e32 v128, v220
	s_cmp_gt_i32 s26, 15
	v_and_b32_e32 v158, 15, v128
	v_and_b32_e32 v160, 64, v128
	v_and_b32_e32 v129, 0xffffff80, v128
	v_lshrrev_b32_e32 v128, 2, v128
	v_add_u32_e32 v130, s4, v129
	v_and_b32_e32 v159, 12, v128
	s_waitcnt vmcnt(3)
	v_or_b32_e32 v136, v130, v159
	v_ashrrev_i32_e32 v128, 14, v130
	s_waitcnt vmcnt(0)
	v_or_b32_e32 v150, 16, v136
	v_or_b32_e32 v148, 32, v136
	v_or_b32_e32 v146, 48, v136
	v_or_b32_e32 v142, 64, v136
	v_or_b32_e32 v140, 0x50, v136
	v_or_b32_e32 v138, 0x60, v136
	v_or_b32_e32 v134, 0x70, v136
	s_mov_b64 s[4:5], -1
	v_ashrrev_i32_e32 v137, 31, v136
	v_lshlrev_b32_e32 v132, 1, v159
	v_mov_b32_e32 v250, s0
	v_and_b32_e32 v250, 0x80, v250
	v_add_u32_e32 v250, v250, v160
	v_mul_u32_u24_e32 v250, 30, v250
	v_lshrrev_b32_e32 v251, 3, v158
	v_mul_u32_u24_e32 v251, 0xf0, v251
	v_add_u32_e32 v250, v250, v251
	v_lshrrev_b32_e32 v251, 2, v159
	v_mul_u32_u24_e32 v251, 0x7c0, v251
	v_sub_u32_e32 v250, v250, v251
	v_ashrrev_i32_e32 v251, 31, v250
	v_and_b32_e32 v252, 8, v159
	v_lshlrev_b32_e32 v252, 5, v252
	v_and_b32_e32 v253, 4, v159
	v_lshl_or_b32 v252, v253, 1, v252
	v_lshl_or_b32 v252, v158, 4, v252
	v_mov_b32_e32 v253, 0
	v_ashrrev_i32_e32 v129, 31, v128
	v_ashrrev_i32_e32 v151, 31, v150
	v_ashrrev_i32_e32 v149, 31, v148
	v_ashrrev_i32_e32 v147, 31, v146
	v_ashrrev_i32_e32 v143, 31, v142
	v_ashrrev_i32_e32 v141, 31, v140
	v_ashrrev_i32_e32 v139, 31, v138
	v_ashrrev_i32_e32 v135, 31, v134
	s_cbranch_scc0 .LBB0_211
	v_lshl_add_u64 v[144:145], v[136:137], 2, s[8:9]
	global_load_dwordx4 v[162:165], v[144:145], off
	s_add_i32 s1, s0, 0xfffff800
	s_and_b32 s5, s0, 0x180
	s_ashr_i32 s4, s1, 9
	v_or_b32_e32 v154, s5, v160
	s_ashr_i32 s5, s4, 31
	v_lshlrev_b64 v[144:145], 9, v[128:129]
	s_lshl_b64 s[4:5], s[4:5], 7
	v_lshrrev_b32_e32 v152, 7, v130
	v_lshl_add_u64 v[130:131], v[144:145], 0, s[4:5]
	v_and_or_b32 v130, v152, s38, v130
	v_lshlrev_b64 v[130:131], 16, v[130:131]
	v_mov_b32_e32 v133, v153
	v_lshl_or_b32 v130, v154, 7, v130
	v_lshl_add_u64 v[178:179], s[12:13], 0, v[252:253]
	v_mov_b32_e32 v145, v131
	v_mov_b32_e32 v181, v131
	v_lshlrev_b64 v[156:157], 1, v[130:131]
	v_or_b32_e32 v144, 0x800, v130
	v_or_b32_e32 v180, 0x1000, v130
	v_or_b32_e32 v130, 0x1800, v130
	v_lshl_add_u64 v[182:183], v[178:179], 0, v[156:157]
	v_lshlrev_b64 v[154:155], 1, v[144:145]
	v_lshlrev_b64 v[144:145], 1, v[180:181]
	v_lshlrev_b64 v[130:131], 1, v[130:131]
	v_lshl_add_u64 v[176:177], v[150:151], 2, s[8:9]
	v_lshl_add_u64 v[180:181], v[178:179], 0, v[154:155]
	v_lshl_add_u64 v[184:185], v[178:179], 0, v[144:145]
	v_lshl_add_u64 v[178:179], v[178:179], 0, v[130:131]
	s_waitcnt vmcnt(0)
	v_mul_f32_e32 v133, v124, v162
	v_mul_f32_e32 v152, v125, v163
	v_mul_f32_e32 v161, v126, v164
	v_mul_f32_e32 v175, v127, v165
	v_mul_f32_e32 v186, v120, v162
	v_mul_f32_e32 v187, v121, v163
	v_mul_f32_e32 v188, v122, v164
	v_mul_f32_e32 v189, v123, v165
	v_mul_f32_e32 v190, v60, v162
	v_mul_f32_e32 v191, v61, v163
	v_mul_f32_e32 v194, v56, v162
	v_mul_f32_e32 v195, v57, v163
	v_cvt_pk_bf16_f32 v162, v133, v152
	v_cvt_pk_bf16_f32 v163, v161, v175
	v_mul_f32_e32 v192, v62, v164
	v_mul_f32_e32 v193, v63, v165
	v_mul_f32_e32 v196, v58, v164
	v_mul_f32_e32 v197, v59, v165
	v_cvt_pk_bf16_f32 v164, v186, v187
	v_cvt_pk_bf16_f32 v165, v188, v189
	v_cvt_pk_bf16_f32 v186, v190, v191
	v_cvt_pk_bf16_f32 v187, v192, v193
	v_cvt_pk_bf16_f32 v188, v194, v195
	v_cvt_pk_bf16_f32 v189, v196, v197
	global_store_dwordx2 v[182:183], v[162:163], off
	global_store_dwordx2 v[180:181], v[164:165], off
	global_store_dwordx2 v[184:185], v[186:187], off
	global_store_dwordx2 v[178:179], v[188:189], off
	global_load_dwordx4 v[162:165], v[176:177], off
	v_bitop3_b32 v133, v136, 28, 16 bitop3:0xc8
	v_lshlrev_b32_e32 v152, 1, v133
	v_lshl_add_u64 v[178:179], s[12:13], 0, v[252:253]
	v_lshl_add_u64 v[180:181], v[178:179], 0, v[156:157]
	v_lshl_add_u64 v[176:177], v[148:149], 2, s[8:9]
	v_lshl_add_u64 v[182:183], v[178:179], 0, v[154:155]
	v_lshl_add_u64 v[184:185], v[178:179], 0, v[144:145]
	v_lshl_add_u64 v[178:179], v[178:179], 0, v[130:131]
	s_waitcnt vmcnt(0)
	v_mul_f32_e32 v133, v116, v162
	v_mul_f32_e32 v152, v117, v163
	v_mul_f32_e32 v161, v118, v164
	v_mul_f32_e32 v175, v119, v165
	v_mul_f32_e32 v186, v112, v162
	v_mul_f32_e32 v187, v113, v163
	v_mul_f32_e32 v188, v114, v164
	v_mul_f32_e32 v189, v115, v165
	v_mul_f32_e32 v190, v52, v162
	v_mul_f32_e32 v191, v53, v163
	v_mul_f32_e32 v194, v48, v162
	v_mul_f32_e32 v195, v49, v163
	v_cvt_pk_bf16_f32 v162, v133, v152
	v_cvt_pk_bf16_f32 v163, v161, v175
	v_mul_f32_e32 v192, v54, v164
	v_mul_f32_e32 v193, v55, v165
	v_mul_f32_e32 v196, v50, v164
	v_mul_f32_e32 v197, v51, v165
	v_cvt_pk_bf16_f32 v164, v186, v187
	v_cvt_pk_bf16_f32 v165, v188, v189
	v_cvt_pk_bf16_f32 v186, v190, v191
	v_cvt_pk_bf16_f32 v187, v192, v193
	v_cvt_pk_bf16_f32 v188, v194, v195
	v_cvt_pk_bf16_f32 v189, v196, v197
	global_store_dwordx2 v[180:181], v[162:163], off offset:512
	global_store_dwordx2 v[182:183], v[164:165], off offset:512
	global_store_dwordx2 v[184:185], v[186:187], off offset:512
	global_store_dwordx2 v[178:179], v[188:189], off offset:512
	global_load_dwordx4 v[162:165], v[176:177], off
	v_bitop3_b32 v133, v136, 44, 32 bitop3:0xc8
	v_lshlrev_b32_e32 v152, 1, v133
	v_lshl_add_u64 v[178:179], s[12:13], 0, v[252:253]
	v_lshl_add_u64 v[180:181], v[178:179], 0, v[156:157]
	v_lshl_add_u64 v[176:177], v[146:147], 2, s[8:9]
	v_lshl_add_u64 v[182:183], v[178:179], 0, v[154:155]
	v_lshl_add_u64 v[184:185], v[178:179], 0, v[144:145]
	v_lshl_add_u64 v[178:179], v[178:179], 0, v[130:131]
	s_waitcnt vmcnt(0)
	v_mul_f32_e32 v133, v108, v162
	v_mul_f32_e32 v152, v109, v163
	v_mul_f32_e32 v161, v110, v164
	v_mul_f32_e32 v175, v111, v165
	v_mul_f32_e32 v186, v104, v162
	v_mul_f32_e32 v187, v105, v163
	v_mul_f32_e32 v188, v106, v164
	v_mul_f32_e32 v189, v107, v165
	v_mul_f32_e32 v190, v44, v162
	v_mul_f32_e32 v191, v45, v163
	v_mul_f32_e32 v194, v40, v162
	v_mul_f32_e32 v195, v41, v163
	v_cvt_pk_bf16_f32 v162, v133, v152
	v_cvt_pk_bf16_f32 v163, v161, v175
	v_mul_f32_e32 v192, v46, v164
	v_mul_f32_e32 v193, v47, v165
	v_mul_f32_e32 v196, v42, v164
	v_mul_f32_e32 v197, v43, v165
	v_cvt_pk_bf16_f32 v164, v186, v187
	v_cvt_pk_bf16_f32 v165, v188, v189
	v_cvt_pk_bf16_f32 v186, v190, v191
	v_cvt_pk_bf16_f32 v187, v192, v193
	v_cvt_pk_bf16_f32 v188, v194, v195
	v_cvt_pk_bf16_f32 v189, v196, v197
	global_store_dwordx2 v[180:181], v[162:163], off offset:1024
	global_store_dwordx2 v[182:183], v[164:165], off offset:1024
	global_store_dwordx2 v[184:185], v[186:187], off offset:1024
	global_store_dwordx2 v[178:179], v[188:189], off offset:1024
	global_load_dwordx4 v[162:165], v[176:177], off
	v_bitop3_b32 v133, v136, 60, 48 bitop3:0xc8
	v_lshlrev_b32_e32 v152, 1, v133
	v_lshl_add_u64 v[178:179], s[12:13], 0, v[252:253]
	v_lshl_add_u64 v[180:181], v[178:179], 0, v[156:157]
	v_lshl_add_u64 v[176:177], v[142:143], 2, s[8:9]
	v_lshl_add_u64 v[182:183], v[178:179], 0, v[154:155]
	v_lshl_add_u64 v[184:185], v[178:179], 0, v[144:145]
	v_lshl_add_u64 v[178:179], v[178:179], 0, v[130:131]
	s_waitcnt vmcnt(0)
	v_mul_f32_e32 v133, v100, v162
	v_mul_f32_e32 v152, v101, v163
	v_mul_f32_e32 v161, v102, v164
	v_mul_f32_e32 v175, v103, v165
	v_mul_f32_e32 v186, v96, v162
	v_mul_f32_e32 v187, v97, v163
	v_mul_f32_e32 v188, v98, v164
	v_mul_f32_e32 v189, v99, v165
	v_mul_f32_e32 v190, v36, v162
	v_mul_f32_e32 v191, v37, v163
	v_mul_f32_e32 v194, v32, v162
	v_mul_f32_e32 v195, v33, v163
	v_cvt_pk_bf16_f32 v162, v133, v152
	v_cvt_pk_bf16_f32 v163, v161, v175
	v_mul_f32_e32 v192, v38, v164
	v_mul_f32_e32 v193, v39, v165
	v_mul_f32_e32 v196, v34, v164
	v_mul_f32_e32 v197, v35, v165
	v_cvt_pk_bf16_f32 v164, v186, v187
	v_cvt_pk_bf16_f32 v165, v188, v189
	v_cvt_pk_bf16_f32 v186, v190, v191
	v_cvt_pk_bf16_f32 v187, v192, v193
	v_cvt_pk_bf16_f32 v188, v194, v195
	v_cvt_pk_bf16_f32 v189, v196, v197
	global_store_dwordx2 v[180:181], v[162:163], off offset:1536
	global_store_dwordx2 v[182:183], v[164:165], off offset:1536
	global_store_dwordx2 v[184:185], v[186:187], off offset:1536
	global_store_dwordx2 v[178:179], v[188:189], off offset:1536
	global_load_dwordx4 v[162:165], v[176:177], off
	v_bitop3_b32 v133, v136, s39, 64 bitop3:0xc8
	v_lshlrev_b32_e32 v152, 1, v133
	v_lshl_add_u64 v[178:179], s[12:13], 0, v[252:253]
	v_lshl_add_u64 v[180:181], v[178:179], 0, v[156:157]
	v_lshl_add_u64 v[176:177], v[140:141], 2, s[8:9]
	v_lshl_add_u64 v[182:183], v[178:179], 0, v[154:155]
	v_lshl_add_u64 v[184:185], v[178:179], 0, v[144:145]
	v_lshl_add_u64 v[178:179], v[178:179], 0, v[130:131]
	s_waitcnt vmcnt(0)
	v_mul_f32_e32 v133, v92, v162
	v_mul_f32_e32 v152, v93, v163
	v_mul_f32_e32 v161, v94, v164
	v_mul_f32_e32 v175, v95, v165
	v_mul_f32_e32 v186, v88, v162
	v_mul_f32_e32 v187, v89, v163
	v_mul_f32_e32 v188, v90, v164
	v_mul_f32_e32 v189, v91, v165
	v_mul_f32_e32 v190, v28, v162
	v_mul_f32_e32 v191, v29, v163
	v_mul_f32_e32 v194, v24, v162
	v_mul_f32_e32 v195, v25, v163
	v_cvt_pk_bf16_f32 v162, v133, v152
	v_cvt_pk_bf16_f32 v163, v161, v175
	v_mul_f32_e32 v192, v30, v164
	v_mul_f32_e32 v193, v31, v165
	v_mul_f32_e32 v196, v26, v164
	v_mul_f32_e32 v197, v27, v165
	v_cvt_pk_bf16_f32 v164, v186, v187
	v_cvt_pk_bf16_f32 v165, v188, v189
	v_cvt_pk_bf16_f32 v186, v190, v191
	v_cvt_pk_bf16_f32 v187, v192, v193
	v_cvt_pk_bf16_f32 v188, v194, v195
	v_cvt_pk_bf16_f32 v189, v196, v197
	global_store_dwordx2 v[180:181], v[162:163], off offset:2048
	global_store_dwordx2 v[182:183], v[164:165], off offset:2048
	global_store_dwordx2 v[184:185], v[186:187], off offset:2048
	global_store_dwordx2 v[178:179], v[188:189], off offset:2048
	global_load_dwordx4 v[162:165], v[176:177], off
	v_bitop3_b32 v133, v136, s40, v166 bitop3:0xc8
	v_lshlrev_b32_e32 v152, 1, v133
	v_lshl_add_u64 v[178:179], s[12:13], 0, v[252:253]
	v_lshl_add_u64 v[180:181], v[178:179], 0, v[156:157]
	v_lshl_add_u64 v[176:177], v[138:139], 2, s[8:9]
	v_lshl_add_u64 v[182:183], v[178:179], 0, v[154:155]
	v_lshl_add_u64 v[184:185], v[178:179], 0, v[144:145]
	v_lshl_add_u64 v[178:179], v[178:179], 0, v[130:131]
	s_waitcnt vmcnt(0)
	v_mul_f32_e32 v133, v84, v162
	v_mul_f32_e32 v152, v85, v163
	v_mul_f32_e32 v161, v86, v164
	v_mul_f32_e32 v175, v87, v165
	v_mul_f32_e32 v186, v80, v162
	v_mul_f32_e32 v187, v81, v163
	v_mul_f32_e32 v188, v82, v164
	v_mul_f32_e32 v189, v83, v165
	v_mul_f32_e32 v190, v20, v162
	v_mul_f32_e32 v191, v21, v163
	v_mul_f32_e32 v194, v16, v162
	v_mul_f32_e32 v195, v17, v163
	v_cvt_pk_bf16_f32 v162, v133, v152
	v_cvt_pk_bf16_f32 v163, v161, v175
	v_mul_f32_e32 v192, v22, v164
	v_mul_f32_e32 v193, v23, v165
	v_mul_f32_e32 v196, v18, v164
	v_mul_f32_e32 v197, v19, v165
	v_cvt_pk_bf16_f32 v164, v186, v187
	v_cvt_pk_bf16_f32 v165, v188, v189
	v_cvt_pk_bf16_f32 v186, v190, v191
	v_cvt_pk_bf16_f32 v187, v192, v193
	v_cvt_pk_bf16_f32 v188, v194, v195
	v_cvt_pk_bf16_f32 v189, v196, v197
	global_store_dwordx2 v[180:181], v[162:163], off offset:2560
	global_store_dwordx2 v[182:183], v[164:165], off offset:2560
	global_store_dwordx2 v[184:185], v[186:187], off offset:2560
	global_store_dwordx2 v[178:179], v[188:189], off offset:2560
	global_load_dwordx4 v[162:165], v[176:177], off
	v_bitop3_b32 v133, v136, s41, v167 bitop3:0xc8
	v_lshlrev_b32_e32 v152, 1, v133
	v_lshl_add_u64 v[178:179], s[12:13], 0, v[252:253]
	v_lshl_add_u64 v[180:181], v[178:179], 0, v[156:157]
	v_lshl_add_u64 v[176:177], v[134:135], 2, s[8:9]
	v_lshl_add_u64 v[182:183], v[178:179], 0, v[154:155]
	v_lshl_add_u64 v[184:185], v[178:179], 0, v[144:145]
	v_lshl_add_u64 v[178:179], v[178:179], 0, v[130:131]
	s_waitcnt vmcnt(0)
	v_mul_f32_e32 v133, v76, v162
	v_mul_f32_e32 v152, v77, v163
	v_mul_f32_e32 v161, v78, v164
	v_mul_f32_e32 v175, v79, v165
	v_mul_f32_e32 v186, v72, v162
	v_mul_f32_e32 v187, v73, v163
	v_mul_f32_e32 v188, v74, v164
	v_mul_f32_e32 v189, v75, v165
	v_mul_f32_e32 v190, v12, v162
	v_mul_f32_e32 v191, v13, v163
	v_mul_f32_e32 v194, v8, v162
	v_mul_f32_e32 v195, v9, v163
	v_cvt_pk_bf16_f32 v162, v133, v152
	v_cvt_pk_bf16_f32 v163, v161, v175
	v_mul_f32_e32 v192, v14, v164
	v_mul_f32_e32 v193, v15, v165
	v_mul_f32_e32 v196, v10, v164
	v_mul_f32_e32 v197, v11, v165
	v_cvt_pk_bf16_f32 v164, v186, v187
	v_cvt_pk_bf16_f32 v165, v188, v189
	v_cvt_pk_bf16_f32 v186, v190, v191
	v_cvt_pk_bf16_f32 v187, v192, v193
	v_cvt_pk_bf16_f32 v188, v194, v195
	v_cvt_pk_bf16_f32 v189, v196, v197
	global_store_dwordx2 v[180:181], v[162:163], off offset:3072
	global_store_dwordx2 v[182:183], v[164:165], off offset:3072
	global_store_dwordx2 v[184:185], v[186:187], off offset:3072
	global_store_dwordx2 v[178:179], v[188:189], off offset:3072
	global_load_dwordx4 v[162:165], v[176:177], off
	v_bitop3_b32 v133, v136, s42, v168 bitop3:0xc8
	v_lshlrev_b32_e32 v152, 1, v133
	v_lshl_add_u64 v[176:177], s[12:13], 0, v[252:253]
	v_lshl_add_u64 v[156:157], v[176:177], 0, v[156:157]
	v_lshl_add_u64 v[154:155], v[176:177], 0, v[154:155]
	v_lshl_add_u64 v[144:145], v[176:177], 0, v[144:145]
	v_lshl_add_u64 v[130:131], v[176:177], 0, v[130:131]
	s_waitcnt vmcnt(0)
	v_mul_f32_e32 v133, v68, v162
	v_mul_f32_e32 v152, v69, v163
	v_mul_f32_e32 v161, v70, v164
	v_mul_f32_e32 v175, v71, v165
	v_mul_f32_e32 v176, v64, v162
	v_mul_f32_e32 v177, v65, v163
	v_mul_f32_e32 v178, v66, v164
	v_mul_f32_e32 v179, v67, v165
	v_mul_f32_e32 v180, v4, v162
	v_mul_f32_e32 v181, v5, v163
	v_mul_f32_e32 v184, v0, v162
	v_mul_f32_e32 v185, v1, v163
	v_cvt_pk_bf16_f32 v162, v133, v152
	v_cvt_pk_bf16_f32 v163, v161, v175
	v_mul_f32_e32 v182, v6, v164
	v_mul_f32_e32 v183, v7, v165
	v_mul_f32_e32 v186, v2, v164
	v_mul_f32_e32 v187, v3, v165
	v_cvt_pk_bf16_f32 v164, v176, v177
	v_cvt_pk_bf16_f32 v165, v178, v179
	v_cvt_pk_bf16_f32 v176, v180, v181
	v_cvt_pk_bf16_f32 v177, v182, v183
	v_cvt_pk_bf16_f32 v178, v184, v185
	v_cvt_pk_bf16_f32 v179, v186, v187
	global_store_dwordx2 v[156:157], v[162:163], off offset:3584
	global_store_dwordx2 v[154:155], v[164:165], off offset:3584
	global_store_dwordx2 v[144:145], v[176:177], off offset:3584
	global_store_dwordx2 v[130:131], v[178:179], off offset:3584
	s_cbranch_execnz .LBB0_206
	s_branch .LBB0_212

.LBB0_502:
	s_ashr_i32 s14, s34, 3
	s_lshr_b32 s28, s14, 28
	s_add_i32 s28, s14, s28
	s_and_b32 s29, s28, -16
	s_sub_i32 s33, s14, s29
	s_lshl_b32 s14, s28, 7
	s_lshl_b32 s28, s34, 8
	s_and_b32 s14, s14, 0xfffff800
	s_and_b32 s28, s28, 0x700
	s_or_b32 s28, s14, s28
	s_ashr_i32 s29, s28, 31
	s_lshl_b32 s35, s33, 7
	s_lshl_b64 s[36:37], s[28:29], 11
	s_add_u32 s36, s3, s36
	s_addc_u32 s37, s4, s37
	s_add_i32 s14, s35, 0x1000
	v_mov_b32_e32 v36, v220
	s_lshl_b64 s[38:39], s[14:15], 11
	s_add_u32 s38, s72, s38
	v_ashrrev_i32_e32 v26, 2, v36
	v_ashrrev_i32_e32 v27, 31, v26
	s_addc_u32 s39, s73, s39
	v_lshlrev_b64 v[0:1], 11, v[26:27]
	v_lshlrev_b32_e32 v4, 4, v36
	v_lshl_add_u64 v[2:3], s[38:39], 0, v[0:1]
	v_lshl_add_u64 v[0:1], s[36:37], 0, v[0:1]
	v_and_b32_e32 v152, 48, v4
	v_lshl_add_u64 v[154:155], v[0:1], 0, v[152:153]
	v_add_co_u32_e32 v28, vcc, s27, v154
	v_lshl_add_u64 v[156:157], v[2:3], 0, v[152:153]
	s_nop 0
	v_addc_co_u32_e32 v29, vcc, 0, v155, vcc
	v_add_co_u32_e32 v30, vcc, s30, v154
	global_load_dwordx4 v[2:5], v[154:155], off
	s_nop 0
	v_addc_co_u32_e32 v31, vcc, 0, v155, vcc
	v_add_co_u32_e32 v32, vcc, s31, v154
	global_load_dwordx4 v[6:9], v[28:29], off
	s_nop 0
	v_addc_co_u32_e32 v33, vcc, 0, v155, vcc
	v_add_co_u32_e32 v34, vcc, s27, v156
	global_load_dwordx4 v[10:13], v[30:31], off
	s_nop 0
	v_addc_co_u32_e32 v35, vcc, 0, v157, vcc
	global_load_dwordx4 v[14:17], v[32:33], off
	global_load_dwordx4 v[18:21], v[156:157], off
	global_load_dwordx4 v[22:25], v[34:35], off
	global_load_dwordx4 v[44:47], v[154:155], off offset:64
	global_load_dwordx4 v[60:63], v[28:29], off offset:64
	global_load_dwordx4 v[68:71], v[30:31], off offset:64
	global_load_dwordx4 v[140:143], v[32:33], off offset:64
	global_load_dwordx4 v[52:55], v[156:157], off offset:64
	global_load_dwordx4 v[144:147], v[34:35], off offset:64
	v_lshrrev_b32_e32 v27, 4, v36
	v_lshrrev_b32_e32 v37, 2, v36
	v_sub_u32_e32 v40, 0, v27
	v_sub_u32_e32 v37, 0, v37
	v_and_b32_e32 v38, 0x3ffff8f, v36
	v_lshlrev_b32_e32 v39, 6, v36
	v_xor_b32_e32 v36, v36, v40
	v_xor_b32_e32 v27, v27, v37
	v_lshlrev_b32_e32 v36, 4, v36
	v_lshlrev_b32_e32 v27, 4, v27
	v_and_b32_e32 v41, 0x1000, v39
	v_and_b32_e32 v36, 48, v36
	v_and_b32_e32 v27, 48, v27
	v_and_b32_e32 v42, 0x3c0, v39
	v_and_b32_e32 v39, 0xffffe3c0, v39
	v_lshl_add_u32 v38, v38, 6, v194
	v_lshl_or_b32 v152, v26, 6, v36
	v_or_b32_e32 v26, v27, v41
	s_mov_b32 s29, -2
	s_mov_b32 s36, s15
	v_mov_b32_e32 v0, 0
	v_mov_b32_e32 v1, v153
	v_or3_b32 v166, v41, v42, v27
	v_add_u32_e32 v167, v27, v39
	v_add_u32_e32 v168, v27, v38
	v_add_u32_e32 v169, v26, v42
	v_lshl_add_u64 v[158:159], v[154:155], 0, s[16:17]
	v_lshl_add_u64 v[160:161], v[154:155], 0, s[22:23]
	v_lshl_add_u64 v[162:163], v[154:155], 0, s[24:25]
	v_lshl_add_u64 v[164:165], v[156:157], 0, s[16:17]
	v_mov_b32_e32 v26, v153
	v_mov_b32_e32 v27, v153
	v_mov_b32_e32 v28, 0
	v_mov_b32_e32 v29, v153
	v_mov_b32_e32 v30, v153
	v_mov_b32_e32 v31, v153
	v_mov_b32_e32 v32, 0
	v_mov_b32_e32 v33, v153
	v_mov_b32_e32 v34, v153
	v_mov_b32_e32 v35, v153
	v_mov_b32_e32 v36, 0
	v_mov_b32_e32 v37, v153
	v_mov_b32_e32 v38, v153
	v_mov_b32_e32 v39, v153
	v_mov_b32_e32 v40, 0
	v_mov_b32_e32 v41, v153
	v_mov_b32_e32 v42, v153
	v_mov_b32_e32 v43, v153
	v_mov_b32_e32 v48, 0
	s_waitcnt vmcnt(11)
	ds_write_b128 v152, v[2:5]
	s_waitcnt vmcnt(10)
	ds_write_b128 v152, v[6:9] offset:4096
	s_waitcnt vmcnt(9)
	ds_write_b128 v152, v[10:13] offset:8192
	s_waitcnt vmcnt(8)
	ds_write_b128 v152, v[14:17] offset:12288
	s_waitcnt vmcnt(7)
	ds_write_b128 v152, v[18:21] offset:32768
	s_waitcnt vmcnt(6)
	ds_write_b128 v152, v[22:25] offset:36864
	v_mov_b32_e32 v2, v153
	v_mov_b32_e32 v3, v153
	v_mov_b32_e32 v4, 0
	v_mov_b32_e32 v5, v153
	v_mov_b32_e32 v6, v153
	v_mov_b32_e32 v7, v153
	v_mov_b32_e32 v8, 0
	v_mov_b32_e32 v9, v153
	v_mov_b32_e32 v10, v153
	v_mov_b32_e32 v11, v153
	v_mov_b32_e32 v12, 0
	v_mov_b32_e32 v13, v153
	v_mov_b32_e32 v14, v153
	v_mov_b32_e32 v15, v153
	v_mov_b32_e32 v16, 0
	v_mov_b32_e32 v17, v153
	v_mov_b32_e32 v18, v153
	v_mov_b32_e32 v19, v153
	v_mov_b32_e32 v20, 0
	v_mov_b32_e32 v21, v153
	v_mov_b32_e32 v22, v153
	v_mov_b32_e32 v23, v153
	v_mov_b32_e32 v24, 0
	v_mov_b32_e32 v25, v153
	v_mov_b32_e32 v49, v153
	v_mov_b32_e32 v50, v153
	v_mov_b32_e32 v51, v153
	v_mov_b32_e32 v56, 0
	v_mov_b32_e32 v57, v153
	v_mov_b32_e32 v58, v153
	v_mov_b32_e32 v59, v153
	v_mov_b32_e32 v64, 0
	v_mov_b32_e32 v65, v153
	v_mov_b32_e32 v66, v153
	v_mov_b32_e32 v67, v153
	v_mov_b32_e32 v72, 0
	v_mov_b32_e32 v73, v153
	v_mov_b32_e32 v74, v153
	v_mov_b32_e32 v75, v153
	v_mov_b32_e32 v76, 0
	v_mov_b32_e32 v77, v153
	v_mov_b32_e32 v78, v153
	v_mov_b32_e32 v79, v153
	v_mov_b32_e32 v80, 0
	v_mov_b32_e32 v81, v153
	v_mov_b32_e32 v82, v153
	v_mov_b32_e32 v83, v153
	v_mov_b32_e32 v84, 0
	v_mov_b32_e32 v85, v153
	v_mov_b32_e32 v86, v153
	v_mov_b32_e32 v87, v153
	v_mov_b32_e32 v88, 0
	v_mov_b32_e32 v89, v153
	v_mov_b32_e32 v90, v153
	v_mov_b32_e32 v91, v153
	v_mov_b32_e32 v92, 0
	v_mov_b32_e32 v93, v153
	v_mov_b32_e32 v94, v153
	v_mov_b32_e32 v95, v153
	v_mov_b32_e32 v96, 0
	v_mov_b32_e32 v97, v153
	v_mov_b32_e32 v98, v153
	v_mov_b32_e32 v99, v153
	v_mov_b32_e32 v100, 0
	v_mov_b32_e32 v101, v153
	v_mov_b32_e32 v102, v153
	v_mov_b32_e32 v103, v153
	v_mov_b32_e32 v104, 0
	v_mov_b32_e32 v105, v153
	v_mov_b32_e32 v106, v153
	v_mov_b32_e32 v107, v153
	v_mov_b32_e32 v108, 0
	v_mov_b32_e32 v109, v153
	v_mov_b32_e32 v110, v153
	v_mov_b32_e32 v111, v153
	v_mov_b32_e32 v112, 0
	v_mov_b32_e32 v113, v153
	v_mov_b32_e32 v114, v153
	v_mov_b32_e32 v115, v153
	v_mov_b32_e32 v116, 0
	v_mov_b32_e32 v117, v153
	v_mov_b32_e32 v118, v153
	v_mov_b32_e32 v119, v153
	v_mov_b32_e32 v120, 0
	v_mov_b32_e32 v121, v153
	v_mov_b32_e32 v122, v153
	v_mov_b32_e32 v123, v153
	v_mov_b32_e32 v124, 0
	v_mov_b32_e32 v125, v153
	v_mov_b32_e32 v126, v153
	v_mov_b32_e32 v127, v153
	v_mov_b32_e32 v128, 0
	v_mov_b32_e32 v129, v153
	v_mov_b32_e32 v130, v153
	v_mov_b32_e32 v131, v153
	v_mov_b32_e32 v132, 0
	v_mov_b32_e32 v133, v153
	v_mov_b32_e32 v134, v153
	v_mov_b32_e32 v135, v153
	v_mov_b32_e32 v136, 0
	v_mov_b32_e32 v137, v153
	v_mov_b32_e32 v138, v153
	v_mov_b32_e32 v139, v153
	v_mov_b32_e32 v148, 0
	v_mov_b32_e32 v149, v153
	v_mov_b32_e32 v150, v153
	v_mov_b32_e32 v151, v153
	s_waitcnt lgkmcnt(0)
	s_barrier
	s_cmpk_lt_u32 s2, 0x100
	s_cbranch_scc1 .Lstag_1
	s_sleep 8
.Lstag_1:
.LBB0_503:
	s_add_i32 s37, s36, 64
	s_min_u32 s14, s37, 0x3e0
	s_lshl_b32 s14, s14, 1
	v_lshl_add_u64 v[170:171], v[154:155], 0, s[14:15]
	v_lshl_add_u64 v[174:175], v[158:159], 0, s[14:15]
	v_lshl_add_u64 v[178:179], v[160:161], 0, s[14:15]
	v_lshl_add_u64 v[182:183], v[162:163], 0, s[14:15]
	v_lshl_add_u64 v[186:187], v[156:157], 0, s[14:15]
	v_lshl_add_u64 v[190:191], v[164:165], 0, s[14:15]
	global_load_dwordx4 v[170:173], v[170:171], off
	ds_read_b128 v[196:199], v169 offset:32768
	global_load_dwordx4 v[174:177], v[174:175], off
	ds_read_b128 v[200:203], v169 offset:33792
	global_load_dwordx4 v[178:181], v[178:179], off
	ds_read_b128 v[204:207], v169 offset:34816
	global_load_dwordx4 v[182:185], v[182:183], off
	ds_read_b128 v[208:211], v169 offset:35840
	global_load_dwordx4 v[186:189], v[186:187], off
	ds_read_b128 v[212:215], v167
	global_load_dwordx4 v[190:193], v[190:191], off
	ds_read_b128 v[216:219], v167 offset:1024
	ds_read_b128 v[222:225], v167 offset:2048
	ds_read_b128 v[226:229], v167 offset:3072
	ds_read_b128 v[230:233], v167 offset:4096
	ds_read_b128 v[234:237], v167 offset:5120
	ds_read_b128 v[238:241], v167 offset:6144
	ds_read_b128 v[242:245], v167 offset:7168
	s_setprio 1
	s_waitcnt lgkmcnt(7)
	v_mfma_f32_16x16x32_bf16 v[148:151], v[196:199], v[212:215], v[148:151]
	v_mfma_f32_16x16x32_bf16 v[136:139], v[200:203], v[212:215], v[136:139]
	v_mfma_f32_16x16x32_bf16 v[132:135], v[204:207], v[212:215], v[132:135]
	v_mfma_f32_16x16x32_bf16 v[128:131], v[208:211], v[212:215], v[128:131]
	s_waitcnt vmcnt(11)
	ds_write_b128 v152, v[44:47] offset:16384
	s_waitcnt lgkmcnt(7)
	v_mfma_f32_16x16x32_bf16 v[124:127], v[196:199], v[216:219], v[124:127]
	v_mfma_f32_16x16x32_bf16 v[120:123], v[200:203], v[216:219], v[120:123]
	v_mfma_f32_16x16x32_bf16 v[116:119], v[204:207], v[216:219], v[116:119]
	v_mfma_f32_16x16x32_bf16 v[112:115], v[208:211], v[216:219], v[112:115]
	s_waitcnt vmcnt(9)
	ds_write_b128 v152, v[60:63] offset:20480
	s_waitcnt lgkmcnt(7)
	v_mfma_f32_16x16x32_bf16 v[108:111], v[196:199], v[222:225], v[108:111]
	v_mfma_f32_16x16x32_bf16 v[104:107], v[200:203], v[222:225], v[104:107]
	v_mfma_f32_16x16x32_bf16 v[100:103], v[204:207], v[222:225], v[100:103]
	v_mfma_f32_16x16x32_bf16 v[96:99], v[208:211], v[222:225], v[96:99]
	s_waitcnt vmcnt(8)
	ds_write_b128 v152, v[68:71] offset:24576
	s_waitcnt lgkmcnt(7)
	v_mfma_f32_16x16x32_bf16 v[92:95], v[196:199], v[226:229], v[92:95]
	v_mfma_f32_16x16x32_bf16 v[88:91], v[200:203], v[226:229], v[88:91]
	v_mfma_f32_16x16x32_bf16 v[84:87], v[204:207], v[226:229], v[84:87]
	v_mfma_f32_16x16x32_bf16 v[80:83], v[208:211], v[226:229], v[80:83]
	s_waitcnt vmcnt(7)
	ds_write_b128 v152, v[140:143] offset:28672
	s_waitcnt lgkmcnt(7)
	v_mfma_f32_16x16x32_bf16 v[76:79], v[196:199], v[230:233], v[76:79]
	v_mfma_f32_16x16x32_bf16 v[72:75], v[200:203], v[230:233], v[72:75]
	v_mfma_f32_16x16x32_bf16 v[64:67], v[204:207], v[230:233], v[64:67]
	v_mfma_f32_16x16x32_bf16 v[56:59], v[208:211], v[230:233], v[56:59]
	s_waitcnt vmcnt(7)
	ds_write_b128 v152, v[52:55] offset:40960
	s_waitcnt lgkmcnt(7)
	v_mfma_f32_16x16x32_bf16 v[48:51], v[196:199], v[234:237], v[48:51]
	v_mfma_f32_16x16x32_bf16 v[40:43], v[200:203], v[234:237], v[40:43]
	v_mfma_f32_16x16x32_bf16 v[36:39], v[204:207], v[234:237], v[36:39]
	v_mfma_f32_16x16x32_bf16 v[32:35], v[208:211], v[234:237], v[32:35]
	s_waitcnt vmcnt(6)
	ds_write_b128 v152, v[144:147] offset:45056
	s_waitcnt lgkmcnt(7)
	v_mfma_f32_16x16x32_bf16 v[28:31], v[196:199], v[238:241], v[28:31]
	v_mfma_f32_16x16x32_bf16 v[24:27], v[200:203], v[238:241], v[24:27]
	v_mfma_f32_16x16x32_bf16 v[20:23], v[204:207], v[238:241], v[20:23]
	v_mfma_f32_16x16x32_bf16 v[16:19], v[208:211], v[238:241], v[16:19]
	s_waitcnt lgkmcnt(6)
	v_mfma_f32_16x16x32_bf16 v[12:15], v[196:199], v[242:245], v[12:15]
	v_mfma_f32_16x16x32_bf16 v[8:11], v[200:203], v[242:245], v[8:11]
	v_mfma_f32_16x16x32_bf16 v[4:7], v[204:207], v[242:245], v[4:7]
	v_mfma_f32_16x16x32_bf16 v[0:3], v[208:211], v[242:245], v[0:3]
	s_setprio 0
	s_min_u32 s14, s36, 0x380
	s_lshl_b32 s14, s14, 1
	s_mov_b32 s39, s15
	s_add_i32 s38, s14, 0xc0
	v_lshl_add_u64 v[44:45], v[154:155], 0, s[14:15]
	v_lshl_add_u64 v[52:53], v[156:157], 0, s[14:15]
	v_lshl_add_u64 v[60:61], v[158:159], 0, s[38:39]
	v_lshl_add_u64 v[68:69], v[160:161], 0, s[38:39]
	v_lshl_add_u64 v[140:141], v[162:163], 0, s[38:39]
	v_lshl_add_u64 v[144:145], v[164:165], 0, s[38:39]
	s_waitcnt lgkmcnt(0)
	s_barrier
	global_load_dwordx4 v[44:47], v[44:45], off offset:192
	ds_read_b128 v[196:199], v166 offset:40960
	global_load_dwordx4 v[52:55], v[52:53], off offset:192
	ds_read_b128 v[200:203], v166 offset:41984
	global_load_dwordx4 v[60:63], v[60:61], off
	ds_read_b128 v[204:207], v166 offset:43008
	global_load_dwordx4 v[68:71], v[68:69], off
	ds_read_b128 v[208:211], v166 offset:44032
	global_load_dwordx4 v[140:143], v[140:141], off
	ds_read_b128 v[212:215], v168
	global_load_dwordx4 v[144:147], v[144:145], off
	ds_read_b128 v[216:219], v168 offset:1024
	ds_read_b128 v[222:225], v168 offset:2048
	ds_read_b128 v[226:229], v168 offset:3072
	ds_read_b128 v[230:233], v168 offset:4096
	ds_read_b128 v[234:237], v168 offset:5120
	ds_read_b128 v[238:241], v168 offset:6144
	ds_read_b128 v[242:245], v168 offset:7168
	s_setprio 1
	s_waitcnt lgkmcnt(7)
	v_mfma_f32_16x16x32_bf16 v[148:151], v[196:199], v[212:215], v[148:151]
	v_mfma_f32_16x16x32_bf16 v[136:139], v[200:203], v[212:215], v[136:139]
	v_mfma_f32_16x16x32_bf16 v[132:135], v[204:207], v[212:215], v[132:135]
	v_mfma_f32_16x16x32_bf16 v[128:131], v[208:211], v[212:215], v[128:131]
	s_waitcnt vmcnt(11)
	ds_write_b128 v152, v[170:173]
	s_waitcnt lgkmcnt(7)
	v_mfma_f32_16x16x32_bf16 v[124:127], v[196:199], v[216:219], v[124:127]
	v_mfma_f32_16x16x32_bf16 v[120:123], v[200:203], v[216:219], v[120:123]
	v_mfma_f32_16x16x32_bf16 v[116:119], v[204:207], v[216:219], v[116:119]
	v_mfma_f32_16x16x32_bf16 v[112:115], v[208:211], v[216:219], v[112:115]
	s_waitcnt vmcnt(10)
	ds_write_b128 v152, v[174:177] offset:4096
	s_waitcnt lgkmcnt(7)
	v_mfma_f32_16x16x32_bf16 v[108:111], v[196:199], v[222:225], v[108:111]
	v_mfma_f32_16x16x32_bf16 v[104:107], v[200:203], v[222:225], v[104:107]
	v_mfma_f32_16x16x32_bf16 v[100:103], v[204:207], v[222:225], v[100:103]
	v_mfma_f32_16x16x32_bf16 v[96:99], v[208:211], v[222:225], v[96:99]
	s_waitcnt vmcnt(9)
	ds_write_b128 v152, v[178:181] offset:8192
	s_waitcnt lgkmcnt(7)
	v_mfma_f32_16x16x32_bf16 v[92:95], v[196:199], v[226:229], v[92:95]
	v_mfma_f32_16x16x32_bf16 v[88:91], v[200:203], v[226:229], v[88:91]
	v_mfma_f32_16x16x32_bf16 v[84:87], v[204:207], v[226:229], v[84:87]
	v_mfma_f32_16x16x32_bf16 v[80:83], v[208:211], v[226:229], v[80:83]
	s_waitcnt vmcnt(8)
	ds_write_b128 v152, v[182:185] offset:12288
	s_waitcnt lgkmcnt(7)
	v_mfma_f32_16x16x32_bf16 v[76:79], v[196:199], v[230:233], v[76:79]
	v_mfma_f32_16x16x32_bf16 v[72:75], v[200:203], v[230:233], v[72:75]
	v_mfma_f32_16x16x32_bf16 v[64:67], v[204:207], v[230:233], v[64:67]
	v_mfma_f32_16x16x32_bf16 v[56:59], v[208:211], v[230:233], v[56:59]
	s_waitcnt vmcnt(7)
	ds_write_b128 v152, v[186:189] offset:32768
	s_waitcnt lgkmcnt(7)
	v_mfma_f32_16x16x32_bf16 v[48:51], v[196:199], v[234:237], v[48:51]
	v_mfma_f32_16x16x32_bf16 v[40:43], v[200:203], v[234:237], v[40:43]
	v_mfma_f32_16x16x32_bf16 v[36:39], v[204:207], v[234:237], v[36:39]
	v_mfma_f32_16x16x32_bf16 v[32:35], v[208:211], v[234:237], v[32:35]
	s_waitcnt vmcnt(6)
	ds_write_b128 v152, v[190:193] offset:36864
	s_waitcnt lgkmcnt(7)
	v_mfma_f32_16x16x32_bf16 v[28:31], v[196:199], v[238:241], v[28:31]
	v_mfma_f32_16x16x32_bf16 v[24:27], v[200:203], v[238:241], v[24:27]
	v_mfma_f32_16x16x32_bf16 v[20:23], v[204:207], v[238:241], v[20:23]
	v_mfma_f32_16x16x32_bf16 v[16:19], v[208:211], v[238:241], v[16:19]
	s_waitcnt lgkmcnt(6)
	v_mfma_f32_16x16x32_bf16 v[12:15], v[196:199], v[242:245], v[12:15]
	v_mfma_f32_16x16x32_bf16 v[8:11], v[200:203], v[242:245], v[8:11]
	v_mfma_f32_16x16x32_bf16 v[4:7], v[204:207], v[242:245], v[4:7]
	v_mfma_f32_16x16x32_bf16 v[0:3], v[208:211], v[242:245], v[0:3]
	s_setprio 0
	s_add_i32 s29, s29, 2
	s_cmp_lt_u32 s29, 30
	s_mov_b32 s36, s37
	s_waitcnt lgkmcnt(0)
	s_barrier
	s_cbranch_scc1 .LBB0_503
	s_waitcnt vmcnt(1)
	v_mov_b32_e32 v142, v220
	v_readlane_b32 s36, v254, 6
	v_and_b32_e32 v45, 0xffffff80, v142
	v_add_u32_e32 v143, s28, v45
	v_lshrrev_b32_e32 v45, 2, v142
	v_and_b32_e32 v44, 64, v142
	v_and_b32_e32 v45, 12, v45
	s_ashr_i32 s28, s33, 2
	v_or3_b32 v140, v44, v45, s35
	s_ashr_i32 s29, s28, 31
	v_ashrrev_i32_e32 v141, 31, v140
	v_readlane_b32 s44, v254, 14
	v_readlane_b32 s45, v254, 15
	s_waitcnt vmcnt(0)
	v_and_or_b32 v144, v142, 15, v143
	s_lshl_b64 s[28:29], s[28:29], 3
	v_lshl_add_u64 v[44:45], v[140:141], 2, s[44:45]
	s_add_u32 s28, s5, s28
	v_lshlrev_b64 v[140:141], 1, v[140:141]
	v_ashrrev_i32_e32 v145, 31, v144
	s_addc_u32 s29, s26, s29
	v_lshl_add_u64 v[142:143], s[70:71], 0, v[140:141]
	v_lshl_add_u64 v[146:147], v[144:145], 2, s[6:7]
	v_lshlrev_b64 v[154:155], 5, v[144:145]
	v_lshlrev_b64 v[190:191], 12, v[144:145]
	global_load_dwordx4 v[68:71], v[44:45], off
	global_load_dwordx4 v[60:63], v[44:45], off offset:64
	global_load_dwordx4 v[52:55], v[44:45], off offset:128
	s_nop 0
	global_load_dwordx4 v[44:47], v[44:45], off offset:192
	v_lshl_add_u64 v[154:155], s[28:29], 0, v[154:155]
	global_load_dword v202, v[146:147], off
	global_load_dwordx2 v[184:185], v[154:155], off
	v_lshl_add_u64 v[146:147], v[142:143], 0, v[190:191]
	global_load_dwordx2 v[196:197], v[146:147], off
	global_load_dwordx2 v[198:199], v[146:147], off offset:32
	global_load_dwordx2 v[200:201], v[146:147], off offset:64
	global_load_dwordx2 v[192:193], v[146:147], off offset:96
	v_or_b32_e32 v146, 16, v144
	v_ashrrev_i32_e32 v147, 31, v146
	v_lshlrev_b64 v[188:189], 12, v[146:147]
	v_lshl_add_u64 v[154:155], v[146:147], 2, s[6:7]
	v_lshlrev_b64 v[156:157], 5, v[146:147]
	v_lshl_add_u64 v[146:147], v[142:143], 0, v[188:189]
	v_lshl_add_u64 v[156:157], s[28:29], 0, v[156:157]
	global_load_dword v195, v[154:155], off
	global_load_dwordx2 v[172:173], v[156:157], off
	global_load_dwordx2 v[186:187], v[146:147], off
	global_load_dwordx2 v[182:183], v[146:147], off offset:32
	global_load_dwordx2 v[180:181], v[146:147], off offset:64
	global_load_dwordx2 v[178:179], v[146:147], off offset:96
	v_or_b32_e32 v146, 32, v144
	v_ashrrev_i32_e32 v147, 31, v146
	v_lshl_add_u64 v[154:155], v[146:147], 2, s[6:7]
	v_lshlrev_b64 v[156:157], 5, v[146:147]
	v_lshl_add_u64 v[156:157], s[28:29], 0, v[156:157]
	global_load_dword v152, v[154:155], off
	global_load_dwordx2 v[160:161], v[156:157], off
	v_or_b32_e32 v154, 48, v144
	v_lshlrev_b64 v[176:177], 12, v[146:147]
	v_ashrrev_i32_e32 v155, 31, v154
	v_lshl_add_u64 v[146:147], v[142:143], 0, v[176:177]
	v_lshlrev_b64 v[156:157], 5, v[154:155]
	v_lshlrev_b64 v[164:165], 12, v[154:155]
	global_load_dwordx2 v[174:175], v[146:147], off
	global_load_dwordx2 v[170:171], v[146:147], off offset:32
	global_load_dwordx2 v[168:169], v[146:147], off offset:64
	global_load_dwordx2 v[166:167], v[146:147], off offset:96
	v_lshl_add_u64 v[146:147], v[154:155], 2, s[6:7]
	v_lshl_add_u64 v[156:157], s[28:29], 0, v[156:157]
	v_lshl_add_u64 v[154:155], v[142:143], 0, v[164:165]
	global_load_dword v145, v[146:147], off
	s_nop 0
	global_load_dwordx2 v[146:147], v[156:157], off
	global_load_dwordx2 v[162:163], v[154:155], off
	global_load_dwordx2 v[158:159], v[154:155], off offset:32
	s_nop 0
	global_load_dwordx2 v[156:157], v[154:155], off offset:64
	s_nop 0
	global_load_dwordx2 v[154:155], v[154:155], off offset:96
	v_readlane_b32 s37, v254, 7
	v_readlane_b32 s38, v254, 8
	v_readlane_b32 s39, v254, 9
	v_readlane_b32 s40, v254, 10
	v_readlane_b32 s41, v254, 11
	v_readlane_b32 s42, v254, 12
	v_readlane_b32 s43, v254, 13
	v_readlane_b32 s46, v254, 16
	v_readlane_b32 s47, v254, 17
	v_readlane_b32 s48, v254, 18
	v_readlane_b32 s49, v254, 19
	v_readlane_b32 s50, v254, 20
	v_readlane_b32 s51, v254, 21
	v_lshl_add_u64 v[140:141], s[8:9], 0, v[140:141]
	s_waitcnt vmcnt(23)
	v_mul_f32_e32 v148, v148, v202
	v_mul_f32_e32 v205, 0xbfb8aa3b, v148
	v_exp_f32_e32 v205, v205
	v_mul_f32_e32 v149, v149, v202
	v_mul_f32_e32 v206, 0xbfb8aa3b, v149
	v_exp_f32_e32 v206, v206
	v_add_f32_e32 v205, 1.0, v205
	v_rcp_f32_e32 v205, v205
	s_waitcnt vmcnt(21)
	v_lshlrev_b32_e32 v203, 16, v196
	v_mul_f32_e32 v150, v150, v202
	v_sub_f32_e32 v203, v203, v184
	v_mul_f32_e32 v148, v148, v205
	v_add_f32_e32 v205, 1.0, v206
	v_rcp_f32_e32 v205, v205
	v_mul_f32_e32 v148, v148, v203
	v_mul_f32_e32 v203, 0xbfb8aa3b, v150
	v_exp_f32_e32 v203, v203
	v_and_b32_e32 v196, 0xffff0000, v196
	v_mul_f32_e32 v151, v151, v202
	v_mul_f32_e32 v149, v149, v205
	v_sub_f32_e32 v196, v196, v184
	v_mul_f32_e32 v149, v149, v196
	v_add_f32_e32 v196, 1.0, v203
	v_mul_f32_e32 v203, 0xbfb8aa3b, v151
	v_exp_f32_e32 v203, v203
	v_rcp_f32_e32 v196, v196
	v_lshlrev_b32_e32 v204, 16, v197
	v_and_b32_e32 v197, 0xffff0000, v197
	v_add_f32_e32 v203, 1.0, v203
	v_rcp_f32_e32 v203, v203
	v_mul_f32_e32 v150, v150, v196
	v_sub_f32_e32 v196, v204, v184
	v_mul_f32_e32 v150, v150, v196
	v_mul_f32_e32 v151, v151, v203
	v_sub_f32_e32 v196, v197, v184
	v_mul_f32_e32 v151, v151, v196
	v_mul_f32_e32 v148, v185, v148
	v_mul_f32_e32 v149, v185, v149
	v_mul_f32_e32 v151, v185, v151
	v_mul_f32_e32 v148, v68, v148
	v_mul_f32_e32 v149, v69, v149
	v_mul_f32_e32 v150, v185, v150
	v_mul_f32_e32 v151, v71, v151
	v_mul_f32_e32 v136, v136, v202
	v_mul_f32_e32 v150, v70, v150
	v_cvt_pk_bf16_f32 v148, v148, v149
	v_cvt_pk_bf16_f32 v149, v150, v151
	v_mul_f32_e32 v151, 0xbfb8aa3b, v136
	v_exp_f32_e32 v151, v151
	v_mul_f32_e32 v137, v137, v202
	v_mul_f32_e32 v197, 0xbfb8aa3b, v137
	v_exp_f32_e32 v197, v197
	v_add_f32_e32 v151, 1.0, v151
	v_rcp_f32_e32 v151, v151
	v_lshl_add_u64 v[190:191], v[140:141], 0, v[190:191]
	global_store_dwordx2 v[190:191], v[148:149], off
	s_waitcnt vmcnt(21)
	v_lshlrev_b32_e32 v148, 16, v198
	v_mul_f32_e32 v136, v136, v151
	v_add_f32_e32 v151, 1.0, v197
	v_rcp_f32_e32 v151, v151
	v_and_b32_e32 v149, 0xffff0000, v198
	v_mul_f32_e32 v138, v138, v202
	v_sub_f32_e32 v148, v148, v184
	v_mul_f32_e32 v139, v139, v202
	v_mul_f32_e32 v136, v136, v148
	v_mul_f32_e32 v137, v137, v151
	v_mul_f32_e32 v148, 0xbfb8aa3b, v138
	v_sub_f32_e32 v149, v149, v184
	v_exp_f32_e32 v148, v148
	v_mul_f32_e32 v137, v137, v149
	v_mul_f32_e32 v149, 0xbfb8aa3b, v139
	v_exp_f32_e32 v149, v149
	v_add_f32_e32 v148, 1.0, v148
	v_rcp_f32_e32 v148, v148
	v_lshlrev_b32_e32 v150, 16, v199
	v_add_f32_e32 v149, 1.0, v149
	v_rcp_f32_e32 v149, v149
	v_and_b32_e32 v196, 0xffff0000, v199
	v_mul_f32_e32 v138, v138, v148
	v_sub_f32_e32 v148, v150, v184
	v_mul_f32_e32 v138, v138, v148
	v_mul_f32_e32 v139, v139, v149
	v_sub_f32_e32 v148, v196, v184
	v_mul_f32_e32 v139, v139, v148
	v_mul_f32_e32 v136, v185, v136
	v_mul_f32_e32 v137, v185, v137
	v_mul_f32_e32 v139, v185, v139
	v_mul_f32_e32 v136, v60, v136
	v_mul_f32_e32 v137, v61, v137
	v_mul_f32_e32 v138, v185, v138
	v_mul_f32_e32 v139, v63, v139
	v_mul_f32_e32 v132, v132, v202
	v_mul_f32_e32 v138, v62, v138
	v_cvt_pk_bf16_f32 v136, v136, v137
	v_cvt_pk_bf16_f32 v137, v138, v139
	v_mul_f32_e32 v139, 0xbfb8aa3b, v132
	v_exp_f32_e32 v139, v139
	v_mul_f32_e32 v133, v133, v202
	v_mul_f32_e32 v149, 0xbfb8aa3b, v133
	v_exp_f32_e32 v149, v149
	v_add_f32_e32 v139, 1.0, v139
	v_rcp_f32_e32 v139, v139
	global_store_dwordx2 v[190:191], v[136:137], off offset:32
	s_waitcnt vmcnt(21)
	v_lshlrev_b32_e32 v136, 16, v200
	v_and_b32_e32 v137, 0xffff0000, v200
	v_mul_f32_e32 v132, v132, v139
	v_add_f32_e32 v139, 1.0, v149
	v_rcp_f32_e32 v139, v139
	v_mul_f32_e32 v134, v134, v202
	v_sub_f32_e32 v136, v136, v184
	v_mul_f32_e32 v135, v135, v202
	v_mul_f32_e32 v132, v132, v136
	v_mul_f32_e32 v133, v133, v139
	v_mul_f32_e32 v136, 0xbfb8aa3b, v134
	v_sub_f32_e32 v137, v137, v184
	v_exp_f32_e32 v136, v136
	v_mul_f32_e32 v133, v133, v137
	v_mul_f32_e32 v137, 0xbfb8aa3b, v135
	v_exp_f32_e32 v137, v137
	v_add_f32_e32 v136, 1.0, v136
	v_rcp_f32_e32 v136, v136
	v_lshlrev_b32_e32 v138, 16, v201
	v_add_f32_e32 v137, 1.0, v137
	v_rcp_f32_e32 v137, v137
	v_and_b32_e32 v148, 0xffff0000, v201
	v_mul_f32_e32 v134, v134, v136
	v_sub_f32_e32 v136, v138, v184
	v_mul_f32_e32 v134, v134, v136
	v_mul_f32_e32 v135, v135, v137
	v_sub_f32_e32 v136, v148, v184
	v_mul_f32_e32 v135, v135, v136
	v_mul_f32_e32 v132, v185, v132
	v_mul_f32_e32 v133, v185, v133
	v_mul_f32_e32 v135, v185, v135
	v_mul_f32_e32 v132, v52, v132
	v_mul_f32_e32 v133, v53, v133
	v_mul_f32_e32 v134, v185, v134
	v_mul_f32_e32 v135, v55, v135
	v_mul_f32_e32 v128, v128, v202
	v_mul_f32_e32 v134, v54, v134
	v_cvt_pk_bf16_f32 v132, v132, v133
	v_cvt_pk_bf16_f32 v133, v134, v135
	v_mul_f32_e32 v135, 0xbfb8aa3b, v128
	v_exp_f32_e32 v135, v135
	v_mul_f32_e32 v129, v129, v202
	v_mul_f32_e32 v137, 0xbfb8aa3b, v129
	v_exp_f32_e32 v137, v137
	v_add_f32_e32 v135, 1.0, v135
	v_rcp_f32_e32 v135, v135
	global_store_dwordx2 v[190:191], v[132:133], off offset:64
	s_waitcnt vmcnt(21)
	v_and_b32_e32 v133, 0xffff0000, v192
	v_mul_f32_e32 v131, v131, v202
	v_mul_f32_e32 v128, v128, v135
	v_add_f32_e32 v135, 1.0, v137
	v_rcp_f32_e32 v135, v135
	v_sub_f32_e32 v133, v133, v184
	v_lshlrev_b32_e32 v132, 16, v192
	v_mul_f32_e32 v130, v130, v202
	v_mul_f32_e32 v129, v129, v135
	v_mul_f32_e32 v129, v129, v133
	v_mul_f32_e32 v133, 0xbfb8aa3b, v131
	v_exp_f32_e32 v133, v133
	v_sub_f32_e32 v132, v132, v184
	v_mul_f32_e32 v128, v128, v132
	v_mul_f32_e32 v132, 0xbfb8aa3b, v130
	v_add_f32_e32 v133, 1.0, v133
	v_rcp_f32_e32 v133, v133
	s_waitcnt vmcnt(20)
	v_mul_f32_e32 v124, v124, v195
	v_exp_f32_e32 v132, v132
	v_mul_f32_e32 v125, v125, v195
	v_mul_f32_e32 v131, v131, v133
	v_mul_f32_e32 v133, 0xbfb8aa3b, v124
	v_exp_f32_e32 v133, v133
	v_add_f32_e32 v132, 1.0, v132
	v_rcp_f32_e32 v132, v132
	v_mul_f32_e32 v135, 0xbfb8aa3b, v125
	v_add_f32_e32 v133, 1.0, v133
	v_rcp_f32_e32 v133, v133
	v_exp_f32_e32 v135, v135
	v_lshlrev_b32_e32 v134, 16, v193
	v_and_b32_e32 v136, 0xffff0000, v193
	v_mul_f32_e32 v130, v130, v132
	v_sub_f32_e32 v132, v134, v184
	v_mul_f32_e32 v130, v130, v132
	v_sub_f32_e32 v132, v136, v184
	v_mul_f32_e32 v124, v124, v133
	v_add_f32_e32 v133, 1.0, v135
	v_mul_f32_e32 v128, v185, v128
	v_mul_f32_e32 v129, v185, v129
	v_mul_f32_e32 v130, v185, v130
	v_mul_f32_e32 v131, v131, v132
	v_rcp_f32_e32 v133, v133
	v_mul_f32_e32 v128, v44, v128
	v_mul_f32_e32 v129, v45, v129
	v_mul_f32_e32 v130, v46, v130
	v_mul_f32_e32 v131, v185, v131
	v_mul_f32_e32 v131, v47, v131
	v_cvt_pk_bf16_f32 v128, v128, v129
	v_cvt_pk_bf16_f32 v129, v130, v131
	s_waitcnt vmcnt(18)
	v_lshlrev_b32_e32 v130, 16, v186
	v_and_b32_e32 v131, 0xffff0000, v186
	v_mul_f32_e32 v126, v126, v195
	v_sub_f32_e32 v130, v130, v172
	v_mul_f32_e32 v127, v127, v195
	v_mul_f32_e32 v124, v124, v130
	v_mul_f32_e32 v125, v125, v133
	v_mul_f32_e32 v130, 0xbfb8aa3b, v126
	v_sub_f32_e32 v131, v131, v172
	v_exp_f32_e32 v130, v130
	v_mul_f32_e32 v125, v125, v131
	v_mul_f32_e32 v131, 0xbfb8aa3b, v127
	v_exp_f32_e32 v131, v131
	v_add_f32_e32 v130, 1.0, v130
	v_rcp_f32_e32 v130, v130
	v_lshlrev_b32_e32 v132, 16, v187
	v_add_f32_e32 v131, 1.0, v131
	v_rcp_f32_e32 v131, v131
	v_and_b32_e32 v134, 0xffff0000, v187
	v_mul_f32_e32 v126, v126, v130
	v_sub_f32_e32 v130, v132, v172
	v_mul_f32_e32 v126, v126, v130
	v_mul_f32_e32 v127, v127, v131
	v_sub_f32_e32 v130, v134, v172
	v_mul_f32_e32 v127, v127, v130
	v_mul_f32_e32 v124, v173, v124
	v_mul_f32_e32 v125, v173, v125
	v_mul_f32_e32 v127, v173, v127
	v_mul_f32_e32 v124, v68, v124
	v_mul_f32_e32 v125, v69, v125
	v_mul_f32_e32 v126, v173, v126
	v_mul_f32_e32 v127, v71, v127
	v_mul_f32_e32 v120, v120, v195
	v_mul_f32_e32 v126, v70, v126
	v_cvt_pk_bf16_f32 v124, v124, v125
	v_cvt_pk_bf16_f32 v125, v126, v127
	v_mul_f32_e32 v127, 0xbfb8aa3b, v120
	v_exp_f32_e32 v127, v127
	v_mul_f32_e32 v121, v121, v195
	v_mul_f32_e32 v131, 0xbfb8aa3b, v121
	v_exp_f32_e32 v131, v131
	v_add_f32_e32 v127, 1.0, v127
	v_rcp_f32_e32 v127, v127
	global_store_dwordx2 v[190:191], v[128:129], off offset:96
	v_lshl_add_u64 v[128:129], v[140:141], 0, v[188:189]
	global_store_dwordx2 v[128:129], v[124:125], off
	v_mul_f32_e32 v120, v120, v127
	v_add_f32_e32 v127, 1.0, v131
	v_rcp_f32_e32 v127, v127
	s_waitcnt vmcnt(19)
	v_lshlrev_b32_e32 v124, 16, v182
	v_and_b32_e32 v125, 0xffff0000, v182
	v_mul_f32_e32 v122, v122, v195
	v_sub_f32_e32 v124, v124, v172
	v_mul_f32_e32 v123, v123, v195
	v_mul_f32_e32 v120, v120, v124
	v_mul_f32_e32 v121, v121, v127
	v_mul_f32_e32 v124, 0xbfb8aa3b, v122
	v_sub_f32_e32 v125, v125, v172
	v_exp_f32_e32 v124, v124
	v_mul_f32_e32 v121, v121, v125
	v_mul_f32_e32 v125, 0xbfb8aa3b, v123
	v_exp_f32_e32 v125, v125
	v_add_f32_e32 v124, 1.0, v124
	v_rcp_f32_e32 v124, v124
	v_lshlrev_b32_e32 v126, 16, v183
	v_add_f32_e32 v125, 1.0, v125
	v_rcp_f32_e32 v125, v125
	v_and_b32_e32 v130, 0xffff0000, v183
	v_mul_f32_e32 v122, v122, v124
	v_sub_f32_e32 v124, v126, v172
	v_mul_f32_e32 v122, v122, v124
	v_mul_f32_e32 v123, v123, v125
	v_sub_f32_e32 v124, v130, v172
	v_mul_f32_e32 v123, v123, v124
	v_mul_f32_e32 v120, v173, v120
	v_mul_f32_e32 v121, v173, v121
	v_mul_f32_e32 v123, v173, v123
	v_mul_f32_e32 v120, v60, v120
	v_mul_f32_e32 v121, v61, v121
	v_mul_f32_e32 v122, v173, v122
	v_mul_f32_e32 v123, v63, v123
	v_mul_f32_e32 v116, v116, v195
	v_mul_f32_e32 v122, v62, v122
	v_cvt_pk_bf16_f32 v120, v120, v121
	v_cvt_pk_bf16_f32 v121, v122, v123
	v_mul_f32_e32 v123, 0xbfb8aa3b, v116
	v_exp_f32_e32 v123, v123
	v_mul_f32_e32 v117, v117, v195
	v_mul_f32_e32 v125, 0xbfb8aa3b, v117
	v_exp_f32_e32 v125, v125
	v_add_f32_e32 v123, 1.0, v123
	v_rcp_f32_e32 v123, v123
	global_store_dwordx2 v[128:129], v[120:121], off offset:32
	s_waitcnt vmcnt(19)
	v_lshlrev_b32_e32 v120, 16, v180
	v_and_b32_e32 v121, 0xffff0000, v180
	v_mul_f32_e32 v116, v116, v123
	v_add_f32_e32 v123, 1.0, v125
	v_rcp_f32_e32 v123, v123
	v_mul_f32_e32 v118, v118, v195
	v_sub_f32_e32 v120, v120, v172
	v_mul_f32_e32 v119, v119, v195
	v_mul_f32_e32 v116, v116, v120
	v_mul_f32_e32 v117, v117, v123
	v_mul_f32_e32 v120, 0xbfb8aa3b, v118
	v_sub_f32_e32 v121, v121, v172
	v_exp_f32_e32 v120, v120
	v_mul_f32_e32 v117, v117, v121
	v_mul_f32_e32 v121, 0xbfb8aa3b, v119
	v_exp_f32_e32 v121, v121
	v_add_f32_e32 v120, 1.0, v120
	v_rcp_f32_e32 v120, v120
	v_lshlrev_b32_e32 v122, 16, v181
	v_add_f32_e32 v121, 1.0, v121
	v_rcp_f32_e32 v121, v121
	v_and_b32_e32 v124, 0xffff0000, v181
	v_mul_f32_e32 v118, v118, v120
	v_sub_f32_e32 v120, v122, v172
	v_mul_f32_e32 v118, v118, v120
	v_mul_f32_e32 v119, v119, v121
	v_sub_f32_e32 v120, v124, v172
	v_mul_f32_e32 v119, v119, v120
	v_mul_f32_e32 v116, v173, v116
	v_mul_f32_e32 v117, v173, v117
	v_mul_f32_e32 v119, v173, v119
	v_mul_f32_e32 v116, v52, v116
	v_mul_f32_e32 v117, v53, v117
	v_mul_f32_e32 v118, v173, v118
	v_mul_f32_e32 v119, v55, v119
	v_mul_f32_e32 v112, v112, v195
	v_mul_f32_e32 v118, v54, v118
	v_cvt_pk_bf16_f32 v116, v116, v117
	v_cvt_pk_bf16_f32 v117, v118, v119
	v_mul_f32_e32 v119, 0xbfb8aa3b, v112
	v_exp_f32_e32 v119, v119
	v_mul_f32_e32 v113, v113, v195
	v_mul_f32_e32 v121, 0xbfb8aa3b, v113
	v_exp_f32_e32 v121, v121
	v_add_f32_e32 v119, 1.0, v119
	v_rcp_f32_e32 v119, v119
	global_store_dwordx2 v[128:129], v[116:117], off offset:64
	s_waitcnt vmcnt(19)
	v_and_b32_e32 v117, 0xffff0000, v178
	v_mul_f32_e32 v115, v115, v195
	v_mul_f32_e32 v112, v112, v119
	v_add_f32_e32 v119, 1.0, v121
	v_rcp_f32_e32 v119, v119
	v_sub_f32_e32 v117, v117, v172
	v_lshlrev_b32_e32 v116, 16, v178
	v_mul_f32_e32 v114, v114, v195
	v_mul_f32_e32 v113, v113, v119
	v_mul_f32_e32 v113, v113, v117
	v_mul_f32_e32 v117, 0xbfb8aa3b, v115
	v_exp_f32_e32 v117, v117
	v_sub_f32_e32 v116, v116, v172
	v_mul_f32_e32 v112, v112, v116
	v_mul_f32_e32 v116, 0xbfb8aa3b, v114
	v_add_f32_e32 v117, 1.0, v117
	v_rcp_f32_e32 v117, v117
	s_waitcnt vmcnt(18)
	v_mul_f32_e32 v108, v108, v152
	v_exp_f32_e32 v116, v116
	v_mul_f32_e32 v109, v109, v152
	v_mul_f32_e32 v115, v115, v117
	v_mul_f32_e32 v117, 0xbfb8aa3b, v108
	v_exp_f32_e32 v117, v117
	v_add_f32_e32 v116, 1.0, v116
	v_rcp_f32_e32 v116, v116
	v_mul_f32_e32 v119, 0xbfb8aa3b, v109
	v_add_f32_e32 v117, 1.0, v117
	v_rcp_f32_e32 v117, v117
	v_exp_f32_e32 v119, v119
	v_lshlrev_b32_e32 v118, 16, v179
	v_and_b32_e32 v120, 0xffff0000, v179
	v_mul_f32_e32 v114, v114, v116
	v_sub_f32_e32 v116, v118, v172
	v_mul_f32_e32 v114, v114, v116
	v_sub_f32_e32 v116, v120, v172
	v_mul_f32_e32 v108, v108, v117
	v_add_f32_e32 v117, 1.0, v119
	v_mul_f32_e32 v112, v173, v112
	v_mul_f32_e32 v113, v173, v113
	v_mul_f32_e32 v114, v173, v114
	v_mul_f32_e32 v115, v115, v116
	v_rcp_f32_e32 v117, v117
	v_mul_f32_e32 v112, v44, v112
	v_mul_f32_e32 v113, v45, v113
	v_mul_f32_e32 v114, v46, v114
	v_mul_f32_e32 v115, v173, v115
	v_mul_f32_e32 v115, v47, v115
	v_cvt_pk_bf16_f32 v112, v112, v113
	v_cvt_pk_bf16_f32 v113, v114, v115
	s_waitcnt vmcnt(16)
	v_lshlrev_b32_e32 v114, 16, v174
	v_and_b32_e32 v115, 0xffff0000, v174
	v_mul_f32_e32 v110, v110, v152
	v_sub_f32_e32 v114, v114, v160
	v_mul_f32_e32 v111, v111, v152
	v_mul_f32_e32 v108, v108, v114
	v_mul_f32_e32 v109, v109, v117
	v_mul_f32_e32 v114, 0xbfb8aa3b, v110
	v_sub_f32_e32 v115, v115, v160
	v_exp_f32_e32 v114, v114
	v_mul_f32_e32 v109, v109, v115
	v_mul_f32_e32 v115, 0xbfb8aa3b, v111
	v_exp_f32_e32 v115, v115
	v_add_f32_e32 v114, 1.0, v114
	v_rcp_f32_e32 v114, v114
	v_lshlrev_b32_e32 v116, 16, v175
	v_add_f32_e32 v115, 1.0, v115
	v_rcp_f32_e32 v115, v115
	v_and_b32_e32 v118, 0xffff0000, v175
	v_mul_f32_e32 v110, v110, v114
	v_sub_f32_e32 v114, v116, v160
	v_mul_f32_e32 v110, v110, v114
	v_mul_f32_e32 v111, v111, v115
	v_sub_f32_e32 v114, v118, v160
	v_mul_f32_e32 v111, v111, v114
	v_mul_f32_e32 v108, v161, v108
	v_mul_f32_e32 v109, v161, v109
	v_mul_f32_e32 v111, v161, v111
	v_mul_f32_e32 v108, v68, v108
	v_mul_f32_e32 v109, v69, v109
	v_mul_f32_e32 v110, v161, v110
	v_mul_f32_e32 v111, v71, v111
	v_mul_f32_e32 v104, v104, v152
	v_mul_f32_e32 v110, v70, v110
	v_cvt_pk_bf16_f32 v108, v108, v109
	v_cvt_pk_bf16_f32 v109, v110, v111
	v_mul_f32_e32 v111, 0xbfb8aa3b, v104
	v_exp_f32_e32 v111, v111
	v_mul_f32_e32 v105, v105, v152
	v_mul_f32_e32 v115, 0xbfb8aa3b, v105
	v_exp_f32_e32 v115, v115
	v_add_f32_e32 v111, 1.0, v111
	v_rcp_f32_e32 v111, v111
	global_store_dwordx2 v[128:129], v[112:113], off offset:96
	v_lshl_add_u64 v[112:113], v[140:141], 0, v[176:177]
	global_store_dwordx2 v[112:113], v[108:109], off
	v_mul_f32_e32 v104, v104, v111
	v_add_f32_e32 v111, 1.0, v115
	v_rcp_f32_e32 v111, v111
	s_waitcnt vmcnt(17)
	v_lshlrev_b32_e32 v108, 16, v170
	v_and_b32_e32 v109, 0xffff0000, v170
	v_mul_f32_e32 v106, v106, v152
	v_sub_f32_e32 v108, v108, v160
	v_mul_f32_e32 v107, v107, v152
	v_mul_f32_e32 v104, v104, v108
	v_mul_f32_e32 v105, v105, v111
	v_mul_f32_e32 v108, 0xbfb8aa3b, v106
	v_sub_f32_e32 v109, v109, v160
	v_exp_f32_e32 v108, v108
	v_mul_f32_e32 v105, v105, v109
	v_mul_f32_e32 v109, 0xbfb8aa3b, v107
	v_exp_f32_e32 v109, v109
	v_add_f32_e32 v108, 1.0, v108
	v_rcp_f32_e32 v108, v108
	v_lshlrev_b32_e32 v110, 16, v171
	v_add_f32_e32 v109, 1.0, v109
	v_rcp_f32_e32 v109, v109
	v_and_b32_e32 v114, 0xffff0000, v171
	v_mul_f32_e32 v106, v106, v108
	v_sub_f32_e32 v108, v110, v160
	v_mul_f32_e32 v106, v106, v108
	v_mul_f32_e32 v107, v107, v109
	v_sub_f32_e32 v108, v114, v160
	v_mul_f32_e32 v107, v107, v108
	v_mul_f32_e32 v104, v161, v104
	v_mul_f32_e32 v105, v161, v105
	v_mul_f32_e32 v107, v161, v107
	v_mul_f32_e32 v104, v60, v104
	v_mul_f32_e32 v105, v61, v105
	v_mul_f32_e32 v106, v161, v106
	v_mul_f32_e32 v107, v63, v107
	v_mul_f32_e32 v100, v100, v152
	v_mul_f32_e32 v106, v62, v106
	v_cvt_pk_bf16_f32 v104, v104, v105
	v_cvt_pk_bf16_f32 v105, v106, v107
	v_mul_f32_e32 v107, 0xbfb8aa3b, v100
	v_exp_f32_e32 v107, v107
	v_mul_f32_e32 v101, v101, v152
	v_mul_f32_e32 v109, 0xbfb8aa3b, v101
	v_exp_f32_e32 v109, v109
	v_add_f32_e32 v107, 1.0, v107
	v_rcp_f32_e32 v107, v107
	global_store_dwordx2 v[112:113], v[104:105], off offset:32
	s_waitcnt vmcnt(17)
	v_lshlrev_b32_e32 v104, 16, v168
	v_and_b32_e32 v105, 0xffff0000, v168
	v_mul_f32_e32 v100, v100, v107
	v_add_f32_e32 v107, 1.0, v109
	v_rcp_f32_e32 v107, v107
	v_mul_f32_e32 v102, v102, v152
	v_sub_f32_e32 v104, v104, v160
	v_mul_f32_e32 v103, v103, v152
	v_mul_f32_e32 v100, v100, v104
	v_mul_f32_e32 v101, v101, v107
	v_mul_f32_e32 v104, 0xbfb8aa3b, v102
	v_sub_f32_e32 v105, v105, v160
	v_exp_f32_e32 v104, v104
	v_mul_f32_e32 v101, v101, v105
	v_mul_f32_e32 v105, 0xbfb8aa3b, v103
	v_exp_f32_e32 v105, v105
	v_add_f32_e32 v104, 1.0, v104
	v_rcp_f32_e32 v104, v104
	v_lshlrev_b32_e32 v106, 16, v169
	v_add_f32_e32 v105, 1.0, v105
	v_rcp_f32_e32 v105, v105
	v_and_b32_e32 v108, 0xffff0000, v169
	v_mul_f32_e32 v102, v102, v104
	v_sub_f32_e32 v104, v106, v160
	v_mul_f32_e32 v102, v102, v104
	v_mul_f32_e32 v103, v103, v105
	v_sub_f32_e32 v104, v108, v160
	v_mul_f32_e32 v103, v103, v104
	v_mul_f32_e32 v100, v161, v100
	v_mul_f32_e32 v101, v161, v101
	v_mul_f32_e32 v103, v161, v103
	v_mul_f32_e32 v100, v52, v100
	v_mul_f32_e32 v101, v53, v101
	v_mul_f32_e32 v102, v161, v102
	v_mul_f32_e32 v103, v55, v103
	v_mul_f32_e32 v96, v96, v152
	v_mul_f32_e32 v102, v54, v102
	v_cvt_pk_bf16_f32 v100, v100, v101
	v_cvt_pk_bf16_f32 v101, v102, v103
	v_mul_f32_e32 v103, 0xbfb8aa3b, v96
	v_exp_f32_e32 v103, v103
	v_mul_f32_e32 v97, v97, v152
	v_mul_f32_e32 v105, 0xbfb8aa3b, v97
	v_exp_f32_e32 v105, v105
	v_add_f32_e32 v103, 1.0, v103
	v_rcp_f32_e32 v103, v103
	global_store_dwordx2 v[112:113], v[100:101], off offset:64
	s_waitcnt vmcnt(17)
	v_and_b32_e32 v101, 0xffff0000, v166
	v_mul_f32_e32 v99, v99, v152
	v_mul_f32_e32 v96, v96, v103
	v_add_f32_e32 v103, 1.0, v105
	v_rcp_f32_e32 v103, v103
	v_sub_f32_e32 v101, v101, v160
	v_lshlrev_b32_e32 v100, 16, v166
	v_mul_f32_e32 v98, v98, v152
	v_mul_f32_e32 v97, v97, v103
	v_mul_f32_e32 v97, v97, v101
	v_mul_f32_e32 v101, 0xbfb8aa3b, v99
	v_exp_f32_e32 v101, v101
	v_sub_f32_e32 v100, v100, v160
	v_mul_f32_e32 v96, v96, v100
	v_mul_f32_e32 v100, 0xbfb8aa3b, v98
	v_add_f32_e32 v101, 1.0, v101
	v_rcp_f32_e32 v101, v101
	s_waitcnt vmcnt(16)
	v_mul_f32_e32 v92, v92, v145
	v_exp_f32_e32 v100, v100
	v_mul_f32_e32 v93, v93, v145
	v_mul_f32_e32 v99, v99, v101
	v_mul_f32_e32 v101, 0xbfb8aa3b, v92
	v_exp_f32_e32 v101, v101
	v_add_f32_e32 v100, 1.0, v100
	v_rcp_f32_e32 v100, v100
	v_mul_f32_e32 v103, 0xbfb8aa3b, v93
	v_add_f32_e32 v101, 1.0, v101
	v_rcp_f32_e32 v101, v101
	v_exp_f32_e32 v103, v103
	v_lshlrev_b32_e32 v102, 16, v167
	v_and_b32_e32 v104, 0xffff0000, v167
	v_mul_f32_e32 v98, v98, v100
	v_sub_f32_e32 v100, v102, v160
	v_mul_f32_e32 v98, v98, v100
	v_sub_f32_e32 v100, v104, v160
	v_mul_f32_e32 v92, v92, v101
	v_add_f32_e32 v101, 1.0, v103
	v_mul_f32_e32 v96, v161, v96
	v_mul_f32_e32 v97, v161, v97
	v_mul_f32_e32 v98, v161, v98
	v_mul_f32_e32 v99, v99, v100
	v_rcp_f32_e32 v101, v101
	v_mul_f32_e32 v96, v44, v96
	v_mul_f32_e32 v97, v45, v97
	v_mul_f32_e32 v98, v46, v98
	v_mul_f32_e32 v99, v161, v99
	v_mul_f32_e32 v99, v47, v99
	v_cvt_pk_bf16_f32 v96, v96, v97
	v_cvt_pk_bf16_f32 v97, v98, v99
	s_waitcnt vmcnt(14)
	v_lshlrev_b32_e32 v98, 16, v162
	v_and_b32_e32 v99, 0xffff0000, v162
	v_mul_f32_e32 v94, v94, v145
	v_sub_f32_e32 v98, v98, v146
	v_mul_f32_e32 v95, v95, v145
	v_mul_f32_e32 v92, v92, v98
	v_mul_f32_e32 v93, v93, v101
	v_mul_f32_e32 v98, 0xbfb8aa3b, v94
	v_sub_f32_e32 v99, v99, v146
	v_exp_f32_e32 v98, v98
	v_mul_f32_e32 v93, v93, v99
	v_mul_f32_e32 v99, 0xbfb8aa3b, v95
	v_exp_f32_e32 v99, v99
	v_add_f32_e32 v98, 1.0, v98
	v_rcp_f32_e32 v98, v98
	v_lshlrev_b32_e32 v100, 16, v163
	v_add_f32_e32 v99, 1.0, v99
	v_rcp_f32_e32 v99, v99
	v_and_b32_e32 v102, 0xffff0000, v163
	v_mul_f32_e32 v94, v94, v98
	v_sub_f32_e32 v98, v100, v146
	v_mul_f32_e32 v94, v94, v98
	v_mul_f32_e32 v95, v95, v99
	v_sub_f32_e32 v98, v102, v146
	v_mul_f32_e32 v95, v95, v98
	v_mul_f32_e32 v92, v147, v92
	v_mul_f32_e32 v93, v147, v93
	v_mul_f32_e32 v95, v147, v95
	v_mul_f32_e32 v92, v68, v92
	v_mul_f32_e32 v93, v69, v93
	v_mul_f32_e32 v94, v147, v94
	v_mul_f32_e32 v95, v71, v95
	v_mul_f32_e32 v88, v88, v145
	v_mul_f32_e32 v94, v70, v94
	v_cvt_pk_bf16_f32 v92, v92, v93
	v_cvt_pk_bf16_f32 v93, v94, v95
	v_mul_f32_e32 v95, 0xbfb8aa3b, v88
	v_exp_f32_e32 v95, v95
	v_mul_f32_e32 v89, v89, v145
	v_mul_f32_e32 v99, 0xbfb8aa3b, v89
	v_exp_f32_e32 v99, v99
	v_add_f32_e32 v95, 1.0, v95
	v_rcp_f32_e32 v95, v95
	global_store_dwordx2 v[112:113], v[96:97], off offset:96
	v_lshl_add_u64 v[96:97], v[140:141], 0, v[164:165]
	global_store_dwordx2 v[96:97], v[92:93], off
	v_mul_f32_e32 v88, v88, v95
	v_add_f32_e32 v95, 1.0, v99
	v_rcp_f32_e32 v95, v95
	s_waitcnt vmcnt(15)
	v_lshlrev_b32_e32 v92, 16, v158
	v_and_b32_e32 v93, 0xffff0000, v158
	v_mul_f32_e32 v90, v90, v145
	v_sub_f32_e32 v92, v92, v146
	v_mul_f32_e32 v91, v91, v145
	v_mul_f32_e32 v88, v88, v92
	v_mul_f32_e32 v89, v89, v95
	v_mul_f32_e32 v92, 0xbfb8aa3b, v90
	v_sub_f32_e32 v93, v93, v146
	v_exp_f32_e32 v92, v92
	v_mul_f32_e32 v89, v89, v93
	v_mul_f32_e32 v93, 0xbfb8aa3b, v91
	v_exp_f32_e32 v93, v93
	v_add_f32_e32 v92, 1.0, v92
	v_rcp_f32_e32 v92, v92
	v_lshlrev_b32_e32 v94, 16, v159
	v_add_f32_e32 v93, 1.0, v93
	v_rcp_f32_e32 v93, v93
	v_and_b32_e32 v98, 0xffff0000, v159
	v_mul_f32_e32 v90, v90, v92
	v_sub_f32_e32 v92, v94, v146
	v_mul_f32_e32 v90, v90, v92
	v_mul_f32_e32 v91, v91, v93
	v_sub_f32_e32 v92, v98, v146
	v_mul_f32_e32 v91, v91, v92
	v_mul_f32_e32 v88, v147, v88
	v_mul_f32_e32 v89, v147, v89
	v_mul_f32_e32 v91, v147, v91
	v_mul_f32_e32 v88, v60, v88
	v_mul_f32_e32 v89, v61, v89
	v_mul_f32_e32 v90, v147, v90
	v_mul_f32_e32 v91, v63, v91
	v_mul_f32_e32 v84, v84, v145
	v_mul_f32_e32 v90, v62, v90
	v_cvt_pk_bf16_f32 v88, v88, v89
	v_cvt_pk_bf16_f32 v89, v90, v91
	v_mul_f32_e32 v91, 0xbfb8aa3b, v84
	v_exp_f32_e32 v91, v91
	v_mul_f32_e32 v85, v85, v145
	v_mul_f32_e32 v93, 0xbfb8aa3b, v85
	v_exp_f32_e32 v93, v93
	v_add_f32_e32 v91, 1.0, v91
	v_rcp_f32_e32 v91, v91
	global_store_dwordx2 v[96:97], v[88:89], off offset:32
	s_waitcnt vmcnt(15)
	v_lshlrev_b32_e32 v88, 16, v156
	v_and_b32_e32 v89, 0xffff0000, v156
	v_mul_f32_e32 v84, v84, v91
	v_add_f32_e32 v91, 1.0, v93
	v_rcp_f32_e32 v91, v91
	v_mul_f32_e32 v86, v86, v145
	v_sub_f32_e32 v88, v88, v146
	v_mul_f32_e32 v87, v87, v145
	v_mul_f32_e32 v84, v84, v88
	v_mul_f32_e32 v85, v85, v91
	v_mul_f32_e32 v88, 0xbfb8aa3b, v86
	v_sub_f32_e32 v89, v89, v146
	v_exp_f32_e32 v88, v88
	v_mul_f32_e32 v85, v85, v89
	v_mul_f32_e32 v89, 0xbfb8aa3b, v87
	v_exp_f32_e32 v89, v89
	v_add_f32_e32 v88, 1.0, v88
	v_rcp_f32_e32 v88, v88
	v_lshlrev_b32_e32 v90, 16, v157
	v_add_f32_e32 v89, 1.0, v89
	v_rcp_f32_e32 v89, v89
	v_and_b32_e32 v92, 0xffff0000, v157
	v_mul_f32_e32 v86, v86, v88
	v_sub_f32_e32 v88, v90, v146
	v_mul_f32_e32 v86, v86, v88
	v_mul_f32_e32 v87, v87, v89
	v_sub_f32_e32 v88, v92, v146
	v_mul_f32_e32 v87, v87, v88
	v_mul_f32_e32 v84, v147, v84
	v_mul_f32_e32 v85, v147, v85
	v_mul_f32_e32 v87, v147, v87
	v_mul_f32_e32 v84, v52, v84
	v_mul_f32_e32 v85, v53, v85
	v_mul_f32_e32 v86, v147, v86
	v_mul_f32_e32 v87, v55, v87
	v_mul_f32_e32 v80, v80, v145
	v_mul_f32_e32 v86, v54, v86
	v_cvt_pk_bf16_f32 v84, v84, v85
	v_cvt_pk_bf16_f32 v85, v86, v87
	v_mul_f32_e32 v87, 0xbfb8aa3b, v80
	v_exp_f32_e32 v87, v87
	v_mul_f32_e32 v81, v81, v145
	v_mul_f32_e32 v89, 0xbfb8aa3b, v81
	v_exp_f32_e32 v89, v89
	v_add_f32_e32 v87, 1.0, v87
	v_rcp_f32_e32 v87, v87
	global_store_dwordx2 v[96:97], v[84:85], off offset:64
	s_waitcnt vmcnt(15)
	v_lshlrev_b32_e32 v84, 16, v154
	v_and_b32_e32 v85, 0xffff0000, v154
	v_mul_f32_e32 v80, v80, v87
	v_add_f32_e32 v87, 1.0, v89
	v_rcp_f32_e32 v87, v87
	v_mul_f32_e32 v82, v82, v145
	v_sub_f32_e32 v84, v84, v146
	v_mul_f32_e32 v83, v83, v145
	v_mul_f32_e32 v80, v80, v84
	v_mul_f32_e32 v81, v81, v87
	v_mul_f32_e32 v84, 0xbfb8aa3b, v82
	v_sub_f32_e32 v85, v85, v146
	v_exp_f32_e32 v84, v84
	v_mul_f32_e32 v81, v81, v85
	v_mul_f32_e32 v85, 0xbfb8aa3b, v83
	v_exp_f32_e32 v85, v85
	v_add_f32_e32 v84, 1.0, v84
	v_rcp_f32_e32 v84, v84
	v_lshlrev_b32_e32 v86, 16, v155
	v_add_f32_e32 v85, 1.0, v85
	v_rcp_f32_e32 v85, v85
	v_and_b32_e32 v88, 0xffff0000, v155
	v_mul_f32_e32 v82, v82, v84
	v_sub_f32_e32 v84, v86, v146
	v_mul_f32_e32 v82, v82, v84
	v_mul_f32_e32 v83, v83, v85
	v_sub_f32_e32 v84, v88, v146
	v_mul_f32_e32 v80, v147, v80
	v_mul_f32_e32 v81, v147, v81
	v_mul_f32_e32 v83, v83, v84
	v_mul_f32_e32 v80, v44, v80
	v_mul_f32_e32 v81, v45, v81
	v_mul_f32_e32 v82, v147, v82
	v_mul_f32_e32 v83, v147, v83
	v_mul_f32_e32 v82, v46, v82
	v_mul_f32_e32 v83, v47, v83
	v_cvt_pk_bf16_f32 v80, v80, v81
	v_cvt_pk_bf16_f32 v81, v82, v83
	global_store_dwordx2 v[96:97], v[80:81], off offset:96
	v_or_b32_e32 v80, 64, v144
	v_ashrrev_i32_e32 v81, 31, v80
	v_lshlrev_b64 v[118:119], 12, v[80:81]
	v_lshl_add_u64 v[82:83], v[80:81], 2, s[6:7]
	v_lshlrev_b64 v[84:85], 5, v[80:81]
	v_lshl_add_u64 v[80:81], v[142:143], 0, v[118:119]
	v_lshl_add_u64 v[84:85], s[28:29], 0, v[84:85]
	global_load_dword v125, v[82:83], off
	global_load_dwordx2 v[112:113], v[84:85], off
	global_load_dwordx2 v[126:127], v[80:81], off
	global_load_dwordx2 v[128:129], v[80:81], off offset:32
	global_load_dwordx2 v[130:131], v[80:81], off offset:64
	global_load_dwordx2 v[120:121], v[80:81], off offset:96
	v_or_b32_e32 v80, 0x50, v144
	v_ashrrev_i32_e32 v81, 31, v80
	v_lshlrev_b64 v[116:117], 12, v[80:81]
	v_lshl_add_u64 v[82:83], v[80:81], 2, s[6:7]
	v_lshlrev_b64 v[84:85], 5, v[80:81]
	v_lshl_add_u64 v[80:81], v[142:143], 0, v[116:117]
	v_lshl_add_u64 v[84:85], s[28:29], 0, v[84:85]
	global_load_dword v124, v[82:83], off
	global_load_dwordx2 v[100:101], v[84:85], off
	global_load_dwordx2 v[114:115], v[80:81], off
	global_load_dwordx2 v[110:111], v[80:81], off offset:32
	global_load_dwordx2 v[108:109], v[80:81], off offset:64
	global_load_dwordx2 v[106:107], v[80:81], off offset:96
	v_or_b32_e32 v80, 0x60, v144
	v_ashrrev_i32_e32 v81, 31, v80
	v_lshl_add_u64 v[82:83], v[80:81], 2, s[6:7]
	v_lshlrev_b64 v[84:85], 5, v[80:81]
	v_lshl_add_u64 v[84:85], s[28:29], 0, v[84:85]
	global_load_dword v123, v[82:83], off
	global_load_dwordx2 v[88:89], v[84:85], off
	v_or_b32_e32 v82, 0x70, v144
	v_lshlrev_b64 v[104:105], 12, v[80:81]
	v_ashrrev_i32_e32 v83, 31, v82
	v_lshl_add_u64 v[80:81], v[142:143], 0, v[104:105]
	v_lshlrev_b64 v[84:85], 5, v[82:83]
	v_lshlrev_b64 v[92:93], 12, v[82:83]
	global_load_dwordx2 v[102:103], v[80:81], off
	global_load_dwordx2 v[98:99], v[80:81], off offset:32
	global_load_dwordx2 v[96:97], v[80:81], off offset:64
	global_load_dwordx2 v[94:95], v[80:81], off offset:96
	v_lshl_add_u64 v[80:81], v[82:83], 2, s[6:7]
	v_lshl_add_u64 v[84:85], s[28:29], 0, v[84:85]
	v_lshl_add_u64 v[82:83], v[142:143], 0, v[92:93]
	global_load_dword v122, v[80:81], off
	s_nop 0
	global_load_dwordx2 v[80:81], v[84:85], off
	global_load_dwordx2 v[90:91], v[82:83], off
	global_load_dwordx2 v[86:87], v[82:83], off offset:32
	s_nop 0
	global_load_dwordx2 v[84:85], v[82:83], off offset:64
	s_nop 0
	global_load_dwordx2 v[82:83], v[82:83], off offset:96
	s_waitcnt vmcnt(23)
	v_mul_f32_e32 v76, v76, v125
	v_mul_f32_e32 v134, 0xbfb8aa3b, v76
	v_exp_f32_e32 v134, v134
	v_mul_f32_e32 v77, v77, v125
	v_mul_f32_e32 v135, 0xbfb8aa3b, v77
	v_exp_f32_e32 v135, v135
	v_add_f32_e32 v134, 1.0, v134
	v_rcp_f32_e32 v134, v134
	s_waitcnt vmcnt(21)
	v_lshlrev_b32_e32 v132, 16, v126
	v_mul_f32_e32 v78, v78, v125
	v_sub_f32_e32 v132, v132, v112
	v_mul_f32_e32 v76, v76, v134
	v_add_f32_e32 v134, 1.0, v135
	v_rcp_f32_e32 v134, v134
	v_mul_f32_e32 v76, v76, v132
	v_mul_f32_e32 v132, 0xbfb8aa3b, v78
	v_exp_f32_e32 v132, v132
	v_and_b32_e32 v126, 0xffff0000, v126
	v_mul_f32_e32 v79, v79, v125
	v_mul_f32_e32 v77, v77, v134
	v_sub_f32_e32 v126, v126, v112
	v_mul_f32_e32 v77, v77, v126
	v_add_f32_e32 v126, 1.0, v132
	v_mul_f32_e32 v132, 0xbfb8aa3b, v79
	v_exp_f32_e32 v132, v132
	v_rcp_f32_e32 v126, v126
	v_lshlrev_b32_e32 v133, 16, v127
	v_and_b32_e32 v127, 0xffff0000, v127
	v_add_f32_e32 v132, 1.0, v132
	v_rcp_f32_e32 v132, v132
	v_mul_f32_e32 v78, v78, v126
	v_sub_f32_e32 v126, v133, v112
	v_mul_f32_e32 v78, v78, v126
	v_mul_f32_e32 v79, v79, v132
	v_sub_f32_e32 v126, v127, v112
	v_mul_f32_e32 v79, v79, v126
	v_mul_f32_e32 v76, v113, v76
	v_mul_f32_e32 v77, v113, v77
	v_mul_f32_e32 v79, v113, v79
	v_mul_f32_e32 v76, v68, v76
	v_mul_f32_e32 v77, v69, v77
	v_mul_f32_e32 v78, v113, v78
	v_mul_f32_e32 v79, v71, v79
	v_mul_f32_e32 v72, v72, v125
	v_mul_f32_e32 v78, v70, v78
	v_cvt_pk_bf16_f32 v76, v76, v77
	v_cvt_pk_bf16_f32 v77, v78, v79
	v_mul_f32_e32 v79, 0xbfb8aa3b, v72
	v_exp_f32_e32 v79, v79
	v_mul_f32_e32 v73, v73, v125
	v_mul_f32_e32 v127, 0xbfb8aa3b, v73
	v_exp_f32_e32 v127, v127
	v_add_f32_e32 v79, 1.0, v79
	v_rcp_f32_e32 v79, v79
	v_lshl_add_u64 v[118:119], v[140:141], 0, v[118:119]
	global_store_dwordx2 v[118:119], v[76:77], off
	s_waitcnt vmcnt(21)
	v_lshlrev_b32_e32 v76, 16, v128
	v_mul_f32_e32 v72, v72, v79
	v_add_f32_e32 v79, 1.0, v127
	v_rcp_f32_e32 v79, v79
	v_and_b32_e32 v77, 0xffff0000, v128
	v_mul_f32_e32 v74, v74, v125
	v_sub_f32_e32 v76, v76, v112
	v_mul_f32_e32 v75, v75, v125
	v_mul_f32_e32 v72, v72, v76
	v_mul_f32_e32 v73, v73, v79
	v_mul_f32_e32 v76, 0xbfb8aa3b, v74
	v_sub_f32_e32 v77, v77, v112
	v_exp_f32_e32 v76, v76
	v_mul_f32_e32 v73, v73, v77
	v_mul_f32_e32 v77, 0xbfb8aa3b, v75
	v_exp_f32_e32 v77, v77
	v_add_f32_e32 v76, 1.0, v76
	v_rcp_f32_e32 v76, v76
	v_lshlrev_b32_e32 v78, 16, v129
	v_add_f32_e32 v77, 1.0, v77
	v_rcp_f32_e32 v77, v77
	v_and_b32_e32 v126, 0xffff0000, v129
	v_mul_f32_e32 v74, v74, v76
	v_sub_f32_e32 v76, v78, v112
	v_mul_f32_e32 v74, v74, v76
	v_mul_f32_e32 v75, v75, v77
	v_sub_f32_e32 v76, v126, v112
	v_mul_f32_e32 v75, v75, v76
	v_mul_f32_e32 v72, v113, v72
	v_mul_f32_e32 v73, v113, v73
	v_mul_f32_e32 v75, v113, v75
	v_mul_f32_e32 v72, v60, v72
	v_mul_f32_e32 v73, v61, v73
	v_mul_f32_e32 v74, v113, v74
	v_mul_f32_e32 v75, v63, v75
	v_mul_f32_e32 v64, v64, v125
	v_mul_f32_e32 v74, v62, v74
	v_cvt_pk_bf16_f32 v72, v72, v73
	v_cvt_pk_bf16_f32 v73, v74, v75
	v_mul_f32_e32 v75, 0xbfb8aa3b, v64
	v_exp_f32_e32 v75, v75
	v_mul_f32_e32 v65, v65, v125
	v_mul_f32_e32 v77, 0xbfb8aa3b, v65
	v_exp_f32_e32 v77, v77
	v_add_f32_e32 v75, 1.0, v75
	v_rcp_f32_e32 v75, v75
	global_store_dwordx2 v[118:119], v[72:73], off offset:32
	s_waitcnt vmcnt(21)
	v_lshlrev_b32_e32 v72, 16, v130
	v_and_b32_e32 v73, 0xffff0000, v130
	v_mul_f32_e32 v64, v64, v75
	v_add_f32_e32 v75, 1.0, v77
	v_rcp_f32_e32 v75, v75
	v_mul_f32_e32 v66, v66, v125
	v_sub_f32_e32 v72, v72, v112
	v_mul_f32_e32 v67, v67, v125
	v_mul_f32_e32 v64, v64, v72
	v_mul_f32_e32 v65, v65, v75
	v_mul_f32_e32 v72, 0xbfb8aa3b, v66
	v_sub_f32_e32 v73, v73, v112
	v_exp_f32_e32 v72, v72
	v_mul_f32_e32 v65, v65, v73
	v_mul_f32_e32 v73, 0xbfb8aa3b, v67
	v_exp_f32_e32 v73, v73
	v_add_f32_e32 v72, 1.0, v72
	v_rcp_f32_e32 v72, v72
	v_lshlrev_b32_e32 v74, 16, v131
	v_add_f32_e32 v73, 1.0, v73
	v_rcp_f32_e32 v73, v73
	v_and_b32_e32 v76, 0xffff0000, v131
	v_mul_f32_e32 v66, v66, v72
	v_sub_f32_e32 v72, v74, v112
	v_mul_f32_e32 v66, v66, v72
	v_mul_f32_e32 v67, v67, v73
	v_sub_f32_e32 v72, v76, v112
	v_mul_f32_e32 v67, v67, v72
	v_mul_f32_e32 v64, v113, v64
	v_mul_f32_e32 v65, v113, v65
	v_mul_f32_e32 v67, v113, v67
	v_mul_f32_e32 v64, v52, v64
	v_mul_f32_e32 v65, v53, v65
	v_mul_f32_e32 v66, v113, v66
	v_mul_f32_e32 v67, v55, v67
	v_mul_f32_e32 v56, v56, v125
	v_mul_f32_e32 v66, v54, v66
	v_cvt_pk_bf16_f32 v64, v64, v65
	v_cvt_pk_bf16_f32 v65, v66, v67
	v_mul_f32_e32 v67, 0xbfb8aa3b, v56
	v_exp_f32_e32 v67, v67
	v_mul_f32_e32 v57, v57, v125
	v_mul_f32_e32 v73, 0xbfb8aa3b, v57
	v_exp_f32_e32 v73, v73
	v_add_f32_e32 v67, 1.0, v67
	v_rcp_f32_e32 v67, v67
	global_store_dwordx2 v[118:119], v[64:65], off offset:64
	s_waitcnt vmcnt(21)
	v_and_b32_e32 v65, 0xffff0000, v120
	v_mul_f32_e32 v59, v59, v125
	v_mul_f32_e32 v56, v56, v67
	v_add_f32_e32 v67, 1.0, v73
	v_rcp_f32_e32 v67, v67
	v_sub_f32_e32 v65, v65, v112
	v_lshlrev_b32_e32 v64, 16, v120
	v_mul_f32_e32 v58, v58, v125
	v_mul_f32_e32 v57, v57, v67
	v_mul_f32_e32 v57, v57, v65
	v_mul_f32_e32 v65, 0xbfb8aa3b, v59
	v_exp_f32_e32 v65, v65
	v_sub_f32_e32 v64, v64, v112
	v_mul_f32_e32 v56, v56, v64
	v_mul_f32_e32 v64, 0xbfb8aa3b, v58
	v_add_f32_e32 v65, 1.0, v65
	v_rcp_f32_e32 v65, v65
	s_waitcnt vmcnt(20)
	v_mul_f32_e32 v48, v48, v124
	v_exp_f32_e32 v64, v64
	v_mul_f32_e32 v49, v49, v124
	v_mul_f32_e32 v59, v59, v65
	v_mul_f32_e32 v65, 0xbfb8aa3b, v48
	v_exp_f32_e32 v65, v65
	v_add_f32_e32 v64, 1.0, v64
	v_rcp_f32_e32 v64, v64
	v_mul_f32_e32 v67, 0xbfb8aa3b, v49
	v_add_f32_e32 v65, 1.0, v65
	v_rcp_f32_e32 v65, v65
	v_exp_f32_e32 v67, v67
	v_lshlrev_b32_e32 v66, 16, v121
	v_and_b32_e32 v72, 0xffff0000, v121
	v_mul_f32_e32 v58, v58, v64
	v_sub_f32_e32 v64, v66, v112
	v_mul_f32_e32 v58, v58, v64
	v_sub_f32_e32 v64, v72, v112
	v_mul_f32_e32 v48, v48, v65
	v_add_f32_e32 v65, 1.0, v67
	v_mul_f32_e32 v56, v113, v56
	v_mul_f32_e32 v57, v113, v57
	v_mul_f32_e32 v58, v113, v58
	v_mul_f32_e32 v59, v59, v64
	v_rcp_f32_e32 v65, v65
	v_mul_f32_e32 v56, v44, v56
	v_mul_f32_e32 v57, v45, v57
	v_mul_f32_e32 v58, v46, v58
	v_mul_f32_e32 v59, v113, v59
	v_mul_f32_e32 v59, v47, v59
	v_cvt_pk_bf16_f32 v56, v56, v57
	v_cvt_pk_bf16_f32 v57, v58, v59
	s_waitcnt vmcnt(18)
	v_lshlrev_b32_e32 v58, 16, v114
	v_and_b32_e32 v59, 0xffff0000, v114
	v_mul_f32_e32 v50, v50, v124
	v_sub_f32_e32 v58, v58, v100
	v_mul_f32_e32 v51, v51, v124
	v_mul_f32_e32 v48, v48, v58
	v_mul_f32_e32 v49, v49, v65
	v_mul_f32_e32 v58, 0xbfb8aa3b, v50
	v_sub_f32_e32 v59, v59, v100
	v_exp_f32_e32 v58, v58
	v_mul_f32_e32 v49, v49, v59
	v_mul_f32_e32 v59, 0xbfb8aa3b, v51
	v_exp_f32_e32 v59, v59
	v_add_f32_e32 v58, 1.0, v58
	v_rcp_f32_e32 v58, v58
	v_lshlrev_b32_e32 v64, 16, v115
	v_add_f32_e32 v59, 1.0, v59
	v_rcp_f32_e32 v59, v59
	v_and_b32_e32 v66, 0xffff0000, v115
	v_mul_f32_e32 v50, v50, v58
	v_sub_f32_e32 v58, v64, v100
	v_mul_f32_e32 v50, v50, v58
	v_mul_f32_e32 v51, v51, v59
	v_sub_f32_e32 v58, v66, v100
	v_mul_f32_e32 v51, v51, v58
	v_mul_f32_e32 v48, v101, v48
	v_mul_f32_e32 v49, v101, v49
	v_mul_f32_e32 v51, v101, v51
	v_mul_f32_e32 v48, v68, v48
	v_mul_f32_e32 v49, v69, v49
	v_mul_f32_e32 v50, v101, v50
	v_mul_f32_e32 v51, v71, v51
	v_mul_f32_e32 v40, v40, v124
	v_mul_f32_e32 v50, v70, v50
	v_cvt_pk_bf16_f32 v48, v48, v49
	v_cvt_pk_bf16_f32 v49, v50, v51
	v_mul_f32_e32 v51, 0xbfb8aa3b, v40
	v_exp_f32_e32 v51, v51
	v_mul_f32_e32 v41, v41, v124
	v_mul_f32_e32 v59, 0xbfb8aa3b, v41
	v_exp_f32_e32 v59, v59
	v_add_f32_e32 v51, 1.0, v51
	v_rcp_f32_e32 v51, v51
	global_store_dwordx2 v[118:119], v[56:57], off offset:96
	v_lshl_add_u64 v[56:57], v[140:141], 0, v[116:117]
	global_store_dwordx2 v[56:57], v[48:49], off
	v_mul_f32_e32 v40, v40, v51
	v_add_f32_e32 v51, 1.0, v59
	v_rcp_f32_e32 v51, v51
	s_waitcnt vmcnt(19)
	v_lshlrev_b32_e32 v48, 16, v110
	v_and_b32_e32 v49, 0xffff0000, v110
	v_mul_f32_e32 v42, v42, v124
	v_sub_f32_e32 v48, v48, v100
	v_mul_f32_e32 v43, v43, v124
	v_mul_f32_e32 v40, v40, v48
	v_mul_f32_e32 v41, v41, v51
	v_mul_f32_e32 v48, 0xbfb8aa3b, v42
	v_sub_f32_e32 v49, v49, v100
	v_exp_f32_e32 v48, v48
	v_mul_f32_e32 v41, v41, v49
	v_mul_f32_e32 v49, 0xbfb8aa3b, v43
	v_exp_f32_e32 v49, v49
	v_add_f32_e32 v48, 1.0, v48
	v_rcp_f32_e32 v48, v48
	v_lshlrev_b32_e32 v50, 16, v111
	v_add_f32_e32 v49, 1.0, v49
	v_rcp_f32_e32 v49, v49
	v_and_b32_e32 v58, 0xffff0000, v111
	v_mul_f32_e32 v42, v42, v48
	v_sub_f32_e32 v48, v50, v100
	v_mul_f32_e32 v42, v42, v48
	v_mul_f32_e32 v43, v43, v49
	v_sub_f32_e32 v48, v58, v100
	v_mul_f32_e32 v43, v43, v48
	v_mul_f32_e32 v40, v101, v40
	v_mul_f32_e32 v41, v101, v41
	v_mul_f32_e32 v43, v101, v43
	v_mul_f32_e32 v40, v60, v40
	v_mul_f32_e32 v41, v61, v41
	v_mul_f32_e32 v42, v101, v42
	v_mul_f32_e32 v43, v63, v43
	v_mul_f32_e32 v36, v36, v124
	v_mul_f32_e32 v42, v62, v42
	v_cvt_pk_bf16_f32 v40, v40, v41
	v_cvt_pk_bf16_f32 v41, v42, v43
	v_mul_f32_e32 v43, 0xbfb8aa3b, v36
	v_exp_f32_e32 v43, v43
	v_mul_f32_e32 v37, v37, v124
	v_mul_f32_e32 v49, 0xbfb8aa3b, v37
	v_exp_f32_e32 v49, v49
	v_add_f32_e32 v43, 1.0, v43
	v_rcp_f32_e32 v43, v43
	global_store_dwordx2 v[56:57], v[40:41], off offset:32
	s_waitcnt vmcnt(19)
	v_lshlrev_b32_e32 v40, 16, v108
	v_and_b32_e32 v41, 0xffff0000, v108
	v_mul_f32_e32 v36, v36, v43
	v_add_f32_e32 v43, 1.0, v49
	v_rcp_f32_e32 v43, v43
	v_mul_f32_e32 v38, v38, v124
	v_sub_f32_e32 v40, v40, v100
	v_mul_f32_e32 v39, v39, v124
	v_mul_f32_e32 v36, v36, v40
	v_mul_f32_e32 v37, v37, v43
	v_mul_f32_e32 v40, 0xbfb8aa3b, v38
	v_sub_f32_e32 v41, v41, v100
	v_exp_f32_e32 v40, v40
	v_mul_f32_e32 v37, v37, v41
	v_mul_f32_e32 v41, 0xbfb8aa3b, v39
	v_exp_f32_e32 v41, v41
	v_add_f32_e32 v40, 1.0, v40
	v_rcp_f32_e32 v40, v40
	v_lshlrev_b32_e32 v42, 16, v109
	v_add_f32_e32 v41, 1.0, v41
	v_rcp_f32_e32 v41, v41
	v_and_b32_e32 v48, 0xffff0000, v109
	v_mul_f32_e32 v38, v38, v40
	v_sub_f32_e32 v40, v42, v100
	v_mul_f32_e32 v38, v38, v40
	v_mul_f32_e32 v39, v39, v41
	v_sub_f32_e32 v40, v48, v100
	v_mul_f32_e32 v39, v39, v40
	v_mul_f32_e32 v36, v101, v36
	v_mul_f32_e32 v37, v101, v37
	v_mul_f32_e32 v39, v101, v39
	v_mul_f32_e32 v36, v52, v36
	v_mul_f32_e32 v37, v53, v37
	v_mul_f32_e32 v38, v101, v38
	v_mul_f32_e32 v39, v55, v39
	v_mul_f32_e32 v32, v32, v124
	v_mul_f32_e32 v38, v54, v38
	v_cvt_pk_bf16_f32 v36, v36, v37
	v_cvt_pk_bf16_f32 v37, v38, v39
	v_mul_f32_e32 v39, 0xbfb8aa3b, v32
	v_exp_f32_e32 v39, v39
	v_mul_f32_e32 v33, v33, v124
	v_mul_f32_e32 v41, 0xbfb8aa3b, v33
	v_exp_f32_e32 v41, v41
	v_add_f32_e32 v39, 1.0, v39
	v_rcp_f32_e32 v39, v39
	global_store_dwordx2 v[56:57], v[36:37], off offset:64
	s_waitcnt vmcnt(19)
	v_and_b32_e32 v37, 0xffff0000, v106
	v_mul_f32_e32 v35, v35, v124
	v_mul_f32_e32 v32, v32, v39
	v_add_f32_e32 v39, 1.0, v41
	v_rcp_f32_e32 v39, v39
	v_sub_f32_e32 v37, v37, v100
	v_lshlrev_b32_e32 v36, 16, v106
	v_mul_f32_e32 v34, v34, v124
	v_mul_f32_e32 v33, v33, v39
	v_mul_f32_e32 v33, v33, v37
	v_mul_f32_e32 v37, 0xbfb8aa3b, v35
	v_exp_f32_e32 v37, v37
	v_sub_f32_e32 v36, v36, v100
	v_mul_f32_e32 v32, v32, v36
	v_mul_f32_e32 v36, 0xbfb8aa3b, v34
	v_add_f32_e32 v37, 1.0, v37
	v_rcp_f32_e32 v37, v37
	s_waitcnt vmcnt(18)
	v_mul_f32_e32 v28, v28, v123
	v_exp_f32_e32 v36, v36
	v_mul_f32_e32 v29, v29, v123
	v_mul_f32_e32 v35, v35, v37
	v_mul_f32_e32 v37, 0xbfb8aa3b, v28
	v_exp_f32_e32 v37, v37
	v_add_f32_e32 v36, 1.0, v36
	v_rcp_f32_e32 v36, v36
	v_mul_f32_e32 v39, 0xbfb8aa3b, v29
	v_add_f32_e32 v37, 1.0, v37
	v_rcp_f32_e32 v37, v37
	v_exp_f32_e32 v39, v39
	v_lshlrev_b32_e32 v38, 16, v107
	v_and_b32_e32 v40, 0xffff0000, v107
	v_mul_f32_e32 v34, v34, v36
	v_sub_f32_e32 v36, v38, v100
	v_mul_f32_e32 v34, v34, v36
	v_sub_f32_e32 v36, v40, v100
	v_mul_f32_e32 v28, v28, v37
	v_add_f32_e32 v37, 1.0, v39
	v_mul_f32_e32 v32, v101, v32
	v_mul_f32_e32 v33, v101, v33
	v_mul_f32_e32 v34, v101, v34
	v_mul_f32_e32 v35, v35, v36
	v_rcp_f32_e32 v37, v37
	v_mul_f32_e32 v32, v44, v32
	v_mul_f32_e32 v33, v45, v33
	v_mul_f32_e32 v34, v46, v34
	v_mul_f32_e32 v35, v101, v35
	v_mul_f32_e32 v35, v47, v35
	v_cvt_pk_bf16_f32 v32, v32, v33
	v_cvt_pk_bf16_f32 v33, v34, v35
	s_waitcnt vmcnt(16)
	v_lshlrev_b32_e32 v34, 16, v102
	v_and_b32_e32 v35, 0xffff0000, v102
	v_mul_f32_e32 v30, v30, v123
	v_sub_f32_e32 v34, v34, v88
	v_mul_f32_e32 v31, v31, v123
	v_mul_f32_e32 v28, v28, v34
	v_mul_f32_e32 v29, v29, v37
	v_mul_f32_e32 v34, 0xbfb8aa3b, v30
	v_sub_f32_e32 v35, v35, v88
	v_exp_f32_e32 v34, v34
	v_mul_f32_e32 v29, v29, v35
	v_mul_f32_e32 v35, 0xbfb8aa3b, v31
	v_exp_f32_e32 v35, v35
	v_add_f32_e32 v34, 1.0, v34
	v_rcp_f32_e32 v34, v34
	v_lshlrev_b32_e32 v36, 16, v103
	v_add_f32_e32 v35, 1.0, v35
	v_rcp_f32_e32 v35, v35
	v_and_b32_e32 v38, 0xffff0000, v103
	v_mul_f32_e32 v30, v30, v34
	v_sub_f32_e32 v34, v36, v88
	v_mul_f32_e32 v30, v30, v34
	v_mul_f32_e32 v31, v31, v35
	v_sub_f32_e32 v34, v38, v88
	v_mul_f32_e32 v31, v31, v34
	v_mul_f32_e32 v28, v89, v28
	v_mul_f32_e32 v29, v89, v29
	v_mul_f32_e32 v31, v89, v31
	v_mul_f32_e32 v28, v68, v28
	v_mul_f32_e32 v29, v69, v29
	v_mul_f32_e32 v30, v89, v30
	v_mul_f32_e32 v31, v71, v31
	v_mul_f32_e32 v24, v24, v123
	v_mul_f32_e32 v30, v70, v30
	v_cvt_pk_bf16_f32 v28, v28, v29
	v_cvt_pk_bf16_f32 v29, v30, v31
	v_mul_f32_e32 v31, 0xbfb8aa3b, v24
	v_exp_f32_e32 v31, v31
	v_mul_f32_e32 v25, v25, v123
	v_mul_f32_e32 v35, 0xbfb8aa3b, v25
	v_exp_f32_e32 v35, v35
	v_add_f32_e32 v31, 1.0, v31
	v_rcp_f32_e32 v31, v31
	global_store_dwordx2 v[56:57], v[32:33], off offset:96
	v_lshl_add_u64 v[32:33], v[140:141], 0, v[104:105]
	global_store_dwordx2 v[32:33], v[28:29], off
	v_mul_f32_e32 v24, v24, v31
	v_add_f32_e32 v31, 1.0, v35
	v_rcp_f32_e32 v31, v31
	s_waitcnt vmcnt(17)
	v_lshlrev_b32_e32 v28, 16, v98
	v_and_b32_e32 v29, 0xffff0000, v98
	v_mul_f32_e32 v26, v26, v123
	v_sub_f32_e32 v28, v28, v88
	v_mul_f32_e32 v27, v27, v123
	v_mul_f32_e32 v24, v24, v28
	v_mul_f32_e32 v25, v25, v31
	v_mul_f32_e32 v28, 0xbfb8aa3b, v26
	v_sub_f32_e32 v29, v29, v88
	v_exp_f32_e32 v28, v28
	v_mul_f32_e32 v25, v25, v29
	v_mul_f32_e32 v29, 0xbfb8aa3b, v27
	v_exp_f32_e32 v29, v29
	v_add_f32_e32 v28, 1.0, v28
	v_rcp_f32_e32 v28, v28
	v_lshlrev_b32_e32 v30, 16, v99
	v_add_f32_e32 v29, 1.0, v29
	v_rcp_f32_e32 v29, v29
	v_and_b32_e32 v34, 0xffff0000, v99
	v_mul_f32_e32 v26, v26, v28
	v_sub_f32_e32 v28, v30, v88
	v_mul_f32_e32 v26, v26, v28
	v_mul_f32_e32 v27, v27, v29
	v_sub_f32_e32 v28, v34, v88
	v_mul_f32_e32 v27, v27, v28
	v_mul_f32_e32 v24, v89, v24
	v_mul_f32_e32 v25, v89, v25
	v_mul_f32_e32 v27, v89, v27
	v_mul_f32_e32 v24, v60, v24
	v_mul_f32_e32 v25, v61, v25
	v_mul_f32_e32 v26, v89, v26
	v_mul_f32_e32 v27, v63, v27
	v_mul_f32_e32 v20, v20, v123
	v_mul_f32_e32 v26, v62, v26
	v_cvt_pk_bf16_f32 v24, v24, v25
	v_cvt_pk_bf16_f32 v25, v26, v27
	v_mul_f32_e32 v27, 0xbfb8aa3b, v20
	v_exp_f32_e32 v27, v27
	v_mul_f32_e32 v21, v21, v123
	v_mul_f32_e32 v29, 0xbfb8aa3b, v21
	v_exp_f32_e32 v29, v29
	v_add_f32_e32 v27, 1.0, v27
	v_rcp_f32_e32 v27, v27
	global_store_dwordx2 v[32:33], v[24:25], off offset:32
	s_waitcnt vmcnt(17)
	v_lshlrev_b32_e32 v24, 16, v96
	v_and_b32_e32 v25, 0xffff0000, v96
	v_mul_f32_e32 v20, v20, v27
	v_add_f32_e32 v27, 1.0, v29
	v_rcp_f32_e32 v27, v27
	v_mul_f32_e32 v22, v22, v123
	v_sub_f32_e32 v24, v24, v88
	v_mul_f32_e32 v23, v23, v123
	v_mul_f32_e32 v20, v20, v24
	v_mul_f32_e32 v21, v21, v27
	v_mul_f32_e32 v24, 0xbfb8aa3b, v22
	v_sub_f32_e32 v25, v25, v88
	v_exp_f32_e32 v24, v24
	v_mul_f32_e32 v21, v21, v25
	v_mul_f32_e32 v25, 0xbfb8aa3b, v23
	v_exp_f32_e32 v25, v25
	v_add_f32_e32 v24, 1.0, v24
	v_rcp_f32_e32 v24, v24
	v_lshlrev_b32_e32 v26, 16, v97
	v_add_f32_e32 v25, 1.0, v25
	v_rcp_f32_e32 v25, v25
	v_and_b32_e32 v28, 0xffff0000, v97
	v_mul_f32_e32 v22, v22, v24
	v_sub_f32_e32 v24, v26, v88
	v_mul_f32_e32 v22, v22, v24
	v_mul_f32_e32 v23, v23, v25
	v_sub_f32_e32 v24, v28, v88
	v_mul_f32_e32 v23, v23, v24
	v_mul_f32_e32 v20, v89, v20
	v_mul_f32_e32 v21, v89, v21
	v_mul_f32_e32 v23, v89, v23
	v_mul_f32_e32 v20, v52, v20
	v_mul_f32_e32 v21, v53, v21
	v_mul_f32_e32 v22, v89, v22
	v_mul_f32_e32 v23, v55, v23
	v_mul_f32_e32 v16, v16, v123
	v_mul_f32_e32 v22, v54, v22
	v_cvt_pk_bf16_f32 v20, v20, v21
	v_cvt_pk_bf16_f32 v21, v22, v23
	v_mul_f32_e32 v23, 0xbfb8aa3b, v16
	v_exp_f32_e32 v23, v23
	v_mul_f32_e32 v17, v17, v123
	v_mul_f32_e32 v25, 0xbfb8aa3b, v17
	v_exp_f32_e32 v25, v25
	v_add_f32_e32 v23, 1.0, v23
	v_rcp_f32_e32 v23, v23
	global_store_dwordx2 v[32:33], v[20:21], off offset:64
	s_waitcnt vmcnt(17)
	v_and_b32_e32 v21, 0xffff0000, v94
	v_mul_f32_e32 v19, v19, v123
	v_mul_f32_e32 v16, v16, v23
	v_add_f32_e32 v23, 1.0, v25
	v_rcp_f32_e32 v23, v23
	v_sub_f32_e32 v21, v21, v88
	v_lshlrev_b32_e32 v20, 16, v94
	v_mul_f32_e32 v18, v18, v123
	v_mul_f32_e32 v17, v17, v23
	v_mul_f32_e32 v17, v17, v21
	v_mul_f32_e32 v21, 0xbfb8aa3b, v19
	v_exp_f32_e32 v21, v21
	v_sub_f32_e32 v20, v20, v88
	v_mul_f32_e32 v16, v16, v20
	v_mul_f32_e32 v20, 0xbfb8aa3b, v18
	v_add_f32_e32 v21, 1.0, v21
	v_rcp_f32_e32 v21, v21
	s_waitcnt vmcnt(16)
	v_mul_f32_e32 v12, v12, v122
	v_exp_f32_e32 v20, v20
	v_mul_f32_e32 v13, v13, v122
	v_mul_f32_e32 v19, v19, v21
	v_mul_f32_e32 v21, 0xbfb8aa3b, v12
	v_exp_f32_e32 v21, v21
	v_add_f32_e32 v20, 1.0, v20
	v_rcp_f32_e32 v20, v20
	v_mul_f32_e32 v23, 0xbfb8aa3b, v13
	v_add_f32_e32 v21, 1.0, v21
	v_rcp_f32_e32 v21, v21
	v_exp_f32_e32 v23, v23
	v_lshlrev_b32_e32 v22, 16, v95
	v_and_b32_e32 v24, 0xffff0000, v95
	v_mul_f32_e32 v18, v18, v20
	v_sub_f32_e32 v20, v22, v88
	v_mul_f32_e32 v18, v18, v20
	v_sub_f32_e32 v20, v24, v88
	v_mul_f32_e32 v12, v12, v21
	v_add_f32_e32 v21, 1.0, v23
	v_mul_f32_e32 v16, v89, v16
	v_mul_f32_e32 v17, v89, v17
	v_mul_f32_e32 v18, v89, v18
	v_mul_f32_e32 v19, v19, v20
	v_rcp_f32_e32 v21, v21
	v_mul_f32_e32 v16, v44, v16
	v_mul_f32_e32 v17, v45, v17
	v_mul_f32_e32 v18, v46, v18
	v_mul_f32_e32 v19, v89, v19
	v_mul_f32_e32 v19, v47, v19
	v_cvt_pk_bf16_f32 v16, v16, v17
	v_cvt_pk_bf16_f32 v17, v18, v19
	s_waitcnt vmcnt(14)
	v_lshlrev_b32_e32 v18, 16, v90
	v_and_b32_e32 v19, 0xffff0000, v90
	v_mul_f32_e32 v14, v14, v122
	v_sub_f32_e32 v18, v18, v80
	v_mul_f32_e32 v15, v15, v122
	v_mul_f32_e32 v12, v12, v18
	v_mul_f32_e32 v13, v13, v21
	v_mul_f32_e32 v18, 0xbfb8aa3b, v14
	v_sub_f32_e32 v19, v19, v80
	v_exp_f32_e32 v18, v18
	v_mul_f32_e32 v13, v13, v19
	v_mul_f32_e32 v19, 0xbfb8aa3b, v15
	v_exp_f32_e32 v19, v19
	v_add_f32_e32 v18, 1.0, v18
	v_rcp_f32_e32 v18, v18
	v_lshlrev_b32_e32 v20, 16, v91
	v_add_f32_e32 v19, 1.0, v19
	v_rcp_f32_e32 v19, v19
	v_and_b32_e32 v22, 0xffff0000, v91
	v_mul_f32_e32 v14, v14, v18
	v_sub_f32_e32 v18, v20, v80
	v_mul_f32_e32 v14, v14, v18
	v_mul_f32_e32 v15, v15, v19
	v_sub_f32_e32 v18, v22, v80
	v_mul_f32_e32 v15, v15, v18
	v_mul_f32_e32 v12, v81, v12
	v_mul_f32_e32 v13, v81, v13
	v_mul_f32_e32 v15, v81, v15
	v_mul_f32_e32 v12, v68, v12
	v_mul_f32_e32 v13, v69, v13
	v_mul_f32_e32 v14, v81, v14
	v_mul_f32_e32 v15, v71, v15
	v_mul_f32_e32 v8, v8, v122
	v_mul_f32_e32 v14, v70, v14
	v_cvt_pk_bf16_f32 v12, v12, v13
	v_cvt_pk_bf16_f32 v13, v14, v15
	v_mul_f32_e32 v15, 0xbfb8aa3b, v8
	v_exp_f32_e32 v15, v15
	v_mul_f32_e32 v9, v9, v122
	v_mul_f32_e32 v19, 0xbfb8aa3b, v9
	v_exp_f32_e32 v19, v19
	v_add_f32_e32 v15, 1.0, v15
	v_rcp_f32_e32 v15, v15
	global_store_dwordx2 v[32:33], v[16:17], off offset:96
	v_lshl_add_u64 v[16:17], v[140:141], 0, v[92:93]
	global_store_dwordx2 v[16:17], v[12:13], off
	v_mul_f32_e32 v8, v8, v15
	v_add_f32_e32 v15, 1.0, v19
	v_rcp_f32_e32 v15, v15
	s_waitcnt vmcnt(15)
	v_lshlrev_b32_e32 v12, 16, v86
	v_and_b32_e32 v13, 0xffff0000, v86
	v_mul_f32_e32 v10, v10, v122
	v_sub_f32_e32 v12, v12, v80
	v_mul_f32_e32 v11, v11, v122
	v_mul_f32_e32 v8, v8, v12
	v_mul_f32_e32 v9, v9, v15
	v_mul_f32_e32 v12, 0xbfb8aa3b, v10
	v_sub_f32_e32 v13, v13, v80
	v_exp_f32_e32 v12, v12
	v_mul_f32_e32 v9, v9, v13
	v_mul_f32_e32 v13, 0xbfb8aa3b, v11
	v_exp_f32_e32 v13, v13
	v_add_f32_e32 v12, 1.0, v12
	v_rcp_f32_e32 v12, v12
	v_lshlrev_b32_e32 v14, 16, v87
	v_add_f32_e32 v13, 1.0, v13
	v_rcp_f32_e32 v13, v13
	v_and_b32_e32 v18, 0xffff0000, v87
	v_mul_f32_e32 v10, v10, v12
	v_sub_f32_e32 v12, v14, v80
	v_mul_f32_e32 v10, v10, v12
	v_mul_f32_e32 v11, v11, v13
	v_sub_f32_e32 v12, v18, v80
	v_mul_f32_e32 v11, v11, v12
	v_mul_f32_e32 v8, v81, v8
	v_mul_f32_e32 v9, v81, v9
	v_mul_f32_e32 v11, v81, v11
	v_mul_f32_e32 v8, v60, v8
	v_mul_f32_e32 v9, v61, v9
	v_mul_f32_e32 v10, v81, v10
	v_mul_f32_e32 v11, v63, v11
	v_mul_f32_e32 v4, v4, v122
	v_mul_f32_e32 v10, v62, v10
	v_cvt_pk_bf16_f32 v8, v8, v9
	v_cvt_pk_bf16_f32 v9, v10, v11
	v_mul_f32_e32 v11, 0xbfb8aa3b, v4
	v_exp_f32_e32 v11, v11
	v_mul_f32_e32 v5, v5, v122
	v_mul_f32_e32 v13, 0xbfb8aa3b, v5
	v_exp_f32_e32 v13, v13
	v_add_f32_e32 v11, 1.0, v11
	v_rcp_f32_e32 v11, v11
	global_store_dwordx2 v[16:17], v[8:9], off offset:32
	s_waitcnt vmcnt(15)
	v_lshlrev_b32_e32 v8, 16, v84
	v_and_b32_e32 v9, 0xffff0000, v84
	v_mul_f32_e32 v4, v4, v11
	v_add_f32_e32 v11, 1.0, v13
	v_rcp_f32_e32 v11, v11
	v_mul_f32_e32 v6, v6, v122
	v_sub_f32_e32 v8, v8, v80
	v_mul_f32_e32 v7, v7, v122
	v_mul_f32_e32 v4, v4, v8
	v_mul_f32_e32 v5, v5, v11
	v_mul_f32_e32 v8, 0xbfb8aa3b, v6
	v_sub_f32_e32 v9, v9, v80
	v_exp_f32_e32 v8, v8
	v_mul_f32_e32 v5, v5, v9
	v_mul_f32_e32 v9, 0xbfb8aa3b, v7
	v_exp_f32_e32 v9, v9
	v_add_f32_e32 v8, 1.0, v8
	v_rcp_f32_e32 v8, v8
	v_lshlrev_b32_e32 v10, 16, v85
	v_add_f32_e32 v9, 1.0, v9
	v_rcp_f32_e32 v9, v9
	v_and_b32_e32 v12, 0xffff0000, v85
	v_mul_f32_e32 v6, v6, v8
	v_sub_f32_e32 v8, v10, v80
	v_mul_f32_e32 v6, v6, v8
	v_mul_f32_e32 v7, v7, v9
	v_sub_f32_e32 v8, v12, v80
	v_mul_f32_e32 v7, v7, v8
	v_mul_f32_e32 v4, v81, v4
	v_mul_f32_e32 v5, v81, v5
	v_mul_f32_e32 v7, v81, v7
	v_mul_f32_e32 v4, v52, v4
	v_mul_f32_e32 v5, v53, v5
	v_mul_f32_e32 v6, v81, v6
	v_mul_f32_e32 v7, v55, v7
	v_mul_f32_e32 v0, v0, v122
	v_mul_f32_e32 v6, v54, v6
	v_cvt_pk_bf16_f32 v4, v4, v5
	v_cvt_pk_bf16_f32 v5, v6, v7
	v_mul_f32_e32 v7, 0xbfb8aa3b, v0
	v_exp_f32_e32 v7, v7
	v_mul_f32_e32 v1, v1, v122
	v_mul_f32_e32 v9, 0xbfb8aa3b, v1
	v_exp_f32_e32 v9, v9
	v_add_f32_e32 v7, 1.0, v7
	v_rcp_f32_e32 v7, v7
	global_store_dwordx2 v[16:17], v[4:5], off offset:64
	s_waitcnt vmcnt(15)
	v_lshlrev_b32_e32 v4, 16, v82
	v_and_b32_e32 v5, 0xffff0000, v82
	v_mul_f32_e32 v0, v0, v7
	v_add_f32_e32 v7, 1.0, v9
	v_rcp_f32_e32 v7, v7
	v_mul_f32_e32 v2, v2, v122
	v_sub_f32_e32 v4, v4, v80
	v_mul_f32_e32 v3, v3, v122
	v_mul_f32_e32 v0, v0, v4
	v_mul_f32_e32 v1, v1, v7
	v_mul_f32_e32 v4, 0xbfb8aa3b, v2
	v_sub_f32_e32 v5, v5, v80
	v_exp_f32_e32 v4, v4
	v_mul_f32_e32 v1, v1, v5
	v_mul_f32_e32 v5, 0xbfb8aa3b, v3
	v_exp_f32_e32 v5, v5
	v_add_f32_e32 v4, 1.0, v4
	v_rcp_f32_e32 v4, v4
	v_lshlrev_b32_e32 v6, 16, v83
	v_add_f32_e32 v5, 1.0, v5
	v_rcp_f32_e32 v5, v5
	v_and_b32_e32 v8, 0xffff0000, v83
	v_mul_f32_e32 v2, v2, v4
	v_sub_f32_e32 v4, v6, v80
	v_mul_f32_e32 v2, v2, v4
	v_mul_f32_e32 v3, v3, v5
	v_sub_f32_e32 v4, v8, v80
	v_mul_f32_e32 v0, v81, v0
	v_mul_f32_e32 v1, v81, v1
	v_mul_f32_e32 v3, v3, v4
	v_mul_f32_e32 v0, v44, v0
	v_mul_f32_e32 v1, v45, v1
	v_mul_f32_e32 v2, v81, v2
	v_mul_f32_e32 v3, v81, v3
	v_mul_f32_e32 v2, v46, v2
	v_mul_f32_e32 v3, v47, v3
	v_cvt_pk_bf16_f32 v0, v0, v1
	v_cvt_pk_bf16_f32 v1, v2, v3
	global_store_dwordx2 v[16:17], v[0:1], off offset:96
	s_add_i32 s34, s34, s74
	s_cmpk_lt_i32 s34, 0x800
	s_cbranch_scc1 .LBB0_502

.LBB0_560:
	s_ashr_i32 s22, s30, 3
	s_lshr_b32 s24, s22, 29
	s_add_i32 s24, s22, s24
	s_and_b32 s25, s24, 0x1fffff8
	s_sub_i32 s22, s22, s25
	s_lshl_b32 s24, s24, 8
	s_lshl_b32 s25, s30, 8
	s_and_b32 s24, s24, 0xfffff800
	s_and_b32 s25, s25, 0x700
	s_or_b32 s28, s24, s25
	s_ashr_i32 s29, s28, 31
	s_lshl_b32 s24, s22, 7
	s_lshl_b64 s[34:35], s[28:29], 12
	s_add_u32 s34, s3, s34
	s_addc_u32 s35, s4, s35
	s_ashr_i32 s25, s24, 31
	v_mov_b32_e32 v36, v220
	s_lshl_b64 s[36:37], s[24:25], 12
	s_add_u32 s36, s5, s36
	v_ashrrev_i32_e32 v26, 2, v36
	v_ashrrev_i32_e32 v27, 31, v26
	s_addc_u32 s37, s8, s37
	v_lshlrev_b64 v[0:1], 12, v[26:27]
	v_lshlrev_b32_e32 v4, 4, v36
	v_lshl_add_u64 v[2:3], s[36:37], 0, v[0:1]
	v_lshl_add_u64 v[0:1], s[34:35], 0, v[0:1]
	v_and_b32_e32 v176, 48, v4
	s_waitcnt vmcnt(9)
	v_lshl_add_u64 v[152:153], v[0:1], 0, v[176:177]
	v_add_co_u32_e32 v28, vcc, s9, v152
	v_lshl_add_u64 v[154:155], v[2:3], 0, v[176:177]
	s_nop 0
	v_addc_co_u32_e32 v29, vcc, 0, v153, vcc
	v_add_co_u32_e32 v30, vcc, s26, v152
	global_load_dwordx4 v[2:5], v[152:153], off
	s_nop 0
	v_addc_co_u32_e32 v31, vcc, 0, v153, vcc
	v_add_co_u32_e32 v32, vcc, s27, v152
	global_load_dwordx4 v[6:9], v[28:29], off
	s_nop 0
	v_addc_co_u32_e32 v33, vcc, 0, v153, vcc
	v_add_co_u32_e32 v34, vcc, s9, v154
	global_load_dwordx4 v[10:13], v[30:31], off
	s_nop 0
	v_addc_co_u32_e32 v35, vcc, 0, v155, vcc
	global_load_dwordx4 v[14:17], v[32:33], off
	global_load_dwordx4 v[18:21], v[154:155], off
	global_load_dwordx4 v[22:25], v[34:35], off
	global_load_dwordx4 v[112:115], v[152:153], off offset:64
	global_load_dwordx4 v[120:123], v[28:29], off offset:64
	global_load_dwordx4 v[124:127], v[30:31], off offset:64
	global_load_dwordx4 v[128:131], v[32:33], off offset:64
	global_load_dwordx4 v[116:119], v[154:155], off offset:64
	global_load_dwordx4 v[132:135], v[34:35], off offset:64
	v_lshrrev_b32_e32 v27, 4, v36
	v_lshrrev_b32_e32 v37, 2, v36
	v_sub_u32_e32 v40, 0, v27
	v_sub_u32_e32 v37, 0, v37
	v_and_b32_e32 v38, 0x3ffff8f, v36
	v_lshlrev_b32_e32 v39, 6, v36
	v_xor_b32_e32 v36, v36, v40
	v_xor_b32_e32 v27, v27, v37
	v_lshlrev_b32_e32 v36, 4, v36
	v_lshlrev_b32_e32 v27, 4, v27
	v_and_b32_e32 v41, 0x1000, v39
	v_and_b32_e32 v36, 48, v36
	v_and_b32_e32 v27, 48, v27
	v_and_b32_e32 v42, 0x3c0, v39
	v_and_b32_e32 v39, 0xffffe3c0, v39
	v_lshl_add_u32 v38, v38, 6, v196
	v_lshl_or_b32 v164, v26, 6, v36
	v_or_b32_e32 v26, v27, v41
	s_mov_b32 s25, -2
	s_mov_b32 s29, s23
	v_mov_b32_e32 v0, 0
	v_mov_b32_e32 v1, v177
	v_or3_b32 v165, v41, v42, v27
	v_add_u32_e32 v166, v27, v39
	v_add_u32_e32 v167, v27, v38
	v_add_u32_e32 v168, v26, v42
	v_lshl_add_u64 v[156:157], v[152:153], 0, s[12:13]
	v_lshl_add_u64 v[158:159], v[152:153], 0, s[14:15]
	v_lshl_add_u64 v[160:161], v[152:153], 0, s[16:17]
	v_lshl_add_u64 v[162:163], v[154:155], 0, s[12:13]
	v_mov_b32_e32 v26, v177
	v_mov_b32_e32 v27, v177
	v_mov_b32_e32 v28, 0
	v_mov_b32_e32 v29, v177
	v_mov_b32_e32 v30, v177
	v_mov_b32_e32 v31, v177
	v_mov_b32_e32 v32, 0
	v_mov_b32_e32 v33, v177
	v_mov_b32_e32 v34, v177
	v_mov_b32_e32 v35, v177
	v_mov_b32_e32 v36, 0
	v_mov_b32_e32 v37, v177
	v_mov_b32_e32 v38, v177
	v_mov_b32_e32 v39, v177
	v_mov_b32_e32 v40, 0
	v_mov_b32_e32 v41, v177
	v_mov_b32_e32 v42, v177
	v_mov_b32_e32 v43, v177
	v_mov_b32_e32 v44, 0
	s_waitcnt vmcnt(11)
	ds_write_b128 v164, v[2:5]
	s_waitcnt vmcnt(10)
	ds_write_b128 v164, v[6:9] offset:4096
	s_waitcnt vmcnt(9)
	ds_write_b128 v164, v[10:13] offset:8192
	s_waitcnt vmcnt(8)
	ds_write_b128 v164, v[14:17] offset:12288
	s_waitcnt vmcnt(7)
	ds_write_b128 v164, v[18:21] offset:32768
	s_waitcnt vmcnt(6)
	ds_write_b128 v164, v[22:25] offset:36864
	v_mov_b32_e32 v2, v177
	v_mov_b32_e32 v3, v177
	v_mov_b32_e32 v4, 0
	v_mov_b32_e32 v5, v177
	v_mov_b32_e32 v6, v177
	v_mov_b32_e32 v7, v177
	v_mov_b32_e32 v8, 0
	v_mov_b32_e32 v9, v177
	v_mov_b32_e32 v10, v177
	v_mov_b32_e32 v11, v177
	v_mov_b32_e32 v12, 0
	v_mov_b32_e32 v13, v177
	v_mov_b32_e32 v14, v177
	v_mov_b32_e32 v15, v177
	v_mov_b32_e32 v16, 0
	v_mov_b32_e32 v17, v177
	v_mov_b32_e32 v18, v177
	v_mov_b32_e32 v19, v177
	v_mov_b32_e32 v20, 0
	v_mov_b32_e32 v21, v177
	v_mov_b32_e32 v22, v177
	v_mov_b32_e32 v23, v177
	v_mov_b32_e32 v24, 0
	v_mov_b32_e32 v25, v177
	v_mov_b32_e32 v45, v177
	v_mov_b32_e32 v46, v177
	v_mov_b32_e32 v47, v177
	v_mov_b32_e32 v48, 0
	v_mov_b32_e32 v49, v177
	v_mov_b32_e32 v50, v177
	v_mov_b32_e32 v51, v177
	v_mov_b32_e32 v52, 0
	v_mov_b32_e32 v53, v177
	v_mov_b32_e32 v54, v177
	v_mov_b32_e32 v55, v177
	v_mov_b32_e32 v56, 0
	v_mov_b32_e32 v57, v177
	v_mov_b32_e32 v58, v177
	v_mov_b32_e32 v59, v177
	v_mov_b32_e32 v60, 0
	v_mov_b32_e32 v61, v177
	v_mov_b32_e32 v62, v177
	v_mov_b32_e32 v63, v177
	v_mov_b32_e32 v64, 0
	v_mov_b32_e32 v65, v177
	v_mov_b32_e32 v66, v177
	v_mov_b32_e32 v67, v177
	v_mov_b32_e32 v68, 0
	v_mov_b32_e32 v69, v177
	v_mov_b32_e32 v70, v177
	v_mov_b32_e32 v71, v177
	v_mov_b32_e32 v72, 0
	v_mov_b32_e32 v73, v177
	v_mov_b32_e32 v74, v177
	v_mov_b32_e32 v75, v177
	v_mov_b32_e32 v76, 0
	v_mov_b32_e32 v77, v177
	v_mov_b32_e32 v78, v177
	v_mov_b32_e32 v79, v177
	v_mov_b32_e32 v80, 0
	v_mov_b32_e32 v81, v177
	v_mov_b32_e32 v82, v177
	v_mov_b32_e32 v83, v177
	v_mov_b32_e32 v84, 0
	v_mov_b32_e32 v85, v177
	v_mov_b32_e32 v86, v177
	v_mov_b32_e32 v87, v177
	v_mov_b32_e32 v88, 0
	v_mov_b32_e32 v89, v177
	v_mov_b32_e32 v90, v177
	v_mov_b32_e32 v91, v177
	v_mov_b32_e32 v92, 0
	v_mov_b32_e32 v93, v177
	v_mov_b32_e32 v94, v177
	v_mov_b32_e32 v95, v177
	v_mov_b32_e32 v96, 0
	v_mov_b32_e32 v97, v177
	v_mov_b32_e32 v98, v177
	v_mov_b32_e32 v99, v177
	v_mov_b32_e32 v100, 0
	v_mov_b32_e32 v101, v177
	v_mov_b32_e32 v102, v177
	v_mov_b32_e32 v103, v177
	v_mov_b32_e32 v104, 0
	v_mov_b32_e32 v105, v177
	v_mov_b32_e32 v106, v177
	v_mov_b32_e32 v107, v177
	v_mov_b32_e32 v108, 0
	v_mov_b32_e32 v109, v177
	v_mov_b32_e32 v110, v177
	v_mov_b32_e32 v111, v177
	v_mov_b32_e32 v136, 0
	v_mov_b32_e32 v137, v177
	v_mov_b32_e32 v138, v177
	v_mov_b32_e32 v139, v177
	v_mov_b32_e32 v140, 0
	v_mov_b32_e32 v141, v177
	v_mov_b32_e32 v142, v177
	v_mov_b32_e32 v143, v177
	v_mov_b32_e32 v144, 0
	v_mov_b32_e32 v145, v177
	v_mov_b32_e32 v146, v177
	v_mov_b32_e32 v147, v177
	v_mov_b32_e32 v148, 0
	v_mov_b32_e32 v149, v177
	v_mov_b32_e32 v150, v177
	v_mov_b32_e32 v151, v177
	s_waitcnt lgkmcnt(0)
	s_barrier
	s_cmpk_lt_u32 s2, 0x100
	s_cbranch_scc1 .Lstag_2
	s_sleep 8
.Lstag_2:
.LBB0_561:
	s_add_i32 s31, s29, 64
	s_min_u32 s22, s31, 0x7e0
	s_lshl_b32 s22, s22, 1
	v_lshl_add_u64 v[174:175], v[156:157], 0, s[22:23]
	global_load_dwordx4 v[178:181], v[174:175], off
	v_lshl_add_u64 v[174:175], v[158:159], 0, s[22:23]
	v_lshl_add_u64 v[170:171], v[152:153], 0, s[22:23]
	v_lshl_add_u64 v[186:187], v[160:161], 0, s[22:23]
	global_load_dwordx4 v[182:185], v[174:175], off
	v_lshl_add_u64 v[174:175], v[154:155], 0, s[22:23]
	v_lshl_add_u64 v[194:195], v[162:163], 0, s[22:23]
	global_load_dwordx4 v[170:173], v[170:171], off
	ds_read_b128 v[202:205], v168 offset:32768
	global_load_dwordx4 v[186:189], v[186:187], off
	ds_read_b128 v[206:209], v168 offset:33792
	global_load_dwordx4 v[190:193], v[174:175], off
	global_load_dwordx4 v[198:201], v[194:195], off
	ds_read_b128 v[210:213], v168 offset:34816
	ds_read_b128 v[214:217], v168 offset:35840
	ds_read_b128 v[222:225], v166
	ds_read_b128 v[226:229], v166 offset:1024
	ds_read_b128 v[230:233], v166 offset:2048
	ds_read_b128 v[234:237], v166 offset:3072
	ds_read_b128 v[238:241], v166 offset:4096
	ds_read_b128 v[242:245], v166 offset:5120
	ds_read_b128 v[246:249], v166 offset:6144
	ds_read_b128 v[250:253], v166 offset:7168
	s_setprio 1
	s_waitcnt lgkmcnt(7)
	v_mfma_f32_16x16x32_bf16 v[148:151], v[202:205], v[222:225], v[148:151]
	v_mfma_f32_16x16x32_bf16 v[144:147], v[206:209], v[222:225], v[144:147]
	v_mfma_f32_16x16x32_bf16 v[140:143], v[210:213], v[222:225], v[140:143]
	v_mfma_f32_16x16x32_bf16 v[136:139], v[214:217], v[222:225], v[136:139]
	s_waitcnt vmcnt(11)
	ds_write_b128 v164, v[112:115] offset:16384
	s_waitcnt lgkmcnt(7)
	v_mfma_f32_16x16x32_bf16 v[108:111], v[202:205], v[226:229], v[108:111]
	v_mfma_f32_16x16x32_bf16 v[104:107], v[206:209], v[226:229], v[104:107]
	v_mfma_f32_16x16x32_bf16 v[100:103], v[210:213], v[226:229], v[100:103]
	v_mfma_f32_16x16x32_bf16 v[96:99], v[214:217], v[226:229], v[96:99]
	s_waitcnt vmcnt(9)
	ds_write_b128 v164, v[120:123] offset:20480
	s_waitcnt lgkmcnt(7)
	v_mfma_f32_16x16x32_bf16 v[92:95], v[202:205], v[230:233], v[92:95]
	v_mfma_f32_16x16x32_bf16 v[88:91], v[206:209], v[230:233], v[88:91]
	v_mfma_f32_16x16x32_bf16 v[84:87], v[210:213], v[230:233], v[84:87]
	v_mfma_f32_16x16x32_bf16 v[80:83], v[214:217], v[230:233], v[80:83]
	s_waitcnt vmcnt(8)
	ds_write_b128 v164, v[124:127] offset:24576
	s_waitcnt lgkmcnt(7)
	v_mfma_f32_16x16x32_bf16 v[76:79], v[202:205], v[234:237], v[76:79]
	v_mfma_f32_16x16x32_bf16 v[72:75], v[206:209], v[234:237], v[72:75]
	v_mfma_f32_16x16x32_bf16 v[68:71], v[210:213], v[234:237], v[68:71]
	v_mfma_f32_16x16x32_bf16 v[64:67], v[214:217], v[234:237], v[64:67]
	s_waitcnt vmcnt(7)
	ds_write_b128 v164, v[128:131] offset:28672
	s_waitcnt lgkmcnt(7)
	v_mfma_f32_16x16x32_bf16 v[60:63], v[202:205], v[238:241], v[60:63]
	v_mfma_f32_16x16x32_bf16 v[56:59], v[206:209], v[238:241], v[56:59]
	v_mfma_f32_16x16x32_bf16 v[52:55], v[210:213], v[238:241], v[52:55]
	v_mfma_f32_16x16x32_bf16 v[48:51], v[214:217], v[238:241], v[48:51]
	s_waitcnt vmcnt(7)
	ds_write_b128 v164, v[116:119] offset:40960
	s_waitcnt lgkmcnt(7)
	v_mfma_f32_16x16x32_bf16 v[44:47], v[202:205], v[242:245], v[44:47]
	v_mfma_f32_16x16x32_bf16 v[40:43], v[206:209], v[242:245], v[40:43]
	v_mfma_f32_16x16x32_bf16 v[36:39], v[210:213], v[242:245], v[36:39]
	v_mfma_f32_16x16x32_bf16 v[32:35], v[214:217], v[242:245], v[32:35]
	s_waitcnt vmcnt(6)
	ds_write_b128 v164, v[132:135] offset:45056
	s_waitcnt lgkmcnt(7)
	v_mfma_f32_16x16x32_bf16 v[28:31], v[202:205], v[246:249], v[28:31]
	v_mfma_f32_16x16x32_bf16 v[24:27], v[206:209], v[246:249], v[24:27]
	v_mfma_f32_16x16x32_bf16 v[20:23], v[210:213], v[246:249], v[20:23]
	v_mfma_f32_16x16x32_bf16 v[16:19], v[214:217], v[246:249], v[16:19]
	s_waitcnt lgkmcnt(6)
	v_mfma_f32_16x16x32_bf16 v[12:15], v[202:205], v[250:253], v[12:15]
	v_mfma_f32_16x16x32_bf16 v[8:11], v[206:209], v[250:253], v[8:11]
	v_mfma_f32_16x16x32_bf16 v[4:7], v[210:213], v[250:253], v[4:7]
	v_mfma_f32_16x16x32_bf16 v[0:3], v[214:217], v[250:253], v[0:3]
	s_setprio 0
	s_min_u32 s22, s29, 0x780
	s_lshl_b32 s22, s22, 1
	s_mov_b32 s35, s23
	s_add_i32 s34, s22, 0xc0
	v_lshl_add_u64 v[112:113], v[152:153], 0, s[22:23]
	v_lshl_add_u64 v[116:117], v[154:155], 0, s[22:23]
	v_lshl_add_u64 v[120:121], v[156:157], 0, s[34:35]
	v_lshl_add_u64 v[124:125], v[158:159], 0, s[34:35]
	v_lshl_add_u64 v[128:129], v[160:161], 0, s[34:35]
	v_lshl_add_u64 v[132:133], v[162:163], 0, s[34:35]
	s_waitcnt lgkmcnt(0)
	s_barrier
	global_load_dwordx4 v[112:115], v[112:113], off offset:192
	ds_read_b128 v[202:205], v165 offset:40960
	global_load_dwordx4 v[116:119], v[116:117], off offset:192
	ds_read_b128 v[206:209], v165 offset:41984
	global_load_dwordx4 v[120:123], v[120:121], off
	ds_read_b128 v[210:213], v165 offset:43008
	global_load_dwordx4 v[124:127], v[124:125], off
	ds_read_b128 v[214:217], v165 offset:44032
	global_load_dwordx4 v[128:131], v[128:129], off
	ds_read_b128 v[222:225], v167
	global_load_dwordx4 v[132:135], v[132:133], off
	ds_read_b128 v[226:229], v167 offset:1024
	ds_read_b128 v[230:233], v167 offset:2048
	ds_read_b128 v[234:237], v167 offset:3072
	ds_read_b128 v[238:241], v167 offset:4096
	ds_read_b128 v[242:245], v167 offset:5120
	ds_read_b128 v[246:249], v167 offset:6144
	ds_read_b128 v[250:253], v167 offset:7168
	s_setprio 1
	s_waitcnt lgkmcnt(7)
	v_mfma_f32_16x16x32_bf16 v[148:151], v[202:205], v[222:225], v[148:151]
	v_mfma_f32_16x16x32_bf16 v[144:147], v[206:209], v[222:225], v[144:147]
	v_mfma_f32_16x16x32_bf16 v[140:143], v[210:213], v[222:225], v[140:143]
	v_mfma_f32_16x16x32_bf16 v[136:139], v[214:217], v[222:225], v[136:139]
	s_waitcnt vmcnt(9)
	ds_write_b128 v164, v[170:173]
	s_waitcnt lgkmcnt(7)
	v_mfma_f32_16x16x32_bf16 v[108:111], v[202:205], v[226:229], v[108:111]
	v_mfma_f32_16x16x32_bf16 v[104:107], v[206:209], v[226:229], v[104:107]
	v_mfma_f32_16x16x32_bf16 v[100:103], v[210:213], v[226:229], v[100:103]
	v_mfma_f32_16x16x32_bf16 v[96:99], v[214:217], v[226:229], v[96:99]
	ds_write_b128 v164, v[178:181] offset:4096
	s_waitcnt lgkmcnt(7)
	v_mfma_f32_16x16x32_bf16 v[92:95], v[202:205], v[230:233], v[92:95]
	v_mfma_f32_16x16x32_bf16 v[88:91], v[206:209], v[230:233], v[88:91]
	v_mfma_f32_16x16x32_bf16 v[84:87], v[210:213], v[230:233], v[84:87]
	v_mfma_f32_16x16x32_bf16 v[80:83], v[214:217], v[230:233], v[80:83]
	ds_write_b128 v164, v[182:185] offset:8192
	s_waitcnt lgkmcnt(7)
	v_mfma_f32_16x16x32_bf16 v[76:79], v[202:205], v[234:237], v[76:79]
	v_mfma_f32_16x16x32_bf16 v[72:75], v[206:209], v[234:237], v[72:75]
	v_mfma_f32_16x16x32_bf16 v[68:71], v[210:213], v[234:237], v[68:71]
	v_mfma_f32_16x16x32_bf16 v[64:67], v[214:217], v[234:237], v[64:67]
	s_waitcnt vmcnt(8)
	ds_write_b128 v164, v[186:189] offset:12288
	s_waitcnt lgkmcnt(7)
	v_mfma_f32_16x16x32_bf16 v[60:63], v[202:205], v[238:241], v[60:63]
	v_mfma_f32_16x16x32_bf16 v[56:59], v[206:209], v[238:241], v[56:59]
	v_mfma_f32_16x16x32_bf16 v[52:55], v[210:213], v[238:241], v[52:55]
	v_mfma_f32_16x16x32_bf16 v[48:51], v[214:217], v[238:241], v[48:51]
	s_waitcnt vmcnt(7)
	ds_write_b128 v164, v[190:193] offset:32768
	s_waitcnt lgkmcnt(7)
	v_mfma_f32_16x16x32_bf16 v[44:47], v[202:205], v[242:245], v[44:47]
	v_mfma_f32_16x16x32_bf16 v[40:43], v[206:209], v[242:245], v[40:43]
	v_mfma_f32_16x16x32_bf16 v[36:39], v[210:213], v[242:245], v[36:39]
	v_mfma_f32_16x16x32_bf16 v[32:35], v[214:217], v[242:245], v[32:35]
	s_waitcnt vmcnt(6)
	ds_write_b128 v164, v[198:201] offset:36864
	s_waitcnt lgkmcnt(7)
	v_mfma_f32_16x16x32_bf16 v[28:31], v[202:205], v[246:249], v[28:31]
	v_mfma_f32_16x16x32_bf16 v[24:27], v[206:209], v[246:249], v[24:27]
	v_mfma_f32_16x16x32_bf16 v[20:23], v[210:213], v[246:249], v[20:23]
	v_mfma_f32_16x16x32_bf16 v[16:19], v[214:217], v[246:249], v[16:19]
	s_waitcnt lgkmcnt(6)
	v_mfma_f32_16x16x32_bf16 v[12:15], v[202:205], v[250:253], v[12:15]
	v_mfma_f32_16x16x32_bf16 v[8:11], v[206:209], v[250:253], v[8:11]
	v_mfma_f32_16x16x32_bf16 v[4:7], v[210:213], v[250:253], v[4:7]
	v_mfma_f32_16x16x32_bf16 v[0:3], v[214:217], v[250:253], v[0:3]
	s_setprio 0
	s_add_i32 s25, s25, 2
	s_cmp_lt_u32 s25, 62
	s_mov_b32 s29, s31
	s_waitcnt lgkmcnt(0)
	s_barrier
	s_cbranch_scc1 .LBB0_561
	s_waitcnt vmcnt(5)
	v_mov_b32_e32 v112, v220
	v_readlane_b32 s36, v254, 6
	v_and_b32_e32 v114, 0xffffff80, v112
	v_bfe_u32 v176, v112, 4, 2
	v_add_u32_e32 v114, s28, v114
	v_and_b32_e32 v113, 64, v112
	v_and_or_b32 v180, v112, 15, v114
	v_lshlrev_b32_e32 v112, 2, v176
	v_or3_b32 v178, v112, v113, s24
	v_ashrrev_i32_e32 v179, 31, v178
	v_lshlrev_b64 v[214:215], 2, v[178:179]
	v_readlane_b32 s37, v254, 7
	v_ashrrev_i32_e32 v181, 31, v180
	v_or_b32_e32 v190, 16, v180
	v_lshl_add_u64 v[182:183], s[36:37], 0, v[214:215]
	v_lshlrev_b64 v[216:217], 12, v[180:181]
	v_ashrrev_i32_e32 v191, 31, v190
	v_or_b32_e32 v186, 32, v180
	v_lshl_add_u64 v[112:113], v[182:183], 0, v[216:217]
	v_lshlrev_b64 v[194:195], 12, v[190:191]
	v_ashrrev_i32_e32 v187, 31, v186
	v_or_b32_e32 v184, 48, v180
	global_load_dwordx4 v[198:201], v[112:113], off nt
	global_load_dwordx4 v[202:205], v[112:113], off offset:64 nt
	global_load_dwordx4 v[206:209], v[112:113], off offset:128 nt
	global_load_dwordx4 v[210:213], v[112:113], off offset:192 nt
	v_lshl_add_u64 v[112:113], v[182:183], 0, v[194:195]
	v_lshlrev_b64 v[192:193], 12, v[186:187]
	v_ashrrev_i32_e32 v185, 31, v184
	global_load_dwordx4 v[172:175], v[112:113], off nt
	global_load_dwordx4 v[168:171], v[112:113], off offset:64 nt
	global_load_dwordx4 v[164:167], v[112:113], off offset:128 nt
	global_load_dwordx4 v[160:163], v[112:113], off offset:192 nt
	v_lshl_add_u64 v[112:113], v[182:183], 0, v[192:193]
	v_lshlrev_b64 v[188:189], 12, v[184:185]
	global_load_dwordx4 v[156:159], v[112:113], off nt
	global_load_dwordx4 v[152:155], v[112:113], off offset:64 nt
	global_load_dwordx4 v[132:135], v[112:113], off offset:128 nt
	global_load_dwordx4 v[128:131], v[112:113], off offset:192 nt
	v_lshl_add_u64 v[112:113], v[182:183], 0, v[188:189]
	global_load_dwordx4 v[124:127], v[112:113], off nt
	global_load_dwordx4 v[120:123], v[112:113], off offset:64 nt
	global_load_dwordx4 v[116:119], v[112:113], off offset:128 nt
	s_nop 0
	global_load_dwordx4 v[112:115], v[112:113], off offset:192 nt
	v_cmp_eq_u32_e32 vcc, 0, v176
	v_readlane_b32 s38, v254, 8
	v_readlane_b32 s39, v254, 9
	v_readlane_b32 s40, v254, 10
	v_readlane_b32 s41, v254, 11
	v_readlane_b32 s42, v254, 12
	v_readlane_b32 s43, v254, 13
	v_readlane_b32 s44, v254, 14
	v_readlane_b32 s45, v254, 15
	v_readlane_b32 s46, v254, 16
	v_readlane_b32 s47, v254, 17
	v_readlane_b32 s48, v254, 18
	v_readlane_b32 s49, v254, 19
	v_readlane_b32 s50, v254, 20
	v_readlane_b32 s51, v254, 21
	v_lshl_add_u64 v[216:217], s[70:71], 0, v[216:217]
	s_waitcnt vmcnt(15)
	v_pk_add_f32 v[148:149], v[148:149], v[198:199]
	v_lshl_add_u64 v[214:215], v[216:217], 0, v[214:215]
	v_pk_add_f32 v[150:151], v[150:151], v[200:201]
	v_mul_f32_e32 v176, v149, v149
	global_store_dwordx4 v[214:215], v[148:151], off
	v_cvt_pk_bf16_f32 v198, v148, v149
	v_lshlrev_b64 v[200:201], 11, v[180:181]
	v_cvt_pk_bf16_f32 v199, v150, v151
	v_lshl_add_u64 v[200:201], s[6:7], 0, v[200:201]
	v_pk_fma_f32 v[148:149], v[148:149], v[148:149], v[176:177] op_sel_hi:[1,1,0]
	v_lshl_add_u64 v[200:201], v[178:179], 1, v[200:201]
	v_pk_fma_f32 v[148:149], v[150:151], v[150:151], v[148:149]
	v_mul_f32_e32 v150, v151, v151
	v_pk_add_f32 v[148:149], v[150:151], v[148:149] op_sel_hi:[0,1]
	s_waitcnt vmcnt(15)
	v_pk_add_f32 v[146:147], v[146:147], v[204:205]
	v_pk_add_f32 v[144:145], v[144:145], v[202:203]
	global_store_dwordx2 v[200:201], v[198:199], off
	v_cvt_pk_bf16_f32 v150, v144, v145
	global_store_dwordx4 v[214:215], v[144:147], off offset:64
	v_cvt_pk_bf16_f32 v151, v146, v147
	global_store_dwordx2 v[200:201], v[150:151], off offset:32
	v_mul_f32_e32 v150, v145, v145
	v_pk_fma_f32 v[144:145], v[144:145], v[144:145], v[150:151] op_sel_hi:[1,1,0]
	s_waitcnt vmcnt(17)
	v_pk_add_f32 v[142:143], v[142:143], v[208:209]
	v_pk_fma_f32 v[144:145], v[146:147], v[146:147], v[144:145]
	v_mul_f32_e32 v146, v147, v147
	v_pk_add_f32 v[144:145], v[146:147], v[144:145] op_sel_hi:[0,1]
	v_pk_add_f32 v[140:141], v[140:141], v[206:207]
	global_store_dwordx4 v[214:215], v[140:143], off offset:128
	v_cvt_pk_bf16_f32 v146, v140, v141
	v_cvt_pk_bf16_f32 v147, v142, v143
	global_store_dwordx2 v[200:201], v[146:147], off offset:64
	v_mul_f32_e32 v146, v141, v141
	v_pk_fma_f32 v[140:141], v[140:141], v[140:141], v[146:147] op_sel_hi:[1,1,0]
	s_waitcnt vmcnt(18)
	v_pk_add_f32 v[138:139], v[138:139], v[212:213]
	v_pk_fma_f32 v[140:141], v[142:143], v[142:143], v[140:141]
	v_mul_f32_e32 v142, v143, v143
	v_pk_add_f32 v[140:141], v[142:143], v[140:141] op_sel_hi:[0,1]
	v_pk_add_f32 v[136:137], v[136:137], v[210:211]
	global_store_dwordx4 v[214:215], v[136:139], off offset:192
	v_cvt_pk_bf16_f32 v142, v136, v137
	v_cvt_pk_bf16_f32 v143, v138, v139
	global_store_dwordx2 v[200:201], v[142:143], off offset:96
	v_mul_f32_e32 v142, v137, v137
	v_pk_fma_f32 v[136:137], v[136:137], v[136:137], v[142:143] op_sel_hi:[1,1,0]
	v_pk_add_f32 v[144:145], v[148:149], v[144:145]
	v_pk_fma_f32 v[136:137], v[138:139], v[138:139], v[136:137]
	v_mul_f32_e32 v138, v139, v139
	v_pk_add_f32 v[140:141], v[144:145], v[140:141]
	v_pk_add_f32 v[136:137], v[138:139], v[136:137] op_sel_hi:[0,1]
	v_pk_add_f32 v[136:137], v[140:141], v[136:137]
	s_nop 0
	v_mov_b32_e32 v137, v136
	s_nop 1
	v_permlane32_swap_b32_e32 v136, v137
	v_add_f32_e32 v136, v136, v137
	v_mov_b32_e32 v137, v136
	s_nop 1
	v_permlane16_swap_b32_e32 v136, v137
	s_and_saveexec_b64 s[24:25], vcc
	s_cbranch_execz .LBB0_564
	v_lshl_add_u64 v[138:139], v[180:181], 2, s[10:11]
	v_add_f32_e32 v136, v136, v137
	global_atomic_add_f32 v[138:139], v136, off

.LBB0_634:
	s_min_u32 s31, s29, 0xe0
	s_lshl_b32 s16, s31, 2
	v_lshl_add_u64 v[58:59], v[42:43], 0, s[16:17]
	v_lshl_add_u64 v[92:93], v[48:49], 0, s[16:17]
	s_lshl_b32 s16, s31, 1
	global_load_dwordx4 v[64:67], v[58:59], off offset:16 nt
	global_load_dwordx4 v[68:71], v[58:59], off nt
	v_lshl_add_u64 v[58:59], v[34:35], 0, s[16:17]
	v_lshl_add_u64 v[100:101], v[40:41], 0, s[16:17]
	global_load_dwordx4 v[88:91], v[92:93], off offset:16 nt
	global_load_dwordx4 v[96:99], v[58:59], off
	s_and_b32 s16, s30, 0x80
	global_load_dwordx4 v[92:95], v[92:93], off nt
	v_add_u32_e32 v57, s16, v50
	global_load_dwordx4 v[100:103], v[100:101], off
	v_or_b32_e32 v58, s16, v56
	v_lshl_or_b32 v57, v57, 6, v51
	v_lshl_or_b32 v58, v58, 6, v51
	ds_read_b128 v[104:107], v57
	ds_read_b128 v[108:111], v57 offset:1024
	ds_read_b128 v[112:115], v58 offset:16384
	ds_read_b128 v[116:119], v58 offset:17408
	ds_read_b128 v[120:123], v57 offset:2048
	ds_read_b128 v[124:127], v57 offset:3072
	ds_read_b128 v[128:131], v58 offset:18432
	ds_read_b128 v[132:135], v58 offset:19456
	s_setprio 1
	s_waitcnt lgkmcnt(5)
	v_mfma_f32_16x16x32_bf16 v[84:87], v[112:115], v[104:107], v[84:87]
	s_waitcnt lgkmcnt(4)
	v_mfma_f32_16x16x32_bf16 v[80:83], v[116:119], v[104:107], v[80:83]
	s_waitcnt lgkmcnt(1)
	v_mfma_f32_16x16x32_bf16 v[76:79], v[128:131], v[104:107], v[76:79]
	s_waitcnt lgkmcnt(0)
	v_mfma_f32_16x16x32_bf16 v[72:75], v[132:135], v[104:107], v[72:75]
	v_mfma_f32_16x16x32_bf16 v[60:63], v[112:115], v[108:111], v[60:63]
	v_mfma_f32_16x16x32_bf16 v[52:55], v[116:119], v[108:111], v[52:55]
	v_mfma_f32_16x16x32_bf16 v[44:47], v[128:131], v[108:111], v[44:47]
	v_mfma_f32_16x16x32_bf16 v[36:39], v[132:135], v[108:111], v[36:39]
	v_mfma_f32_16x16x32_bf16 v[28:31], v[112:115], v[120:123], v[28:31]
	v_mfma_f32_16x16x32_bf16 v[24:27], v[116:119], v[120:123], v[24:27]
	v_mfma_f32_16x16x32_bf16 v[20:23], v[128:131], v[120:123], v[20:23]
	v_mfma_f32_16x16x32_bf16 v[16:19], v[132:135], v[120:123], v[16:19]
	v_mfma_f32_16x16x32_bf16 v[12:15], v[112:115], v[124:127], v[12:15]
	v_mfma_f32_16x16x32_bf16 v[8:11], v[116:119], v[124:127], v[8:11]
	v_mfma_f32_16x16x32_bf16 v[4:7], v[128:131], v[124:127], v[4:7]
	v_mfma_f32_16x16x32_bf16 v[0:3], v[132:135], v[124:127], v[0:3]
	s_setprio 0
	s_waitcnt vmcnt(4)
	v_and_b32_sdwa v58, v70, v199 dst_sel:DWORD dst_unused:UNUSED_PAD src0_sel:WORD_1 src1_sel:DWORD
	v_and_b32_sdwa v59, v68, v199 dst_sel:DWORD dst_unused:UNUSED_PAD src0_sel:WORD_1 src1_sel:DWORD
	v_add3_u32 v59, v68, v59, s9
	v_add3_u32 v58, v70, v58, s9
	v_and_b32_sdwa v68, v71, v199 dst_sel:DWORD dst_unused:UNUSED_PAD src0_sel:WORD_1 src1_sel:DWORD
	v_and_b32_sdwa v70, v69, v199 dst_sel:DWORD dst_unused:UNUSED_PAD src0_sel:WORD_1 src1_sel:DWORD
	v_add3_u32 v68, v71, v68, s9
	v_add3_u32 v69, v69, v70, s9
	v_and_b32_e32 v68, 0xffff0000, v68
	v_and_b32_e32 v70, 0xffff0000, v69
	v_or_b32_sdwa v69, v68, v58 dst_sel:DWORD dst_unused:UNUSED_PAD src0_sel:DWORD src1_sel:WORD_1
	v_or_b32_sdwa v68, v70, v59 dst_sel:DWORD dst_unused:UNUSED_PAD src0_sel:DWORD src1_sel:WORD_1
	v_and_b32_sdwa v58, v66, v199 dst_sel:DWORD dst_unused:UNUSED_PAD src0_sel:WORD_1 src1_sel:DWORD
	v_and_b32_sdwa v59, v64, v199 dst_sel:DWORD dst_unused:UNUSED_PAD src0_sel:WORD_1 src1_sel:DWORD
	v_add3_u32 v59, v64, v59, s9
	v_add3_u32 v58, v66, v58, s9
	v_and_b32_sdwa v64, v67, v199 dst_sel:DWORD dst_unused:UNUSED_PAD src0_sel:WORD_1 src1_sel:DWORD
	v_and_b32_sdwa v66, v65, v199 dst_sel:DWORD dst_unused:UNUSED_PAD src0_sel:WORD_1 src1_sel:DWORD
	v_add3_u32 v64, v67, v64, s9
	v_add3_u32 v65, v65, v66, s9
	v_and_b32_e32 v64, 0xffff0000, v64
	v_and_b32_e32 v65, 0xffff0000, v65
	v_or_b32_sdwa v71, v64, v58 dst_sel:DWORD dst_unused:UNUSED_PAD src0_sel:DWORD src1_sel:WORD_1
	v_or_b32_sdwa v70, v65, v59 dst_sel:DWORD dst_unused:UNUSED_PAD src0_sel:DWORD src1_sel:WORD_1
	s_waitcnt vmcnt(1)
	v_and_b32_sdwa v64, v95, v199 dst_sel:DWORD dst_unused:UNUSED_PAD src0_sel:WORD_1 src1_sel:DWORD
	v_and_b32_sdwa v65, v93, v199 dst_sel:DWORD dst_unused:UNUSED_PAD src0_sel:WORD_1 src1_sel:DWORD
	v_and_b32_sdwa v58, v94, v199 dst_sel:DWORD dst_unused:UNUSED_PAD src0_sel:WORD_1 src1_sel:DWORD
	v_and_b32_sdwa v59, v92, v199 dst_sel:DWORD dst_unused:UNUSED_PAD src0_sel:WORD_1 src1_sel:DWORD
	v_add3_u32 v64, v95, v64, s9
	v_add3_u32 v65, v93, v65, s9
	s_xor_b32 s16, s16, 0x80
	v_add3_u32 v59, v92, v59, s9
	v_add3_u32 v58, v94, v58, s9
	v_and_b32_e32 v64, 0xffff0000, v64
	v_and_b32_e32 v66, 0xffff0000, v65
	v_add_u32_e32 v57, s16, v32
	v_or_b32_sdwa v65, v64, v58 dst_sel:DWORD dst_unused:UNUSED_PAD src0_sel:DWORD src1_sel:WORD_1
	v_or_b32_sdwa v64, v66, v59 dst_sel:DWORD dst_unused:UNUSED_PAD src0_sel:DWORD src1_sel:WORD_1
	v_and_b32_sdwa v66, v91, v199 dst_sel:DWORD dst_unused:UNUSED_PAD src0_sel:WORD_1 src1_sel:DWORD
	v_and_b32_sdwa v67, v89, v199 dst_sel:DWORD dst_unused:UNUSED_PAD src0_sel:WORD_1 src1_sel:DWORD
	v_lshl_or_b32 v57, v57, 6, v33
	v_and_b32_sdwa v58, v90, v199 dst_sel:DWORD dst_unused:UNUSED_PAD src0_sel:WORD_1 src1_sel:DWORD
	v_and_b32_sdwa v59, v88, v199 dst_sel:DWORD dst_unused:UNUSED_PAD src0_sel:WORD_1 src1_sel:DWORD
	v_add3_u32 v66, v91, v66, s9
	v_add3_u32 v67, v89, v67, s9
	ds_write_b128 v57, v[68:71]
	v_add3_u32 v59, v88, v59, s9
	v_add3_u32 v58, v90, v58, s9
	v_and_b32_e32 v66, 0xffff0000, v66
	v_and_b32_e32 v68, 0xffff0000, v67
	s_addk_i32 s30, 0x80
	s_add_i32 s29, s29, 32
	v_or_b32_sdwa v67, v66, v58 dst_sel:DWORD dst_unused:UNUSED_PAD src0_sel:DWORD src1_sel:WORD_1
	v_or_b32_sdwa v66, v68, v59 dst_sel:DWORD dst_unused:UNUSED_PAD src0_sel:DWORD src1_sel:WORD_1
	s_cmpk_lg_i32 s30, 0x400
	ds_write_b128 v57, v[64:67] offset:4096
	ds_write_b128 v57, v[96:99] offset:16384
	s_waitcnt vmcnt(0)
	ds_write_b128 v57, v[100:103] offset:20480
	s_waitcnt lgkmcnt(0)
	s_barrier
	s_cbranch_scc1 .LBB0_634
	s_lshl_b64 s[30:31], s[22:23], 11
	v_mov_b32_e32 v118, v220
	s_add_u32 s30, s5, s30
	s_addc_u32 s31, s6, s31
	v_ashrrev_i32_e32 v70, 2, v118
	s_lshl_b64 s[34:35], s[0:1], 11
	v_add_u32_e32 v116, 64, v70
	s_add_u32 s34, s7, s34
	v_ashrrev_i32_e32 v117, 31, v116
	s_addc_u32 s35, s8, s35
	v_lshlrev_b64 v[32:33], 11, v[116:117]
	v_min_i32_e32 v34, 0x7f, v70
	v_lshlrev_b32_e32 v35, 4, v118
	v_lshl_add_u64 v[32:33], s[34:35], 0, v[32:33]
	v_and_b32_e32 v176, 48, v35
	v_ashrrev_i32_e32 v35, 31, v34
	v_ashrrev_i32_e32 v71, 31, v70
	v_min_i32_e32 v40, 0x7f, v116
	v_lshl_add_u64 v[130:131], v[32:33], 0, v[176:177]
	v_lshlrev_b64 v[32:33], 11, v[34:35]
	v_lshlrev_b64 v[42:43], 11, v[70:71]
	v_lshl_add_u64 v[32:33], s[30:31], 0, v[32:33]
	v_ashrrev_i32_e32 v41, 31, v40
	v_lshl_add_u64 v[42:43], s[34:35], 0, v[42:43]
	v_lshl_add_u64 v[132:133], v[32:33], 0, v[176:177]
	v_lshlrev_b64 v[32:33], 11, v[40:41]
	v_lshl_add_u64 v[128:129], v[42:43], 0, v[176:177]
	v_lshl_add_u64 v[32:33], s[30:31], 0, v[32:33]
	global_load_dwordx4 v[88:91], v[132:133], off
	global_load_dwordx4 v[92:95], v[128:129], off
	v_lshl_add_u64 v[134:135], v[32:33], 0, v[176:177]
	global_load_dwordx4 v[96:99], v[130:131], off
	global_load_dwordx4 v[108:111], v[134:135], off
	global_load_dwordx4 v[100:103], v[128:129], off offset:64
	global_load_dwordx4 v[104:107], v[132:133], off offset:64
	global_load_dwordx4 v[112:115], v[130:131], off offset:64
	global_load_dwordx4 v[120:123], v[134:135], off offset:64
	v_lshrrev_b32_e32 v71, 4, v118
	v_lshrrev_b32_e32 v117, 2, v118
	v_sub_u32_e32 v126, 0, v71
	v_and_b32_e32 v119, 15, v118
	v_lshrrev_b32_e32 v124, 1, v118
	v_lshlrev_b32_e32 v125, 6, v118
	v_sub_u32_e32 v117, 0, v117
	v_xor_b32_e32 v118, v118, v126
	v_and_or_b32 v119, v124, s25, v119
	v_xor_b32_e32 v71, v71, v117
	v_lshlrev_b32_e32 v117, 4, v118
	v_lshlrev_b32_e32 v145, 6, v119
	v_lshlrev_b32_e32 v71, 4, v71
	v_and_b32_e32 v117, 48, v117
	v_mov_b32_e32 v32, 0
	v_and_b32_e32 v144, 0x13c0, v125
	v_add_u32_e32 v118, 0x2000, v145
	v_and_b32_e32 v146, 48, v71
	v_lshl_or_b32 v147, v70, 6, v117
	s_mov_b32 s23, 0
	s_mov_b32 s1, -2
	v_mov_b32_e32 v33, v32
	v_mov_b32_e32 v34, v32
	v_mov_b32_e32 v35, v32
	v_mov_b32_e32 v40, v32
	v_mov_b32_e32 v41, v32
	v_mov_b32_e32 v42, v32
	v_mov_b32_e32 v43, v32
	v_mov_b32_e32 v48, v32
	v_mov_b32_e32 v49, v32
	v_mov_b32_e32 v50, v32
	v_mov_b32_e32 v51, v32
	v_mov_b32_e32 v56, v32
	v_mov_b32_e32 v57, v32
	v_mov_b32_e32 v58, v32
	v_mov_b32_e32 v59, v32
	v_mov_b32_e32 v64, v32
	v_mov_b32_e32 v65, v32
	v_mov_b32_e32 v66, v32
	v_mov_b32_e32 v67, v32
	v_mov_b32_e32 v68, v32
	v_mov_b32_e32 v69, v32
	v_lshl_or_b32 v156, v116, 6, v117
	v_or_b32_e32 v157, v146, v144
	v_add_u32_e32 v158, v146, v118
	v_mov_b32_e32 v70, v32
	v_mov_b32_e32 v71, v32
	v_mov_b32_e32 v116, v32
	v_mov_b32_e32 v117, v32
	v_mov_b32_e32 v118, v32
	v_mov_b32_e32 v119, v32
	v_mov_b32_e32 v124, v32
	v_mov_b32_e32 v125, v32
	v_mov_b32_e32 v126, v32
	v_mov_b32_e32 v127, v32
	v_mov_b32_e32 v136, v32
	s_waitcnt vmcnt(6)
	ds_write_b128 v147, v[92:95] offset:16384
	ds_write_b128 v147, v[88:91]
	s_waitcnt vmcnt(5)
	ds_write_b128 v156, v[96:99] offset:16384
	s_waitcnt vmcnt(4)
	ds_write_b128 v156, v[108:111]
	v_mov_b32_e32 v88, v32
	v_mov_b32_e32 v89, v32
	v_mov_b32_e32 v90, v32
	v_mov_b32_e32 v91, v32
	v_mov_b32_e32 v92, v32
	v_mov_b32_e32 v93, v32
	v_mov_b32_e32 v94, v32
	v_mov_b32_e32 v95, v32
	v_mov_b32_e32 v96, v32
	v_mov_b32_e32 v97, v32
	v_mov_b32_e32 v98, v32
	v_mov_b32_e32 v99, v32
	v_mov_b32_e32 v108, v32
	v_mov_b32_e32 v109, v32
	v_mov_b32_e32 v110, v32
	v_mov_b32_e32 v111, v32
	v_mov_b32_e32 v137, v32
	v_mov_b32_e32 v138, v32
	v_mov_b32_e32 v139, v32
	v_mov_b32_e32 v140, v32
	v_mov_b32_e32 v141, v32
	v_mov_b32_e32 v142, v32
	v_mov_b32_e32 v143, v32
	v_mov_b32_e32 v148, v32
	v_mov_b32_e32 v149, v32
	v_mov_b32_e32 v150, v32
	v_mov_b32_e32 v151, v32
	v_mov_b32_e32 v152, v32
	v_mov_b32_e32 v153, v32
	v_mov_b32_e32 v154, v32
	v_mov_b32_e32 v155, v32
	s_waitcnt lgkmcnt(0)
	s_barrier
	s_cmpk_lt_u32 s2, 0x100
	s_cbranch_scc1 .Lstag_3
	s_sleep 8
.Lstag_3:
.LBB0_636:
	s_add_i32 s29, s23, 64
	s_min_u32 s16, s29, 0x3e0
	s_lshl_b32 s16, s16, 1
	v_lshl_add_u64 v[160:161], v[132:133], 0, s[16:17]
	v_lshl_add_u64 v[164:165], v[134:135], 0, s[16:17]
	v_lshl_add_u64 v[168:169], v[128:129], 0, s[16:17]
	v_lshl_add_u64 v[172:173], v[130:131], 0, s[16:17]
	global_load_dwordx4 v[160:163], v[160:161], off
	v_add_u32_e32 v159, v146, v145
	global_load_dwordx4 v[164:167], v[164:165], off
	v_add_u32_e32 v176, v146, v144
	global_load_dwordx4 v[168:171], v[168:169], off
	ds_read_b128 v[178:181], v159
	global_load_dwordx4 v[172:175], v[172:173], off
	ds_read_b128 v[182:185], v159 offset:1024
	ds_read_b128 v[186:189], v176 offset:16384
	ds_read_b128 v[190:193], v176 offset:17408
	ds_read_b128 v[194:197], v159 offset:2048
	ds_read_b128 v[200:203], v159 offset:3072
	ds_read_b128 v[204:207], v176 offset:18432
	ds_read_b128 v[208:211], v176 offset:19456
	s_setprio 1
	s_waitcnt lgkmcnt(5)
	v_mfma_f32_16x16x32_bf16 v[152:155], v[186:189], v[178:181], v[152:155]
	s_waitcnt lgkmcnt(4)
	v_mfma_f32_16x16x32_bf16 v[148:151], v[190:193], v[178:181], v[148:151]
	s_waitcnt lgkmcnt(1)
	v_mfma_f32_16x16x32_bf16 v[140:143], v[204:207], v[178:181], v[140:143]
	s_waitcnt lgkmcnt(0)
	v_mfma_f32_16x16x32_bf16 v[136:139], v[208:211], v[178:181], v[136:139]
	v_mfma_f32_16x16x32_bf16 v[124:127], v[186:189], v[182:185], v[124:127]
	v_mfma_f32_16x16x32_bf16 v[116:119], v[190:193], v[182:185], v[116:119]
	v_mfma_f32_16x16x32_bf16 v[108:111], v[204:207], v[182:185], v[108:111]
	v_mfma_f32_16x16x32_bf16 v[96:99], v[208:211], v[182:185], v[96:99]
	v_mfma_f32_16x16x32_bf16 v[92:95], v[186:189], v[194:197], v[92:95]
	v_mfma_f32_16x16x32_bf16 v[88:91], v[190:193], v[194:197], v[88:91]
	v_mfma_f32_16x16x32_bf16 v[68:71], v[204:207], v[194:197], v[68:71]
	v_mfma_f32_16x16x32_bf16 v[64:67], v[208:211], v[194:197], v[64:67]
	v_mfma_f32_16x16x32_bf16 v[56:59], v[186:189], v[200:203], v[56:59]
	v_mfma_f32_16x16x32_bf16 v[48:51], v[190:193], v[200:203], v[48:51]
	v_mfma_f32_16x16x32_bf16 v[40:43], v[204:207], v[200:203], v[40:43]
	v_mfma_f32_16x16x32_bf16 v[32:35], v[208:211], v[200:203], v[32:35]
	s_setprio 0
	s_min_u32 s16, s23, 0x380
	s_lshl_b32 s16, s16, 1
	s_waitcnt vmcnt(5)
	ds_write_b128 v147, v[100:103] offset:24576
	s_waitcnt vmcnt(4)
	ds_write_b128 v147, v[112:115] offset:28672
	v_lshl_add_u64 v[100:101], v[132:133], 0, s[16:17]
	v_lshl_add_u64 v[102:103], v[134:135], 0, s[16:17]
	v_lshl_add_u64 v[112:113], v[128:129], 0, s[16:17]
	v_lshl_add_u64 v[114:115], v[130:131], 0, s[16:17]
	ds_write_b128 v147, v[104:107] offset:8192
	s_waitcnt vmcnt(4)
	ds_write_b128 v147, v[120:123] offset:12288
	s_waitcnt lgkmcnt(0)
	s_barrier
	global_load_dwordx4 v[104:107], v[100:101], off offset:192
	global_load_dwordx4 v[120:123], v[102:103], off offset:192
	ds_read_b128 v[178:181], v158
	global_load_dwordx4 v[100:103], v[112:113], off offset:192
	ds_read_b128 v[182:185], v157 offset:24576
	global_load_dwordx4 v[112:115], v[114:115], off offset:192
	ds_read_b128 v[186:189], v158 offset:1024
	ds_read_b128 v[190:193], v157 offset:25600
	ds_read_b128 v[194:197], v158 offset:2048
	ds_read_b128 v[200:203], v157 offset:26624
	ds_read_b128 v[204:207], v158 offset:3072
	ds_read_b128 v[208:211], v157 offset:27648
	s_setprio 1
	s_waitcnt lgkmcnt(6)
	v_mfma_f32_16x16x32_bf16 v[152:155], v[182:185], v[178:181], v[152:155]
	s_waitcnt lgkmcnt(4)
	v_mfma_f32_16x16x32_bf16 v[148:151], v[190:193], v[178:181], v[148:151]
	s_waitcnt lgkmcnt(2)
	v_mfma_f32_16x16x32_bf16 v[140:143], v[200:203], v[178:181], v[140:143]
	s_waitcnt lgkmcnt(0)
	v_mfma_f32_16x16x32_bf16 v[136:139], v[208:211], v[178:181], v[136:139]
	v_mfma_f32_16x16x32_bf16 v[124:127], v[182:185], v[186:189], v[124:127]
	v_mfma_f32_16x16x32_bf16 v[116:119], v[190:193], v[186:189], v[116:119]
	v_mfma_f32_16x16x32_bf16 v[108:111], v[200:203], v[186:189], v[108:111]
	v_mfma_f32_16x16x32_bf16 v[96:99], v[208:211], v[186:189], v[96:99]
	v_mfma_f32_16x16x32_bf16 v[92:95], v[182:185], v[194:197], v[92:95]
	v_mfma_f32_16x16x32_bf16 v[88:91], v[190:193], v[194:197], v[88:91]
	v_mfma_f32_16x16x32_bf16 v[68:71], v[200:203], v[194:197], v[68:71]
	v_mfma_f32_16x16x32_bf16 v[64:67], v[208:211], v[194:197], v[64:67]
	v_mfma_f32_16x16x32_bf16 v[56:59], v[182:185], v[204:207], v[56:59]
	v_mfma_f32_16x16x32_bf16 v[48:51], v[190:193], v[204:207], v[48:51]
	v_mfma_f32_16x16x32_bf16 v[40:43], v[200:203], v[204:207], v[40:43]
	v_mfma_f32_16x16x32_bf16 v[32:35], v[208:211], v[204:207], v[32:35]
	s_setprio 0
	s_add_i32 s1, s1, 2
	s_cmp_lt_u32 s1, 30
	s_mov_b32 s23, s29
	s_waitcnt vmcnt(7)
	ds_write_b128 v147, v[160:163]
	s_waitcnt vmcnt(6)
	ds_write_b128 v156, v[164:167]
	s_waitcnt vmcnt(5)
	ds_write_b128 v147, v[168:171] offset:16384
	s_waitcnt vmcnt(4)
	ds_write_b128 v156, v[172:175] offset:16384
	s_waitcnt lgkmcnt(0)
	s_barrier
	s_cbranch_scc1 .LBB0_636
	s_waitcnt vmcnt(1)
	v_mov_b32_e32 v102, v220
	s_nop 0
	v_ashrrev_i32_e32 v100, 1, v102
	v_and_b32_e32 v100, 0xffffffc0, v100
	v_add_u32_e32 v100, s22, v100
	v_and_or_b32 v192, v102, 15, v100
	v_ashrrev_i32_e32 v193, 31, v192
	v_lshl_add_u64 v[100:101], v[192:193], 2, s[10:11]
	global_load_dword v224, v[100:101], off
	v_bfe_u32 v100, v102, 4, 2
	v_and_b32_e32 v101, 64, v102
	v_lshlrev_b32_e32 v102, 2, v100
	v_or3_b32 v182, v102, v101, s0
	v_ashrrev_i32_e32 v183, 31, v182
	v_cmp_eq_u32_e32 vcc, 0, v100
	v_lshlrev_b64 v[100:101], 2, v[182:183]
	v_lshl_add_u64 v[102:103], s[70:71], 0, v[100:101]
	v_lshlrev_b64 v[104:105], 12, v[192:193]
	v_lshl_add_u64 v[106:107], v[102:103], 0, v[104:105]
	global_load_dwordx4 v[206:209], v[106:107], off offset:64
	global_load_dwordx4 v[202:205], v[106:107], off
	v_or_b32_e32 v188, 16, v192
	v_or_b32_e32 v184, 32, v192
	v_or_b32_e32 v178, 48, v192
	v_lshl_add_u64 v[104:105], s[70:71], 0, v[104:105]
	v_ashrrev_i32_e32 v189, 31, v188
	v_ashrrev_i32_e32 v185, 31, v184
	v_ashrrev_i32_e32 v179, 31, v178
	v_lshl_add_u64 v[196:197], v[104:105], 0, v[100:101]
	v_lshlrev_b64 v[218:219], 11, v[192:193]
	s_waitcnt vmcnt(3)
	v_lshl_add_u64 v[112:113], v[188:189], 2, s[10:11]
	v_lshlrev_b64 v[194:195], 12, v[188:189]
	v_lshl_add_u64 v[114:115], v[184:185], 2, s[10:11]
	v_lshlrev_b64 v[190:191], 12, v[184:185]
	v_lshlrev_b64 v[186:187], 12, v[178:179]
	v_lshlrev_b64 v[180:181], 1, v[182:183]
	v_lshl_add_u64 v[120:121], v[178:179], 2, s[10:11]
	v_lshl_add_u64 v[122:123], s[12:13], 0, v[218:219]
	global_load_dword v201, v[112:113], off
	v_lshl_add_u64 v[112:113], v[102:103], 0, v[194:195]
	global_load_dword v200, v[114:115], off
	v_lshl_add_u64 v[114:115], v[102:103], 0, v[190:191]
	v_lshl_add_u64 v[102:103], v[102:103], 0, v[186:187]
	global_load_dword v176, v[120:121], off
	v_lshl_add_u64 v[222:223], v[122:123], 0, v[180:181]
	global_load_dwordx4 v[210:213], v[106:107], off offset:128
	global_load_dwordx4 v[214:217], v[106:107], off offset:192
	global_load_dwordx4 v[172:175], v[112:113], off
	global_load_dwordx4 v[168:171], v[112:113], off offset:64
	global_load_dwordx4 v[164:167], v[112:113], off offset:128
	global_load_dwordx4 v[160:163], v[112:113], off offset:192
	global_load_dwordx4 v[156:159], v[114:115], off
	global_load_dwordx4 v[144:147], v[114:115], off offset:64
	global_load_dwordx4 v[132:135], v[114:115], off offset:128
	global_load_dwordx4 v[128:131], v[114:115], off offset:192
	s_waitcnt vmcnt(15)
	v_fmamk_f32 v100, v224, 0x3a800000, v198
	v_mul_f32_e32 v101, 0x4b800000, v100
	v_cmp_gt_f32_e64 s[0:1], s26, v100
	s_nop 1
	v_cndmask_b32_e64 v100, v100, v101, s[0:1]
	v_rsq_f32_e32 v224, v100
	global_load_dwordx4 v[120:123], v[102:103], off
	global_load_dwordx4 v[112:115], v[102:103], off offset:64
	global_load_dwordx4 v[104:107], v[102:103], off offset:128
	s_nop 0
	global_load_dwordx4 v[100:103], v[102:103], off offset:192
	v_mul_f32_e32 v225, 0x45800000, v224
	v_cndmask_b32_e64 v224, v224, v225, s[0:1]
	v_mul_f32_e32 v154, v154, v224
	v_mul_f32_e32 v155, v155, v224
	v_mul_f32_e32 v150, v150, v224
	v_mul_f32_e32 v151, v151, v224
	v_mul_f32_e32 v154, 0xbfb8aa3b, v154
	v_mul_f32_e32 v155, 0xbfb8aa3b, v155
	v_mul_f32_e32 v150, 0xbfb8aa3b, v150
	v_mul_f32_e32 v151, 0xbfb8aa3b, v151
	v_exp_f32_e32 v154, v154
	v_exp_f32_e32 v155, v155
	v_exp_f32_e32 v150, v150
	v_exp_f32_e32 v151, v151
	v_mul_f32_e32 v152, v152, v224
	v_mul_f32_e32 v153, v153, v224
	v_mul_f32_e32 v148, v148, v224
	v_mul_f32_e32 v149, v149, v224
	v_mul_f32_e32 v152, 0xbfb8aa3b, v152
	v_mul_f32_e32 v153, 0xbfb8aa3b, v153
	v_mul_f32_e32 v148, 0xbfb8aa3b, v148
	v_mul_f32_e32 v149, 0xbfb8aa3b, v149
	v_add_f32_e32 v154, 1.0, v154
	v_add_f32_e32 v155, 1.0, v155
	v_add_f32_e32 v227, 1.0, v150
	v_add_f32_e32 v228, 1.0, v151
	v_exp_f32_e32 v152, v152
	v_exp_f32_e32 v153, v153
	v_exp_f32_e32 v148, v148
	v_exp_f32_e32 v149, v149
	v_rcp_f32_e32 v150, v154
	v_rcp_f32_e32 v151, v155
	v_rcp_f32_e32 v154, v227
	v_rcp_f32_e32 v155, v228
	v_mul_f32_e32 v140, v140, v224
	v_mul_f32_e32 v140, 0xbfb8aa3b, v140
	v_add_f32_e32 v152, 1.0, v152
	v_add_f32_e32 v153, 1.0, v153
	v_add_f32_e32 v225, 1.0, v148
	v_add_f32_e32 v226, 1.0, v149
	s_waitcnt vmcnt(18)
	v_pk_fma_f32 v[82:83], v[82:83], v[154:155], v[208:209]
	v_exp_f32_e32 v154, v140
	v_mul_f32_e32 v140, v141, v224
	v_rcp_f32_e32 v148, v152
	v_rcp_f32_e32 v149, v153
	v_rcp_f32_e32 v152, v225
	v_rcp_f32_e32 v153, v226
	v_mul_f32_e32 v140, 0xbfb8aa3b, v140
	v_mul_f32_e32 v142, v142, v224
	v_exp_f32_e32 v141, v140
	v_mul_f32_e32 v142, 0xbfb8aa3b, v142
	v_mul_f32_e32 v143, v143, v224
	v_exp_f32_e32 v142, v142
	v_mul_f32_e32 v143, 0xbfb8aa3b, v143
	v_exp_f32_e32 v143, v143
	s_waitcnt vmcnt(17)
	v_pk_fma_f32 v[84:85], v[84:85], v[148:149], v[202:203]
	v_pk_fma_f32 v[80:81], v[80:81], v[152:153], v[206:207]
	v_mul_f32_e32 v148, v85, v85
	v_mul_f32_e32 v152, v81, v81
	v_add_f32_e32 v141, 1.0, v141
	v_pk_fma_f32 v[86:87], v[86:87], v[150:151], v[204:205]
	v_pk_fma_f32 v[148:149], v[84:85], v[84:85], v[148:149] op_sel_hi:[1,1,0]
	v_pk_fma_f32 v[152:153], v[80:81], v[80:81], v[152:153] op_sel_hi:[1,1,0]
	v_rcp_f32_e32 v155, v141
	v_add_f32_e32 v141, 1.0, v142
	v_mul_f32_e32 v150, v87, v87
	v_pk_fma_f32 v[148:149], v[86:87], v[86:87], v[148:149]
	v_pk_fma_f32 v[152:153], v[82:83], v[82:83], v[152:153]
	v_mul_f32_e32 v140, v83, v83
	v_rcp_f32_e32 v142, v141
	v_add_f32_e32 v141, 1.0, v143
	v_mul_f32_e32 v136, v136, v224
	v_pk_add_f32 v[148:149], v[150:151], v[148:149] op_sel_hi:[0,1]
	v_rcp_f32_e32 v143, v141
	v_pk_add_f32 v[140:141], v[140:141], v[152:153] op_sel_hi:[0,1]
	v_mul_f32_e32 v136, 0xbfb8aa3b, v136
	v_pk_add_f32 v[140:141], v[148:149], v[140:141]
	v_exp_f32_e32 v148, v136
	v_mul_f32_e32 v136, v137, v224
	v_mul_f32_e32 v136, 0xbfb8aa3b, v136
	v_mul_f32_e32 v138, v138, v224
	v_exp_f32_e32 v137, v136
	v_mul_f32_e32 v138, 0xbfb8aa3b, v138
	v_mul_f32_e32 v139, v139, v224
	v_add_f32_e32 v154, 1.0, v154
	v_exp_f32_e32 v138, v138
	v_mul_f32_e32 v139, 0xbfb8aa3b, v139
	v_rcp_f32_e32 v154, v154
	v_exp_f32_e32 v139, v139
	v_add_f32_e32 v137, 1.0, v137
	v_add_f32_e32 v148, 1.0, v148
	v_rcp_f32_e32 v149, v137
	v_add_f32_e32 v137, 1.0, v138
	s_waitcnt vmcnt(13)
	v_pk_fma_f32 v[76:77], v[76:77], v[154:155], v[210:211]
	v_rcp_f32_e32 v148, v148
	v_rcp_f32_e32 v138, v137
	v_add_f32_e32 v137, 1.0, v139
	v_pk_fma_f32 v[78:79], v[78:79], v[142:143], v[212:213]
	v_mul_f32_e32 v142, v77, v77
	v_rcp_f32_e32 v139, v137
	v_pk_fma_f32 v[142:143], v[76:77], v[76:77], v[142:143] op_sel_hi:[1,1,0]
	v_mul_f32_e32 v136, v79, v79
	v_pk_fma_f32 v[142:143], v[78:79], v[78:79], v[142:143]
	v_lshl_add_u64 v[150:151], s[72:73], 0, v[218:219]
	v_pk_add_f32 v[136:137], v[136:137], v[142:143] op_sel_hi:[0,1]
	s_waitcnt vmcnt(12)
	v_pk_fma_f32 v[72:73], v[72:73], v[148:149], v[214:215]
	v_lshl_add_u64 v[150:151], v[150:151], 0, v[180:181]
	v_pk_add_f32 v[136:137], v[136:137], v[140:141]
	v_pk_fma_f32 v[74:75], v[74:75], v[138:139], v[216:217]
	v_and_b32_sdwa v138, v86, v199 dst_sel:DWORD dst_unused:UNUSED_PAD src0_sel:WORD_1 src1_sel:DWORD
	v_and_b32_sdwa v139, v84, v199 dst_sel:DWORD dst_unused:UNUSED_PAD src0_sel:WORD_1 src1_sel:DWORD
	global_store_dwordx4 v[196:197], v[84:87], off
	s_nop 1
	v_add3_u32 v84, v84, v139, s9
	v_add3_u32 v86, v86, v138, s9
	v_and_b32_sdwa v138, v87, v199 dst_sel:DWORD dst_unused:UNUSED_PAD src0_sel:WORD_1 src1_sel:DWORD
	v_and_b32_sdwa v139, v85, v199 dst_sel:DWORD dst_unused:UNUSED_PAD src0_sel:WORD_1 src1_sel:DWORD
	v_add3_u32 v87, v87, v138, s9
	v_add3_u32 v85, v85, v139, s9
	v_and_b32_e32 v87, 0xffff0000, v87
	v_and_b32_e32 v138, 0xffff0000, v85
	v_or_b32_sdwa v85, v87, v86 dst_sel:DWORD dst_unused:UNUSED_PAD src0_sel:DWORD src1_sel:WORD_1
	v_or_b32_sdwa v84, v138, v84 dst_sel:DWORD dst_unused:UNUSED_PAD src0_sel:DWORD src1_sel:WORD_1
	global_store_dwordx2 v[222:223], v[84:85], off
	global_store_dwordx4 v[196:197], v[80:83], off offset:64
	v_and_b32_sdwa v84, v82, v199 dst_sel:DWORD dst_unused:UNUSED_PAD src0_sel:WORD_1 src1_sel:DWORD
	v_and_b32_sdwa v85, v80, v199 dst_sel:DWORD dst_unused:UNUSED_PAD src0_sel:WORD_1 src1_sel:DWORD
	v_add3_u32 v82, v82, v84, s9
	v_and_b32_sdwa v84, v83, v199 dst_sel:DWORD dst_unused:UNUSED_PAD src0_sel:WORD_1 src1_sel:DWORD
	v_add3_u32 v80, v80, v85, s9
	v_and_b32_sdwa v85, v81, v199 dst_sel:DWORD dst_unused:UNUSED_PAD src0_sel:WORD_1 src1_sel:DWORD
	v_add3_u32 v83, v83, v84, s9
	v_add3_u32 v81, v81, v85, s9
	v_and_b32_e32 v83, 0xffff0000, v83
	v_and_b32_e32 v84, 0xffff0000, v81
	v_or_b32_sdwa v81, v83, v82 dst_sel:DWORD dst_unused:UNUSED_PAD src0_sel:DWORD src1_sel:WORD_1
	v_add_co_u32_e64 v82, s[0:1], s27, v150
	v_or_b32_sdwa v80, v84, v80 dst_sel:DWORD dst_unused:UNUSED_PAD src0_sel:DWORD src1_sel:WORD_1
	s_nop 0
	v_addc_co_u32_e64 v83, s[0:1], 0, v151, s[0:1]
	global_store_dwordx2 v[82:83], v[80:81], off offset:32
	global_store_dwordx4 v[196:197], v[76:79], off offset:128
	v_and_b32_sdwa v80, v78, v199 dst_sel:DWORD dst_unused:UNUSED_PAD src0_sel:WORD_1 src1_sel:DWORD
	v_and_b32_sdwa v81, v76, v199 dst_sel:DWORD dst_unused:UNUSED_PAD src0_sel:WORD_1 src1_sel:DWORD
	v_add3_u32 v76, v76, v81, s9
	v_add3_u32 v78, v78, v80, s9
	v_and_b32_sdwa v80, v79, v199 dst_sel:DWORD dst_unused:UNUSED_PAD src0_sel:WORD_1 src1_sel:DWORD
	v_and_b32_sdwa v81, v77, v199 dst_sel:DWORD dst_unused:UNUSED_PAD src0_sel:WORD_1 src1_sel:DWORD
	v_add3_u32 v79, v79, v80, s9
	v_add3_u32 v77, v77, v81, s9
	v_and_b32_e32 v79, 0xffff0000, v79
	v_and_b32_e32 v80, 0xffff0000, v77
	v_or_b32_sdwa v77, v79, v78 dst_sel:DWORD dst_unused:UNUSED_PAD src0_sel:DWORD src1_sel:WORD_1
	v_or_b32_sdwa v76, v80, v76 dst_sel:DWORD dst_unused:UNUSED_PAD src0_sel:DWORD src1_sel:WORD_1
	global_store_dwordx2 v[82:83], v[76:77], off offset:64
	global_store_dwordx4 v[196:197], v[72:75], off offset:192
	v_and_b32_sdwa v77, v72, v199 dst_sel:DWORD dst_unused:UNUSED_PAD src0_sel:WORD_1 src1_sel:DWORD
	v_add3_u32 v78, v72, v77, s9
	v_and_b32_sdwa v77, v75, v199 dst_sel:DWORD dst_unused:UNUSED_PAD src0_sel:WORD_1 src1_sel:DWORD
	v_and_b32_sdwa v79, v73, v199 dst_sel:DWORD dst_unused:UNUSED_PAD src0_sel:WORD_1 src1_sel:DWORD
	v_and_b32_sdwa v76, v74, v199 dst_sel:DWORD dst_unused:UNUSED_PAD src0_sel:WORD_1 src1_sel:DWORD
	v_add3_u32 v77, v75, v77, s9
	v_add3_u32 v79, v73, v79, s9
	v_add3_u32 v76, v74, v76, s9
	v_and_b32_e32 v77, 0xffff0000, v77
	v_and_b32_e32 v79, 0xffff0000, v79
	v_or_b32_sdwa v77, v77, v76 dst_sel:DWORD dst_unused:UNUSED_PAD src0_sel:DWORD src1_sel:WORD_1
	v_or_b32_sdwa v76, v79, v78 dst_sel:DWORD dst_unused:UNUSED_PAD src0_sel:DWORD src1_sel:WORD_1
	global_store_dwordx2 v[82:83], v[76:77], off offset:96
	v_mul_f32_e32 v76, v73, v73
	v_pk_fma_f32 v[72:73], v[72:73], v[72:73], v[76:77] op_sel_hi:[1,1,0]
	s_nop 0
	v_pk_fma_f32 v[72:73], v[74:75], v[74:75], v[72:73]
	v_mul_f32_e32 v74, v75, v75
	v_pk_add_f32 v[72:73], v[74:75], v[72:73] op_sel_hi:[0,1]
	v_pk_add_f32 v[72:73], v[72:73], v[136:137]
	s_nop 0
	v_mov_b32_e32 v73, v72
	s_nop 1
	v_permlane32_swap_b32_e32 v72, v73
	v_add_f32_e32 v72, v72, v73
	v_mov_b32_e32 v73, v72
	s_nop 1
	v_permlane16_swap_b32_e32 v72, v73
	s_and_saveexec_b64 s[0:1], vcc
	s_cbranch_execz .LBB0_639
	v_lshl_add_u64 v[74:75], v[192:193], 2, s[14:15]
	v_add_f32_e32 v72, v72, v73
	global_atomic_add_f32 v[74:75], v72, off

.LBB0_704:
	s_lshl_b32 s1, s51, 7
	s_lshl_b32 s0, s33, 10
	s_and_b32 s1, s1, 0x300
	s_or_b32 s0, s0, s1
	s_andn2_b64 vcc, exec, s[12:13]
	s_and_b32 s12, s16, 3
	s_cbranch_vccnz .LBB0_708
	s_ashr_i32 s1, s0, 31
	s_lshl_b32 s10, s52, 7
	s_lshl_b64 s[26:27], s[0:1], 11
	s_add_u32 s26, s5, s26
	s_addc_u32 s27, s6, s27
	s_ashr_i32 s11, s10, 31
	v_mov_b32_e32 v40, v220
	s_lshl_b64 s[10:11], s[10:11], 11
	s_add_u32 s10, s7, s10
	v_ashrrev_i32_e32 v30, 2, v40
	v_ashrrev_i32_e32 v31, 31, v30
	s_addc_u32 s11, s8, s11
	v_lshlrev_b64 v[0:1], 11, v[30:31]
	v_lshlrev_b32_e32 v4, 4, v40
	v_lshl_add_u64 v[2:3], s[10:11], 0, v[0:1]
	v_lshl_add_u64 v[0:1], s[26:27], 0, v[0:1]
	v_and_b32_e32 v152, 48, v4
	v_lshl_add_u64 v[154:155], v[0:1], 0, v[152:153]
	v_add_co_u32_e32 v32, vcc, s9, v154
	v_lshl_add_u64 v[156:157], v[2:3], 0, v[152:153]
	s_nop 0
	v_addc_co_u32_e32 v33, vcc, 0, v155, vcc
	v_add_co_u32_e32 v34, vcc, s31, v154
	global_load_dwordx4 v[6:9], v[154:155], off
	s_nop 0
	v_addc_co_u32_e32 v35, vcc, 0, v155, vcc
	v_add_co_u32_e32 v36, vcc, s35, v154
	global_load_dwordx4 v[10:13], v[32:33], off
	s_nop 0
	v_addc_co_u32_e32 v37, vcc, 0, v155, vcc
	v_add_co_u32_e32 v38, vcc, s9, v156
	global_load_dwordx4 v[14:17], v[34:35], off
	s_nop 0
	v_addc_co_u32_e32 v39, vcc, 0, v157, vcc
	global_load_dwordx4 v[18:21], v[36:37], off
	global_load_dwordx4 v[22:25], v[156:157], off
	global_load_dwordx4 v[26:29], v[38:39], off
	global_load_dwordx4 v[112:115], v[154:155], off offset:64
	global_load_dwordx4 v[120:123], v[32:33], off offset:64
	global_load_dwordx4 v[124:127], v[34:35], off offset:64
	global_load_dwordx4 v[128:131], v[36:37], off offset:64
	global_load_dwordx4 v[116:119], v[156:157], off offset:64
	global_load_dwordx4 v[132:135], v[38:39], off offset:64
	v_lshrrev_b32_e32 v31, 4, v40
	v_lshrrev_b32_e32 v41, 2, v40
	v_sub_u32_e32 v44, 0, v31
	v_sub_u32_e32 v41, 0, v41
	v_and_b32_e32 v42, 0x3ffff8f, v40
	v_lshlrev_b32_e32 v43, 6, v40
	v_xor_b32_e32 v40, v40, v44
	v_xor_b32_e32 v31, v31, v41
	v_lshlrev_b32_e32 v40, 4, v40
	v_lshlrev_b32_e32 v31, 4, v31
	v_and_b32_e32 v45, 0x1000, v43
	v_and_b32_e32 v40, 48, v40
	v_and_b32_e32 v31, 48, v31
	v_mov_b32_e32 v0, 0
	v_and_b32_e32 v46, 0x3c0, v43
	v_and_b32_e32 v43, 0xffffe3c0, v43
	v_lshl_add_u32 v42, v42, 6, v167
	v_lshl_or_b32 v152, v30, 6, v40
	v_or_b32_e32 v30, v31, v45
	s_mov_b32 s10, 0
	s_mov_b32 s1, -2
	v_mov_b32_e32 v1, v0
	v_mov_b32_e32 v2, v0
	v_mov_b32_e32 v3, v0
	v_mov_b32_e32 v4, v0
	v_mov_b32_e32 v5, v0
	v_lshl_add_u64 v[158:159], v[154:155], 0, s[22:23]
	v_lshl_add_u64 v[160:161], v[154:155], 0, s[24:25]
	v_lshl_add_u64 v[162:163], v[154:155], 0, s[28:29]
	v_or3_b32 v168, v45, v46, v31
	v_add_u32_e32 v169, v31, v43
	v_add_u32_e32 v170, v31, v42
	v_add_u32_e32 v171, v30, v46
	v_lshl_add_u64 v[164:165], v[156:157], 0, s[22:23]
	v_mov_b32_e32 v30, v0
	v_mov_b32_e32 v31, v0
	v_mov_b32_e32 v32, v0
	v_mov_b32_e32 v33, v0
	v_mov_b32_e32 v34, v0
	v_mov_b32_e32 v35, v0
	v_mov_b32_e32 v36, v0
	v_mov_b32_e32 v37, v0
	v_mov_b32_e32 v38, v0
	v_mov_b32_e32 v39, v0
	v_mov_b32_e32 v40, v0
	v_mov_b32_e32 v41, v0
	v_mov_b32_e32 v42, v0
	v_mov_b32_e32 v43, v0
	v_mov_b32_e32 v44, v0
	v_mov_b32_e32 v45, v0
	v_mov_b32_e32 v46, v0
	s_waitcnt vmcnt(11)
	ds_write_b128 v152, v[6:9]
	s_waitcnt vmcnt(10)
	ds_write_b128 v152, v[10:13] offset:4096
	s_waitcnt vmcnt(9)
	ds_write_b128 v152, v[14:17] offset:8192
	s_waitcnt vmcnt(8)
	ds_write_b128 v152, v[18:21] offset:12288
	s_waitcnt vmcnt(7)
	ds_write_b128 v152, v[22:25] offset:32768
	s_waitcnt vmcnt(6)
	ds_write_b128 v152, v[26:29] offset:36864
	v_mov_b32_e32 v6, v0
	v_mov_b32_e32 v7, v0
	v_mov_b32_e32 v8, v0
	v_mov_b32_e32 v9, v0
	v_mov_b32_e32 v10, v0
	v_mov_b32_e32 v11, v0
	v_mov_b32_e32 v12, v0
	v_mov_b32_e32 v13, v0
	v_mov_b32_e32 v14, v0
	v_mov_b32_e32 v15, v0
	v_mov_b32_e32 v16, v0
	v_mov_b32_e32 v17, v0
	v_mov_b32_e32 v18, v0
	v_mov_b32_e32 v19, v0
	v_mov_b32_e32 v20, v0
	v_mov_b32_e32 v21, v0
	v_mov_b32_e32 v22, v0
	v_mov_b32_e32 v23, v0
	v_mov_b32_e32 v24, v0
	v_mov_b32_e32 v25, v0
	v_mov_b32_e32 v26, v0
	v_mov_b32_e32 v27, v0
	v_mov_b32_e32 v28, v0
	v_mov_b32_e32 v29, v0
	v_mov_b32_e32 v47, v0
	v_mov_b32_e32 v48, v0
	v_mov_b32_e32 v49, v0
	v_mov_b32_e32 v50, v0
	v_mov_b32_e32 v51, v0
	v_mov_b32_e32 v52, v0
	v_mov_b32_e32 v53, v0
	v_mov_b32_e32 v54, v0
	v_mov_b32_e32 v55, v0
	v_mov_b32_e32 v56, v0
	v_mov_b32_e32 v57, v0
	v_mov_b32_e32 v58, v0
	v_mov_b32_e32 v59, v0
	v_mov_b32_e32 v60, v0
	v_mov_b32_e32 v61, v0
	v_mov_b32_e32 v62, v0
	v_mov_b32_e32 v63, v0
	v_mov_b32_e32 v64, v0
	v_mov_b32_e32 v65, v0
	v_mov_b32_e32 v66, v0
	v_mov_b32_e32 v67, v0
	v_mov_b32_e32 v68, v0
	v_mov_b32_e32 v69, v0
	v_mov_b32_e32 v70, v0
	v_mov_b32_e32 v71, v0
	v_mov_b32_e32 v72, v0
	v_mov_b32_e32 v73, v0
	v_mov_b32_e32 v74, v0
	v_mov_b32_e32 v75, v0
	v_mov_b32_e32 v76, v0
	v_mov_b32_e32 v77, v0
	v_mov_b32_e32 v78, v0
	v_mov_b32_e32 v79, v0
	v_mov_b32_e32 v80, v0
	v_mov_b32_e32 v81, v0
	v_mov_b32_e32 v82, v0
	v_mov_b32_e32 v83, v0
	v_mov_b32_e32 v84, v0
	v_mov_b32_e32 v85, v0
	v_mov_b32_e32 v86, v0
	v_mov_b32_e32 v87, v0
	v_mov_b32_e32 v88, v0
	v_mov_b32_e32 v89, v0
	v_mov_b32_e32 v90, v0
	v_mov_b32_e32 v91, v0
	v_mov_b32_e32 v92, v0
	v_mov_b32_e32 v93, v0
	v_mov_b32_e32 v94, v0
	v_mov_b32_e32 v95, v0
	v_mov_b32_e32 v96, v0
	v_mov_b32_e32 v97, v0
	v_mov_b32_e32 v98, v0
	v_mov_b32_e32 v99, v0
	v_mov_b32_e32 v100, v0
	v_mov_b32_e32 v101, v0
	v_mov_b32_e32 v102, v0
	v_mov_b32_e32 v103, v0
	v_mov_b32_e32 v104, v0
	v_mov_b32_e32 v105, v0
	v_mov_b32_e32 v106, v0
	v_mov_b32_e32 v107, v0
	v_mov_b32_e32 v108, v0
	v_mov_b32_e32 v109, v0
	v_mov_b32_e32 v110, v0
	v_mov_b32_e32 v111, v0
	v_mov_b32_e32 v136, v0
	v_mov_b32_e32 v137, v0
	v_mov_b32_e32 v138, v0
	v_mov_b32_e32 v139, v0
	v_mov_b32_e32 v140, v0
	v_mov_b32_e32 v141, v0
	v_mov_b32_e32 v142, v0
	v_mov_b32_e32 v143, v0
	v_mov_b32_e32 v144, v0
	v_mov_b32_e32 v145, v0
	v_mov_b32_e32 v146, v0
	v_mov_b32_e32 v147, v0
	v_mov_b32_e32 v148, v0
	v_mov_b32_e32 v149, v0
	v_mov_b32_e32 v150, v0
	v_mov_b32_e32 v151, v0
	s_waitcnt lgkmcnt(0)
	s_barrier
	s_cmpk_lt_u32 s2, 0x100
	s_cbranch_scc1 .Lstag_4
	s_sleep 8
.Lstag_4:
.LBB0_706:
	s_add_i32 s11, s10, 64
	s_min_u32 s13, s11, 0x3e0
	s_lshl_b32 s16, s13, 1
	v_lshl_add_u64 v[172:173], v[154:155], 0, s[16:17]
	v_lshl_add_u64 v[176:177], v[158:159], 0, s[16:17]
	v_lshl_add_u64 v[180:181], v[160:161], 0, s[16:17]
	v_lshl_add_u64 v[184:185], v[162:163], 0, s[16:17]
	v_lshl_add_u64 v[188:189], v[156:157], 0, s[16:17]
	v_lshl_add_u64 v[192:193], v[164:165], 0, s[16:17]
	global_load_dwordx4 v[172:175], v[172:173], off
	ds_read_b128 v[196:199], v171 offset:32768
	global_load_dwordx4 v[176:179], v[176:177], off
	ds_read_b128 v[200:203], v171 offset:33792
	global_load_dwordx4 v[180:183], v[180:181], off
	ds_read_b128 v[204:207], v171 offset:34816
	global_load_dwordx4 v[184:187], v[184:185], off
	ds_read_b128 v[208:211], v171 offset:35840
	global_load_dwordx4 v[188:191], v[188:189], off
	ds_read_b128 v[212:215], v169
	global_load_dwordx4 v[192:195], v[192:193], off
	ds_read_b128 v[216:219], v169 offset:1024
	ds_read_b128 v[222:225], v169 offset:2048
	ds_read_b128 v[226:229], v169 offset:3072
	ds_read_b128 v[230:233], v169 offset:4096
	ds_read_b128 v[234:237], v169 offset:5120
	ds_read_b128 v[238:241], v169 offset:6144
	ds_read_b128 v[242:245], v169 offset:7168
	s_setprio 1
	s_waitcnt lgkmcnt(7)
	v_mfma_f32_16x16x32_bf16 v[148:151], v[196:199], v[212:215], v[148:151]
	v_mfma_f32_16x16x32_bf16 v[144:147], v[200:203], v[212:215], v[144:147]
	v_mfma_f32_16x16x32_bf16 v[140:143], v[204:207], v[212:215], v[140:143]
	v_mfma_f32_16x16x32_bf16 v[136:139], v[208:211], v[212:215], v[136:139]
	s_waitcnt vmcnt(11)
	ds_write_b128 v152, v[112:115] offset:16384
	s_waitcnt lgkmcnt(7)
	v_mfma_f32_16x16x32_bf16 v[108:111], v[196:199], v[216:219], v[108:111]
	v_mfma_f32_16x16x32_bf16 v[104:107], v[200:203], v[216:219], v[104:107]
	v_mfma_f32_16x16x32_bf16 v[100:103], v[204:207], v[216:219], v[100:103]
	v_mfma_f32_16x16x32_bf16 v[96:99], v[208:211], v[216:219], v[96:99]
	s_waitcnt vmcnt(9)
	ds_write_b128 v152, v[120:123] offset:20480
	s_waitcnt lgkmcnt(7)
	v_mfma_f32_16x16x32_bf16 v[92:95], v[196:199], v[222:225], v[92:95]
	v_mfma_f32_16x16x32_bf16 v[88:91], v[200:203], v[222:225], v[88:91]
	v_mfma_f32_16x16x32_bf16 v[84:87], v[204:207], v[222:225], v[84:87]
	v_mfma_f32_16x16x32_bf16 v[80:83], v[208:211], v[222:225], v[80:83]
	s_waitcnt vmcnt(8)
	ds_write_b128 v152, v[124:127] offset:24576
	s_waitcnt lgkmcnt(7)
	v_mfma_f32_16x16x32_bf16 v[76:79], v[196:199], v[226:229], v[76:79]
	v_mfma_f32_16x16x32_bf16 v[72:75], v[200:203], v[226:229], v[72:75]
	v_mfma_f32_16x16x32_bf16 v[68:71], v[204:207], v[226:229], v[68:71]
	v_mfma_f32_16x16x32_bf16 v[64:67], v[208:211], v[226:229], v[64:67]
	s_waitcnt vmcnt(7)
	ds_write_b128 v152, v[128:131] offset:28672
	s_waitcnt lgkmcnt(7)
	v_mfma_f32_16x16x32_bf16 v[60:63], v[196:199], v[230:233], v[60:63]
	v_mfma_f32_16x16x32_bf16 v[56:59], v[200:203], v[230:233], v[56:59]
	v_mfma_f32_16x16x32_bf16 v[52:55], v[204:207], v[230:233], v[52:55]
	v_mfma_f32_16x16x32_bf16 v[48:51], v[208:211], v[230:233], v[48:51]
	s_waitcnt vmcnt(7)
	ds_write_b128 v152, v[116:119] offset:40960
	s_waitcnt lgkmcnt(7)
	v_mfma_f32_16x16x32_bf16 v[44:47], v[196:199], v[234:237], v[44:47]
	v_mfma_f32_16x16x32_bf16 v[40:43], v[200:203], v[234:237], v[40:43]
	v_mfma_f32_16x16x32_bf16 v[36:39], v[204:207], v[234:237], v[36:39]
	v_mfma_f32_16x16x32_bf16 v[32:35], v[208:211], v[234:237], v[32:35]
	s_waitcnt vmcnt(6)
	ds_write_b128 v152, v[132:135] offset:45056
	s_waitcnt lgkmcnt(7)
	v_mfma_f32_16x16x32_bf16 v[28:31], v[196:199], v[238:241], v[28:31]
	v_mfma_f32_16x16x32_bf16 v[24:27], v[200:203], v[238:241], v[24:27]
	v_mfma_f32_16x16x32_bf16 v[20:23], v[204:207], v[238:241], v[20:23]
	v_mfma_f32_16x16x32_bf16 v[16:19], v[208:211], v[238:241], v[16:19]
	s_waitcnt lgkmcnt(6)
	v_mfma_f32_16x16x32_bf16 v[12:15], v[196:199], v[242:245], v[12:15]
	v_mfma_f32_16x16x32_bf16 v[8:11], v[200:203], v[242:245], v[8:11]
	v_mfma_f32_16x16x32_bf16 v[4:7], v[204:207], v[242:245], v[4:7]
	v_mfma_f32_16x16x32_bf16 v[0:3], v[208:211], v[242:245], v[0:3]
	s_setprio 0
	s_min_u32 s10, s10, 0x380
	s_lshl_b32 s16, s10, 1
	s_mov_b32 s27, s17
	s_add_i32 s26, s16, 0xc0
	v_lshl_add_u64 v[112:113], v[154:155], 0, s[16:17]
	v_lshl_add_u64 v[116:117], v[156:157], 0, s[16:17]
	v_lshl_add_u64 v[120:121], v[158:159], 0, s[26:27]
	v_lshl_add_u64 v[124:125], v[160:161], 0, s[26:27]
	v_lshl_add_u64 v[128:129], v[162:163], 0, s[26:27]
	v_lshl_add_u64 v[132:133], v[164:165], 0, s[26:27]
	s_waitcnt lgkmcnt(0)
	s_barrier
	global_load_dwordx4 v[112:115], v[112:113], off offset:192
	ds_read_b128 v[196:199], v168 offset:40960
	global_load_dwordx4 v[116:119], v[116:117], off offset:192
	ds_read_b128 v[200:203], v168 offset:41984
	global_load_dwordx4 v[120:123], v[120:121], off
	ds_read_b128 v[204:207], v168 offset:43008
	global_load_dwordx4 v[124:127], v[124:125], off
	ds_read_b128 v[208:211], v168 offset:44032
	global_load_dwordx4 v[128:131], v[128:129], off
	ds_read_b128 v[212:215], v170
	global_load_dwordx4 v[132:135], v[132:133], off
	ds_read_b128 v[216:219], v170 offset:1024
	ds_read_b128 v[222:225], v170 offset:2048
	ds_read_b128 v[226:229], v170 offset:3072
	ds_read_b128 v[230:233], v170 offset:4096
	ds_read_b128 v[234:237], v170 offset:5120
	ds_read_b128 v[238:241], v170 offset:6144
	ds_read_b128 v[242:245], v170 offset:7168
	s_setprio 1
	s_waitcnt lgkmcnt(7)
	v_mfma_f32_16x16x32_bf16 v[148:151], v[196:199], v[212:215], v[148:151]
	v_mfma_f32_16x16x32_bf16 v[144:147], v[200:203], v[212:215], v[144:147]
	v_mfma_f32_16x16x32_bf16 v[140:143], v[204:207], v[212:215], v[140:143]
	v_mfma_f32_16x16x32_bf16 v[136:139], v[208:211], v[212:215], v[136:139]
	s_waitcnt vmcnt(11)
	ds_write_b128 v152, v[172:175]
	s_waitcnt lgkmcnt(7)
	v_mfma_f32_16x16x32_bf16 v[108:111], v[196:199], v[216:219], v[108:111]
	v_mfma_f32_16x16x32_bf16 v[104:107], v[200:203], v[216:219], v[104:107]
	v_mfma_f32_16x16x32_bf16 v[100:103], v[204:207], v[216:219], v[100:103]
	v_mfma_f32_16x16x32_bf16 v[96:99], v[208:211], v[216:219], v[96:99]
	s_waitcnt vmcnt(10)
	ds_write_b128 v152, v[176:179] offset:4096
	s_waitcnt lgkmcnt(7)
	v_mfma_f32_16x16x32_bf16 v[92:95], v[196:199], v[222:225], v[92:95]
	v_mfma_f32_16x16x32_bf16 v[88:91], v[200:203], v[222:225], v[88:91]
	v_mfma_f32_16x16x32_bf16 v[84:87], v[204:207], v[222:225], v[84:87]
	v_mfma_f32_16x16x32_bf16 v[80:83], v[208:211], v[222:225], v[80:83]
	s_waitcnt vmcnt(9)
	ds_write_b128 v152, v[180:183] offset:8192
	s_waitcnt lgkmcnt(7)
	v_mfma_f32_16x16x32_bf16 v[76:79], v[196:199], v[226:229], v[76:79]
	v_mfma_f32_16x16x32_bf16 v[72:75], v[200:203], v[226:229], v[72:75]
	v_mfma_f32_16x16x32_bf16 v[68:71], v[204:207], v[226:229], v[68:71]
	v_mfma_f32_16x16x32_bf16 v[64:67], v[208:211], v[226:229], v[64:67]
	s_waitcnt vmcnt(8)
	ds_write_b128 v152, v[184:187] offset:12288
	s_waitcnt lgkmcnt(7)
	v_mfma_f32_16x16x32_bf16 v[60:63], v[196:199], v[230:233], v[60:63]
	v_mfma_f32_16x16x32_bf16 v[56:59], v[200:203], v[230:233], v[56:59]
	v_mfma_f32_16x16x32_bf16 v[52:55], v[204:207], v[230:233], v[52:55]
	v_mfma_f32_16x16x32_bf16 v[48:51], v[208:211], v[230:233], v[48:51]
	s_waitcnt vmcnt(7)
	ds_write_b128 v152, v[188:191] offset:32768
	s_waitcnt lgkmcnt(7)
	v_mfma_f32_16x16x32_bf16 v[44:47], v[196:199], v[234:237], v[44:47]
	v_mfma_f32_16x16x32_bf16 v[40:43], v[200:203], v[234:237], v[40:43]
	v_mfma_f32_16x16x32_bf16 v[36:39], v[204:207], v[234:237], v[36:39]
	v_mfma_f32_16x16x32_bf16 v[32:35], v[208:211], v[234:237], v[32:35]
	s_waitcnt vmcnt(6)
	ds_write_b128 v152, v[192:195] offset:36864
	s_waitcnt lgkmcnt(7)
	v_mfma_f32_16x16x32_bf16 v[28:31], v[196:199], v[238:241], v[28:31]
	v_mfma_f32_16x16x32_bf16 v[24:27], v[200:203], v[238:241], v[24:27]
	v_mfma_f32_16x16x32_bf16 v[20:23], v[204:207], v[238:241], v[20:23]
	v_mfma_f32_16x16x32_bf16 v[16:19], v[208:211], v[238:241], v[16:19]
	s_waitcnt lgkmcnt(6)
	v_mfma_f32_16x16x32_bf16 v[12:15], v[196:199], v[242:245], v[12:15]
	v_mfma_f32_16x16x32_bf16 v[8:11], v[200:203], v[242:245], v[8:11]
	v_mfma_f32_16x16x32_bf16 v[4:7], v[204:207], v[242:245], v[4:7]
	v_mfma_f32_16x16x32_bf16 v[0:3], v[208:211], v[242:245], v[0:3]
	s_setprio 0
	s_add_i32 s1, s1, 2
	s_cmp_lt_u32 s1, 30
	s_mov_b32 s10, s11
	s_waitcnt lgkmcnt(0)
	s_barrier
	s_cbranch_scc1 .LBB0_706
	s_waitcnt vmcnt(4)
	v_mov_b32_e32 v116, v220
	s_nop 0
	v_and_b32_e32 v112, 0xffffff80, v116
	v_add_u32_e32 v117, s0, v112
	v_and_or_b32 v114, v116, 15, v117
	v_ashrrev_i32_e32 v115, 31, v114
	v_lshl_add_u64 v[112:113], v[114:115], 2, s[14:15]
	global_load_dword v122, v[112:113], off
	v_and_b32_e32 v112, 64, v116
	v_lshrrev_b32_e32 v115, 1, v116
	v_ashrrev_i32_e32 v116, 14, v117
	v_ashrrev_i32_e32 v117, 31, v116
	v_lshlrev_b32_e32 v152, 1, v112
	v_or_b32_e32 v118, 16, v114
	v_lshlrev_b64 v[116:117], 16, v[116:117]
	v_lshl_add_u64 v[112:113], s[38:39], 0, v[152:153]
	v_and_b32_e32 v152, 24, v115
	v_ashrrev_i32_e32 v119, 31, v118
	v_lshl_or_b32 v115, s12, 14, v116
	s_waitcnt vmcnt(4)
	v_lshl_add_u64 v[120:121], v[118:119], 2, s[14:15]
	v_lshl_add_u64 v[112:113], v[112:113], 0, v[152:153]
	s_waitcnt vmcnt(0)
	v_fmamk_f32 v116, v122, 0x3a800000, v166
	v_mul_f32_e32 v119, 0x4b800000, v116
	v_cmp_gt_f32_e32 vcc, s40, v116
	s_nop 1
	v_cndmask_b32_e32 v116, v116, v119, vcc
	v_rsq_f32_e32 v119, v116
	v_and_or_b32 v116, v114, s41, v115
	v_lshlrev_b64 v[122:123], 8, v[116:117]
	v_lshl_add_u64 v[122:123], v[112:113], 0, v[122:123]
	v_mul_f32_e32 v116, 0x45800000, v119
	v_cndmask_b32_e32 v116, v119, v116, vcc
	v_mul_f32_e32 v124, v149, v116
	v_mul_f32_e32 v125, v150, v116
	v_mul_f32_e32 v119, v148, v116
	v_mul_f32_e32 v126, v151, v116
	v_mul_f32_e32 v127, v144, v116
	v_mul_f32_e32 v128, v145, v116
	v_mul_f32_e32 v129, v146, v116
	v_mul_f32_e32 v130, v147, v116
	v_mul_f32_e32 v131, v140, v116
	v_cvt_pk_bf16_f32 v124, v119, v124
	v_cvt_pk_bf16_f32 v125, v125, v126
	v_mul_f32_e32 v132, v141, v116
	v_mul_f32_e32 v133, v142, v116
	v_mul_f32_e32 v134, v143, v116
	v_mul_f32_e32 v135, v136, v116
	v_mul_f32_e32 v136, v137, v116
	v_mul_f32_e32 v137, v138, v116
	v_mul_f32_e32 v116, v139, v116
	v_cvt_pk_bf16_f32 v126, v127, v128
	v_cvt_pk_bf16_f32 v127, v129, v130
	v_cvt_pk_bf16_f32 v128, v131, v132
	v_cvt_pk_bf16_f32 v129, v133, v134
	v_cvt_pk_bf16_f32 v130, v135, v136
	v_cvt_pk_bf16_f32 v131, v137, v116
	global_store_dwordx2 v[122:123], v[124:125], off
	global_store_dwordx2 v[122:123], v[126:127], off offset:32
	global_store_dwordx2 v[122:123], v[128:129], off offset:64
	global_store_dwordx2 v[122:123], v[130:131], off offset:96
	global_load_dword v116, v[120:121], off
	v_or_b32_e32 v120, 32, v114
	v_ashrrev_i32_e32 v121, 31, v120
	v_lshl_add_u64 v[122:123], v[120:121], 2, s[14:15]
	s_waitcnt vmcnt(0)
	v_fmamk_f32 v116, v116, 0x3a800000, v166
	v_mul_f32_e32 v119, 0x4b800000, v116
	v_cmp_gt_f32_e32 vcc, s40, v116
	s_nop 1
	v_cndmask_b32_e32 v116, v116, v119, vcc
	v_rsq_f32_e32 v121, v116
	v_and_or_b32 v116, v118, s42, v115
	v_lshlrev_b64 v[118:119], 8, v[116:117]
	v_lshl_add_u64 v[118:119], v[112:113], 0, v[118:119]
	v_mul_f32_e32 v116, 0x45800000, v121
	v_cndmask_b32_e32 v116, v121, v116, vcc
	v_mul_f32_e32 v108, v108, v116
	v_mul_f32_e32 v109, v109, v116
	v_mul_f32_e32 v110, v110, v116
	v_mul_f32_e32 v111, v111, v116
	v_mul_f32_e32 v100, v100, v116
	v_mul_f32_e32 v101, v101, v116
	v_mul_f32_e32 v102, v102, v116
	v_mul_f32_e32 v103, v103, v116
	v_mul_f32_e32 v121, v96, v116
	v_mul_f32_e32 v124, v97, v116
	v_cvt_pk_bf16_f32 v96, v108, v109
	v_cvt_pk_bf16_f32 v97, v110, v111
	v_mul_f32_e32 v104, v104, v116
	v_mul_f32_e32 v105, v105, v116
	v_mul_f32_e32 v106, v106, v116
	v_mul_f32_e32 v107, v107, v116
	v_mul_f32_e32 v125, v98, v116
	v_mul_f32_e32 v116, v99, v116
	v_cvt_pk_bf16_f32 v98, v104, v105
	v_cvt_pk_bf16_f32 v99, v106, v107
	v_cvt_pk_bf16_f32 v100, v100, v101
	v_cvt_pk_bf16_f32 v101, v102, v103
	v_cvt_pk_bf16_f32 v102, v121, v124
	v_cvt_pk_bf16_f32 v103, v125, v116
	global_store_dwordx2 v[118:119], v[96:97], off
	global_store_dwordx2 v[118:119], v[98:99], off offset:32
	global_store_dwordx2 v[118:119], v[100:101], off offset:64
	global_store_dwordx2 v[118:119], v[102:103], off offset:96
	global_load_dword v100, v[122:123], off
	v_or_b32_e32 v96, 48, v114
	v_ashrrev_i32_e32 v97, 31, v96
	v_lshl_add_u64 v[98:99], v[96:97], 2, s[14:15]
	v_and_or_b32 v116, v120, s43, v115
	s_waitcnt vmcnt(0)
	v_fmamk_f32 v97, v100, 0x3a800000, v166
	v_mul_f32_e32 v100, 0x4b800000, v97
	v_cmp_gt_f32_e32 vcc, s40, v97
	s_nop 1
	v_cndmask_b32_e32 v97, v97, v100, vcc
	v_rsq_f32_e32 v97, v97
	v_lshlrev_b64 v[100:101], 8, v[116:117]
	v_lshl_add_u64 v[100:101], v[112:113], 0, v[100:101]
	v_and_or_b32 v116, v96, s44, v115
	v_mul_f32_e32 v102, 0x45800000, v97
	v_cndmask_b32_e32 v97, v97, v102, vcc
	v_mul_f32_e32 v92, v92, v97
	v_mul_f32_e32 v93, v93, v97
	v_mul_f32_e32 v94, v94, v97
	v_mul_f32_e32 v95, v95, v97
	v_mul_f32_e32 v84, v84, v97
	v_mul_f32_e32 v85, v85, v97
	v_mul_f32_e32 v86, v86, v97
	v_mul_f32_e32 v87, v87, v97
	v_mul_f32_e32 v102, v80, v97
	v_mul_f32_e32 v103, v81, v97
	v_cvt_pk_bf16_f32 v80, v92, v93
	v_cvt_pk_bf16_f32 v81, v94, v95
	v_mul_f32_e32 v88, v88, v97
	v_mul_f32_e32 v89, v89, v97
	v_mul_f32_e32 v90, v90, v97
	v_mul_f32_e32 v91, v91, v97
	v_mul_f32_e32 v104, v82, v97
	v_mul_f32_e32 v97, v83, v97
	v_cvt_pk_bf16_f32 v82, v88, v89
	v_cvt_pk_bf16_f32 v83, v90, v91
	v_cvt_pk_bf16_f32 v84, v84, v85
	v_cvt_pk_bf16_f32 v85, v86, v87
	v_cvt_pk_bf16_f32 v86, v102, v103
	v_cvt_pk_bf16_f32 v87, v104, v97
	global_store_dwordx2 v[100:101], v[80:81], off
	global_store_dwordx2 v[100:101], v[82:83], off offset:32
	global_store_dwordx2 v[100:101], v[84:85], off offset:64
	global_store_dwordx2 v[100:101], v[86:87], off offset:96
	global_load_dword v84, v[98:99], off
	v_or_b32_e32 v80, 64, v114
	v_ashrrev_i32_e32 v81, 31, v80
	v_lshl_add_u64 v[82:83], v[80:81], 2, s[14:15]
	s_waitcnt vmcnt(0)
	v_fmamk_f32 v81, v84, 0x3a800000, v166
	v_mul_f32_e32 v84, 0x4b800000, v81
	v_cmp_gt_f32_e32 vcc, s40, v81
	s_nop 1
	v_cndmask_b32_e32 v81, v81, v84, vcc
	v_rsq_f32_e32 v81, v81
	v_lshlrev_b64 v[84:85], 8, v[116:117]
	v_lshl_add_u64 v[84:85], v[112:113], 0, v[84:85]
	v_and_or_b32 v116, v80, s45, v115
	v_mul_f32_e32 v86, 0x45800000, v81
	v_cndmask_b32_e32 v81, v81, v86, vcc
	v_mul_f32_e32 v76, v76, v81
	v_mul_f32_e32 v77, v77, v81
	v_mul_f32_e32 v78, v78, v81
	v_mul_f32_e32 v79, v79, v81
	v_mul_f32_e32 v68, v68, v81
	v_mul_f32_e32 v69, v69, v81
	v_mul_f32_e32 v70, v70, v81
	v_mul_f32_e32 v71, v71, v81
	v_mul_f32_e32 v86, v64, v81
	v_mul_f32_e32 v87, v65, v81
	v_cvt_pk_bf16_f32 v64, v76, v77
	v_cvt_pk_bf16_f32 v65, v78, v79
	v_mul_f32_e32 v72, v72, v81
	v_mul_f32_e32 v73, v73, v81
	v_mul_f32_e32 v74, v74, v81
	v_mul_f32_e32 v75, v75, v81
	v_mul_f32_e32 v88, v66, v81
	v_mul_f32_e32 v81, v67, v81
	v_cvt_pk_bf16_f32 v66, v72, v73
	v_cvt_pk_bf16_f32 v67, v74, v75
	v_cvt_pk_bf16_f32 v68, v68, v69
	v_cvt_pk_bf16_f32 v69, v70, v71
	v_cvt_pk_bf16_f32 v70, v86, v87
	v_cvt_pk_bf16_f32 v71, v88, v81
	global_store_dwordx2 v[84:85], v[64:65], off
	global_store_dwordx2 v[84:85], v[66:67], off offset:32
	global_store_dwordx2 v[84:85], v[68:69], off offset:64
	global_store_dwordx2 v[84:85], v[70:71], off offset:96
	global_load_dword v68, v[82:83], off
	v_or_b32_e32 v64, 0x50, v114
	v_ashrrev_i32_e32 v65, 31, v64
	v_lshl_add_u64 v[66:67], v[64:65], 2, s[14:15]
	s_waitcnt vmcnt(0)
	v_fmamk_f32 v65, v68, 0x3a800000, v166
	v_mul_f32_e32 v68, 0x4b800000, v65
	v_cmp_gt_f32_e32 vcc, s40, v65
	s_nop 1
	v_cndmask_b32_e32 v65, v65, v68, vcc
	v_rsq_f32_e32 v65, v65
	v_lshlrev_b64 v[68:69], 8, v[116:117]
	v_lshl_add_u64 v[68:69], v[112:113], 0, v[68:69]
	v_and_or_b32 v116, v64, s46, v115
	v_mul_f32_e32 v70, 0x45800000, v65
	v_cndmask_b32_e32 v65, v65, v70, vcc
	v_mul_f32_e32 v60, v60, v65
	v_mul_f32_e32 v61, v61, v65
	v_mul_f32_e32 v62, v62, v65
	v_mul_f32_e32 v63, v63, v65
	v_mul_f32_e32 v52, v52, v65
	v_mul_f32_e32 v53, v53, v65
	v_mul_f32_e32 v54, v54, v65
	v_mul_f32_e32 v55, v55, v65
	v_mul_f32_e32 v70, v48, v65
	v_mul_f32_e32 v71, v49, v65
	v_cvt_pk_bf16_f32 v48, v60, v61
	v_cvt_pk_bf16_f32 v49, v62, v63
	v_mul_f32_e32 v56, v56, v65
	v_mul_f32_e32 v57, v57, v65
	v_mul_f32_e32 v58, v58, v65
	v_mul_f32_e32 v59, v59, v65
	v_mul_f32_e32 v72, v50, v65
	v_mul_f32_e32 v65, v51, v65
	v_cvt_pk_bf16_f32 v50, v56, v57
	v_cvt_pk_bf16_f32 v51, v58, v59
	v_cvt_pk_bf16_f32 v52, v52, v53
	v_cvt_pk_bf16_f32 v53, v54, v55
	v_cvt_pk_bf16_f32 v54, v70, v71
	v_cvt_pk_bf16_f32 v55, v72, v65
	global_store_dwordx2 v[68:69], v[48:49], off
	global_store_dwordx2 v[68:69], v[50:51], off offset:32
	global_store_dwordx2 v[68:69], v[52:53], off offset:64
	global_store_dwordx2 v[68:69], v[54:55], off offset:96
	global_load_dword v52, v[66:67], off
	v_or_b32_e32 v48, 0x60, v114
	v_ashrrev_i32_e32 v49, 31, v48
	v_lshl_add_u64 v[50:51], v[48:49], 2, s[14:15]
	s_waitcnt vmcnt(0)
	v_fmamk_f32 v49, v52, 0x3a800000, v166
	v_mul_f32_e32 v52, 0x4b800000, v49
	v_cmp_gt_f32_e32 vcc, s40, v49
	s_nop 1
	v_cndmask_b32_e32 v49, v49, v52, vcc
	v_rsq_f32_e32 v49, v49
	v_lshlrev_b64 v[52:53], 8, v[116:117]
	v_lshl_add_u64 v[52:53], v[112:113], 0, v[52:53]
	v_and_or_b32 v116, v48, s47, v115
	v_mul_f32_e32 v54, 0x45800000, v49
	v_cndmask_b32_e32 v49, v49, v54, vcc
	v_mul_f32_e32 v44, v44, v49
	v_mul_f32_e32 v45, v45, v49
	v_mul_f32_e32 v46, v46, v49
	v_mul_f32_e32 v47, v47, v49
	v_mul_f32_e32 v36, v36, v49
	v_mul_f32_e32 v37, v37, v49
	v_mul_f32_e32 v38, v38, v49
	v_mul_f32_e32 v39, v39, v49
	v_mul_f32_e32 v54, v32, v49
	v_mul_f32_e32 v55, v33, v49
	v_cvt_pk_bf16_f32 v32, v44, v45
	v_cvt_pk_bf16_f32 v33, v46, v47
	v_mul_f32_e32 v40, v40, v49
	v_mul_f32_e32 v41, v41, v49
	v_mul_f32_e32 v42, v42, v49
	v_mul_f32_e32 v43, v43, v49
	v_mul_f32_e32 v56, v34, v49
	v_mul_f32_e32 v49, v35, v49
	v_cvt_pk_bf16_f32 v34, v40, v41
	v_cvt_pk_bf16_f32 v35, v42, v43
	v_cvt_pk_bf16_f32 v36, v36, v37
	v_cvt_pk_bf16_f32 v37, v38, v39
	v_cvt_pk_bf16_f32 v38, v54, v55
	v_cvt_pk_bf16_f32 v39, v56, v49
	global_store_dwordx2 v[52:53], v[32:33], off
	global_store_dwordx2 v[52:53], v[34:35], off offset:32
	global_store_dwordx2 v[52:53], v[36:37], off offset:64
	global_store_dwordx2 v[52:53], v[38:39], off offset:96
	global_load_dword v36, v[50:51], off
	v_or_b32_e32 v32, 0x70, v114
	v_ashrrev_i32_e32 v33, 31, v32
	v_lshl_add_u64 v[34:35], v[32:33], 2, s[14:15]
	s_waitcnt vmcnt(0)
	v_fmamk_f32 v33, v36, 0x3a800000, v166
	v_mul_f32_e32 v36, 0x4b800000, v33
	v_cmp_gt_f32_e32 vcc, s40, v33
	s_nop 1
	v_cndmask_b32_e32 v33, v33, v36, vcc
	v_rsq_f32_e32 v33, v33
	v_lshlrev_b64 v[36:37], 8, v[116:117]
	v_lshl_add_u64 v[36:37], v[112:113], 0, v[36:37]
	v_and_or_b32 v116, v32, s48, v115
	v_mul_f32_e32 v38, 0x45800000, v33
	v_cndmask_b32_e32 v33, v33, v38, vcc
	v_mul_f32_e32 v28, v28, v33
	v_mul_f32_e32 v29, v29, v33
	v_mul_f32_e32 v30, v30, v33
	v_mul_f32_e32 v31, v31, v33
	v_mul_f32_e32 v20, v20, v33
	v_mul_f32_e32 v21, v21, v33
	v_mul_f32_e32 v22, v22, v33
	v_mul_f32_e32 v23, v23, v33
	v_mul_f32_e32 v38, v16, v33
	v_mul_f32_e32 v39, v17, v33
	v_cvt_pk_bf16_f32 v16, v28, v29
	v_cvt_pk_bf16_f32 v17, v30, v31
	v_mul_f32_e32 v24, v24, v33
	v_mul_f32_e32 v25, v25, v33
	v_mul_f32_e32 v26, v26, v33
	v_mul_f32_e32 v27, v27, v33
	v_mul_f32_e32 v40, v18, v33
	v_mul_f32_e32 v33, v19, v33
	v_cvt_pk_bf16_f32 v18, v24, v25
	v_cvt_pk_bf16_f32 v19, v26, v27
	v_cvt_pk_bf16_f32 v20, v20, v21
	v_cvt_pk_bf16_f32 v21, v22, v23
	v_cvt_pk_bf16_f32 v22, v38, v39
	v_cvt_pk_bf16_f32 v23, v40, v33
	global_store_dwordx2 v[36:37], v[16:17], off
	global_store_dwordx2 v[36:37], v[18:19], off offset:32
	global_store_dwordx2 v[36:37], v[20:21], off offset:64
	global_store_dwordx2 v[36:37], v[22:23], off offset:96
	global_load_dword v16, v[34:35], off
	s_waitcnt vmcnt(0)
	v_fmamk_f32 v16, v16, 0x3a800000, v166
	v_mul_f32_e32 v17, 0x4b800000, v16
	v_cmp_gt_f32_e32 vcc, s40, v16
	s_nop 1
	v_cndmask_b32_e32 v16, v16, v17, vcc
	v_rsq_f32_e32 v18, v16
	v_lshlrev_b64 v[16:17], 8, v[116:117]
	v_lshl_add_u64 v[16:17], v[112:113], 0, v[16:17]
	v_mul_f32_e32 v19, 0x45800000, v18
	v_cndmask_b32_e32 v18, v18, v19, vcc
	v_mul_f32_e32 v12, v12, v18
	v_mul_f32_e32 v13, v13, v18
	v_mul_f32_e32 v14, v14, v18
	v_mul_f32_e32 v15, v15, v18
	v_mul_f32_e32 v4, v4, v18
	v_mul_f32_e32 v5, v5, v18
	v_mul_f32_e32 v6, v6, v18
	v_mul_f32_e32 v7, v7, v18
	v_mul_f32_e32 v19, v0, v18
	v_mul_f32_e32 v20, v1, v18
	v_cvt_pk_bf16_f32 v0, v12, v13
	v_cvt_pk_bf16_f32 v1, v14, v15
	v_mul_f32_e32 v8, v8, v18
	v_mul_f32_e32 v9, v9, v18
	v_mul_f32_e32 v10, v10, v18
	v_mul_f32_e32 v11, v11, v18
	v_mul_f32_e32 v21, v2, v18
	v_mul_f32_e32 v18, v3, v18
	v_cvt_pk_bf16_f32 v2, v8, v9
	v_cvt_pk_bf16_f32 v3, v10, v11
	v_cvt_pk_bf16_f32 v4, v4, v5
	v_cvt_pk_bf16_f32 v5, v6, v7
	v_cvt_pk_bf16_f32 v6, v19, v20
	v_cvt_pk_bf16_f32 v7, v21, v18
	global_store_dwordx2 v[16:17], v[0:1], off
	global_store_dwordx2 v[16:17], v[2:3], off offset:32
	global_store_dwordx2 v[16:17], v[4:5], off offset:64
	global_store_dwordx2 v[16:17], v[6:7], off offset:96
	s_branch .LBB0_699
.LBB0_708:
	s_and_b64 vcc, exec, s[10:11]
	s_cbranch_vccz .LBB0_699
	s_ashr_i32 s1, s0, 31
	s_lshl_b64 s[10:11], s[0:1], 11
	s_add_u32 s10, s5, s10
	v_mov_b32_e32 v7, v220
	s_addc_u32 s11, s6, s11
	s_lshl_b32 s1, s52, 18
	s_add_u32 s26, s7, s1
	v_ashrrev_i32_e32 v32, 2, v7
	v_ashrrev_i32_e32 v33, 31, v32
	s_addc_u32 s27, s8, 0
	v_lshlrev_b64 v[0:1], 11, v[32:33]
	v_lshlrev_b32_e32 v4, 4, v7
	v_lshl_add_u64 v[2:3], s[26:27], 0, v[0:1]
	v_lshl_add_u64 v[0:1], s[10:11], 0, v[0:1]
	v_and_b32_e32 v152, 48, v4
	v_lshl_add_u64 v[154:155], v[0:1], 0, v[152:153]
	v_add_co_u32_e32 v34, vcc, s9, v154
	v_lshl_add_u64 v[156:157], v[2:3], 0, v[152:153]
	s_nop 0
	v_addc_co_u32_e32 v35, vcc, 0, v155, vcc
	v_add_co_u32_e32 v36, vcc, s31, v154
	global_load_dwordx4 v[8:11], v[154:155], off
	s_nop 0
	v_addc_co_u32_e32 v37, vcc, 0, v155, vcc
	v_add_co_u32_e32 v38, vcc, s35, v154
	global_load_dwordx4 v[12:15], v[34:35], off
	s_nop 0
	v_addc_co_u32_e32 v39, vcc, 0, v155, vcc
	v_add_co_u32_e32 v40, vcc, s9, v156
	global_load_dwordx4 v[16:19], v[36:37], off
	s_nop 0
	v_addc_co_u32_e32 v41, vcc, 0, v157, vcc
	global_load_dwordx4 v[20:23], v[38:39], off
	global_load_dwordx4 v[24:27], v[156:157], off
	global_load_dwordx4 v[28:31], v[40:41], off
	global_load_dwordx4 v[112:115], v[154:155], off offset:64
	global_load_dwordx4 v[120:123], v[34:35], off offset:64
	global_load_dwordx4 v[124:127], v[36:37], off offset:64
	global_load_dwordx4 v[132:135], v[38:39], off offset:64
	global_load_dwordx4 v[116:119], v[156:157], off offset:64
	global_load_dwordx4 v[136:139], v[40:41], off offset:64
	v_lshrrev_b32_e32 v33, 4, v7
	v_lshrrev_b32_e32 v42, 2, v7
	v_sub_u32_e32 v45, 0, v33
	v_sub_u32_e32 v42, 0, v42
	v_and_b32_e32 v43, 0x3ffff8f, v7
	v_lshlrev_b32_e32 v44, 6, v7
	v_xor_b32_e32 v7, v7, v45
	v_xor_b32_e32 v33, v33, v42
	v_lshlrev_b32_e32 v7, 4, v7
	v_lshlrev_b32_e32 v33, 4, v33
	v_and_b32_e32 v46, 0x1000, v44
	v_and_b32_e32 v7, 48, v7
	v_and_b32_e32 v33, 48, v33
	v_mov_b32_e32 v0, 0
	v_and_b32_e32 v47, 0x3c0, v44
	v_and_b32_e32 v44, 0xffffe3c0, v44
	v_lshl_add_u32 v43, v43, 6, v167
	v_lshl_or_b32 v152, v32, 6, v7
	v_or_b32_e32 v7, v33, v46
	s_mov_b32 s10, 0
	s_mov_b32 s1, -2
	v_mov_b32_e32 v1, v0
	v_mov_b32_e32 v2, v0
	v_mov_b32_e32 v3, v0
	v_mov_b32_e32 v4, v0
	v_mov_b32_e32 v5, v0
	v_mov_b32_e32 v6, v0
	v_lshl_add_u64 v[158:159], v[154:155], 0, s[22:23]
	v_lshl_add_u64 v[160:161], v[154:155], 0, s[24:25]
	v_lshl_add_u64 v[162:163], v[154:155], 0, s[28:29]
	v_or3_b32 v168, v46, v47, v33
	v_add_u32_e32 v169, v33, v44
	v_add_u32_e32 v170, v33, v43
	v_lshl_add_u64 v[164:165], v[156:157], 0, s[22:23]
	v_add_u32_e32 v171, v7, v47
	v_mov_b32_e32 v7, v0
	v_mov_b32_e32 v32, v0
	v_mov_b32_e32 v33, v0
	v_mov_b32_e32 v34, v0
	v_mov_b32_e32 v35, v0
	v_mov_b32_e32 v36, v0
	v_mov_b32_e32 v37, v0
	v_mov_b32_e32 v38, v0
	v_mov_b32_e32 v39, v0
	v_mov_b32_e32 v40, v0
	v_mov_b32_e32 v41, v0
	v_mov_b32_e32 v42, v0
	v_mov_b32_e32 v43, v0
	v_mov_b32_e32 v44, v0
	v_mov_b32_e32 v45, v0
	v_mov_b32_e32 v46, v0
	v_mov_b32_e32 v47, v0
	s_waitcnt vmcnt(11)
	ds_write_b128 v152, v[8:11]
	s_waitcnt vmcnt(10)
	ds_write_b128 v152, v[12:15] offset:4096
	s_waitcnt vmcnt(9)
	ds_write_b128 v152, v[16:19] offset:8192
	s_waitcnt vmcnt(8)
	ds_write_b128 v152, v[20:23] offset:12288
	s_waitcnt vmcnt(7)
	ds_write_b128 v152, v[24:27] offset:32768
	s_waitcnt vmcnt(6)
	ds_write_b128 v152, v[28:31] offset:36864
	v_mov_b32_e32 v8, v0
	v_mov_b32_e32 v9, v0
	v_mov_b32_e32 v10, v0
	v_mov_b32_e32 v11, v0
	v_mov_b32_e32 v12, v0
	v_mov_b32_e32 v13, v0
	v_mov_b32_e32 v14, v0
	v_mov_b32_e32 v15, v0
	v_mov_b32_e32 v16, v0
	v_mov_b32_e32 v17, v0
	v_mov_b32_e32 v18, v0
	v_mov_b32_e32 v19, v0
	v_mov_b32_e32 v20, v0
	v_mov_b32_e32 v21, v0
	v_mov_b32_e32 v22, v0
	v_mov_b32_e32 v23, v0
	v_mov_b32_e32 v24, v0
	v_mov_b32_e32 v25, v0
	v_mov_b32_e32 v26, v0
	v_mov_b32_e32 v27, v0
	v_mov_b32_e32 v28, v0
	v_mov_b32_e32 v29, v0
	v_mov_b32_e32 v30, v0
	v_mov_b32_e32 v31, v0
	v_mov_b32_e32 v48, v0
	v_mov_b32_e32 v49, v0
	v_mov_b32_e32 v50, v0
	v_mov_b32_e32 v51, v0
	v_mov_b32_e32 v52, v0
	v_mov_b32_e32 v53, v0
	v_mov_b32_e32 v54, v0
	v_mov_b32_e32 v55, v0
	v_mov_b32_e32 v56, v0
	v_mov_b32_e32 v57, v0
	v_mov_b32_e32 v58, v0
	v_mov_b32_e32 v59, v0
	v_mov_b32_e32 v60, v0
	v_mov_b32_e32 v61, v0
	v_mov_b32_e32 v62, v0
	v_mov_b32_e32 v63, v0
	v_mov_b32_e32 v64, v0
	v_mov_b32_e32 v65, v0
	v_mov_b32_e32 v66, v0
	v_mov_b32_e32 v67, v0
	v_mov_b32_e32 v68, v0
	v_mov_b32_e32 v69, v0
	v_mov_b32_e32 v70, v0
	v_mov_b32_e32 v71, v0
	v_mov_b32_e32 v72, v0
	v_mov_b32_e32 v73, v0
	v_mov_b32_e32 v74, v0
	v_mov_b32_e32 v75, v0
	v_mov_b32_e32 v76, v0
	v_mov_b32_e32 v77, v0
	v_mov_b32_e32 v78, v0
	v_mov_b32_e32 v79, v0
	v_mov_b32_e32 v80, v0
	v_mov_b32_e32 v81, v0
	v_mov_b32_e32 v82, v0
	v_mov_b32_e32 v83, v0
	v_mov_b32_e32 v84, v0
	v_mov_b32_e32 v85, v0
	v_mov_b32_e32 v86, v0
	v_mov_b32_e32 v87, v0
	v_mov_b32_e32 v88, v0
	v_mov_b32_e32 v89, v0
	v_mov_b32_e32 v90, v0
	v_mov_b32_e32 v91, v0
	v_mov_b32_e32 v92, v0
	v_mov_b32_e32 v93, v0
	v_mov_b32_e32 v94, v0
	v_mov_b32_e32 v95, v0
	v_mov_b32_e32 v96, v0
	v_mov_b32_e32 v97, v0
	v_mov_b32_e32 v98, v0
	v_mov_b32_e32 v99, v0
	v_mov_b32_e32 v100, v0
	v_mov_b32_e32 v101, v0
	v_mov_b32_e32 v102, v0
	v_mov_b32_e32 v103, v0
	v_mov_b32_e32 v104, v0
	v_mov_b32_e32 v105, v0
	v_mov_b32_e32 v106, v0
	v_mov_b32_e32 v107, v0
	v_mov_b32_e32 v108, v0
	v_mov_b32_e32 v109, v0
	v_mov_b32_e32 v110, v0
	v_mov_b32_e32 v111, v0
	v_mov_b32_e32 v128, v0
	v_mov_b32_e32 v129, v0
	v_mov_b32_e32 v130, v0
	v_mov_b32_e32 v131, v0
	v_mov_b32_e32 v140, v0
	v_mov_b32_e32 v141, v0
	v_mov_b32_e32 v142, v0
	v_mov_b32_e32 v143, v0
	v_mov_b32_e32 v144, v0
	v_mov_b32_e32 v145, v0
	v_mov_b32_e32 v146, v0
	v_mov_b32_e32 v147, v0
	v_mov_b32_e32 v148, v0
	v_mov_b32_e32 v149, v0
	v_mov_b32_e32 v150, v0
	v_mov_b32_e32 v151, v0
	s_waitcnt lgkmcnt(0)
	s_barrier
	s_cmpk_lt_u32 s2, 0x100
	s_cbranch_scc1 .Lstag_5
	s_sleep 8
.Lstag_5:
.LBB0_710:
	s_add_i32 s11, s10, 64
	s_min_u32 s13, s11, 0x3e0
	s_lshl_b32 s16, s13, 1
	v_lshl_add_u64 v[172:173], v[154:155], 0, s[16:17]
	v_lshl_add_u64 v[176:177], v[158:159], 0, s[16:17]
	v_lshl_add_u64 v[180:181], v[160:161], 0, s[16:17]
	v_lshl_add_u64 v[184:185], v[162:163], 0, s[16:17]
	v_lshl_add_u64 v[188:189], v[156:157], 0, s[16:17]
	v_lshl_add_u64 v[192:193], v[164:165], 0, s[16:17]
	global_load_dwordx4 v[172:175], v[172:173], off
	ds_read_b128 v[196:199], v171 offset:32768
	global_load_dwordx4 v[176:179], v[176:177], off
	ds_read_b128 v[200:203], v171 offset:33792
	global_load_dwordx4 v[180:183], v[180:181], off
	ds_read_b128 v[204:207], v171 offset:34816
	global_load_dwordx4 v[184:187], v[184:185], off
	ds_read_b128 v[208:211], v171 offset:35840
	global_load_dwordx4 v[188:191], v[188:189], off
	ds_read_b128 v[212:215], v169
	global_load_dwordx4 v[192:195], v[192:193], off
	ds_read_b128 v[216:219], v169 offset:1024
	ds_read_b128 v[222:225], v169 offset:2048
	ds_read_b128 v[226:229], v169 offset:3072
	ds_read_b128 v[230:233], v169 offset:4096
	ds_read_b128 v[234:237], v169 offset:5120
	ds_read_b128 v[238:241], v169 offset:6144
	ds_read_b128 v[242:245], v169 offset:7168
	s_setprio 1
	s_waitcnt lgkmcnt(7)
	v_mfma_f32_16x16x32_bf16 v[148:151], v[212:215], v[196:199], v[148:151]
	v_mfma_f32_16x16x32_bf16 v[144:147], v[212:215], v[200:203], v[144:147]
	v_mfma_f32_16x16x32_bf16 v[140:143], v[212:215], v[204:207], v[140:143]
	v_mfma_f32_16x16x32_bf16 v[128:131], v[212:215], v[208:211], v[128:131]
	s_waitcnt vmcnt(11)
	ds_write_b128 v152, v[112:115] offset:16384
	s_waitcnt lgkmcnt(7)
	v_mfma_f32_16x16x32_bf16 v[108:111], v[216:219], v[196:199], v[108:111]
	v_mfma_f32_16x16x32_bf16 v[104:107], v[216:219], v[200:203], v[104:107]
	v_mfma_f32_16x16x32_bf16 v[100:103], v[216:219], v[204:207], v[100:103]
	v_mfma_f32_16x16x32_bf16 v[96:99], v[216:219], v[208:211], v[96:99]
	s_waitcnt vmcnt(9)
	ds_write_b128 v152, v[120:123] offset:20480
	s_waitcnt lgkmcnt(7)
	v_mfma_f32_16x16x32_bf16 v[92:95], v[222:225], v[196:199], v[92:95]
	v_mfma_f32_16x16x32_bf16 v[88:91], v[222:225], v[200:203], v[88:91]
	v_mfma_f32_16x16x32_bf16 v[84:87], v[222:225], v[204:207], v[84:87]
	v_mfma_f32_16x16x32_bf16 v[80:83], v[222:225], v[208:211], v[80:83]
	s_waitcnt vmcnt(8)
	ds_write_b128 v152, v[124:127] offset:24576
	s_waitcnt lgkmcnt(7)
	v_mfma_f32_16x16x32_bf16 v[76:79], v[226:229], v[196:199], v[76:79]
	v_mfma_f32_16x16x32_bf16 v[72:75], v[226:229], v[200:203], v[72:75]
	v_mfma_f32_16x16x32_bf16 v[68:71], v[226:229], v[204:207], v[68:71]
	v_mfma_f32_16x16x32_bf16 v[64:67], v[226:229], v[208:211], v[64:67]
	s_waitcnt vmcnt(7)
	ds_write_b128 v152, v[132:135] offset:28672
	s_waitcnt lgkmcnt(7)
	v_mfma_f32_16x16x32_bf16 v[60:63], v[230:233], v[196:199], v[60:63]
	v_mfma_f32_16x16x32_bf16 v[56:59], v[230:233], v[200:203], v[56:59]
	v_mfma_f32_16x16x32_bf16 v[52:55], v[230:233], v[204:207], v[52:55]
	v_mfma_f32_16x16x32_bf16 v[48:51], v[230:233], v[208:211], v[48:51]
	s_waitcnt vmcnt(7)
	ds_write_b128 v152, v[116:119] offset:40960
	s_waitcnt lgkmcnt(7)
	v_mfma_f32_16x16x32_bf16 v[44:47], v[234:237], v[196:199], v[44:47]
	v_mfma_f32_16x16x32_bf16 v[40:43], v[234:237], v[200:203], v[40:43]
	v_mfma_f32_16x16x32_bf16 v[36:39], v[234:237], v[204:207], v[36:39]
	v_mfma_f32_16x16x32_bf16 v[32:35], v[234:237], v[208:211], v[32:35]
	s_waitcnt vmcnt(6)
	ds_write_b128 v152, v[136:139] offset:45056
	s_waitcnt lgkmcnt(7)
	v_mfma_f32_16x16x32_bf16 v[28:31], v[238:241], v[196:199], v[28:31]
	v_mfma_f32_16x16x32_bf16 v[24:27], v[238:241], v[200:203], v[24:27]
	v_mfma_f32_16x16x32_bf16 v[20:23], v[238:241], v[204:207], v[20:23]
	v_mfma_f32_16x16x32_bf16 v[16:19], v[238:241], v[208:211], v[16:19]
	s_waitcnt lgkmcnt(6)
	v_mfma_f32_16x16x32_bf16 v[12:15], v[242:245], v[196:199], v[12:15]
	v_mfma_f32_16x16x32_bf16 v[8:11], v[242:245], v[200:203], v[8:11]
	v_mfma_f32_16x16x32_bf16 v[4:7], v[242:245], v[204:207], v[4:7]
	v_mfma_f32_16x16x32_bf16 v[0:3], v[242:245], v[208:211], v[0:3]
	s_setprio 0
	s_min_u32 s10, s10, 0x380
	s_lshl_b32 s16, s10, 1
	s_mov_b32 s27, s17
	s_add_i32 s26, s16, 0xc0
	v_lshl_add_u64 v[112:113], v[154:155], 0, s[16:17]
	v_lshl_add_u64 v[116:117], v[156:157], 0, s[16:17]
	v_lshl_add_u64 v[120:121], v[158:159], 0, s[26:27]
	v_lshl_add_u64 v[124:125], v[160:161], 0, s[26:27]
	v_lshl_add_u64 v[132:133], v[162:163], 0, s[26:27]
	v_lshl_add_u64 v[136:137], v[164:165], 0, s[26:27]
	s_waitcnt lgkmcnt(0)
	s_barrier
	global_load_dwordx4 v[112:115], v[112:113], off offset:192
	ds_read_b128 v[196:199], v168 offset:40960
	global_load_dwordx4 v[116:119], v[116:117], off offset:192
	ds_read_b128 v[200:203], v168 offset:41984
	global_load_dwordx4 v[120:123], v[120:121], off
	ds_read_b128 v[204:207], v168 offset:43008
	global_load_dwordx4 v[124:127], v[124:125], off
	ds_read_b128 v[208:211], v168 offset:44032
	global_load_dwordx4 v[132:135], v[132:133], off
	ds_read_b128 v[212:215], v170
	global_load_dwordx4 v[136:139], v[136:137], off
	ds_read_b128 v[216:219], v170 offset:1024
	ds_read_b128 v[222:225], v170 offset:2048
	ds_read_b128 v[226:229], v170 offset:3072
	ds_read_b128 v[230:233], v170 offset:4096
	ds_read_b128 v[234:237], v170 offset:5120
	ds_read_b128 v[238:241], v170 offset:6144
	ds_read_b128 v[242:245], v170 offset:7168
	s_setprio 1
	s_waitcnt lgkmcnt(7)
	v_mfma_f32_16x16x32_bf16 v[148:151], v[212:215], v[196:199], v[148:151]
	v_mfma_f32_16x16x32_bf16 v[144:147], v[212:215], v[200:203], v[144:147]
	v_mfma_f32_16x16x32_bf16 v[140:143], v[212:215], v[204:207], v[140:143]
	v_mfma_f32_16x16x32_bf16 v[128:131], v[212:215], v[208:211], v[128:131]
	s_waitcnt vmcnt(11)
	ds_write_b128 v152, v[172:175]
	s_waitcnt lgkmcnt(7)
	v_mfma_f32_16x16x32_bf16 v[108:111], v[216:219], v[196:199], v[108:111]
	v_mfma_f32_16x16x32_bf16 v[104:107], v[216:219], v[200:203], v[104:107]
	v_mfma_f32_16x16x32_bf16 v[100:103], v[216:219], v[204:207], v[100:103]
	v_mfma_f32_16x16x32_bf16 v[96:99], v[216:219], v[208:211], v[96:99]
	s_waitcnt vmcnt(10)
	ds_write_b128 v152, v[176:179] offset:4096
	s_waitcnt lgkmcnt(7)
	v_mfma_f32_16x16x32_bf16 v[92:95], v[222:225], v[196:199], v[92:95]
	v_mfma_f32_16x16x32_bf16 v[88:91], v[222:225], v[200:203], v[88:91]
	v_mfma_f32_16x16x32_bf16 v[84:87], v[222:225], v[204:207], v[84:87]
	v_mfma_f32_16x16x32_bf16 v[80:83], v[222:225], v[208:211], v[80:83]
	s_waitcnt vmcnt(9)
	ds_write_b128 v152, v[180:183] offset:8192
	s_waitcnt lgkmcnt(7)
	v_mfma_f32_16x16x32_bf16 v[76:79], v[226:229], v[196:199], v[76:79]
	v_mfma_f32_16x16x32_bf16 v[72:75], v[226:229], v[200:203], v[72:75]
	v_mfma_f32_16x16x32_bf16 v[68:71], v[226:229], v[204:207], v[68:71]
	v_mfma_f32_16x16x32_bf16 v[64:67], v[226:229], v[208:211], v[64:67]
	s_waitcnt vmcnt(8)
	ds_write_b128 v152, v[184:187] offset:12288
	s_waitcnt lgkmcnt(7)
	v_mfma_f32_16x16x32_bf16 v[60:63], v[230:233], v[196:199], v[60:63]
	v_mfma_f32_16x16x32_bf16 v[56:59], v[230:233], v[200:203], v[56:59]
	v_mfma_f32_16x16x32_bf16 v[52:55], v[230:233], v[204:207], v[52:55]
	v_mfma_f32_16x16x32_bf16 v[48:51], v[230:233], v[208:211], v[48:51]
	s_waitcnt vmcnt(7)
	ds_write_b128 v152, v[188:191] offset:32768
	s_waitcnt lgkmcnt(7)
	v_mfma_f32_16x16x32_bf16 v[44:47], v[234:237], v[196:199], v[44:47]
	v_mfma_f32_16x16x32_bf16 v[40:43], v[234:237], v[200:203], v[40:43]
	v_mfma_f32_16x16x32_bf16 v[36:39], v[234:237], v[204:207], v[36:39]
	v_mfma_f32_16x16x32_bf16 v[32:35], v[234:237], v[208:211], v[32:35]
	s_waitcnt vmcnt(6)
	ds_write_b128 v152, v[192:195] offset:36864
	s_waitcnt lgkmcnt(7)
	v_mfma_f32_16x16x32_bf16 v[28:31], v[238:241], v[196:199], v[28:31]
	v_mfma_f32_16x16x32_bf16 v[24:27], v[238:241], v[200:203], v[24:27]
	v_mfma_f32_16x16x32_bf16 v[20:23], v[238:241], v[204:207], v[20:23]
	v_mfma_f32_16x16x32_bf16 v[16:19], v[238:241], v[208:211], v[16:19]
	s_waitcnt lgkmcnt(6)
	v_mfma_f32_16x16x32_bf16 v[12:15], v[242:245], v[196:199], v[12:15]
	v_mfma_f32_16x16x32_bf16 v[8:11], v[242:245], v[200:203], v[8:11]
	v_mfma_f32_16x16x32_bf16 v[4:7], v[242:245], v[204:207], v[4:7]
	v_mfma_f32_16x16x32_bf16 v[0:3], v[242:245], v[208:211], v[0:3]
	s_setprio 0
	s_add_i32 s1, s1, 2
	s_cmp_lt_u32 s1, 30
	s_mov_b32 s10, s11
	s_waitcnt lgkmcnt(0)
	s_barrier
	s_cbranch_scc1 .LBB0_710
	s_waitcnt vmcnt(5)
	v_mov_b32_e32 v114, v220
	v_mov_b32_e32 v115, v153
	v_and_b32_e32 v112, 0xffffff80, v114
	s_waitcnt vmcnt(4)
	v_add_u32_e32 v116, s0, v112
	v_lshrrev_b32_e32 v112, 2, v114
	v_and_b32_e32 v118, 12, v112
	s_waitcnt vmcnt(3)
	v_or_b32_e32 v120, v118, v116
	v_ashrrev_i32_e32 v121, 31, v120
	v_lshl_add_u64 v[112:113], v[120:121], 2, s[14:15]
	global_load_dwordx4 v[132:135], v[112:113], off
	v_ashrrev_i32_e32 v122, 14, v116
	v_ashrrev_i32_e32 v123, 31, v122
	v_lshlrev_b64 v[122:123], 10, v[122:123]
	v_mov_b64_e32 v[112:113], s[34:35]
	s_waitcnt vmcnt(3)
	v_lshrrev_b32_e32 v126, 6, v116
	v_or_b32_e32 v124, 16, v120
	v_lshl_or_b32 v121, s12, 8, v122
	v_ashrrev_i32_e32 v125, 31, v124
	v_and_or_b32 v122, v126, s49, v121
	s_waitcnt vmcnt(1)
	v_lshl_add_u64 v[136:137], v[124:125], 2, s[14:15]
	v_lshlrev_b64 v[124:125], 14, v[122:123]
	v_lshlrev_b32_e32 v114, 7, v114
	v_lshlrev_b32_e32 v152, 1, v118
	v_lshl_add_u64 v[124:125], s[38:39], 0, v[124:125]
	v_and_b32_e32 v114, 0x2780, v114
	v_lshl_add_u64 v[126:127], v[124:125], 0, v[152:153]
	v_mov_b32_e32 v117, v153
	v_mov_b32_e32 v119, v153
	v_or_b32_e32 v116, 0x1000, v114
	v_or_b32_e32 v118, 0x1800, v114
	v_lshl_add_u64 v[124:125], v[126:127], 0, v[114:115]
	v_lshl_add_u64 v[138:139], v[126:127], 0, v[116:117]
	v_lshl_add_u64 v[154:155], v[126:127], 0, v[118:119]
	s_waitcnt vmcnt(0)
	v_pk_fma_f32 v[132:133], v[132:133], s[30:31], v[112:113] op_sel_hi:[1,0,0]
	v_pk_fma_f32 v[134:135], v[134:135], s[30:31], v[112:113] op_sel_hi:[1,0,0]
	v_mul_f32_e32 v122, 0x4b800000, v132
	v_mul_f32_e32 v156, 0x4b800000, v133
	v_mul_f32_e32 v157, 0x4b800000, v134
	v_mul_f32_e32 v158, 0x4b800000, v135
	v_cmp_gt_f32_e32 vcc, s40, v132
	v_cmp_gt_f32_e64 s[0:1], s40, v133
	v_cmp_gt_f32_e64 s[10:11], s40, v134
	v_cmp_gt_f32_e64 s[12:13], s40, v135
	v_cndmask_b32_e32 v122, v132, v122, vcc
	v_cndmask_b32_e64 v132, v133, v156, s[0:1]
	v_cndmask_b32_e64 v133, v134, v157, s[10:11]
	v_cndmask_b32_e64 v134, v135, v158, s[12:13]
	v_rsq_f32_e32 v122, v122
	v_rsq_f32_e32 v132, v132
	v_rsq_f32_e32 v133, v133
	v_rsq_f32_e32 v134, v134
	v_mul_f32_e32 v135, 0x45800000, v122
	v_mul_f32_e32 v156, 0x45800000, v132
	v_mul_f32_e32 v157, 0x45800000, v133
	v_mul_f32_e32 v158, 0x45800000, v134
	v_cndmask_b32_e32 v122, v122, v135, vcc
	v_cndmask_b32_e64 v132, v132, v156, s[0:1]
	v_cndmask_b32_e64 v133, v133, v157, s[10:11]
	v_cndmask_b32_e64 v134, v134, v158, s[12:13]
	v_mul_f32_e32 v135, v148, v122
	v_mul_f32_e32 v148, v149, v132
	v_mul_f32_e32 v149, v150, v133
	v_mul_f32_e32 v150, v151, v134
	v_mul_f32_e32 v144, v144, v122
	v_mul_f32_e32 v140, v140, v122
	v_mul_f32_e32 v122, v128, v122
	v_mul_f32_e32 v151, v129, v132
	v_cvt_pk_bf16_f32 v128, v135, v148
	v_cvt_pk_bf16_f32 v129, v149, v150
	v_mul_f32_e32 v145, v145, v132
	v_mul_f32_e32 v146, v146, v133
	v_mul_f32_e32 v147, v147, v134
	v_mul_f32_e32 v141, v141, v132
	v_mul_f32_e32 v142, v142, v133
	v_mul_f32_e32 v143, v143, v134
	v_mul_f32_e32 v156, v130, v133
	v_mul_f32_e32 v157, v131, v134
	v_cvt_pk_bf16_f32 v130, v144, v145
	v_cvt_pk_bf16_f32 v131, v146, v147
	v_cvt_pk_bf16_f32 v132, v140, v141
	v_cvt_pk_bf16_f32 v133, v142, v143
	v_cvt_pk_bf16_f32 v134, v122, v151
	v_cvt_pk_bf16_f32 v135, v156, v157
	global_store_dwordx2 v[124:125], v[128:129], off
	global_store_dwordx2 v[124:125], v[130:131], off offset:2048
	global_store_dwordx2 v[138:139], v[132:133], off
	global_store_dwordx2 v[154:155], v[134:135], off
	global_load_dwordx4 v[128:131], v[136:137], off
	v_or_b32_e32 v132, 32, v120
	v_ashrrev_i32_e32 v133, 31, v132
	v_lshl_add_u64 v[134:135], v[126:127], 0, 32
	v_lshl_add_u64 v[132:133], v[132:133], 2, s[14:15]
	v_lshl_add_u64 v[136:137], v[134:135], 0, v[116:117]
	v_lshl_add_u64 v[134:135], v[134:135], 0, v[118:119]
	s_waitcnt vmcnt(0)
	v_pk_fma_f32 v[128:129], v[128:129], s[30:31], v[112:113] op_sel_hi:[1,0,0]
	v_pk_fma_f32 v[130:131], v[130:131], s[30:31], v[112:113] op_sel_hi:[1,0,0]
	v_mul_f32_e32 v122, 0x4b800000, v128
	v_mul_f32_e32 v138, 0x4b800000, v129
	v_mul_f32_e32 v139, 0x4b800000, v130
	v_mul_f32_e32 v140, 0x4b800000, v131
	v_cmp_gt_f32_e32 vcc, s40, v128
	v_cmp_gt_f32_e64 s[0:1], s40, v129
	v_cmp_gt_f32_e64 s[10:11], s40, v130
	v_cmp_gt_f32_e64 s[12:13], s40, v131
	v_cndmask_b32_e32 v122, v128, v122, vcc
	v_cndmask_b32_e64 v128, v129, v138, s[0:1]
	v_cndmask_b32_e64 v129, v130, v139, s[10:11]
	v_cndmask_b32_e64 v130, v131, v140, s[12:13]
	v_rsq_f32_e32 v122, v122
	v_rsq_f32_e32 v128, v128
	v_rsq_f32_e32 v129, v129
	v_rsq_f32_e32 v130, v130
	v_mul_f32_e32 v131, 0x45800000, v122
	v_mul_f32_e32 v138, 0x45800000, v128
	v_mul_f32_e32 v139, 0x45800000, v129
	v_mul_f32_e32 v140, 0x45800000, v130
	v_cndmask_b32_e32 v122, v122, v131, vcc
	v_cndmask_b32_e64 v128, v128, v138, s[0:1]
	v_cndmask_b32_e64 v129, v129, v139, s[10:11]
	v_cndmask_b32_e64 v130, v130, v140, s[12:13]
	v_mul_f32_e32 v108, v108, v122
	v_mul_f32_e32 v109, v109, v128
	v_mul_f32_e32 v110, v110, v129
	v_mul_f32_e32 v111, v111, v130
	v_mul_f32_e32 v104, v104, v122
	v_mul_f32_e32 v105, v105, v128
	v_mul_f32_e32 v100, v100, v122
	v_mul_f32_e32 v101, v101, v128
	v_mul_f32_e32 v102, v102, v129
	v_mul_f32_e32 v103, v103, v130
	v_mul_f32_e32 v122, v96, v122
	v_mul_f32_e32 v128, v97, v128
	v_cvt_pk_bf16_f32 v96, v108, v109
	v_cvt_pk_bf16_f32 v97, v110, v111
	v_mul_f32_e32 v106, v106, v129
	v_mul_f32_e32 v107, v107, v130
	v_mul_f32_e32 v129, v98, v129
	v_mul_f32_e32 v130, v99, v130
	v_cvt_pk_bf16_f32 v98, v104, v105
	v_cvt_pk_bf16_f32 v99, v106, v107
	v_cvt_pk_bf16_f32 v100, v100, v101
	v_cvt_pk_bf16_f32 v101, v102, v103
	v_cvt_pk_bf16_f32 v102, v122, v128
	v_cvt_pk_bf16_f32 v103, v129, v130
	global_store_dwordx2 v[124:125], v[96:97], off offset:32
	global_store_dwordx2 v[124:125], v[98:99], off offset:2080
	global_store_dwordx2 v[136:137], v[100:101], off
	global_store_dwordx2 v[134:135], v[102:103], off
	global_load_dwordx4 v[96:99], v[132:133], off
	v_or_b32_e32 v100, 48, v120
	v_ashrrev_i32_e32 v101, 31, v100
	v_lshl_add_u64 v[102:103], v[126:127], 0, 64
	v_lshl_add_u64 v[100:101], v[100:101], 2, s[14:15]
	v_lshl_add_u64 v[104:105], v[102:103], 0, v[116:117]
	v_lshl_add_u64 v[102:103], v[102:103], 0, v[118:119]
	s_waitcnt vmcnt(0)
	v_pk_fma_f32 v[96:97], v[96:97], s[30:31], v[112:113] op_sel_hi:[1,0,0]
	v_pk_fma_f32 v[98:99], v[98:99], s[30:31], v[112:113] op_sel_hi:[1,0,0]
	v_mul_f32_e32 v106, 0x4b800000, v96
	v_mul_f32_e32 v107, 0x4b800000, v97
	v_mul_f32_e32 v108, 0x4b800000, v98
	v_mul_f32_e32 v109, 0x4b800000, v99
	v_cmp_gt_f32_e32 vcc, s40, v96
	v_cmp_gt_f32_e64 s[0:1], s40, v97
	v_cmp_gt_f32_e64 s[10:11], s40, v98
	v_cmp_gt_f32_e64 s[12:13], s40, v99
	v_cndmask_b32_e32 v96, v96, v106, vcc
	v_cndmask_b32_e64 v97, v97, v107, s[0:1]
	v_cndmask_b32_e64 v98, v98, v108, s[10:11]
	v_cndmask_b32_e64 v99, v99, v109, s[12:13]
	v_rsq_f32_e32 v96, v96
	v_rsq_f32_e32 v97, v97
	v_rsq_f32_e32 v98, v98
	v_rsq_f32_e32 v99, v99
	v_mul_f32_e32 v106, 0x45800000, v96
	v_mul_f32_e32 v107, 0x45800000, v97
	v_mul_f32_e32 v108, 0x45800000, v98
	v_mul_f32_e32 v109, 0x45800000, v99
	v_cndmask_b32_e32 v96, v96, v106, vcc
	v_cndmask_b32_e64 v97, v97, v107, s[0:1]
	v_cndmask_b32_e64 v98, v98, v108, s[10:11]
	v_cndmask_b32_e64 v99, v99, v109, s[12:13]
	v_mul_f32_e32 v92, v92, v96
	v_mul_f32_e32 v93, v93, v97
	v_mul_f32_e32 v94, v94, v98
	v_mul_f32_e32 v95, v95, v99
	v_mul_f32_e32 v88, v88, v96
	v_mul_f32_e32 v89, v89, v97
	v_mul_f32_e32 v84, v84, v96
	v_mul_f32_e32 v85, v85, v97
	v_mul_f32_e32 v86, v86, v98
	v_mul_f32_e32 v87, v87, v99
	v_mul_f32_e32 v96, v80, v96
	v_mul_f32_e32 v97, v81, v97
	v_cvt_pk_bf16_f32 v80, v92, v93
	v_cvt_pk_bf16_f32 v81, v94, v95
	v_mul_f32_e32 v90, v90, v98
	v_mul_f32_e32 v91, v91, v99
	v_mul_f32_e32 v98, v82, v98
	v_mul_f32_e32 v99, v83, v99
	v_cvt_pk_bf16_f32 v82, v88, v89
	v_cvt_pk_bf16_f32 v83, v90, v91
	v_cvt_pk_bf16_f32 v84, v84, v85
	v_cvt_pk_bf16_f32 v85, v86, v87
	v_cvt_pk_bf16_f32 v86, v96, v97
	v_cvt_pk_bf16_f32 v87, v98, v99
	global_store_dwordx2 v[124:125], v[80:81], off offset:64
	global_store_dwordx2 v[124:125], v[82:83], off offset:2112
	global_store_dwordx2 v[104:105], v[84:85], off
	global_store_dwordx2 v[102:103], v[86:87], off
	global_load_dwordx4 v[80:83], v[100:101], off
	v_or_b32_e32 v84, 64, v120
	v_ashrrev_i32_e32 v85, 31, v84
	v_lshl_add_u64 v[86:87], v[84:85], 2, s[14:15]
	v_lshl_add_u64 v[88:89], v[126:127], 0, s[36:37]
	v_lshl_add_u64 v[90:91], v[88:89], 0, v[116:117]
	v_lshl_add_u64 v[88:89], v[88:89], 0, v[118:119]
	s_waitcnt vmcnt(0)
	v_pk_fma_f32 v[80:81], v[80:81], s[30:31], v[112:113] op_sel_hi:[1,0,0]
	v_pk_fma_f32 v[82:83], v[82:83], s[30:31], v[112:113] op_sel_hi:[1,0,0]
	v_mul_f32_e32 v85, 0x4b800000, v80
	v_mul_f32_e32 v92, 0x4b800000, v81
	v_mul_f32_e32 v93, 0x4b800000, v82
	v_mul_f32_e32 v94, 0x4b800000, v83
	v_cmp_gt_f32_e32 vcc, s40, v80
	v_cmp_gt_f32_e64 s[0:1], s40, v81
	v_cmp_gt_f32_e64 s[10:11], s40, v82
	v_cmp_gt_f32_e64 s[12:13], s40, v83
	v_cndmask_b32_e32 v80, v80, v85, vcc
	v_cndmask_b32_e64 v81, v81, v92, s[0:1]
	v_cndmask_b32_e64 v82, v82, v93, s[10:11]
	v_cndmask_b32_e64 v83, v83, v94, s[12:13]
	v_rsq_f32_e32 v80, v80
	v_rsq_f32_e32 v81, v81
	v_rsq_f32_e32 v82, v82
	v_rsq_f32_e32 v83, v83
	v_mul_f32_e32 v85, 0x45800000, v80
	v_mul_f32_e32 v92, 0x45800000, v81
	v_mul_f32_e32 v93, 0x45800000, v82
	v_mul_f32_e32 v94, 0x45800000, v83
	v_cndmask_b32_e32 v80, v80, v85, vcc
	v_cndmask_b32_e64 v81, v81, v92, s[0:1]
	v_cndmask_b32_e64 v82, v82, v93, s[10:11]
	v_cndmask_b32_e64 v83, v83, v94, s[12:13]
	v_mul_f32_e32 v76, v76, v80
	v_mul_f32_e32 v77, v77, v81
	v_mul_f32_e32 v78, v78, v82
	v_mul_f32_e32 v79, v79, v83
	v_mul_f32_e32 v72, v72, v80
	v_mul_f32_e32 v73, v73, v81
	v_mul_f32_e32 v68, v68, v80
	v_mul_f32_e32 v69, v69, v81
	v_mul_f32_e32 v70, v70, v82
	v_mul_f32_e32 v71, v71, v83
	v_mul_f32_e32 v80, v64, v80
	v_mul_f32_e32 v81, v65, v81
	v_cvt_pk_bf16_f32 v64, v76, v77
	v_cvt_pk_bf16_f32 v65, v78, v79
	v_mul_f32_e32 v74, v74, v82
	v_mul_f32_e32 v75, v75, v83
	v_mul_f32_e32 v82, v66, v82
	v_mul_f32_e32 v83, v67, v83
	v_cvt_pk_bf16_f32 v66, v72, v73
	v_cvt_pk_bf16_f32 v67, v74, v75
	v_cvt_pk_bf16_f32 v68, v68, v69
	v_cvt_pk_bf16_f32 v69, v70, v71
	v_cvt_pk_bf16_f32 v70, v80, v81
	v_cvt_pk_bf16_f32 v71, v82, v83
	global_store_dwordx2 v[124:125], v[64:65], off offset:96
	global_store_dwordx2 v[124:125], v[66:67], off offset:2144
	global_store_dwordx2 v[90:91], v[68:69], off
	global_store_dwordx2 v[88:89], v[70:71], off
	global_load_dwordx4 v[64:67], v[86:87], off
	v_or_b32_e32 v68, 0x50, v120
	v_ashrrev_i32_e32 v69, 31, v68
	v_lshl_add_u64 v[70:71], v[68:69], 2, s[14:15]
	v_lshrrev_b32_e32 v72, 6, v84
	v_and_or_b32 v122, v72, s50, v121
	v_lshlrev_b64 v[72:73], 14, v[122:123]
	v_lshl_add_u64 v[72:73], s[38:39], 0, v[72:73]
	v_lshl_add_u64 v[72:73], v[72:73], 0, v[152:153]
	v_lshl_add_u64 v[74:75], v[72:73], 0, v[114:115]
	v_lshl_add_u64 v[76:77], v[72:73], 0, v[116:117]
	v_lshl_add_u64 v[72:73], v[72:73], 0, v[118:119]
	s_waitcnt vmcnt(0)
	v_pk_fma_f32 v[64:65], v[64:65], s[30:31], v[112:113] op_sel_hi:[1,0,0]
	v_pk_fma_f32 v[66:67], v[66:67], s[30:31], v[112:113] op_sel_hi:[1,0,0]
	v_mul_f32_e32 v69, 0x4b800000, v64
	v_mul_f32_e32 v78, 0x4b800000, v65
	v_mul_f32_e32 v79, 0x4b800000, v66
	v_mul_f32_e32 v80, 0x4b800000, v67
	v_cmp_gt_f32_e32 vcc, s40, v64
	v_cmp_gt_f32_e64 s[0:1], s40, v65
	v_cmp_gt_f32_e64 s[10:11], s40, v66
	v_cmp_gt_f32_e64 s[12:13], s40, v67
	v_cndmask_b32_e32 v64, v64, v69, vcc
	v_cndmask_b32_e64 v65, v65, v78, s[0:1]
	v_cndmask_b32_e64 v66, v66, v79, s[10:11]
	v_cndmask_b32_e64 v67, v67, v80, s[12:13]
	v_rsq_f32_e32 v64, v64
	v_rsq_f32_e32 v65, v65
	v_rsq_f32_e32 v66, v66
	v_rsq_f32_e32 v67, v67
	v_mul_f32_e32 v69, 0x45800000, v64
	v_mul_f32_e32 v78, 0x45800000, v65
	v_mul_f32_e32 v79, 0x45800000, v66
	v_mul_f32_e32 v80, 0x45800000, v67
	v_cndmask_b32_e32 v64, v64, v69, vcc
	v_cndmask_b32_e64 v65, v65, v78, s[0:1]
	v_cndmask_b32_e64 v66, v66, v79, s[10:11]
	v_cndmask_b32_e64 v67, v67, v80, s[12:13]
	v_mul_f32_e32 v60, v60, v64
	v_mul_f32_e32 v61, v61, v65
	v_mul_f32_e32 v62, v62, v66
	v_mul_f32_e32 v63, v63, v67
	v_mul_f32_e32 v56, v56, v64
	v_mul_f32_e32 v57, v57, v65
	v_mul_f32_e32 v52, v52, v64
	v_mul_f32_e32 v53, v53, v65
	v_mul_f32_e32 v54, v54, v66
	v_mul_f32_e32 v55, v55, v67
	v_mul_f32_e32 v64, v48, v64
	v_mul_f32_e32 v65, v49, v65
	v_cvt_pk_bf16_f32 v48, v60, v61
	v_cvt_pk_bf16_f32 v49, v62, v63
	v_mul_f32_e32 v58, v58, v66
	v_mul_f32_e32 v59, v59, v67
	v_mul_f32_e32 v66, v50, v66
	v_mul_f32_e32 v67, v51, v67
	v_cvt_pk_bf16_f32 v50, v56, v57
	v_cvt_pk_bf16_f32 v51, v58, v59
	v_cvt_pk_bf16_f32 v52, v52, v53
	v_cvt_pk_bf16_f32 v53, v54, v55
	v_cvt_pk_bf16_f32 v54, v64, v65
	v_cvt_pk_bf16_f32 v55, v66, v67
	global_store_dwordx2 v[74:75], v[48:49], off
	global_store_dwordx2 v[74:75], v[50:51], off offset:2048
	global_store_dwordx2 v[76:77], v[52:53], off
	global_store_dwordx2 v[72:73], v[54:55], off
	global_load_dwordx4 v[48:51], v[70:71], off
	v_or_b32_e32 v52, 0x60, v120
	v_ashrrev_i32_e32 v53, 31, v52
	v_lshl_add_u64 v[54:55], v[52:53], 2, s[14:15]
	v_lshrrev_b32_e32 v56, 6, v68
	v_and_or_b32 v122, v56, s50, v121
	v_lshlrev_b64 v[56:57], 14, v[122:123]
	v_lshl_add_u64 v[56:57], s[38:39], 0, v[56:57]
	v_lshl_add_u64 v[56:57], v[56:57], 0, v[152:153]
	v_lshl_add_u64 v[58:59], v[56:57], 0, 32
	v_lshl_add_u64 v[56:57], v[56:57], 0, v[114:115]
	v_lshl_add_u64 v[60:61], v[58:59], 0, v[116:117]
	v_lshl_add_u64 v[58:59], v[58:59], 0, v[118:119]
	s_waitcnt vmcnt(0)
	v_pk_fma_f32 v[48:49], v[48:49], s[30:31], v[112:113] op_sel_hi:[1,0,0]
	v_pk_fma_f32 v[50:51], v[50:51], s[30:31], v[112:113] op_sel_hi:[1,0,0]
	v_mul_f32_e32 v53, 0x4b800000, v48
	v_mul_f32_e32 v62, 0x4b800000, v49
	v_mul_f32_e32 v63, 0x4b800000, v50
	v_mul_f32_e32 v64, 0x4b800000, v51
	v_cmp_gt_f32_e32 vcc, s40, v48
	v_cmp_gt_f32_e64 s[0:1], s40, v49
	v_cmp_gt_f32_e64 s[10:11], s40, v50
	v_cmp_gt_f32_e64 s[12:13], s40, v51
	v_cndmask_b32_e32 v48, v48, v53, vcc
	v_cndmask_b32_e64 v49, v49, v62, s[0:1]
	v_cndmask_b32_e64 v50, v50, v63, s[10:11]
	v_cndmask_b32_e64 v51, v51, v64, s[12:13]
	v_rsq_f32_e32 v48, v48
	v_rsq_f32_e32 v49, v49
	v_rsq_f32_e32 v50, v50
	v_rsq_f32_e32 v51, v51
	v_mul_f32_e32 v53, 0x45800000, v48
	v_mul_f32_e32 v62, 0x45800000, v49
	v_mul_f32_e32 v63, 0x45800000, v50
	v_mul_f32_e32 v64, 0x45800000, v51
	v_cndmask_b32_e32 v48, v48, v53, vcc
	v_cndmask_b32_e64 v49, v49, v62, s[0:1]
	v_cndmask_b32_e64 v50, v50, v63, s[10:11]
	v_cndmask_b32_e64 v51, v51, v64, s[12:13]
	v_mul_f32_e32 v44, v44, v48
	v_mul_f32_e32 v45, v45, v49
	v_mul_f32_e32 v46, v46, v50
	v_mul_f32_e32 v47, v47, v51
	v_mul_f32_e32 v40, v40, v48
	v_mul_f32_e32 v41, v41, v49
	v_mul_f32_e32 v36, v36, v48
	v_mul_f32_e32 v37, v37, v49
	v_mul_f32_e32 v38, v38, v50
	v_mul_f32_e32 v39, v39, v51
	v_mul_f32_e32 v48, v32, v48
	v_mul_f32_e32 v49, v33, v49
	v_cvt_pk_bf16_f32 v32, v44, v45
	v_cvt_pk_bf16_f32 v33, v46, v47
	v_mul_f32_e32 v42, v42, v50
	v_mul_f32_e32 v43, v43, v51
	v_mul_f32_e32 v50, v34, v50
	v_mul_f32_e32 v51, v35, v51
	v_cvt_pk_bf16_f32 v34, v40, v41
	v_cvt_pk_bf16_f32 v35, v42, v43
	v_cvt_pk_bf16_f32 v36, v36, v37
	v_cvt_pk_bf16_f32 v37, v38, v39
	v_cvt_pk_bf16_f32 v38, v48, v49
	v_cvt_pk_bf16_f32 v39, v50, v51
	global_store_dwordx2 v[56:57], v[32:33], off offset:32
	global_store_dwordx2 v[56:57], v[34:35], off offset:2080
	global_store_dwordx2 v[60:61], v[36:37], off
	global_store_dwordx2 v[58:59], v[38:39], off
	global_load_dwordx4 v[32:35], v[54:55], off
	v_or_b32_e32 v36, 0x70, v120
	v_ashrrev_i32_e32 v37, 31, v36
	v_lshl_add_u64 v[38:39], v[36:37], 2, s[14:15]
	v_lshrrev_b32_e32 v40, 6, v52
	v_and_or_b32 v122, v40, s50, v121
	v_lshlrev_b64 v[40:41], 14, v[122:123]
	v_lshl_add_u64 v[40:41], s[38:39], 0, v[40:41]
	v_lshl_add_u64 v[40:41], v[40:41], 0, v[152:153]
	v_lshl_add_u64 v[42:43], v[40:41], 0, 64
	v_lshl_add_u64 v[40:41], v[40:41], 0, v[114:115]
	v_lshl_add_u64 v[44:45], v[42:43], 0, v[116:117]
	v_lshl_add_u64 v[42:43], v[42:43], 0, v[118:119]
	s_waitcnt vmcnt(0)
	v_pk_fma_f32 v[32:33], v[32:33], s[30:31], v[112:113] op_sel_hi:[1,0,0]
	v_pk_fma_f32 v[34:35], v[34:35], s[30:31], v[112:113] op_sel_hi:[1,0,0]
	v_mul_f32_e32 v37, 0x4b800000, v32
	v_mul_f32_e32 v46, 0x4b800000, v33
	v_mul_f32_e32 v47, 0x4b800000, v34
	v_mul_f32_e32 v48, 0x4b800000, v35
	v_cmp_gt_f32_e32 vcc, s40, v32
	v_cmp_gt_f32_e64 s[0:1], s40, v33
	v_cmp_gt_f32_e64 s[10:11], s40, v34
	v_cmp_gt_f32_e64 s[12:13], s40, v35
	v_cndmask_b32_e32 v32, v32, v37, vcc
	v_cndmask_b32_e64 v33, v33, v46, s[0:1]
	v_cndmask_b32_e64 v34, v34, v47, s[10:11]
	v_cndmask_b32_e64 v35, v35, v48, s[12:13]
	v_rsq_f32_e32 v32, v32
	v_rsq_f32_e32 v33, v33
	v_rsq_f32_e32 v34, v34
	v_rsq_f32_e32 v35, v35
	v_mul_f32_e32 v37, 0x45800000, v32
	v_mul_f32_e32 v46, 0x45800000, v33
	v_mul_f32_e32 v47, 0x45800000, v34
	v_mul_f32_e32 v48, 0x45800000, v35
	v_cndmask_b32_e32 v32, v32, v37, vcc
	v_cndmask_b32_e64 v33, v33, v46, s[0:1]
	v_cndmask_b32_e64 v34, v34, v47, s[10:11]
	v_cndmask_b32_e64 v35, v35, v48, s[12:13]
	v_mul_f32_e32 v28, v28, v32
	v_mul_f32_e32 v29, v29, v33
	v_mul_f32_e32 v30, v30, v34
	v_mul_f32_e32 v31, v31, v35
	v_mul_f32_e32 v24, v24, v32
	v_mul_f32_e32 v25, v25, v33
	v_mul_f32_e32 v20, v20, v32
	v_mul_f32_e32 v21, v21, v33
	v_mul_f32_e32 v22, v22, v34
	v_mul_f32_e32 v23, v23, v35
	v_mul_f32_e32 v32, v16, v32
	v_mul_f32_e32 v33, v17, v33
	v_cvt_pk_bf16_f32 v16, v28, v29
	v_cvt_pk_bf16_f32 v17, v30, v31
	v_mul_f32_e32 v26, v26, v34
	v_mul_f32_e32 v27, v27, v35
	v_mul_f32_e32 v34, v18, v34
	v_mul_f32_e32 v35, v19, v35
	v_cvt_pk_bf16_f32 v18, v24, v25
	v_cvt_pk_bf16_f32 v19, v26, v27
	v_cvt_pk_bf16_f32 v20, v20, v21
	v_cvt_pk_bf16_f32 v21, v22, v23
	v_cvt_pk_bf16_f32 v22, v32, v33
	v_cvt_pk_bf16_f32 v23, v34, v35
	global_store_dwordx2 v[40:41], v[16:17], off offset:64
	global_store_dwordx2 v[40:41], v[18:19], off offset:2112
	global_store_dwordx2 v[44:45], v[20:21], off
	global_store_dwordx2 v[42:43], v[22:23], off
	global_load_dwordx4 v[16:19], v[38:39], off
	v_lshrrev_b32_e32 v20, 6, v36
	v_and_or_b32 v122, v20, s50, v121
	v_lshlrev_b64 v[20:21], 14, v[122:123]
	v_lshl_add_u64 v[20:21], s[38:39], 0, v[20:21]
	v_lshl_add_u64 v[20:21], v[20:21], 0, v[152:153]
	v_lshl_add_u64 v[22:23], v[20:21], 0, s[36:37]
	v_lshl_add_u64 v[20:21], v[20:21], 0, v[114:115]
	v_lshl_add_u64 v[24:25], v[22:23], 0, v[116:117]
	v_lshl_add_u64 v[22:23], v[22:23], 0, v[118:119]
	s_waitcnt vmcnt(0)
	v_pk_fma_f32 v[16:17], v[16:17], s[30:31], v[112:113] op_sel_hi:[1,0,0]
	v_pk_fma_f32 v[18:19], v[18:19], s[30:31], v[112:113] op_sel_hi:[1,0,0]
	v_mul_f32_e32 v26, 0x4b800000, v16
	v_mul_f32_e32 v27, 0x4b800000, v17
	v_mul_f32_e32 v28, 0x4b800000, v18
	v_mul_f32_e32 v29, 0x4b800000, v19
	v_cmp_gt_f32_e32 vcc, s40, v16
	v_cmp_gt_f32_e64 s[0:1], s40, v17
	v_cmp_gt_f32_e64 s[10:11], s40, v18
	v_cmp_gt_f32_e64 s[12:13], s40, v19
	v_cndmask_b32_e32 v16, v16, v26, vcc
	v_cndmask_b32_e64 v17, v17, v27, s[0:1]
	v_cndmask_b32_e64 v18, v18, v28, s[10:11]
	v_cndmask_b32_e64 v19, v19, v29, s[12:13]
	v_rsq_f32_e32 v16, v16
	v_rsq_f32_e32 v17, v17
	v_rsq_f32_e32 v18, v18
	v_rsq_f32_e32 v19, v19
	v_mul_f32_e32 v26, 0x45800000, v16
	v_mul_f32_e32 v27, 0x45800000, v17
	v_mul_f32_e32 v28, 0x45800000, v18
	v_mul_f32_e32 v29, 0x45800000, v19
	v_cndmask_b32_e32 v16, v16, v26, vcc
	v_cndmask_b32_e64 v17, v17, v27, s[0:1]
	v_cndmask_b32_e64 v18, v18, v28, s[10:11]
	v_cndmask_b32_e64 v19, v19, v29, s[12:13]
	v_mul_f32_e32 v12, v12, v16
	v_mul_f32_e32 v13, v13, v17
	v_mul_f32_e32 v14, v14, v18
	v_mul_f32_e32 v15, v15, v19
	v_mul_f32_e32 v8, v8, v16
	v_mul_f32_e32 v9, v9, v17
	v_mul_f32_e32 v4, v4, v16
	v_mul_f32_e32 v5, v5, v17
	v_mul_f32_e32 v6, v6, v18
	v_mul_f32_e32 v7, v7, v19
	v_mul_f32_e32 v16, v0, v16
	v_mul_f32_e32 v17, v1, v17
	v_cvt_pk_bf16_f32 v0, v12, v13
	v_cvt_pk_bf16_f32 v1, v14, v15
	v_mul_f32_e32 v10, v10, v18
	v_mul_f32_e32 v11, v11, v19
	v_mul_f32_e32 v18, v2, v18
	v_mul_f32_e32 v19, v3, v19
	v_cvt_pk_bf16_f32 v2, v8, v9
	v_cvt_pk_bf16_f32 v3, v10, v11
	v_cvt_pk_bf16_f32 v4, v4, v5
	v_cvt_pk_bf16_f32 v5, v6, v7
	v_cvt_pk_bf16_f32 v6, v16, v17
	v_cvt_pk_bf16_f32 v7, v18, v19
	global_store_dwordx2 v[20:21], v[0:1], off offset:96
	global_store_dwordx2 v[20:21], v[2:3], off offset:2144
	global_store_dwordx2 v[24:25], v[4:5], off
	global_store_dwordx2 v[22:23], v[6:7], off
	s_branch .LBB0_699

.LBB0_768:
	s_ashr_i32 s10, s4, 3
	s_mul_hi_i32 s11, s10, 0x78787879
	s_lshr_b32 s12, s11, 31
	s_ashr_i32 s11, s11, 3
	s_add_i32 s11, s11, s12
	s_mul_i32 s12, s11, 17
	s_sub_i32 s10, s10, s12
	s_lshl_b32 s12, s4, 8
	s_lshl_b32 s11, s11, 11
	s_and_b32 s12, s12, 0x700
	s_or_b32 s12, s11, s12
	s_ashr_i32 s13, s12, 31
	s_lshl_b32 s10, s10, 7
	s_lshl_b64 s[14:15], s[12:13], 11
	s_add_u32 s14, s6, s14
	s_addc_u32 s15, s7, s15
	s_ashr_i32 s11, s10, 31
	v_mov_b32_e32 v36, v220
	s_lshl_b64 s[16:17], s[10:11], 11
	s_add_u32 s16, s8, s16
	v_ashrrev_i32_e32 v26, 2, v36
	v_ashrrev_i32_e32 v27, 31, v26
	s_addc_u32 s17, s9, s17
	v_lshlrev_b64 v[0:1], 11, v[26:27]
	v_lshlrev_b32_e32 v4, 4, v36
	v_lshl_add_u64 v[2:3], s[16:17], 0, v[0:1]
	v_lshl_add_u64 v[0:1], s[14:15], 0, v[0:1]
	v_and_b32_e32 v152, 48, v4
	v_lshl_add_u64 v[154:155], v[0:1], 0, v[152:153]
	v_add_co_u32_e32 v28, vcc, s38, v154
	v_lshl_add_u64 v[156:157], v[2:3], 0, v[152:153]
	s_nop 0
	v_addc_co_u32_e32 v29, vcc, 0, v155, vcc
	v_add_co_u32_e32 v30, vcc, s39, v154
	global_load_dwordx4 v[2:5], v[154:155], off
	s_nop 0
	v_addc_co_u32_e32 v31, vcc, 0, v155, vcc
	v_add_co_u32_e32 v32, vcc, s40, v154
	global_load_dwordx4 v[6:9], v[28:29], off
	s_nop 0
	v_addc_co_u32_e32 v33, vcc, 0, v155, vcc
	v_add_co_u32_e32 v34, vcc, s38, v156
	global_load_dwordx4 v[10:13], v[30:31], off
	s_nop 0
	v_addc_co_u32_e32 v35, vcc, 0, v157, vcc
	global_load_dwordx4 v[14:17], v[32:33], off
	global_load_dwordx4 v[18:21], v[156:157], off
	global_load_dwordx4 v[22:25], v[34:35], off
	global_load_dwordx4 v[120:123], v[154:155], off offset:64
	global_load_dwordx4 v[128:131], v[28:29], off offset:64
	global_load_dwordx4 v[132:135], v[30:31], off offset:64
	global_load_dwordx4 v[136:139], v[32:33], off offset:64
	global_load_dwordx4 v[124:127], v[156:157], off offset:64
	global_load_dwordx4 v[140:143], v[34:35], off offset:64
	v_lshrrev_b32_e32 v1, 4, v36
	v_lshrrev_b32_e32 v27, 2, v36
	v_sub_u32_e32 v39, 0, v1
	v_sub_u32_e32 v27, 0, v27
	v_and_b32_e32 v37, 0x3ffff8f, v36
	v_lshlrev_b32_e32 v38, 6, v36
	v_xor_b32_e32 v36, v36, v39
	v_xor_b32_e32 v1, v1, v27
	v_lshlrev_b32_e32 v27, 4, v36
	v_lshlrev_b32_e32 v1, 4, v1
	v_and_b32_e32 v40, 0x1000, v38
	v_and_b32_e32 v27, 48, v27
	v_and_b32_e32 v1, 48, v1
	v_and_b32_e32 v41, 0x3c0, v38
	v_and_b32_e32 v38, 0xffffe3c0, v38
	v_lshl_add_u32 v37, v37, 6, v166
	v_lshl_or_b32 v152, v26, 6, v27
	v_or_b32_e32 v26, v1, v40
	s_mov_b32 s11, -2
	s_mov_b32 s13, s35
	v_mov_b32_e32 v0, 0
	v_or3_b32 v168, v40, v41, v1
	v_add_u32_e32 v169, v1, v38
	v_add_u32_e32 v170, v1, v37
	v_add_u32_e32 v171, v26, v41
	v_lshl_add_u64 v[158:159], v[154:155], 0, s[24:25]
	v_lshl_add_u64 v[160:161], v[154:155], 0, s[28:29]
	v_lshl_add_u64 v[162:163], v[154:155], 0, s[30:31]
	v_lshl_add_u64 v[164:165], v[156:157], 0, s[24:25]
	v_mov_b32_e32 v1, v153
	v_mov_b32_e32 v26, v153
	v_mov_b32_e32 v27, v153
	v_mov_b32_e32 v28, 0
	v_mov_b32_e32 v29, v153
	v_mov_b32_e32 v30, v153
	v_mov_b32_e32 v31, v153
	v_mov_b32_e32 v32, 0
	v_mov_b32_e32 v33, v153
	v_mov_b32_e32 v34, v153
	v_mov_b32_e32 v35, v153
	v_mov_b32_e32 v36, 0
	v_mov_b32_e32 v37, v153
	v_mov_b32_e32 v38, v153
	v_mov_b32_e32 v39, v153
	v_mov_b32_e32 v40, 0
	v_mov_b32_e32 v41, v153
	v_mov_b32_e32 v42, v153
	v_mov_b32_e32 v43, v153
	v_mov_b32_e32 v44, 0
	s_waitcnt vmcnt(11)
	ds_write_b128 v152, v[2:5]
	s_waitcnt vmcnt(10)
	ds_write_b128 v152, v[6:9] offset:4096
	s_waitcnt vmcnt(9)
	ds_write_b128 v152, v[10:13] offset:8192
	s_waitcnt vmcnt(8)
	ds_write_b128 v152, v[14:17] offset:12288
	s_waitcnt vmcnt(7)
	ds_write_b128 v152, v[18:21] offset:32768
	s_waitcnt vmcnt(6)
	ds_write_b128 v152, v[22:25] offset:36864
	v_mov_b32_e32 v2, v153
	v_mov_b32_e32 v3, v153
	v_mov_b32_e32 v4, 0
	v_mov_b32_e32 v5, v153
	v_mov_b32_e32 v6, v153
	v_mov_b32_e32 v7, v153
	v_mov_b32_e32 v8, 0
	v_mov_b32_e32 v9, v153
	v_mov_b32_e32 v10, v153
	v_mov_b32_e32 v11, v153
	v_mov_b32_e32 v12, 0
	v_mov_b32_e32 v13, v153
	v_mov_b32_e32 v14, v153
	v_mov_b32_e32 v15, v153
	v_mov_b32_e32 v16, 0
	v_mov_b32_e32 v17, v153
	v_mov_b32_e32 v18, v153
	v_mov_b32_e32 v19, v153
	v_mov_b32_e32 v20, 0
	v_mov_b32_e32 v21, v153
	v_mov_b32_e32 v22, v153
	v_mov_b32_e32 v23, v153
	v_mov_b32_e32 v24, 0
	v_mov_b32_e32 v25, v153
	v_mov_b32_e32 v45, v153
	v_mov_b32_e32 v46, v153
	v_mov_b32_e32 v47, v153
	v_mov_b32_e32 v48, 0
	v_mov_b32_e32 v49, v153
	v_mov_b32_e32 v50, v153
	v_mov_b32_e32 v51, v153
	v_mov_b32_e32 v52, 0
	v_mov_b32_e32 v53, v153
	v_mov_b32_e32 v54, v153
	v_mov_b32_e32 v55, v153
	v_mov_b32_e32 v56, 0
	v_mov_b32_e32 v57, v153
	v_mov_b32_e32 v58, v153
	v_mov_b32_e32 v59, v153
	v_mov_b32_e32 v60, 0
	v_mov_b32_e32 v61, v153
	v_mov_b32_e32 v62, v153
	v_mov_b32_e32 v63, v153
	v_mov_b32_e32 v64, 0
	v_mov_b32_e32 v65, v153
	v_mov_b32_e32 v66, v153
	v_mov_b32_e32 v67, v153
	v_mov_b32_e32 v68, 0
	v_mov_b32_e32 v69, v153
	v_mov_b32_e32 v70, v153
	v_mov_b32_e32 v71, v153
	v_mov_b32_e32 v72, 0
	v_mov_b32_e32 v73, v153
	v_mov_b32_e32 v74, v153
	v_mov_b32_e32 v75, v153
	v_mov_b32_e32 v76, 0
	v_mov_b32_e32 v77, v153
	v_mov_b32_e32 v78, v153
	v_mov_b32_e32 v79, v153
	v_mov_b32_e32 v80, 0
	v_mov_b32_e32 v81, v153
	v_mov_b32_e32 v82, v153
	v_mov_b32_e32 v83, v153
	v_mov_b32_e32 v84, 0
	v_mov_b32_e32 v85, v153
	v_mov_b32_e32 v86, v153
	v_mov_b32_e32 v87, v153
	v_mov_b32_e32 v88, 0
	v_mov_b32_e32 v89, v153
	v_mov_b32_e32 v90, v153
	v_mov_b32_e32 v91, v153
	v_mov_b32_e32 v92, 0
	v_mov_b32_e32 v93, v153
	v_mov_b32_e32 v94, v153
	v_mov_b32_e32 v95, v153
	v_mov_b32_e32 v96, 0
	v_mov_b32_e32 v97, v153
	v_mov_b32_e32 v98, v153
	v_mov_b32_e32 v99, v153
	v_mov_b32_e32 v100, 0
	v_mov_b32_e32 v101, v153
	v_mov_b32_e32 v102, v153
	v_mov_b32_e32 v103, v153
	v_mov_b32_e32 v104, 0
	v_mov_b32_e32 v105, v153
	v_mov_b32_e32 v106, v153
	v_mov_b32_e32 v107, v153
	v_mov_b32_e32 v108, 0
	v_mov_b32_e32 v109, v153
	v_mov_b32_e32 v110, v153
	v_mov_b32_e32 v111, v153
	v_mov_b32_e32 v112, 0
	v_mov_b32_e32 v113, v153
	v_mov_b32_e32 v114, v153
	v_mov_b32_e32 v115, v153
	v_mov_b32_e32 v116, 0
	v_mov_b32_e32 v117, v153
	v_mov_b32_e32 v118, v153
	v_mov_b32_e32 v119, v153
	v_mov_b32_e32 v144, 0
	v_mov_b32_e32 v145, v153
	v_mov_b32_e32 v146, v153
	v_mov_b32_e32 v147, v153
	v_mov_b32_e32 v148, 0
	v_mov_b32_e32 v149, v153
	v_mov_b32_e32 v150, v153
	v_mov_b32_e32 v151, v153
	s_waitcnt lgkmcnt(0)
	s_barrier
	s_cmpk_lt_u32 s2, 0x100
	s_cbranch_scc1 .Lstag_6
	s_sleep 8
.Lstag_6:
.LBB0_769:
	s_add_i32 s14, s13, 64
	s_min_u32 s15, s14, 0x3e0
	s_lshl_b32 s34, s15, 1
	v_lshl_add_u64 v[172:173], v[154:155], 0, s[34:35]
	v_lshl_add_u64 v[176:177], v[158:159], 0, s[34:35]
	v_lshl_add_u64 v[180:181], v[160:161], 0, s[34:35]
	v_lshl_add_u64 v[184:185], v[162:163], 0, s[34:35]
	v_lshl_add_u64 v[188:189], v[156:157], 0, s[34:35]
	v_lshl_add_u64 v[192:193], v[164:165], 0, s[34:35]
	global_load_dwordx4 v[172:175], v[172:173], off
	ds_read_b128 v[196:199], v171 offset:32768
	global_load_dwordx4 v[176:179], v[176:177], off
	ds_read_b128 v[200:203], v171 offset:33792
	global_load_dwordx4 v[180:183], v[180:181], off
	ds_read_b128 v[204:207], v171 offset:34816
	global_load_dwordx4 v[184:187], v[184:185], off
	ds_read_b128 v[208:211], v171 offset:35840
	global_load_dwordx4 v[188:191], v[188:189], off
	ds_read_b128 v[212:215], v169
	global_load_dwordx4 v[192:195], v[192:193], off
	ds_read_b128 v[216:219], v169 offset:1024
	ds_read_b128 v[222:225], v169 offset:2048
	ds_read_b128 v[226:229], v169 offset:3072
	ds_read_b128 v[230:233], v169 offset:4096
	ds_read_b128 v[234:237], v169 offset:5120
	ds_read_b128 v[238:241], v169 offset:6144
	ds_read_b128 v[242:245], v169 offset:7168
	s_setprio 1
	s_waitcnt lgkmcnt(7)
	v_mfma_f32_16x16x32_bf16 v[148:151], v[196:199], v[212:215], v[148:151]
	v_mfma_f32_16x16x32_bf16 v[144:147], v[200:203], v[212:215], v[144:147]
	v_mfma_f32_16x16x32_bf16 v[116:119], v[204:207], v[212:215], v[116:119]
	v_mfma_f32_16x16x32_bf16 v[112:115], v[208:211], v[212:215], v[112:115]
	s_waitcnt vmcnt(11)
	ds_write_b128 v152, v[120:123] offset:16384
	s_waitcnt lgkmcnt(7)
	v_mfma_f32_16x16x32_bf16 v[108:111], v[196:199], v[216:219], v[108:111]
	v_mfma_f32_16x16x32_bf16 v[104:107], v[200:203], v[216:219], v[104:107]
	v_mfma_f32_16x16x32_bf16 v[100:103], v[204:207], v[216:219], v[100:103]
	v_mfma_f32_16x16x32_bf16 v[96:99], v[208:211], v[216:219], v[96:99]
	s_waitcnt vmcnt(9)
	ds_write_b128 v152, v[128:131] offset:20480
	s_waitcnt lgkmcnt(7)
	v_mfma_f32_16x16x32_bf16 v[92:95], v[196:199], v[222:225], v[92:95]
	v_mfma_f32_16x16x32_bf16 v[88:91], v[200:203], v[222:225], v[88:91]
	v_mfma_f32_16x16x32_bf16 v[84:87], v[204:207], v[222:225], v[84:87]
	v_mfma_f32_16x16x32_bf16 v[80:83], v[208:211], v[222:225], v[80:83]
	s_waitcnt vmcnt(8)
	ds_write_b128 v152, v[132:135] offset:24576
	s_waitcnt lgkmcnt(7)
	v_mfma_f32_16x16x32_bf16 v[76:79], v[196:199], v[226:229], v[76:79]
	v_mfma_f32_16x16x32_bf16 v[72:75], v[200:203], v[226:229], v[72:75]
	v_mfma_f32_16x16x32_bf16 v[68:71], v[204:207], v[226:229], v[68:71]
	v_mfma_f32_16x16x32_bf16 v[64:67], v[208:211], v[226:229], v[64:67]
	s_waitcnt vmcnt(7)
	ds_write_b128 v152, v[136:139] offset:28672
	s_waitcnt lgkmcnt(7)
	v_mfma_f32_16x16x32_bf16 v[60:63], v[196:199], v[230:233], v[60:63]
	v_mfma_f32_16x16x32_bf16 v[56:59], v[200:203], v[230:233], v[56:59]
	v_mfma_f32_16x16x32_bf16 v[52:55], v[204:207], v[230:233], v[52:55]
	v_mfma_f32_16x16x32_bf16 v[48:51], v[208:211], v[230:233], v[48:51]
	s_waitcnt vmcnt(7)
	ds_write_b128 v152, v[124:127] offset:40960
	s_waitcnt lgkmcnt(7)
	v_mfma_f32_16x16x32_bf16 v[44:47], v[196:199], v[234:237], v[44:47]
	v_mfma_f32_16x16x32_bf16 v[40:43], v[200:203], v[234:237], v[40:43]
	v_mfma_f32_16x16x32_bf16 v[36:39], v[204:207], v[234:237], v[36:39]
	v_mfma_f32_16x16x32_bf16 v[32:35], v[208:211], v[234:237], v[32:35]
	s_waitcnt vmcnt(6)
	ds_write_b128 v152, v[140:143] offset:45056
	s_waitcnt lgkmcnt(7)
	v_mfma_f32_16x16x32_bf16 v[28:31], v[196:199], v[238:241], v[28:31]
	v_mfma_f32_16x16x32_bf16 v[24:27], v[200:203], v[238:241], v[24:27]
	v_mfma_f32_16x16x32_bf16 v[20:23], v[204:207], v[238:241], v[20:23]
	v_mfma_f32_16x16x32_bf16 v[16:19], v[208:211], v[238:241], v[16:19]
	s_waitcnt lgkmcnt(6)
	v_mfma_f32_16x16x32_bf16 v[12:15], v[196:199], v[242:245], v[12:15]
	v_mfma_f32_16x16x32_bf16 v[8:11], v[200:203], v[242:245], v[8:11]
	v_mfma_f32_16x16x32_bf16 v[4:7], v[204:207], v[242:245], v[4:7]
	v_mfma_f32_16x16x32_bf16 v[0:3], v[208:211], v[242:245], v[0:3]
	s_setprio 0
	s_min_u32 s13, s13, 0x380
	s_lshl_b32 s34, s13, 1
	s_mov_b32 s17, s35
	s_add_i32 s16, s34, 0xc0
	v_lshl_add_u64 v[120:121], v[154:155], 0, s[34:35]
	v_lshl_add_u64 v[124:125], v[156:157], 0, s[34:35]
	v_lshl_add_u64 v[128:129], v[158:159], 0, s[16:17]
	v_lshl_add_u64 v[132:133], v[160:161], 0, s[16:17]
	v_lshl_add_u64 v[136:137], v[162:163], 0, s[16:17]
	v_lshl_add_u64 v[140:141], v[164:165], 0, s[16:17]
	s_waitcnt lgkmcnt(0)
	s_barrier
	global_load_dwordx4 v[120:123], v[120:121], off offset:192
	ds_read_b128 v[196:199], v168 offset:40960
	global_load_dwordx4 v[124:127], v[124:125], off offset:192
	ds_read_b128 v[200:203], v168 offset:41984
	global_load_dwordx4 v[128:131], v[128:129], off
	ds_read_b128 v[204:207], v168 offset:43008
	global_load_dwordx4 v[132:135], v[132:133], off
	ds_read_b128 v[208:211], v168 offset:44032
	global_load_dwordx4 v[136:139], v[136:137], off
	ds_read_b128 v[212:215], v170
	global_load_dwordx4 v[140:143], v[140:141], off
	ds_read_b128 v[216:219], v170 offset:1024
	ds_read_b128 v[222:225], v170 offset:2048
	ds_read_b128 v[226:229], v170 offset:3072
	ds_read_b128 v[230:233], v170 offset:4096
	ds_read_b128 v[234:237], v170 offset:5120
	ds_read_b128 v[238:241], v170 offset:6144
	ds_read_b128 v[242:245], v170 offset:7168
	s_setprio 1
	s_waitcnt lgkmcnt(7)
	v_mfma_f32_16x16x32_bf16 v[148:151], v[196:199], v[212:215], v[148:151]
	v_mfma_f32_16x16x32_bf16 v[144:147], v[200:203], v[212:215], v[144:147]
	v_mfma_f32_16x16x32_bf16 v[116:119], v[204:207], v[212:215], v[116:119]
	v_mfma_f32_16x16x32_bf16 v[112:115], v[208:211], v[212:215], v[112:115]
	s_waitcnt vmcnt(11)
	ds_write_b128 v152, v[172:175]
	s_waitcnt lgkmcnt(7)
	v_mfma_f32_16x16x32_bf16 v[108:111], v[196:199], v[216:219], v[108:111]
	v_mfma_f32_16x16x32_bf16 v[104:107], v[200:203], v[216:219], v[104:107]
	v_mfma_f32_16x16x32_bf16 v[100:103], v[204:207], v[216:219], v[100:103]
	v_mfma_f32_16x16x32_bf16 v[96:99], v[208:211], v[216:219], v[96:99]
	s_waitcnt vmcnt(10)
	ds_write_b128 v152, v[176:179] offset:4096
	s_waitcnt lgkmcnt(7)
	v_mfma_f32_16x16x32_bf16 v[92:95], v[196:199], v[222:225], v[92:95]
	v_mfma_f32_16x16x32_bf16 v[88:91], v[200:203], v[222:225], v[88:91]
	v_mfma_f32_16x16x32_bf16 v[84:87], v[204:207], v[222:225], v[84:87]
	v_mfma_f32_16x16x32_bf16 v[80:83], v[208:211], v[222:225], v[80:83]
	s_waitcnt vmcnt(9)
	ds_write_b128 v152, v[180:183] offset:8192
	s_waitcnt lgkmcnt(7)
	v_mfma_f32_16x16x32_bf16 v[76:79], v[196:199], v[226:229], v[76:79]
	v_mfma_f32_16x16x32_bf16 v[72:75], v[200:203], v[226:229], v[72:75]
	v_mfma_f32_16x16x32_bf16 v[68:71], v[204:207], v[226:229], v[68:71]
	v_mfma_f32_16x16x32_bf16 v[64:67], v[208:211], v[226:229], v[64:67]
	s_waitcnt vmcnt(8)
	ds_write_b128 v152, v[184:187] offset:12288
	s_waitcnt lgkmcnt(7)
	v_mfma_f32_16x16x32_bf16 v[60:63], v[196:199], v[230:233], v[60:63]
	v_mfma_f32_16x16x32_bf16 v[56:59], v[200:203], v[230:233], v[56:59]
	v_mfma_f32_16x16x32_bf16 v[52:55], v[204:207], v[230:233], v[52:55]
	v_mfma_f32_16x16x32_bf16 v[48:51], v[208:211], v[230:233], v[48:51]
	s_waitcnt vmcnt(7)
	ds_write_b128 v152, v[188:191] offset:32768
	s_waitcnt lgkmcnt(7)
	v_mfma_f32_16x16x32_bf16 v[44:47], v[196:199], v[234:237], v[44:47]
	v_mfma_f32_16x16x32_bf16 v[40:43], v[200:203], v[234:237], v[40:43]
	v_mfma_f32_16x16x32_bf16 v[36:39], v[204:207], v[234:237], v[36:39]
	v_mfma_f32_16x16x32_bf16 v[32:35], v[208:211], v[234:237], v[32:35]
	s_waitcnt vmcnt(6)
	ds_write_b128 v152, v[192:195] offset:36864
	s_waitcnt lgkmcnt(7)
	v_mfma_f32_16x16x32_bf16 v[28:31], v[196:199], v[238:241], v[28:31]
	v_mfma_f32_16x16x32_bf16 v[24:27], v[200:203], v[238:241], v[24:27]
	v_mfma_f32_16x16x32_bf16 v[20:23], v[204:207], v[238:241], v[20:23]
	v_mfma_f32_16x16x32_bf16 v[16:19], v[208:211], v[238:241], v[16:19]
	s_waitcnt lgkmcnt(6)
	v_mfma_f32_16x16x32_bf16 v[12:15], v[196:199], v[242:245], v[12:15]
	v_mfma_f32_16x16x32_bf16 v[8:11], v[200:203], v[242:245], v[8:11]
	v_mfma_f32_16x16x32_bf16 v[4:7], v[204:207], v[242:245], v[4:7]
	v_mfma_f32_16x16x32_bf16 v[0:3], v[208:211], v[242:245], v[0:3]
	s_setprio 0
	s_add_i32 s11, s11, 2
	s_cmp_lt_u32 s11, 30
	s_mov_b32 s13, s14
	s_waitcnt lgkmcnt(0)
	s_barrier
	s_cbranch_scc1 .LBB0_769
	s_waitcnt vmcnt(4)
	v_mov_b32_e32 v126, v220
	v_mov_b64_e32 v[124:125], s[72:73]
	v_and_b32_e32 v120, 0xffffff80, v126
	v_add_u32_e32 v120, s12, v120
	v_and_or_b32 v122, v126, 15, v120
	v_ashrrev_i32_e32 v123, 31, v122
	v_lshl_add_u64 v[120:121], v[122:123], 2, s[0:1]
	global_load_dword v120, v[120:121], off
	v_and_b32_e32 v121, 64, v126
	v_lshrrev_b32_e32 v126, 2, v126
	v_and_b32_e32 v126, 12, v126
	s_waitcnt vmcnt(0)
	v_fmamk_f32 v120, v120, 0x3a800000, v167
	v_mul_f32_e32 v127, 0x4b800000, v120
	v_cmp_gt_f32_e32 vcc, s42, v120
	s_nop 1
	v_cndmask_b32_e32 v120, v120, v127, vcc
	v_rsq_f32_e32 v127, v120
	v_or3_b32 v120, v121, v126, s10
	v_mad_i64_i32 v[124:125], s[10:11], v122, s41, v[124:125]
	v_mul_f32_e32 v121, 0x45800000, v127
	v_cndmask_b32_e32 v129, v127, v121, vcc
	v_mul_f32_e32 v132, v148, v129
	v_mul_f32_e32 v131, v149, v129
	v_mul_f32_e32 v130, v150, v129
	v_mul_f32_e32 v128, v151, v129
	v_cmp_lt_i32_e64 s[10:11], s43, v120
	s_and_saveexec_b64 s[12:13], s[10:11]
	s_xor_b64 s[12:13], exec, s[12:13]
	s_cbranch_execz .LBB0_774
	v_cmp_gt_u32_e32 vcc, s44, v120
	s_and_saveexec_b64 s[14:15], vcc
	s_cbranch_execz .LBB0_773
	v_mul_f32_e32 v121, 0xbfb8aa3b, v132
	v_exp_f32_e32 v121, v121
	v_mul_f32_e32 v126, 0xbfb8aa3b, v131
	v_mul_f32_e32 v127, 0xbfb8aa3b, v128
	v_exp_f32_e32 v126, v126
	v_add_f32_e32 v121, 1.0, v121
	v_rcp_f32_e32 v132, v121
	v_mul_f32_e32 v121, 0xbfb8aa3b, v130
	v_exp_f32_e32 v121, v121
	v_exp_f32_e32 v127, v127
	v_add_f32_e32 v126, 1.0, v126
	v_rcp_f32_e32 v133, v126
	v_add_f32_e32 v121, 1.0, v121
	v_rcp_f32_e32 v134, v121
	v_add_f32_e32 v121, 1.0, v127
	v_rcp_f32_e32 v135, v121
	v_mov_b32_e32 v121, v153
	v_lshl_add_u64 v[126:127], v[120:121], 2, v[124:125]
	v_add_co_u32_e32 v126, vcc, 0x2ffe000, v126
	s_nop 1
	v_addc_co_u32_e32 v127, vcc, 0, v127, vcc
	global_store_dwordx4 v[126:127], v[132:135], off

.LBB0_968:
	s_ashr_i32 s12, s38, 7
	s_lshl_b32 s1, s38, 6
	s_and_b32 s14, s1, 0x380
	s_lshl_b32 s1, s38, 7
	s_ashr_i32 s13, s12, 31
	s_ashr_i32 s0, s38, 4
	s_and_b32 s1, s1, 0x80
	s_lshl_b64 s[16:17], s[12:13], 25
	s_add_u32 s10, s4, s16
	s_addc_u32 s13, s5, s17
	s_lshl_b32 s15, s0, 22
	s_and_b32 s15, s15, 0x1c00000
	s_add_u32 s10, s10, s15
	s_addc_u32 s13, s13, 0
	s_lshl_b32 s15, s14, 12
	s_add_u32 s16, s10, s15
	s_addc_u32 s17, s13, 0
	s_cmpk_lt_u32 s38, 0x80
	s_cselect_b32 s10, s20, 0x1800000
	s_add_u32 s10, s72, s10
	v_mov_b32_e32 v13, v220
	s_addc_u32 s13, s73, 0
	s_lshl_b32 s15, s1, 13
	s_add_u32 s40, s10, s15
	v_ashrrev_i32_e32 v30, 2, v13
	v_add_u32_e32 v32, 64, v30
	s_addc_u32 s41, s13, 0
	s_xor_b32 s10, s14, 0x3fe
	v_ashrrev_i32_e32 v33, 31, v32
	v_lshlrev_b64 v[0:1], 13, v[32:33]
	v_min_i32_e32 v2, s10, v30
	v_lshlrev_b32_e32 v3, 4, v13
	v_lshl_add_u64 v[0:1], s[40:41], 0, v[0:1]
	v_and_b32_e32 v80, 48, v3
	v_ashrrev_i32_e32 v3, 31, v2
	v_min_i32_e32 v4, s10, v32
	v_lshl_add_u64 v[84:85], v[0:1], 0, v[80:81]
	v_lshlrev_b64 v[0:1], 12, v[2:3]
	v_ashrrev_i32_e32 v31, 31, v30
	v_lshl_add_u64 v[0:1], s[16:17], 0, v[0:1]
	v_ashrrev_i32_e32 v5, 31, v4
	v_lshlrev_b64 v[6:7], 13, v[30:31]
	v_lshl_add_u64 v[86:87], v[0:1], 0, v[80:81]
	v_lshlrev_b64 v[0:1], 12, v[4:5]
	v_lshl_add_u64 v[6:7], s[40:41], 0, v[6:7]
	v_lshl_add_u64 v[0:1], s[16:17], 0, v[0:1]
	v_lshl_add_u64 v[82:83], v[6:7], 0, v[80:81]
	v_lshl_add_u64 v[88:89], v[0:1], 0, v[80:81]
	global_load_dwordx4 v[14:17], v[86:87], off
	global_load_dwordx4 v[18:21], v[82:83], off
	global_load_dwordx4 v[22:25], v[84:85], off
	global_load_dwordx4 v[26:29], v[88:89], off
	global_load_dwordx4 v[64:67], v[82:83], off offset:64
	global_load_dwordx4 v[68:71], v[84:85], off offset:64
	global_load_dwordx4 v[72:75], v[86:87], off offset:64
	global_load_dwordx4 v[76:79], v[88:89], off offset:64
	v_lshrrev_b32_e32 v31, 4, v13
	v_lshrrev_b32_e32 v33, 2, v13
	v_sub_u32_e32 v37, 0, v31
	v_and_b32_e32 v34, 15, v13
	v_lshrrev_b32_e32 v35, 1, v13
	v_lshlrev_b32_e32 v36, 6, v13
	v_sub_u32_e32 v33, 0, v33
	v_xor_b32_e32 v13, v13, v37
	v_and_or_b32 v34, v35, s22, v34
	v_xor_b32_e32 v31, v31, v33
	v_lshlrev_b32_e32 v13, 4, v13
	v_lshlrev_b32_e32 v33, 6, v34
	v_lshlrev_b32_e32 v31, 4, v31
	v_and_b32_e32 v13, 48, v13
	v_and_b32_e32 v35, 0x13c0, v36
	v_add_u32_e32 v34, 0x2000, v33
	v_and_b32_e32 v31, 48, v31
	v_lshl_or_b32 v80, v30, 6, v13
	s_mov_b32 s13, -2
	s_mov_b32 s15, s11
	v_mov_b32_e32 v0, 0
	v_mov_b32_e32 v1, v81
	v_mov_b32_e32 v2, v81
	v_mov_b32_e32 v3, v81
	v_mov_b32_e32 v4, 0
	v_mov_b32_e32 v5, v81
	v_mov_b32_e32 v6, v81
	v_mov_b32_e32 v7, v81
	v_mov_b32_e32 v8, 0
	v_mov_b32_e32 v9, v81
	v_mov_b32_e32 v10, v81
	v_mov_b32_e32 v11, v81
	v_mov_b32_e32 v12, 0
	v_lshl_or_b32 v92, v32, 6, v13
	v_or_b32_e32 v93, v31, v35
	v_add_u32_e32 v94, v31, v33
	v_add_u32_e32 v95, v31, v35
	v_add_u32_e32 v96, v31, v34
	v_mov_b32_e32 v13, v81
	v_mov_b32_e32 v30, v81
	v_mov_b32_e32 v31, v81
	v_mov_b32_e32 v32, 0
	v_mov_b32_e32 v33, v81
	v_mov_b32_e32 v34, v81
	v_mov_b32_e32 v35, v81
	v_mov_b32_e32 v36, 0
	v_mov_b32_e32 v37, v81
	v_mov_b32_e32 v38, v81
	s_waitcnt vmcnt(6)
	ds_write_b128 v80, v[18:21] offset:16384
	s_waitcnt vmcnt(5)
	ds_write_b128 v92, v[22:25] offset:16384
	ds_write_b128 v80, v[14:17]
	s_waitcnt vmcnt(4)
	ds_write_b128 v92, v[26:29]
	v_mov_b32_e32 v14, v81
	v_mov_b32_e32 v15, v81
	v_mov_b32_e32 v16, 0
	v_mov_b32_e32 v17, v81
	v_mov_b32_e32 v18, v81
	v_mov_b32_e32 v19, v81
	v_mov_b32_e32 v20, 0
	v_mov_b32_e32 v21, v81
	v_mov_b32_e32 v22, v81
	v_mov_b32_e32 v23, v81
	v_mov_b32_e32 v24, 0
	v_mov_b32_e32 v25, v81
	v_mov_b32_e32 v26, v81
	v_mov_b32_e32 v27, v81
	v_mov_b32_e32 v28, 0
	v_mov_b32_e32 v29, v81
	v_mov_b32_e32 v39, v81
	v_mov_b32_e32 v40, 0
	v_mov_b32_e32 v41, v81
	v_mov_b32_e32 v42, v81
	v_mov_b32_e32 v43, v81
	v_mov_b32_e32 v44, 0
	v_mov_b32_e32 v45, v81
	v_mov_b32_e32 v46, v81
	v_mov_b32_e32 v47, v81
	v_mov_b32_e32 v48, 0
	v_mov_b32_e32 v49, v81
	v_mov_b32_e32 v50, v81
	v_mov_b32_e32 v51, v81
	v_mov_b32_e32 v52, 0
	v_mov_b32_e32 v53, v81
	v_mov_b32_e32 v54, v81
	v_mov_b32_e32 v55, v81
	v_mov_b32_e32 v56, 0
	v_mov_b32_e32 v57, v81
	v_mov_b32_e32 v58, v81
	v_mov_b32_e32 v59, v81
	v_mov_b32_e32 v60, 0
	v_mov_b32_e32 v61, v81
	v_mov_b32_e32 v62, v81
	v_mov_b32_e32 v63, v81
	s_waitcnt lgkmcnt(0)
	s_barrier
	s_cmpk_lt_u32 s2, 0x100
	s_cbranch_scc1 .Lstag_7
	s_sleep 8
.Lstag_7:
.LBB0_969:
	s_add_i32 s16, s15, 64
	s_min_u32 s10, s16, 0xfe0
	s_lshl_b32 s10, s10, 1
	v_lshl_add_u64 v[98:99], v[86:87], 0, s[10:11]
	v_lshl_add_u64 v[102:103], v[88:89], 0, s[10:11]
	v_lshl_add_u64 v[106:107], v[82:83], 0, s[10:11]
	v_lshl_add_u64 v[110:111], v[84:85], 0, s[10:11]
	global_load_dwordx4 v[98:101], v[98:99], off
	ds_read_b128 v[114:117], v94
	global_load_dwordx4 v[102:105], v[102:103], off
	ds_read_b128 v[118:121], v94 offset:1024
	global_load_dwordx4 v[106:109], v[106:107], off
	ds_read_b128 v[122:125], v95 offset:16384
	global_load_dwordx4 v[110:113], v[110:111], off
	ds_read_b128 v[126:129], v95 offset:17408
	ds_read_b128 v[130:133], v94 offset:2048
	ds_read_b128 v[134:137], v94 offset:3072
	ds_read_b128 v[138:141], v95 offset:18432
	ds_read_b128 v[142:145], v95 offset:19456
	s_setprio 1
	s_waitcnt lgkmcnt(5)
	v_mfma_f32_16x16x32_bf16 v[60:63], v[114:117], v[122:125], v[60:63]
	s_waitcnt lgkmcnt(4)
	v_mfma_f32_16x16x32_bf16 v[56:59], v[114:117], v[126:129], v[56:59]
	s_waitcnt lgkmcnt(1)
	v_mfma_f32_16x16x32_bf16 v[52:55], v[114:117], v[138:141], v[52:55]
	s_waitcnt lgkmcnt(0)
	v_mfma_f32_16x16x32_bf16 v[48:51], v[114:117], v[142:145], v[48:51]
	v_mfma_f32_16x16x32_bf16 v[44:47], v[118:121], v[122:125], v[44:47]
	v_mfma_f32_16x16x32_bf16 v[40:43], v[118:121], v[126:129], v[40:43]
	v_mfma_f32_16x16x32_bf16 v[36:39], v[118:121], v[138:141], v[36:39]
	v_mfma_f32_16x16x32_bf16 v[32:35], v[118:121], v[142:145], v[32:35]
	v_mfma_f32_16x16x32_bf16 v[28:31], v[130:133], v[122:125], v[28:31]
	v_mfma_f32_16x16x32_bf16 v[24:27], v[130:133], v[126:129], v[24:27]
	v_mfma_f32_16x16x32_bf16 v[20:23], v[130:133], v[138:141], v[20:23]
	v_mfma_f32_16x16x32_bf16 v[16:19], v[130:133], v[142:145], v[16:19]
	v_mfma_f32_16x16x32_bf16 v[12:15], v[134:137], v[122:125], v[12:15]
	v_mfma_f32_16x16x32_bf16 v[8:11], v[134:137], v[126:129], v[8:11]
	v_mfma_f32_16x16x32_bf16 v[4:7], v[134:137], v[138:141], v[4:7]
	v_mfma_f32_16x16x32_bf16 v[0:3], v[134:137], v[142:145], v[0:3]
	s_setprio 0
	s_min_u32 s10, s15, 0xf80
	s_lshl_b32 s10, s10, 1
	s_waitcnt vmcnt(5)
	ds_write_b128 v80, v[64:67] offset:24576
	s_waitcnt vmcnt(4)
	ds_write_b128 v80, v[68:71] offset:28672
	v_lshl_add_u64 v[64:65], v[86:87], 0, s[10:11]
	v_lshl_add_u64 v[66:67], v[88:89], 0, s[10:11]
	v_lshl_add_u64 v[68:69], v[82:83], 0, s[10:11]
	v_lshl_add_u64 v[70:71], v[84:85], 0, s[10:11]
	s_waitcnt vmcnt(5)
	ds_write_b128 v80, v[72:75] offset:8192
	s_waitcnt vmcnt(4)
	ds_write_b128 v80, v[76:79] offset:12288
	s_waitcnt lgkmcnt(0)
	s_barrier
	global_load_dwordx4 v[72:75], v[64:65], off offset:192
	global_load_dwordx4 v[76:79], v[66:67], off offset:192
	ds_read_b128 v[114:117], v96
	global_load_dwordx4 v[64:67], v[68:69], off offset:192
	ds_read_b128 v[118:121], v93 offset:24576
	global_load_dwordx4 v[68:71], v[70:71], off offset:192
	ds_read_b128 v[122:125], v96 offset:1024
	ds_read_b128 v[126:129], v93 offset:25600
	ds_read_b128 v[130:133], v96 offset:2048
	ds_read_b128 v[134:137], v93 offset:26624
	ds_read_b128 v[138:141], v96 offset:3072
	ds_read_b128 v[142:145], v93 offset:27648
	s_setprio 1
	s_waitcnt lgkmcnt(6)
	v_mfma_f32_16x16x32_bf16 v[60:63], v[114:117], v[118:121], v[60:63]
	s_waitcnt lgkmcnt(4)
	v_mfma_f32_16x16x32_bf16 v[56:59], v[114:117], v[126:129], v[56:59]
	s_waitcnt lgkmcnt(2)
	v_mfma_f32_16x16x32_bf16 v[52:55], v[114:117], v[134:137], v[52:55]
	s_waitcnt lgkmcnt(0)
	v_mfma_f32_16x16x32_bf16 v[48:51], v[114:117], v[142:145], v[48:51]
	v_mfma_f32_16x16x32_bf16 v[44:47], v[122:125], v[118:121], v[44:47]
	v_mfma_f32_16x16x32_bf16 v[40:43], v[122:125], v[126:129], v[40:43]
	v_mfma_f32_16x16x32_bf16 v[36:39], v[122:125], v[134:137], v[36:39]
	v_mfma_f32_16x16x32_bf16 v[32:35], v[122:125], v[142:145], v[32:35]
	v_mfma_f32_16x16x32_bf16 v[28:31], v[130:133], v[118:121], v[28:31]
	v_mfma_f32_16x16x32_bf16 v[24:27], v[130:133], v[126:129], v[24:27]
	v_mfma_f32_16x16x32_bf16 v[20:23], v[130:133], v[134:137], v[20:23]
	v_mfma_f32_16x16x32_bf16 v[16:19], v[130:133], v[142:145], v[16:19]
	v_mfma_f32_16x16x32_bf16 v[12:15], v[138:141], v[118:121], v[12:15]
	v_mfma_f32_16x16x32_bf16 v[8:11], v[138:141], v[126:129], v[8:11]
	v_mfma_f32_16x16x32_bf16 v[4:7], v[138:141], v[134:137], v[4:7]
	v_mfma_f32_16x16x32_bf16 v[0:3], v[138:141], v[142:145], v[0:3]
	s_setprio 0
	s_add_i32 s13, s13, 2
	s_cmpk_lt_u32 s13, 0x7e
	s_mov_b32 s15, s16
	s_waitcnt vmcnt(7)
	ds_write_b128 v80, v[98:101]
	s_waitcnt vmcnt(6)
	ds_write_b128 v92, v[102:105]
	s_waitcnt vmcnt(5)
	ds_write_b128 v80, v[106:109] offset:16384
	s_waitcnt vmcnt(4)
	ds_write_b128 v92, v[110:113] offset:16384
	s_waitcnt lgkmcnt(0)
	s_barrier
	s_cbranch_scc1 .LBB0_969
	s_lshl_b32 s12, s12, 13
	v_mov_b32_e32 v200, v220
	s_ashr_i32 s13, s12, 31
	s_lshl_b64 s[12:13], s[12:13], 2
	s_waitcnt vmcnt(1)
	v_and_b32_e32 v64, 0x4f, v200
	v_or_b32_e32 v201, s1, v64
	s_add_u32 s12, s6, s12
	s_addc_u32 s13, s7, s13
	v_lshlrev_b32_e32 v80, 2, v201
	v_lshl_add_u64 v[64:65], s[12:13], 0, v[80:81]
	v_add_co_u32_e32 v66, vcc, s24, v64
	s_ashr_i32 s1, s0, 31
	s_nop 0
	v_addc_co_u32_e32 v67, vcc, 0, v65, vcc
	v_add_co_u32_e32 v104, vcc, s23, v64
	s_lshl_b64 s[0:1], s[0:1], 19
	s_nop 0
	v_addc_co_u32_e32 v105, vcc, 0, v65, vcc
	v_add_co_u32_e32 v112, vcc, s25, v64
	s_nop 1
	v_addc_co_u32_e32 v113, vcc, 0, v65, vcc
	v_add_co_u32_e32 v116, vcc, s26, v64
	s_nop 1
	v_addc_co_u32_e32 v117, vcc, 0, v65, vcc
	v_add_co_u32_e32 v120, vcc, s27, v64
	s_nop 1
	v_addc_co_u32_e32 v121, vcc, 0, v65, vcc
	v_add_co_u32_e32 v134, vcc, s28, v64
	s_nop 1
	v_addc_co_u32_e32 v135, vcc, 0, v65, vcc
	v_add_co_u32_e32 v64, vcc, s29, v64
	s_nop 1
	v_addc_co_u32_e32 v65, vcc, 0, v65, vcc
	global_load_dword v68, v80, s[12:13] offset:1024
	global_load_dword v139, v80, s[12:13] offset:2048
	global_load_dword v136, v80, s[12:13] offset:1088
	global_load_dword v137, v80, s[12:13] offset:2112
	global_load_dword v69, v80, s[12:13] offset:1152
	global_load_dword v70, v80, s[12:13] offset:2176
	global_load_dword v71, v80, s[12:13] offset:1216
	global_load_dword v72, v80, s[12:13] offset:192
	global_load_dword v151, v80, s[12:13] offset:3072
	global_load_dword v152, v[104:105], off offset:-4096
	global_load_dword v149, v[104:105], off
	global_load_dword v141, v80, s[12:13] offset:3136
	global_load_dword v140, v[104:105], off offset:64
	global_load_dword v84, v80, s[12:13] offset:3200
	global_load_dword v73, v80, s[12:13] offset:3264
	global_load_dword v74, v80, s[12:13] offset:2240
	global_load_dword v155, v[66:67], off offset:1024
	global_load_dword v156, v[66:67], off offset:2048
	global_load_dword v142, v[66:67], off offset:64
	global_load_dword v143, v[66:67], off offset:1088
	global_load_dword v87, v[66:67], off offset:128
	global_load_dword v88, v[66:67], off offset:1152
	global_load_dword v75, v[66:67], off offset:1216
	global_load_dword v76, v[66:67], off offset:192
	global_load_dword v159, v[66:67], off offset:3072
	global_load_dword v145, v[66:67], off offset:2112
	global_load_dword v146, v[66:67], off offset:3136
	global_load_dword v144, v[112:113], off offset:64
	global_load_dword v93, v[66:67], off offset:2176
	global_load_dword v94, v[66:67], off offset:3200
	global_load_dword v77, v[66:67], off offset:3264
	global_load_dword v78, v[66:67], off offset:2240
	global_load_dword v162, v[104:105], off offset:1024
	global_load_dword v163, v[104:105], off offset:2048
	global_load_dword v147, v[104:105], off offset:1088
	global_load_dword v148, v[104:105], off offset:2112
	global_load_dword v97, v[104:105], off offset:128
	global_load_dword v98, v[104:105], off offset:1152
	global_load_dword v79, v[104:105], off offset:1216
	global_load_dword v82, v[104:105], off offset:192
	global_load_dword v167, v[104:105], off offset:3072
	global_load_dword v168, v[116:117], off offset:-4096
	global_load_dword v164, v[116:117], off
	global_load_dword v150, v[104:105], off offset:3136
	global_load_dword v101, v[104:105], off offset:2176
	global_load_dword v102, v[104:105], off offset:3200
	global_load_dword v83, v[104:105], off offset:3264
	global_load_dword v85, v[104:105], off offset:2240
	global_load_dword v171, v[112:113], off offset:1024
	global_load_dword v172, v[112:113], off offset:2048
	global_load_dword v153, v[112:113], off offset:1088
	global_load_dword v154, v[112:113], off offset:2112
	s_nop 0
	global_load_dword v105, v[112:113], off offset:128
	global_load_dword v106, v[112:113], off offset:1152
	global_load_dword v86, v[112:113], off offset:1216
	global_load_dword v89, v[112:113], off offset:192
	global_load_dword v175, v[112:113], off offset:3072
	global_load_dword v158, v[112:113], off offset:3136
	global_load_dword v157, v[120:121], off offset:64
	global_load_dword v110, v[112:113], off offset:2176
	global_load_dword v111, v[112:113], off offset:3200
	global_load_dword v108, v[120:121], off offset:128
	global_load_dword v92, v[112:113], off offset:3264
	global_load_dword v95, v[112:113], off offset:2240
	global_load_dword v178, v[116:117], off offset:1024
	global_load_dword v179, v[116:117], off offset:2048
	global_load_dword v160, v[116:117], off offset:64
	global_load_dword v161, v[116:117], off offset:1088
	global_load_dword v114, v[116:117], off offset:128
	global_load_dword v115, v[116:117], off offset:1152
	global_load_dword v96, v[116:117], off offset:1216
	global_load_dword v99, v[116:117], off offset:192
	global_load_dword v182, v[116:117], off offset:3072
	global_load_dword v183, v[134:135], off offset:-4096
	global_load_dword v165, v[116:117], off offset:2112
	global_load_dword v166, v[116:117], off offset:3136
	global_load_dword v118, v[116:117], off offset:2176
	global_load_dword v119, v[116:117], off offset:3200
	global_load_dword v100, v[116:117], off offset:3264
	global_load_dword v103, v[116:117], off offset:2240
	global_load_dword v186, v[120:121], off offset:1024
	global_load_dword v187, v[120:121], off offset:2048
	global_load_dword v169, v[120:121], off offset:1088
	global_load_dword v170, v[120:121], off offset:2112
	global_load_dword v122, v[120:121], off offset:1152
	global_load_dword v123, v[120:121], off offset:2176
	global_load_dword v104, v[120:121], off offset:1216
	global_load_dword v107, v[120:121], off offset:192
	global_load_dword v190, v[120:121], off offset:3072
	global_load_dword v188, v[64:65], off
	global_load_dword v174, v[120:121], off offset:3136
	global_load_dword v173, v[64:65], off offset:64
	global_load_dword v127, v[120:121], off offset:3200
	global_load_dword v125, v[64:65], off offset:128
	global_load_dword v109, v[120:121], off offset:3264
	global_load_dword v112, v[120:121], off offset:2240
	global_load_dword v191, v[134:135], off
	global_load_dword v192, v[134:135], off offset:1024
	global_load_dword v176, v[134:135], off offset:64
	global_load_dword v177, v[134:135], off offset:1088
	global_load_dword v129, v[134:135], off offset:128
	global_load_dword v130, v[134:135], off offset:1152
	global_load_dword v113, v[134:135], off offset:1216
	global_load_dword v116, v[134:135], off offset:192
	global_load_dword v193, v[134:135], off offset:2048
	global_load_dword v194, v[134:135], off offset:3072
	global_load_dword v180, v[134:135], off offset:2112
	global_load_dword v181, v[134:135], off offset:3136
	global_load_dword v131, v[134:135], off offset:2176
	global_load_dword v132, v[134:135], off offset:3200
	global_load_dword v117, v[134:135], off offset:3264
	global_load_dword v120, v[134:135], off offset:2240
	global_load_dword v195, v[64:65], off offset:1024
	global_load_dword v196, v[64:65], off offset:2048
	global_load_dword v184, v[64:65], off offset:1088
	global_load_dword v185, v[64:65], off offset:2112
	global_load_dword v133, v[64:65], off offset:1152
	global_load_dword v134, v[64:65], off offset:2176
	global_load_dword v121, v[64:65], off offset:1216
	global_load_dword v124, v[64:65], off offset:192
	global_load_dword v199, v80, s[12:13]
	global_load_dword v197, v[64:65], off offset:3072
	global_load_dword v198, v80, s[12:13] offset:64
	global_load_dword v189, v[64:65], off offset:3136
	global_load_dword v138, v80, s[12:13] offset:128
	global_load_dword v135, v[64:65], off offset:3200
	global_load_dword v126, v[64:65], off offset:3264
	global_load_dword v128, v[64:65], off offset:2240
	v_ashrrev_i32_e32 v64, 1, v200
	v_and_b32_e32 v64, 0xffffffc0, v64
	v_lshrrev_b32_e32 v65, 2, v200
	v_add_u32_e32 v64, s14, v64
	v_and_or_b32 v64, v65, 12, v64
	s_add_u32 s12, s8, s0
	v_ashrrev_i32_e32 v65, 31, v64
	s_addc_u32 s13, s9, s1
	v_lshlrev_b64 v[66:67], 9, v[64:65]
	v_cmp_lt_i32_e32 vcc, s21, v64
	v_lshl_add_u64 v[66:67], s[12:13], 0, v[66:67]
	v_lshlrev_b32_e32 v80, 1, v201
	s_and_saveexec_b64 s[0:1], vcc
	s_xor_b64 s[0:1], exec, s[0:1]
	s_cbranch_execz .LBB0_972
	v_lshl_add_u64 v[200:201], v[66:67], 0, v[80:81]
	global_store_short v[200:201], v81, off

.LBB0_1736:
	s_ashr_i32 s12, s23, 3
	s_lshr_b32 s20, s12, 28
	s_add_i32 s20, s12, s20
	s_and_b32 s21, s20, 0x1fffff0
	s_sub_i32 s12, s12, s21
	s_lshl_b32 s20, s20, 7
	s_lshl_b32 s21, s23, 8
	s_and_b32 s20, s20, 0xfffff800
	s_and_b32 s21, s21, 0x700
	s_or_b32 s20, s20, s21
	s_ashr_i32 s21, s20, 31
	s_lshl_b32 s24, s12, 7
	s_lshl_b64 s[26:27], s[20:21], 11
	s_add_u32 s26, s3, s26
	s_addc_u32 s27, s4, s27
	s_add_i32 s12, s24, 0x880
	v_mov_b32_e32 v36, v220
	s_lshl_b64 s[28:29], s[12:13], 11
	s_add_u32 s28, s5, s28
	v_ashrrev_i32_e32 v26, 2, v36
	v_ashrrev_i32_e32 v27, 31, v26
	s_addc_u32 s29, s6, s29
	v_lshlrev_b64 v[0:1], 11, v[26:27]
	v_lshlrev_b32_e32 v4, 4, v36
	v_lshl_add_u64 v[2:3], s[28:29], 0, v[0:1]
	v_lshl_add_u64 v[0:1], s[26:27], 0, v[0:1]
	v_and_b32_e32 v152, 48, v4
	v_lshl_add_u64 v[154:155], v[0:1], 0, v[152:153]
	v_add_co_u32_e32 v28, vcc, s7, v154
	v_lshl_add_u64 v[156:157], v[2:3], 0, v[152:153]
	s_nop 0
	v_addc_co_u32_e32 v29, vcc, 0, v155, vcc
	v_add_co_u32_e32 v30, vcc, s8, v154
	global_load_dwordx4 v[2:5], v[154:155], off
	s_nop 0
	v_addc_co_u32_e32 v31, vcc, 0, v155, vcc
	v_add_co_u32_e32 v32, vcc, s9, v154
	global_load_dwordx4 v[6:9], v[28:29], off
	s_nop 0
	v_addc_co_u32_e32 v33, vcc, 0, v155, vcc
	v_add_co_u32_e32 v34, vcc, s7, v156
	global_load_dwordx4 v[10:13], v[30:31], off
	s_nop 0
	v_addc_co_u32_e32 v35, vcc, 0, v157, vcc
	global_load_dwordx4 v[14:17], v[32:33], off
	global_load_dwordx4 v[18:21], v[156:157], off
	global_load_dwordx4 v[22:25], v[34:35], off
	global_load_dwordx4 v[120:123], v[154:155], off offset:64
	global_load_dwordx4 v[124:127], v[28:29], off offset:64
	global_load_dwordx4 v[128:131], v[30:31], off offset:64
	global_load_dwordx4 v[136:139], v[32:33], off offset:64
	global_load_dwordx4 v[132:135], v[156:157], off offset:64
	global_load_dwordx4 v[140:143], v[34:35], off offset:64
	v_lshrrev_b32_e32 v27, 4, v36
	v_lshrrev_b32_e32 v37, 2, v36
	v_sub_u32_e32 v40, 0, v27
	v_sub_u32_e32 v37, 0, v37
	v_and_b32_e32 v38, 0x3ffff8f, v36
	v_lshlrev_b32_e32 v39, 6, v36
	v_xor_b32_e32 v36, v36, v40
	v_xor_b32_e32 v27, v27, v37
	v_lshlrev_b32_e32 v36, 4, v36
	v_lshlrev_b32_e32 v27, 4, v27
	v_and_b32_e32 v41, 0x1000, v39
	v_and_b32_e32 v36, 48, v36
	v_and_b32_e32 v27, 48, v27
	v_and_b32_e32 v42, 0x3c0, v39
	v_and_b32_e32 v39, 0xffffe3c0, v39
	v_lshl_add_u32 v38, v38, 6, v166
	v_lshl_or_b32 v152, v26, 6, v36
	v_or_b32_e32 v26, v27, v41
	s_mov_b32 s21, -2
	s_mov_b32 s25, s13
	v_mov_b32_e32 v0, 0
	v_mov_b32_e32 v1, v153
	v_or3_b32 v168, v41, v42, v27
	v_add_u32_e32 v169, v27, v39
	v_add_u32_e32 v170, v27, v38
	v_add_u32_e32 v171, v26, v42
	v_lshl_add_u64 v[158:159], v[154:155], 0, s[14:15]
	v_lshl_add_u64 v[160:161], v[154:155], 0, s[16:17]
	v_lshl_add_u64 v[162:163], v[154:155], 0, s[18:19]
	v_lshl_add_u64 v[164:165], v[156:157], 0, s[14:15]
	v_mov_b32_e32 v26, v153
	v_mov_b32_e32 v27, v153
	v_mov_b32_e32 v28, 0
	v_mov_b32_e32 v29, v153
	v_mov_b32_e32 v30, v153
	v_mov_b32_e32 v31, v153
	v_mov_b32_e32 v32, 0
	v_mov_b32_e32 v33, v153
	v_mov_b32_e32 v34, v153
	v_mov_b32_e32 v35, v153
	v_mov_b32_e32 v36, 0
	v_mov_b32_e32 v37, v153
	v_mov_b32_e32 v38, v153
	v_mov_b32_e32 v39, v153
	v_mov_b32_e32 v40, 0
	v_mov_b32_e32 v41, v153
	v_mov_b32_e32 v42, v153
	v_mov_b32_e32 v43, v153
	v_mov_b32_e32 v44, 0
	s_waitcnt vmcnt(11)
	ds_write_b128 v152, v[2:5]
	s_waitcnt vmcnt(10)
	ds_write_b128 v152, v[6:9] offset:4096
	s_waitcnt vmcnt(9)
	ds_write_b128 v152, v[10:13] offset:8192
	s_waitcnt vmcnt(8)
	ds_write_b128 v152, v[14:17] offset:12288
	s_waitcnt vmcnt(7)
	ds_write_b128 v152, v[18:21] offset:32768
	s_waitcnt vmcnt(6)
	ds_write_b128 v152, v[22:25] offset:36864
	v_mov_b32_e32 v2, v153
	v_mov_b32_e32 v3, v153
	v_mov_b32_e32 v4, 0
	v_mov_b32_e32 v5, v153
	v_mov_b32_e32 v6, v153
	v_mov_b32_e32 v7, v153
	v_mov_b32_e32 v8, 0
	v_mov_b32_e32 v9, v153
	v_mov_b32_e32 v10, v153
	v_mov_b32_e32 v11, v153
	v_mov_b32_e32 v12, 0
	v_mov_b32_e32 v13, v153
	v_mov_b32_e32 v14, v153
	v_mov_b32_e32 v15, v153
	v_mov_b32_e32 v16, 0
	v_mov_b32_e32 v17, v153
	v_mov_b32_e32 v18, v153
	v_mov_b32_e32 v19, v153
	v_mov_b32_e32 v20, 0
	v_mov_b32_e32 v21, v153
	v_mov_b32_e32 v22, v153
	v_mov_b32_e32 v23, v153
	v_mov_b32_e32 v24, 0
	v_mov_b32_e32 v25, v153
	v_mov_b32_e32 v45, v153
	v_mov_b32_e32 v46, v153
	v_mov_b32_e32 v47, v153
	v_mov_b32_e32 v48, 0
	v_mov_b32_e32 v49, v153
	v_mov_b32_e32 v50, v153
	v_mov_b32_e32 v51, v153
	v_mov_b32_e32 v52, 0
	v_mov_b32_e32 v53, v153
	v_mov_b32_e32 v54, v153
	v_mov_b32_e32 v55, v153
	v_mov_b32_e32 v56, 0
	v_mov_b32_e32 v57, v153
	v_mov_b32_e32 v58, v153
	v_mov_b32_e32 v59, v153
	v_mov_b32_e32 v60, 0
	v_mov_b32_e32 v61, v153
	v_mov_b32_e32 v62, v153
	v_mov_b32_e32 v63, v153
	v_mov_b32_e32 v64, 0
	v_mov_b32_e32 v65, v153
	v_mov_b32_e32 v66, v153
	v_mov_b32_e32 v67, v153
	v_mov_b32_e32 v68, 0
	v_mov_b32_e32 v69, v153
	v_mov_b32_e32 v70, v153
	v_mov_b32_e32 v71, v153
	v_mov_b32_e32 v72, 0
	v_mov_b32_e32 v73, v153
	v_mov_b32_e32 v74, v153
	v_mov_b32_e32 v75, v153
	v_mov_b32_e32 v76, 0
	v_mov_b32_e32 v77, v153
	v_mov_b32_e32 v78, v153
	v_mov_b32_e32 v79, v153
	v_mov_b32_e32 v80, 0
	v_mov_b32_e32 v81, v153
	v_mov_b32_e32 v82, v153
	v_mov_b32_e32 v83, v153
	v_mov_b32_e32 v84, 0
	v_mov_b32_e32 v85, v153
	v_mov_b32_e32 v86, v153
	v_mov_b32_e32 v87, v153
	v_mov_b32_e32 v88, 0
	v_mov_b32_e32 v89, v153
	v_mov_b32_e32 v90, v153
	v_mov_b32_e32 v91, v153
	v_mov_b32_e32 v92, 0
	v_mov_b32_e32 v93, v153
	v_mov_b32_e32 v94, v153
	v_mov_b32_e32 v95, v153
	v_mov_b32_e32 v96, 0
	v_mov_b32_e32 v97, v153
	v_mov_b32_e32 v98, v153
	v_mov_b32_e32 v99, v153
	v_mov_b32_e32 v100, 0
	v_mov_b32_e32 v101, v153
	v_mov_b32_e32 v102, v153
	v_mov_b32_e32 v103, v153
	v_mov_b32_e32 v104, 0
	v_mov_b32_e32 v105, v153
	v_mov_b32_e32 v106, v153
	v_mov_b32_e32 v107, v153
	v_mov_b32_e32 v108, 0
	v_mov_b32_e32 v109, v153
	v_mov_b32_e32 v110, v153
	v_mov_b32_e32 v111, v153
	v_mov_b32_e32 v112, 0
	v_mov_b32_e32 v113, v153
	v_mov_b32_e32 v114, v153
	v_mov_b32_e32 v115, v153
	v_mov_b32_e32 v116, 0
	v_mov_b32_e32 v117, v153
	v_mov_b32_e32 v118, v153
	v_mov_b32_e32 v119, v153
	v_mov_b32_e32 v144, 0
	v_mov_b32_e32 v145, v153
	v_mov_b32_e32 v146, v153
	v_mov_b32_e32 v147, v153
	v_mov_b32_e32 v148, 0
	v_mov_b32_e32 v149, v153
	v_mov_b32_e32 v150, v153
	v_mov_b32_e32 v151, v153
	s_waitcnt lgkmcnt(0)
	s_barrier
	s_cmpk_lt_u32 s2, 0x100
	s_cbranch_scc1 .Lstag_8
	s_sleep 8
.Lstag_8:
.LBB0_1737:
	s_add_i32 s26, s25, 64
	s_min_u32 s12, s26, 0x3e0
	s_lshl_b32 s12, s12, 1
	v_lshl_add_u64 v[172:173], v[154:155], 0, s[12:13]
	v_lshl_add_u64 v[176:177], v[158:159], 0, s[12:13]
	v_lshl_add_u64 v[180:181], v[160:161], 0, s[12:13]
	v_lshl_add_u64 v[184:185], v[162:163], 0, s[12:13]
	v_lshl_add_u64 v[188:189], v[156:157], 0, s[12:13]
	v_lshl_add_u64 v[192:193], v[164:165], 0, s[12:13]
	global_load_dwordx4 v[172:175], v[172:173], off
	ds_read_b128 v[196:199], v171 offset:32768
	global_load_dwordx4 v[176:179], v[176:177], off
	ds_read_b128 v[200:203], v171 offset:33792
	global_load_dwordx4 v[180:183], v[180:181], off
	ds_read_b128 v[204:207], v171 offset:34816
	global_load_dwordx4 v[184:187], v[184:185], off
	ds_read_b128 v[208:211], v171 offset:35840
	global_load_dwordx4 v[188:191], v[188:189], off
	ds_read_b128 v[212:215], v169
	global_load_dwordx4 v[192:195], v[192:193], off
	ds_read_b128 v[216:219], v169 offset:1024
	ds_read_b128 v[222:225], v169 offset:2048
	ds_read_b128 v[226:229], v169 offset:3072
	ds_read_b128 v[230:233], v169 offset:4096
	ds_read_b128 v[234:237], v169 offset:5120
	ds_read_b128 v[238:241], v169 offset:6144
	ds_read_b128 v[242:245], v169 offset:7168
	s_setprio 1
	s_waitcnt lgkmcnt(7)
	v_mfma_f32_16x16x32_bf16 v[148:151], v[196:199], v[212:215], v[148:151]
	v_mfma_f32_16x16x32_bf16 v[144:147], v[200:203], v[212:215], v[144:147]
	v_mfma_f32_16x16x32_bf16 v[116:119], v[204:207], v[212:215], v[116:119]
	v_mfma_f32_16x16x32_bf16 v[112:115], v[208:211], v[212:215], v[112:115]
	s_waitcnt vmcnt(11)
	ds_write_b128 v152, v[120:123] offset:16384
	s_waitcnt lgkmcnt(7)
	v_mfma_f32_16x16x32_bf16 v[108:111], v[196:199], v[216:219], v[108:111]
	v_mfma_f32_16x16x32_bf16 v[104:107], v[200:203], v[216:219], v[104:107]
	v_mfma_f32_16x16x32_bf16 v[100:103], v[204:207], v[216:219], v[100:103]
	v_mfma_f32_16x16x32_bf16 v[96:99], v[208:211], v[216:219], v[96:99]
	s_waitcnt vmcnt(9)
	ds_write_b128 v152, v[124:127] offset:20480
	s_waitcnt lgkmcnt(7)
	v_mfma_f32_16x16x32_bf16 v[92:95], v[196:199], v[222:225], v[92:95]
	v_mfma_f32_16x16x32_bf16 v[88:91], v[200:203], v[222:225], v[88:91]
	v_mfma_f32_16x16x32_bf16 v[84:87], v[204:207], v[222:225], v[84:87]
	v_mfma_f32_16x16x32_bf16 v[80:83], v[208:211], v[222:225], v[80:83]
	s_waitcnt vmcnt(8)
	ds_write_b128 v152, v[128:131] offset:24576
	s_waitcnt lgkmcnt(7)
	v_mfma_f32_16x16x32_bf16 v[76:79], v[196:199], v[226:229], v[76:79]
	v_mfma_f32_16x16x32_bf16 v[72:75], v[200:203], v[226:229], v[72:75]
	v_mfma_f32_16x16x32_bf16 v[68:71], v[204:207], v[226:229], v[68:71]
	v_mfma_f32_16x16x32_bf16 v[64:67], v[208:211], v[226:229], v[64:67]
	s_waitcnt vmcnt(7)
	ds_write_b128 v152, v[136:139] offset:28672
	s_waitcnt lgkmcnt(7)
	v_mfma_f32_16x16x32_bf16 v[60:63], v[196:199], v[230:233], v[60:63]
	v_mfma_f32_16x16x32_bf16 v[56:59], v[200:203], v[230:233], v[56:59]
	v_mfma_f32_16x16x32_bf16 v[52:55], v[204:207], v[230:233], v[52:55]
	v_mfma_f32_16x16x32_bf16 v[48:51], v[208:211], v[230:233], v[48:51]
	s_waitcnt vmcnt(6)
	ds_write_b128 v152, v[140:143] offset:45056
	s_waitcnt lgkmcnt(7)
	v_mfma_f32_16x16x32_bf16 v[44:47], v[196:199], v[234:237], v[44:47]
	v_mfma_f32_16x16x32_bf16 v[40:43], v[200:203], v[234:237], v[40:43]
	v_mfma_f32_16x16x32_bf16 v[36:39], v[204:207], v[234:237], v[36:39]
	v_mfma_f32_16x16x32_bf16 v[32:35], v[208:211], v[234:237], v[32:35]
	ds_write_b128 v152, v[132:135] offset:40960
	s_waitcnt lgkmcnt(7)
	v_mfma_f32_16x16x32_bf16 v[28:31], v[196:199], v[238:241], v[28:31]
	v_mfma_f32_16x16x32_bf16 v[24:27], v[200:203], v[238:241], v[24:27]
	v_mfma_f32_16x16x32_bf16 v[20:23], v[204:207], v[238:241], v[20:23]
	v_mfma_f32_16x16x32_bf16 v[16:19], v[208:211], v[238:241], v[16:19]
	s_waitcnt lgkmcnt(6)
	v_mfma_f32_16x16x32_bf16 v[12:15], v[196:199], v[242:245], v[12:15]
	v_mfma_f32_16x16x32_bf16 v[8:11], v[200:203], v[242:245], v[8:11]
	v_mfma_f32_16x16x32_bf16 v[4:7], v[204:207], v[242:245], v[4:7]
	v_mfma_f32_16x16x32_bf16 v[0:3], v[208:211], v[242:245], v[0:3]
	s_setprio 0
	s_min_u32 s12, s25, 0x380
	s_lshl_b32 s12, s12, 1
	s_mov_b32 s29, s13
	s_add_i32 s28, s12, 0xc0
	v_lshl_add_u64 v[120:121], v[154:155], 0, s[12:13]
	v_lshl_add_u64 v[124:125], v[156:157], 0, s[12:13]
	v_lshl_add_u64 v[126:127], v[158:159], 0, s[28:29]
	v_lshl_add_u64 v[128:129], v[160:161], 0, s[28:29]
	v_lshl_add_u64 v[136:137], v[162:163], 0, s[28:29]
	v_lshl_add_u64 v[140:141], v[164:165], 0, s[28:29]
	s_waitcnt lgkmcnt(0)
	s_barrier
	global_load_dwordx4 v[120:123], v[120:121], off offset:192
	ds_read_b128 v[196:199], v168 offset:40960
	global_load_dwordx4 v[132:135], v[124:125], off offset:192
	ds_read_b128 v[200:203], v168 offset:41984
	global_load_dwordx4 v[124:127], v[126:127], off
	ds_read_b128 v[204:207], v168 offset:43008
	global_load_dwordx4 v[128:131], v[128:129], off
	ds_read_b128 v[208:211], v168 offset:44032
	global_load_dwordx4 v[136:139], v[136:137], off
	ds_read_b128 v[212:215], v170
	global_load_dwordx4 v[140:143], v[140:141], off
	ds_read_b128 v[216:219], v170 offset:1024
	ds_read_b128 v[222:225], v170 offset:2048
	ds_read_b128 v[226:229], v170 offset:3072
	ds_read_b128 v[230:233], v170 offset:4096
	ds_read_b128 v[234:237], v170 offset:5120
	ds_read_b128 v[238:241], v170 offset:6144
	ds_read_b128 v[242:245], v170 offset:7168
	s_setprio 1
	s_waitcnt lgkmcnt(7)
	v_mfma_f32_16x16x32_bf16 v[148:151], v[196:199], v[212:215], v[148:151]
	v_mfma_f32_16x16x32_bf16 v[144:147], v[200:203], v[212:215], v[144:147]
	v_mfma_f32_16x16x32_bf16 v[116:119], v[204:207], v[212:215], v[116:119]
	v_mfma_f32_16x16x32_bf16 v[112:115], v[208:211], v[212:215], v[112:115]
	s_waitcnt vmcnt(11)
	ds_write_b128 v152, v[172:175]
	s_waitcnt lgkmcnt(7)
	v_mfma_f32_16x16x32_bf16 v[108:111], v[196:199], v[216:219], v[108:111]
	v_mfma_f32_16x16x32_bf16 v[104:107], v[200:203], v[216:219], v[104:107]
	v_mfma_f32_16x16x32_bf16 v[100:103], v[204:207], v[216:219], v[100:103]
	v_mfma_f32_16x16x32_bf16 v[96:99], v[208:211], v[216:219], v[96:99]
	s_waitcnt vmcnt(10)
	ds_write_b128 v152, v[176:179] offset:4096
	s_waitcnt lgkmcnt(7)
	v_mfma_f32_16x16x32_bf16 v[92:95], v[196:199], v[222:225], v[92:95]
	v_mfma_f32_16x16x32_bf16 v[88:91], v[200:203], v[222:225], v[88:91]
	v_mfma_f32_16x16x32_bf16 v[84:87], v[204:207], v[222:225], v[84:87]
	v_mfma_f32_16x16x32_bf16 v[80:83], v[208:211], v[222:225], v[80:83]
	s_waitcnt vmcnt(9)
	ds_write_b128 v152, v[180:183] offset:8192
	s_waitcnt lgkmcnt(7)
	v_mfma_f32_16x16x32_bf16 v[76:79], v[196:199], v[226:229], v[76:79]
	v_mfma_f32_16x16x32_bf16 v[72:75], v[200:203], v[226:229], v[72:75]
	v_mfma_f32_16x16x32_bf16 v[68:71], v[204:207], v[226:229], v[68:71]
	v_mfma_f32_16x16x32_bf16 v[64:67], v[208:211], v[226:229], v[64:67]
	s_waitcnt vmcnt(8)
	ds_write_b128 v152, v[184:187] offset:12288
	s_waitcnt lgkmcnt(7)
	v_mfma_f32_16x16x32_bf16 v[60:63], v[196:199], v[230:233], v[60:63]
	v_mfma_f32_16x16x32_bf16 v[56:59], v[200:203], v[230:233], v[56:59]
	v_mfma_f32_16x16x32_bf16 v[52:55], v[204:207], v[230:233], v[52:55]
	v_mfma_f32_16x16x32_bf16 v[48:51], v[208:211], v[230:233], v[48:51]
	s_waitcnt vmcnt(7)
	ds_write_b128 v152, v[188:191] offset:32768
	s_waitcnt lgkmcnt(7)
	v_mfma_f32_16x16x32_bf16 v[44:47], v[196:199], v[234:237], v[44:47]
	v_mfma_f32_16x16x32_bf16 v[40:43], v[200:203], v[234:237], v[40:43]
	v_mfma_f32_16x16x32_bf16 v[36:39], v[204:207], v[234:237], v[36:39]
	v_mfma_f32_16x16x32_bf16 v[32:35], v[208:211], v[234:237], v[32:35]
	s_waitcnt vmcnt(6)
	ds_write_b128 v152, v[192:195] offset:36864
	s_waitcnt lgkmcnt(7)
	v_mfma_f32_16x16x32_bf16 v[28:31], v[196:199], v[238:241], v[28:31]
	v_mfma_f32_16x16x32_bf16 v[24:27], v[200:203], v[238:241], v[24:27]
	v_mfma_f32_16x16x32_bf16 v[20:23], v[204:207], v[238:241], v[20:23]
	v_mfma_f32_16x16x32_bf16 v[16:19], v[208:211], v[238:241], v[16:19]
	s_waitcnt lgkmcnt(6)
	v_mfma_f32_16x16x32_bf16 v[12:15], v[196:199], v[242:245], v[12:15]
	v_mfma_f32_16x16x32_bf16 v[8:11], v[200:203], v[242:245], v[8:11]
	v_mfma_f32_16x16x32_bf16 v[4:7], v[204:207], v[242:245], v[4:7]
	v_mfma_f32_16x16x32_bf16 v[0:3], v[208:211], v[242:245], v[0:3]
	s_setprio 0
	s_add_i32 s21, s21, 2
	s_cmp_lt_u32 s21, 30
	s_mov_b32 s25, s26
	s_waitcnt lgkmcnt(0)
	s_barrier
	s_cbranch_scc1 .LBB0_1737
	s_waitcnt vmcnt(5)
	v_mov_b32_e32 v120, v220
	s_nop 0
	v_and_b32_e32 v122, 0xffffff80, v120
	v_add_u32_e32 v122, s20, v122
	v_and_b32_e32 v121, 64, v120
	v_and_or_b32 v122, v120, 15, v122
	v_lshrrev_b32_e32 v120, 2, v120
	v_and_b32_e32 v120, 12, v120
	v_or3_b32 v120, v121, v120, s24
	v_ashrrev_i32_e32 v121, 31, v120
	v_ashrrev_i32_e32 v123, 31, v122
	v_lshl_add_u64 v[120:121], v[120:121], 1, s[10:11]
	s_waitcnt vmcnt(3)
	v_lshl_add_u64 v[124:125], v[122:123], 2, s[0:1]
	v_lshlrev_b64 v[126:127], 12, v[122:123]
	v_lshl_add_u64 v[162:163], v[120:121], 0, v[126:127]
	global_load_dword v152, v[124:125], off
	global_load_dwordx2 v[168:169], v[162:163], off
	global_load_dwordx2 v[170:171], v[162:163], off offset:32
	global_load_dwordx2 v[172:173], v[162:163], off offset:64
	v_or_b32_e32 v124, 16, v122
	v_ashrrev_i32_e32 v125, 31, v124
	v_lshl_add_u64 v[126:127], v[124:125], 2, s[0:1]
	v_lshlrev_b64 v[124:125], 12, v[124:125]
	s_waitcnt vmcnt(4)
	v_lshl_add_u64 v[142:143], v[120:121], 0, v[124:125]
	v_or_b32_e32 v124, 32, v122
	v_ashrrev_i32_e32 v125, 31, v124
	global_load_dwordx2 v[174:175], v[162:163], off offset:96
	global_load_dword v176, v[126:127], off
	global_load_dwordx2 v[164:165], v[142:143], off
	global_load_dwordx2 v[160:161], v[142:143], off offset:32
	v_lshl_add_u64 v[126:127], v[124:125], 2, s[0:1]
	v_lshlrev_b64 v[124:125], 12, v[124:125]
	v_lshl_add_u64 v[132:133], v[120:121], 0, v[124:125]
	v_or_b32_e32 v124, 48, v122
	v_ashrrev_i32_e32 v125, 31, v124
	global_load_dwordx2 v[158:159], v[142:143], off offset:64
	global_load_dwordx2 v[156:157], v[142:143], off offset:96
	global_load_dword v177, v[126:127], off
	global_load_dwordx2 v[154:155], v[132:133], off
	v_lshl_add_u64 v[126:127], v[124:125], 2, s[0:1]
	v_lshlrev_b64 v[124:125], 12, v[124:125]
	v_lshl_add_u64 v[124:125], v[120:121], 0, v[124:125]
	global_load_dwordx2 v[140:141], v[132:133], off offset:32
	global_load_dwordx2 v[138:139], v[132:133], off offset:64
	global_load_dwordx2 v[136:137], v[132:133], off offset:96
	global_load_dword v123, v[126:127], off
	global_load_dwordx2 v[134:135], v[124:125], off
	global_load_dwordx2 v[130:131], v[124:125], off offset:32
	global_load_dwordx2 v[128:129], v[124:125], off offset:64
	s_nop 0
	global_load_dwordx2 v[126:127], v[124:125], off offset:96
	s_waitcnt vmcnt(19)
	v_fmamk_f32 v152, v152, 0x3a800000, v167
	v_mul_f32_e32 v178, 0x4b800000, v152
	v_cmp_gt_f32_e32 vcc, s22, v152
	s_nop 1
	v_cndmask_b32_e32 v152, v152, v178, vcc
	v_rsq_f32_e32 v152, v152
	s_waitcnt vmcnt(18)
	v_lshlrev_b32_e32 v178, 16, v168
	v_and_b32_e32 v168, 0xffff0000, v168
	v_mul_f32_e32 v179, 0x45800000, v152
	v_cndmask_b32_e32 v152, v152, v179, vcc
	v_mul_f32_e32 v148, v148, v152
	v_mul_f32_e32 v180, 0xbfb8aa3b, v148
	v_exp_f32_e32 v180, v180
	v_mul_f32_e32 v149, v149, v152
	v_mul_f32_e32 v181, 0xbfb8aa3b, v149
	v_exp_f32_e32 v181, v181
	v_add_f32_e32 v180, 1.0, v180
	v_rcp_f32_e32 v180, v180
	v_mul_f32_e32 v150, v150, v152
	v_mul_f32_e32 v151, v151, v152
	v_lshlrev_b32_e32 v179, 16, v169
	v_mul_f32_e32 v148, v148, v180
	v_mul_f32_e32 v148, v148, v178
	v_add_f32_e32 v178, 1.0, v181
	v_mul_f32_e32 v180, 0xbfb8aa3b, v150
	v_mul_f32_e32 v181, 0xbfb8aa3b, v151
	v_rcp_f32_e32 v178, v178
	v_exp_f32_e32 v180, v180
	v_exp_f32_e32 v181, v181
	v_and_b32_e32 v169, 0xffff0000, v169
	v_mul_f32_e32 v149, v149, v178
	v_add_f32_e32 v178, 1.0, v180
	v_add_f32_e32 v180, 1.0, v181
	v_rcp_f32_e32 v180, v180
	v_rcp_f32_e32 v178, v178
	v_mul_f32_e32 v149, v149, v168
	v_mul_f32_e32 v144, v144, v152
	v_mul_f32_e32 v151, v151, v180
	v_mul_f32_e32 v150, v150, v178
	v_mul_f32_e32 v151, v151, v169
	v_mul_f32_e32 v150, v150, v179
	v_cvt_pk_bf16_f32 v148, v148, v149
	v_cvt_pk_bf16_f32 v149, v150, v151
	v_mul_f32_e32 v151, 0xbfb8aa3b, v144
	v_exp_f32_e32 v151, v151
	v_mul_f32_e32 v145, v145, v152
	v_mul_f32_e32 v169, 0xbfb8aa3b, v145
	v_exp_f32_e32 v169, v169
	v_add_f32_e32 v151, 1.0, v151
	v_rcp_f32_e32 v151, v151
	global_store_dwordx2 v[162:163], v[148:149], off
	s_waitcnt vmcnt(18)
	v_lshlrev_b32_e32 v148, 16, v170
	v_mul_f32_e32 v146, v146, v152
	v_mul_f32_e32 v147, v147, v152
	v_mul_f32_e32 v144, v144, v151
	v_mul_f32_e32 v144, v144, v148
	v_add_f32_e32 v148, 1.0, v169
	v_mul_f32_e32 v151, 0xbfb8aa3b, v146
	v_mul_f32_e32 v169, 0xbfb8aa3b, v147
	v_rcp_f32_e32 v148, v148
	v_exp_f32_e32 v151, v151
	v_exp_f32_e32 v169, v169
	v_and_b32_e32 v149, 0xffff0000, v170
	v_mul_f32_e32 v145, v145, v148
	v_add_f32_e32 v148, 1.0, v151
	v_add_f32_e32 v151, 1.0, v169
	v_rcp_f32_e32 v151, v151
	v_rcp_f32_e32 v148, v148
	v_and_b32_e32 v168, 0xffff0000, v171
	v_lshlrev_b32_e32 v150, 16, v171
	v_mul_f32_e32 v147, v147, v151
	v_mul_f32_e32 v145, v145, v149
	v_mul_f32_e32 v146, v146, v148
	v_mul_f32_e32 v147, v147, v168
	v_mul_f32_e32 v116, v116, v152
	v_mul_f32_e32 v146, v146, v150
	v_cvt_pk_bf16_f32 v144, v144, v145
	v_cvt_pk_bf16_f32 v145, v146, v147
	v_mul_f32_e32 v147, 0xbfb8aa3b, v116
	v_exp_f32_e32 v147, v147
	v_mul_f32_e32 v117, v117, v152
	v_mul_f32_e32 v149, 0xbfb8aa3b, v117
	v_exp_f32_e32 v149, v149
	v_add_f32_e32 v147, 1.0, v147
	v_rcp_f32_e32 v147, v147
	global_store_dwordx2 v[162:163], v[144:145], off offset:32
	s_waitcnt vmcnt(18)
	v_lshlrev_b32_e32 v144, 16, v172
	v_mul_f32_e32 v118, v118, v152
	v_mul_f32_e32 v119, v119, v152
	v_mul_f32_e32 v116, v116, v147
	v_mul_f32_e32 v116, v116, v144
	v_add_f32_e32 v144, 1.0, v149
	v_mul_f32_e32 v147, 0xbfb8aa3b, v118
	v_mul_f32_e32 v149, 0xbfb8aa3b, v119
	v_rcp_f32_e32 v144, v144
	v_exp_f32_e32 v147, v147
	v_exp_f32_e32 v149, v149
	v_and_b32_e32 v145, 0xffff0000, v172
	v_mul_f32_e32 v117, v117, v144
	v_add_f32_e32 v144, 1.0, v147
	v_add_f32_e32 v147, 1.0, v149
	v_rcp_f32_e32 v147, v147
	v_rcp_f32_e32 v144, v144
	v_and_b32_e32 v148, 0xffff0000, v173
	v_lshlrev_b32_e32 v146, 16, v173
	v_mul_f32_e32 v119, v119, v147
	v_mul_f32_e32 v117, v117, v145
	v_mul_f32_e32 v118, v118, v144
	v_mul_f32_e32 v119, v119, v148
	v_mul_f32_e32 v112, v112, v152
	v_mul_f32_e32 v118, v118, v146
	v_cvt_pk_bf16_f32 v116, v116, v117
	v_cvt_pk_bf16_f32 v117, v118, v119
	v_mul_f32_e32 v119, 0xbfb8aa3b, v112
	v_exp_f32_e32 v119, v119
	v_mul_f32_e32 v113, v113, v152
	v_mul_f32_e32 v145, 0xbfb8aa3b, v113
	v_exp_f32_e32 v145, v145
	v_add_f32_e32 v119, 1.0, v119
	v_rcp_f32_e32 v119, v119
	global_store_dwordx2 v[162:163], v[116:117], off offset:64
	s_waitcnt vmcnt(18)
	v_lshlrev_b32_e32 v116, 16, v174
	v_mul_f32_e32 v114, v114, v152
	v_mul_f32_e32 v112, v112, v119
	v_mul_f32_e32 v112, v112, v116
	v_add_f32_e32 v116, 1.0, v145
	v_mul_f32_e32 v119, 0xbfb8aa3b, v114
	v_rcp_f32_e32 v116, v116
	v_exp_f32_e32 v119, v119
	v_mul_f32_e32 v115, v115, v152
	v_mul_f32_e32 v145, 0xbfb8aa3b, v115
	v_mul_f32_e32 v113, v113, v116
	v_add_f32_e32 v116, 1.0, v119
	v_rcp_f32_e32 v116, v116
	v_exp_f32_e32 v145, v145
	v_and_b32_e32 v117, 0xffff0000, v174
	v_mul_f32_e32 v113, v113, v117
	v_mul_f32_e32 v114, v114, v116
	s_waitcnt vmcnt(17)
	v_fmamk_f32 v116, v176, 0x3a800000, v167
	v_add_f32_e32 v119, 1.0, v145
	v_mul_f32_e32 v117, 0x4b800000, v116
	v_cmp_gt_f32_e32 vcc, s22, v116
	v_rcp_f32_e32 v119, v119
	v_lshlrev_b32_e32 v118, 16, v175
	v_cndmask_b32_e32 v116, v116, v117, vcc
	v_rsq_f32_e32 v116, v116
	v_and_b32_e32 v144, 0xffff0000, v175
	v_mul_f32_e32 v115, v115, v119
	v_cvt_pk_bf16_f32 v112, v112, v113
	v_mul_f32_e32 v114, v114, v118
	v_mul_f32_e32 v115, v115, v144
	v_cvt_pk_bf16_f32 v113, v114, v115
	global_store_dwordx2 v[162:163], v[112:113], off offset:96
	v_mul_f32_e32 v112, 0x45800000, v116
	v_cndmask_b32_e32 v112, v116, v112, vcc
	v_mul_f32_e32 v108, v108, v112
	v_mul_f32_e32 v116, 0xbfb8aa3b, v108
	v_exp_f32_e32 v116, v116
	v_mul_f32_e32 v109, v109, v112
	v_mul_f32_e32 v118, 0xbfb8aa3b, v109
	v_exp_f32_e32 v118, v118
	v_add_f32_e32 v116, 1.0, v116
	v_rcp_f32_e32 v116, v116
	s_waitcnt vmcnt(17)
	v_lshlrev_b32_e32 v113, 16, v164
	v_mul_f32_e32 v110, v110, v112
	v_mul_f32_e32 v111, v111, v112
	v_mul_f32_e32 v108, v108, v116
	v_mul_f32_e32 v108, v108, v113
	v_add_f32_e32 v113, 1.0, v118
	v_mul_f32_e32 v116, 0xbfb8aa3b, v110
	v_mul_f32_e32 v118, 0xbfb8aa3b, v111
	v_rcp_f32_e32 v113, v113
	v_exp_f32_e32 v116, v116
	v_exp_f32_e32 v118, v118
	v_and_b32_e32 v114, 0xffff0000, v164
	v_mul_f32_e32 v109, v109, v113
	v_add_f32_e32 v113, 1.0, v116
	v_add_f32_e32 v116, 1.0, v118
	v_rcp_f32_e32 v116, v116
	v_rcp_f32_e32 v113, v113
	v_and_b32_e32 v117, 0xffff0000, v165
	v_lshlrev_b32_e32 v115, 16, v165
	v_mul_f32_e32 v111, v111, v116
	v_mul_f32_e32 v109, v109, v114
	v_mul_f32_e32 v110, v110, v113
	v_mul_f32_e32 v111, v111, v117
	v_mul_f32_e32 v104, v104, v112
	v_mul_f32_e32 v110, v110, v115
	v_cvt_pk_bf16_f32 v108, v108, v109
	v_cvt_pk_bf16_f32 v109, v110, v111
	v_mul_f32_e32 v111, 0xbfb8aa3b, v104
	v_exp_f32_e32 v111, v111
	v_mul_f32_e32 v105, v105, v112
	v_mul_f32_e32 v114, 0xbfb8aa3b, v105
	v_exp_f32_e32 v114, v114
	v_add_f32_e32 v111, 1.0, v111
	v_rcp_f32_e32 v111, v111
	global_store_dwordx2 v[142:143], v[108:109], off
	s_waitcnt vmcnt(17)
	v_lshlrev_b32_e32 v108, 16, v160
	v_mul_f32_e32 v106, v106, v112
	v_mul_f32_e32 v107, v107, v112
	v_mul_f32_e32 v104, v104, v111
	v_mul_f32_e32 v104, v104, v108
	v_add_f32_e32 v108, 1.0, v114
	v_mul_f32_e32 v111, 0xbfb8aa3b, v106
	v_mul_f32_e32 v114, 0xbfb8aa3b, v107
	v_rcp_f32_e32 v108, v108
	v_exp_f32_e32 v111, v111
	v_exp_f32_e32 v114, v114
	v_and_b32_e32 v109, 0xffff0000, v160
	v_mul_f32_e32 v105, v105, v108
	v_add_f32_e32 v108, 1.0, v111
	v_add_f32_e32 v111, 1.0, v114
	v_rcp_f32_e32 v111, v111
	v_rcp_f32_e32 v108, v108
	v_and_b32_e32 v113, 0xffff0000, v161
	v_lshlrev_b32_e32 v110, 16, v161
	v_mul_f32_e32 v107, v107, v111
	v_mul_f32_e32 v105, v105, v109
	v_mul_f32_e32 v106, v106, v108
	v_mul_f32_e32 v107, v107, v113
	v_mul_f32_e32 v100, v100, v112
	v_mul_f32_e32 v106, v106, v110
	v_cvt_pk_bf16_f32 v104, v104, v105
	v_cvt_pk_bf16_f32 v105, v106, v107
	v_mul_f32_e32 v107, 0xbfb8aa3b, v100
	v_exp_f32_e32 v107, v107
	v_mul_f32_e32 v101, v101, v112
	v_mul_f32_e32 v109, 0xbfb8aa3b, v101
	v_exp_f32_e32 v109, v109
	v_add_f32_e32 v107, 1.0, v107
	v_rcp_f32_e32 v107, v107
	global_store_dwordx2 v[142:143], v[104:105], off offset:32
	s_waitcnt vmcnt(17)
	v_lshlrev_b32_e32 v104, 16, v158
	v_mul_f32_e32 v102, v102, v112
	v_mul_f32_e32 v103, v103, v112
	v_mul_f32_e32 v100, v100, v107
	v_mul_f32_e32 v100, v100, v104
	v_add_f32_e32 v104, 1.0, v109
	v_mul_f32_e32 v107, 0xbfb8aa3b, v102
	v_mul_f32_e32 v109, 0xbfb8aa3b, v103
	v_rcp_f32_e32 v104, v104
	v_exp_f32_e32 v107, v107
	v_exp_f32_e32 v109, v109
	v_and_b32_e32 v105, 0xffff0000, v158
	v_mul_f32_e32 v101, v101, v104
	v_add_f32_e32 v104, 1.0, v107
	v_add_f32_e32 v107, 1.0, v109
	v_rcp_f32_e32 v107, v107
	v_rcp_f32_e32 v104, v104
	v_and_b32_e32 v108, 0xffff0000, v159
	v_lshlrev_b32_e32 v106, 16, v159
	v_mul_f32_e32 v103, v103, v107
	v_mul_f32_e32 v101, v101, v105
	v_mul_f32_e32 v102, v102, v104
	v_mul_f32_e32 v103, v103, v108
	v_mul_f32_e32 v96, v96, v112
	v_mul_f32_e32 v102, v102, v106
	v_cvt_pk_bf16_f32 v100, v100, v101
	v_cvt_pk_bf16_f32 v101, v102, v103
	v_mul_f32_e32 v103, 0xbfb8aa3b, v96
	v_exp_f32_e32 v103, v103
	v_mul_f32_e32 v97, v97, v112
	v_mul_f32_e32 v105, 0xbfb8aa3b, v97
	v_exp_f32_e32 v105, v105
	v_add_f32_e32 v103, 1.0, v103
	v_rcp_f32_e32 v103, v103
	global_store_dwordx2 v[142:143], v[100:101], off offset:64
	s_waitcnt vmcnt(17)
	v_lshlrev_b32_e32 v100, 16, v156
	v_mul_f32_e32 v98, v98, v112
	v_mul_f32_e32 v96, v96, v103
	v_mul_f32_e32 v96, v96, v100
	v_add_f32_e32 v100, 1.0, v105
	v_mul_f32_e32 v103, 0xbfb8aa3b, v98
	v_rcp_f32_e32 v100, v100
	v_exp_f32_e32 v103, v103
	v_mul_f32_e32 v99, v99, v112
	v_mul_f32_e32 v105, 0xbfb8aa3b, v99
	v_mul_f32_e32 v97, v97, v100
	v_add_f32_e32 v100, 1.0, v103
	v_rcp_f32_e32 v100, v100
	v_exp_f32_e32 v105, v105
	v_and_b32_e32 v101, 0xffff0000, v156
	v_mul_f32_e32 v97, v97, v101
	v_mul_f32_e32 v98, v98, v100
	s_waitcnt vmcnt(16)
	v_fmamk_f32 v100, v177, 0x3a800000, v167
	v_add_f32_e32 v103, 1.0, v105
	v_mul_f32_e32 v101, 0x4b800000, v100
	v_cmp_gt_f32_e32 vcc, s22, v100
	v_rcp_f32_e32 v103, v103
	v_lshlrev_b32_e32 v102, 16, v157
	v_cndmask_b32_e32 v100, v100, v101, vcc
	v_rsq_f32_e32 v100, v100
	v_and_b32_e32 v104, 0xffff0000, v157
	v_mul_f32_e32 v99, v99, v103
	v_cvt_pk_bf16_f32 v96, v96, v97
	v_mul_f32_e32 v98, v98, v102
	v_mul_f32_e32 v99, v99, v104
	v_cvt_pk_bf16_f32 v97, v98, v99
	global_store_dwordx2 v[142:143], v[96:97], off offset:96
	v_mul_f32_e32 v96, 0x45800000, v100
	v_cndmask_b32_e32 v96, v100, v96, vcc
	v_mul_f32_e32 v92, v92, v96
	v_mul_f32_e32 v100, 0xbfb8aa3b, v92
	v_exp_f32_e32 v100, v100
	v_mul_f32_e32 v93, v93, v96
	v_mul_f32_e32 v102, 0xbfb8aa3b, v93
	v_exp_f32_e32 v102, v102
	v_add_f32_e32 v100, 1.0, v100
	v_rcp_f32_e32 v100, v100
	s_waitcnt vmcnt(16)
	v_lshlrev_b32_e32 v97, 16, v154
	v_mul_f32_e32 v94, v94, v96
	v_mul_f32_e32 v95, v95, v96
	v_mul_f32_e32 v92, v92, v100
	v_mul_f32_e32 v92, v92, v97
	v_add_f32_e32 v97, 1.0, v102
	v_mul_f32_e32 v100, 0xbfb8aa3b, v94
	v_mul_f32_e32 v102, 0xbfb8aa3b, v95
	v_rcp_f32_e32 v97, v97
	v_exp_f32_e32 v100, v100
	v_exp_f32_e32 v102, v102
	v_and_b32_e32 v98, 0xffff0000, v154
	v_mul_f32_e32 v93, v93, v97
	v_add_f32_e32 v97, 1.0, v100
	v_add_f32_e32 v100, 1.0, v102
	v_rcp_f32_e32 v100, v100
	v_rcp_f32_e32 v97, v97
	v_and_b32_e32 v101, 0xffff0000, v155
	v_lshlrev_b32_e32 v99, 16, v155
	v_mul_f32_e32 v95, v95, v100
	v_mul_f32_e32 v93, v93, v98
	v_mul_f32_e32 v94, v94, v97
	v_mul_f32_e32 v95, v95, v101
	v_mul_f32_e32 v88, v88, v96
	v_mul_f32_e32 v94, v94, v99
	v_cvt_pk_bf16_f32 v92, v92, v93
	v_cvt_pk_bf16_f32 v93, v94, v95
	v_mul_f32_e32 v95, 0xbfb8aa3b, v88
	v_exp_f32_e32 v95, v95
	v_mul_f32_e32 v89, v89, v96
	v_mul_f32_e32 v98, 0xbfb8aa3b, v89
	v_exp_f32_e32 v98, v98
	v_add_f32_e32 v95, 1.0, v95
	v_rcp_f32_e32 v95, v95
	global_store_dwordx2 v[132:133], v[92:93], off
	s_waitcnt vmcnt(16)
	v_lshlrev_b32_e32 v92, 16, v140
	v_mul_f32_e32 v90, v90, v96
	v_mul_f32_e32 v91, v91, v96
	v_mul_f32_e32 v88, v88, v95
	v_mul_f32_e32 v88, v88, v92
	v_add_f32_e32 v92, 1.0, v98
	v_mul_f32_e32 v95, 0xbfb8aa3b, v90
	v_mul_f32_e32 v98, 0xbfb8aa3b, v91
	v_rcp_f32_e32 v92, v92
	v_exp_f32_e32 v95, v95
	v_exp_f32_e32 v98, v98
	v_and_b32_e32 v93, 0xffff0000, v140
	v_mul_f32_e32 v89, v89, v92
	v_add_f32_e32 v92, 1.0, v95
	v_add_f32_e32 v95, 1.0, v98
	v_rcp_f32_e32 v95, v95
	v_rcp_f32_e32 v92, v92
	v_and_b32_e32 v97, 0xffff0000, v141
	v_lshlrev_b32_e32 v94, 16, v141
	v_mul_f32_e32 v91, v91, v95
	v_mul_f32_e32 v89, v89, v93
	v_mul_f32_e32 v90, v90, v92
	v_mul_f32_e32 v91, v91, v97
	v_mul_f32_e32 v84, v84, v96
	v_mul_f32_e32 v90, v90, v94
	v_cvt_pk_bf16_f32 v88, v88, v89
	v_cvt_pk_bf16_f32 v89, v90, v91
	v_mul_f32_e32 v91, 0xbfb8aa3b, v84
	v_exp_f32_e32 v91, v91
	v_mul_f32_e32 v85, v85, v96
	v_mul_f32_e32 v93, 0xbfb8aa3b, v85
	v_exp_f32_e32 v93, v93
	v_add_f32_e32 v91, 1.0, v91
	v_rcp_f32_e32 v91, v91
	global_store_dwordx2 v[132:133], v[88:89], off offset:32
	s_waitcnt vmcnt(16)
	v_lshlrev_b32_e32 v88, 16, v138
	v_mul_f32_e32 v86, v86, v96
	v_mul_f32_e32 v87, v87, v96
	v_mul_f32_e32 v84, v84, v91
	v_mul_f32_e32 v84, v84, v88
	v_add_f32_e32 v88, 1.0, v93
	v_mul_f32_e32 v91, 0xbfb8aa3b, v86
	v_mul_f32_e32 v93, 0xbfb8aa3b, v87
	v_rcp_f32_e32 v88, v88
	v_exp_f32_e32 v91, v91
	v_exp_f32_e32 v93, v93
	v_and_b32_e32 v89, 0xffff0000, v138
	v_mul_f32_e32 v85, v85, v88
	v_add_f32_e32 v88, 1.0, v91
	v_add_f32_e32 v91, 1.0, v93
	v_rcp_f32_e32 v91, v91
	v_rcp_f32_e32 v88, v88
	v_and_b32_e32 v92, 0xffff0000, v139
	v_lshlrev_b32_e32 v90, 16, v139
	v_mul_f32_e32 v87, v87, v91
	v_mul_f32_e32 v85, v85, v89
	v_mul_f32_e32 v86, v86, v88
	v_mul_f32_e32 v87, v87, v92
	v_mul_f32_e32 v80, v80, v96
	v_mul_f32_e32 v86, v86, v90
	v_cvt_pk_bf16_f32 v84, v84, v85
	v_cvt_pk_bf16_f32 v85, v86, v87
	v_mul_f32_e32 v87, 0xbfb8aa3b, v80
	v_exp_f32_e32 v87, v87
	v_mul_f32_e32 v81, v81, v96
	v_mul_f32_e32 v89, 0xbfb8aa3b, v81
	v_exp_f32_e32 v89, v89
	v_add_f32_e32 v87, 1.0, v87
	v_rcp_f32_e32 v87, v87
	global_store_dwordx2 v[132:133], v[84:85], off offset:64
	s_waitcnt vmcnt(16)
	v_lshlrev_b32_e32 v84, 16, v136
	v_mul_f32_e32 v82, v82, v96
	v_mul_f32_e32 v80, v80, v87
	v_mul_f32_e32 v80, v80, v84
	v_add_f32_e32 v84, 1.0, v89
	v_mul_f32_e32 v87, 0xbfb8aa3b, v82
	v_rcp_f32_e32 v84, v84
	v_exp_f32_e32 v87, v87
	v_mul_f32_e32 v83, v83, v96
	v_mul_f32_e32 v89, 0xbfb8aa3b, v83
	v_mul_f32_e32 v81, v81, v84
	v_add_f32_e32 v84, 1.0, v87
	v_rcp_f32_e32 v84, v84
	v_exp_f32_e32 v89, v89
	v_and_b32_e32 v85, 0xffff0000, v136
	v_mul_f32_e32 v81, v81, v85
	v_mul_f32_e32 v82, v82, v84
	s_waitcnt vmcnt(15)
	v_fmamk_f32 v84, v123, 0x3a800000, v167
	v_add_f32_e32 v87, 1.0, v89
	v_mul_f32_e32 v85, 0x4b800000, v84
	v_cmp_gt_f32_e32 vcc, s22, v84
	v_rcp_f32_e32 v87, v87
	v_lshlrev_b32_e32 v86, 16, v137
	v_cndmask_b32_e32 v84, v84, v85, vcc
	v_rsq_f32_e32 v84, v84
	v_and_b32_e32 v88, 0xffff0000, v137
	v_mul_f32_e32 v83, v83, v87
	v_cvt_pk_bf16_f32 v80, v80, v81
	v_mul_f32_e32 v82, v82, v86
	v_mul_f32_e32 v83, v83, v88
	v_cvt_pk_bf16_f32 v81, v82, v83
	global_store_dwordx2 v[132:133], v[80:81], off offset:96
	v_mul_f32_e32 v80, 0x45800000, v84
	v_cndmask_b32_e32 v80, v84, v80, vcc
	v_mul_f32_e32 v76, v76, v80
	v_mul_f32_e32 v84, 0xbfb8aa3b, v76
	v_exp_f32_e32 v84, v84
	v_mul_f32_e32 v77, v77, v80
	v_mul_f32_e32 v86, 0xbfb8aa3b, v77
	v_exp_f32_e32 v86, v86
	v_add_f32_e32 v84, 1.0, v84
	v_rcp_f32_e32 v84, v84
	s_waitcnt vmcnt(15)
	v_lshlrev_b32_e32 v81, 16, v134
	v_mul_f32_e32 v78, v78, v80
	v_mul_f32_e32 v79, v79, v80
	v_mul_f32_e32 v76, v76, v84
	v_mul_f32_e32 v76, v76, v81
	v_add_f32_e32 v81, 1.0, v86
	v_mul_f32_e32 v84, 0xbfb8aa3b, v78
	v_mul_f32_e32 v86, 0xbfb8aa3b, v79
	v_rcp_f32_e32 v81, v81
	v_exp_f32_e32 v84, v84
	v_exp_f32_e32 v86, v86
	v_and_b32_e32 v82, 0xffff0000, v134
	v_mul_f32_e32 v77, v77, v81
	v_add_f32_e32 v81, 1.0, v84
	v_add_f32_e32 v84, 1.0, v86
	v_rcp_f32_e32 v84, v84
	v_rcp_f32_e32 v81, v81
	v_and_b32_e32 v85, 0xffff0000, v135
	v_lshlrev_b32_e32 v83, 16, v135
	v_mul_f32_e32 v79, v79, v84
	v_mul_f32_e32 v77, v77, v82
	v_mul_f32_e32 v78, v78, v81
	v_mul_f32_e32 v79, v79, v85
	v_mul_f32_e32 v72, v72, v80
	v_mul_f32_e32 v78, v78, v83
	v_cvt_pk_bf16_f32 v76, v76, v77
	v_cvt_pk_bf16_f32 v77, v78, v79
	v_mul_f32_e32 v79, 0xbfb8aa3b, v72
	v_exp_f32_e32 v79, v79
	v_mul_f32_e32 v73, v73, v80
	v_mul_f32_e32 v82, 0xbfb8aa3b, v73
	v_exp_f32_e32 v82, v82
	v_add_f32_e32 v79, 1.0, v79
	v_rcp_f32_e32 v79, v79
	global_store_dwordx2 v[124:125], v[76:77], off
	s_waitcnt vmcnt(15)
	v_lshlrev_b32_e32 v76, 16, v130
	v_mul_f32_e32 v74, v74, v80
	v_mul_f32_e32 v75, v75, v80
	v_mul_f32_e32 v72, v72, v79
	v_mul_f32_e32 v72, v72, v76
	v_add_f32_e32 v76, 1.0, v82
	v_mul_f32_e32 v79, 0xbfb8aa3b, v74
	v_mul_f32_e32 v82, 0xbfb8aa3b, v75
	v_rcp_f32_e32 v76, v76
	v_exp_f32_e32 v79, v79
	v_exp_f32_e32 v82, v82
	v_and_b32_e32 v77, 0xffff0000, v130
	v_mul_f32_e32 v73, v73, v76
	v_add_f32_e32 v76, 1.0, v79
	v_add_f32_e32 v79, 1.0, v82
	v_rcp_f32_e32 v79, v79
	v_rcp_f32_e32 v76, v76
	v_and_b32_e32 v81, 0xffff0000, v131
	v_lshlrev_b32_e32 v78, 16, v131
	v_mul_f32_e32 v75, v75, v79
	v_mul_f32_e32 v73, v73, v77
	v_mul_f32_e32 v74, v74, v76
	v_mul_f32_e32 v75, v75, v81
	v_mul_f32_e32 v68, v68, v80
	v_mul_f32_e32 v74, v74, v78
	v_cvt_pk_bf16_f32 v72, v72, v73
	v_cvt_pk_bf16_f32 v73, v74, v75
	v_mul_f32_e32 v75, 0xbfb8aa3b, v68
	v_exp_f32_e32 v75, v75
	v_mul_f32_e32 v69, v69, v80
	v_mul_f32_e32 v77, 0xbfb8aa3b, v69
	v_exp_f32_e32 v77, v77
	v_add_f32_e32 v75, 1.0, v75
	v_rcp_f32_e32 v75, v75
	global_store_dwordx2 v[124:125], v[72:73], off offset:32
	s_waitcnt vmcnt(15)
	v_lshlrev_b32_e32 v72, 16, v128
	v_mul_f32_e32 v70, v70, v80
	v_mul_f32_e32 v71, v71, v80
	v_mul_f32_e32 v68, v68, v75
	v_mul_f32_e32 v68, v68, v72
	v_add_f32_e32 v72, 1.0, v77
	v_mul_f32_e32 v75, 0xbfb8aa3b, v70
	v_mul_f32_e32 v77, 0xbfb8aa3b, v71
	v_rcp_f32_e32 v72, v72
	v_exp_f32_e32 v75, v75
	v_exp_f32_e32 v77, v77
	v_and_b32_e32 v73, 0xffff0000, v128
	v_mul_f32_e32 v69, v69, v72
	v_add_f32_e32 v72, 1.0, v75
	v_add_f32_e32 v75, 1.0, v77
	v_rcp_f32_e32 v75, v75
	v_rcp_f32_e32 v72, v72
	v_and_b32_e32 v76, 0xffff0000, v129
	v_lshlrev_b32_e32 v74, 16, v129
	v_mul_f32_e32 v71, v71, v75
	v_mul_f32_e32 v69, v69, v73
	v_mul_f32_e32 v70, v70, v72
	v_mul_f32_e32 v71, v71, v76
	v_mul_f32_e32 v64, v64, v80
	v_mul_f32_e32 v70, v70, v74
	v_cvt_pk_bf16_f32 v68, v68, v69
	v_cvt_pk_bf16_f32 v69, v70, v71
	v_mul_f32_e32 v71, 0xbfb8aa3b, v64
	v_exp_f32_e32 v71, v71
	v_mul_f32_e32 v65, v65, v80
	v_mul_f32_e32 v73, 0xbfb8aa3b, v65
	v_exp_f32_e32 v73, v73
	v_add_f32_e32 v71, 1.0, v71
	v_rcp_f32_e32 v71, v71
	global_store_dwordx2 v[124:125], v[68:69], off offset:64
	s_waitcnt vmcnt(15)
	v_lshlrev_b32_e32 v68, 16, v126
	v_mul_f32_e32 v66, v66, v80
	v_mul_f32_e32 v67, v67, v80
	v_mul_f32_e32 v64, v64, v71
	v_mul_f32_e32 v64, v64, v68
	v_add_f32_e32 v68, 1.0, v73
	v_mul_f32_e32 v71, 0xbfb8aa3b, v66
	v_mul_f32_e32 v73, 0xbfb8aa3b, v67
	v_rcp_f32_e32 v68, v68
	v_exp_f32_e32 v71, v71
	v_exp_f32_e32 v73, v73
	v_and_b32_e32 v69, 0xffff0000, v126
	v_mul_f32_e32 v65, v65, v68
	v_add_f32_e32 v68, 1.0, v71
	v_add_f32_e32 v71, 1.0, v73
	v_rcp_f32_e32 v68, v68
	v_rcp_f32_e32 v71, v71
	v_lshlrev_b32_e32 v70, 16, v127
	v_and_b32_e32 v72, 0xffff0000, v127
	v_mul_f32_e32 v65, v65, v69
	v_mul_f32_e32 v66, v66, v68
	v_mul_f32_e32 v67, v67, v71
	v_mul_f32_e32 v66, v66, v70
	v_mul_f32_e32 v67, v67, v72
	v_cvt_pk_bf16_f32 v64, v64, v65
	v_cvt_pk_bf16_f32 v65, v66, v67
	global_store_dwordx2 v[124:125], v[64:65], off offset:96
	v_or_b32_e32 v64, 64, v122
	v_ashrrev_i32_e32 v65, 31, v64
	v_lshl_add_u64 v[66:67], v[64:65], 2, s[0:1]
	v_lshlrev_b64 v[64:65], 12, v[64:65]
	v_lshl_add_u64 v[92:93], v[120:121], 0, v[64:65]
	v_or_b32_e32 v64, 0x50, v122
	v_ashrrev_i32_e32 v65, 31, v64
	global_load_dword v97, v[66:67], off
	global_load_dwordx2 v[98:99], v[92:93], off
	global_load_dwordx2 v[100:101], v[92:93], off offset:32
	global_load_dwordx2 v[102:103], v[92:93], off offset:64
	v_lshl_add_u64 v[66:67], v[64:65], 2, s[0:1]
	v_lshlrev_b64 v[64:65], 12, v[64:65]
	v_lshl_add_u64 v[82:83], v[120:121], 0, v[64:65]
	v_or_b32_e32 v64, 0x60, v122
	v_ashrrev_i32_e32 v65, 31, v64
	global_load_dwordx2 v[104:105], v[92:93], off offset:96
	global_load_dword v106, v[66:67], off
	global_load_dwordx2 v[94:95], v[82:83], off
	global_load_dwordx2 v[90:91], v[82:83], off offset:32
	v_lshl_add_u64 v[66:67], v[64:65], 2, s[0:1]
	v_lshlrev_b64 v[64:65], 12, v[64:65]
	v_lshl_add_u64 v[72:73], v[120:121], 0, v[64:65]
	v_or_b32_e32 v64, 0x70, v122
	v_ashrrev_i32_e32 v65, 31, v64
	global_load_dwordx2 v[88:89], v[82:83], off offset:64
	global_load_dwordx2 v[86:87], v[82:83], off offset:96
	global_load_dword v107, v[66:67], off
	global_load_dwordx2 v[84:85], v[72:73], off
	v_lshl_add_u64 v[66:67], v[64:65], 2, s[0:1]
	v_lshlrev_b64 v[64:65], 12, v[64:65]
	v_lshl_add_u64 v[64:65], v[120:121], 0, v[64:65]
	global_load_dwordx2 v[80:81], v[72:73], off offset:32
	global_load_dwordx2 v[78:79], v[72:73], off offset:64
	global_load_dwordx2 v[76:77], v[72:73], off offset:96
	global_load_dword v96, v[66:67], off
	global_load_dwordx2 v[74:75], v[64:65], off
	global_load_dwordx2 v[70:71], v[64:65], off offset:32
	global_load_dwordx2 v[68:69], v[64:65], off offset:64
	s_nop 0
	global_load_dwordx2 v[66:67], v[64:65], off offset:96
	s_waitcnt vmcnt(19)
	v_fmamk_f32 v97, v97, 0x3a800000, v167
	v_mul_f32_e32 v108, 0x4b800000, v97
	v_cmp_gt_f32_e32 vcc, s22, v97
	s_nop 1
	v_cndmask_b32_e32 v97, v97, v108, vcc
	v_rsq_f32_e32 v97, v97
	s_waitcnt vmcnt(18)
	v_lshlrev_b32_e32 v108, 16, v98
	v_and_b32_e32 v98, 0xffff0000, v98
	v_mul_f32_e32 v109, 0x45800000, v97
	v_cndmask_b32_e32 v97, v97, v109, vcc
	v_mul_f32_e32 v60, v60, v97
	v_mul_f32_e32 v110, 0xbfb8aa3b, v60
	v_exp_f32_e32 v110, v110
	v_mul_f32_e32 v61, v61, v97
	v_mul_f32_e32 v111, 0xbfb8aa3b, v61
	v_exp_f32_e32 v111, v111
	v_add_f32_e32 v110, 1.0, v110
	v_rcp_f32_e32 v110, v110
	v_mul_f32_e32 v62, v62, v97
	v_mul_f32_e32 v63, v63, v97
	v_lshlrev_b32_e32 v109, 16, v99
	v_mul_f32_e32 v60, v60, v110
	v_mul_f32_e32 v60, v60, v108
	v_add_f32_e32 v108, 1.0, v111
	v_mul_f32_e32 v110, 0xbfb8aa3b, v62
	v_mul_f32_e32 v111, 0xbfb8aa3b, v63
	v_rcp_f32_e32 v108, v108
	v_exp_f32_e32 v110, v110
	v_exp_f32_e32 v111, v111
	v_and_b32_e32 v99, 0xffff0000, v99
	v_mul_f32_e32 v61, v61, v108
	v_add_f32_e32 v108, 1.0, v110
	v_add_f32_e32 v110, 1.0, v111
	v_rcp_f32_e32 v110, v110
	v_rcp_f32_e32 v108, v108
	v_mul_f32_e32 v61, v61, v98
	v_mul_f32_e32 v56, v56, v97
	v_mul_f32_e32 v63, v63, v110
	v_mul_f32_e32 v62, v62, v108
	v_mul_f32_e32 v63, v63, v99
	v_mul_f32_e32 v62, v62, v109
	v_cvt_pk_bf16_f32 v60, v60, v61
	v_cvt_pk_bf16_f32 v61, v62, v63
	v_mul_f32_e32 v63, 0xbfb8aa3b, v56
	v_exp_f32_e32 v63, v63
	v_mul_f32_e32 v57, v57, v97
	v_mul_f32_e32 v99, 0xbfb8aa3b, v57
	v_exp_f32_e32 v99, v99
	v_add_f32_e32 v63, 1.0, v63
	v_rcp_f32_e32 v63, v63
	global_store_dwordx2 v[92:93], v[60:61], off
	s_waitcnt vmcnt(18)
	v_lshlrev_b32_e32 v60, 16, v100
	v_mul_f32_e32 v58, v58, v97
	v_mul_f32_e32 v59, v59, v97
	v_mul_f32_e32 v56, v56, v63
	v_mul_f32_e32 v56, v56, v60
	v_add_f32_e32 v60, 1.0, v99
	v_mul_f32_e32 v63, 0xbfb8aa3b, v58
	v_mul_f32_e32 v99, 0xbfb8aa3b, v59
	v_rcp_f32_e32 v60, v60
	v_exp_f32_e32 v63, v63
	v_exp_f32_e32 v99, v99
	v_and_b32_e32 v61, 0xffff0000, v100
	v_mul_f32_e32 v57, v57, v60
	v_add_f32_e32 v60, 1.0, v63
	v_add_f32_e32 v63, 1.0, v99
	v_rcp_f32_e32 v63, v63
	v_rcp_f32_e32 v60, v60
	v_and_b32_e32 v98, 0xffff0000, v101
	v_lshlrev_b32_e32 v62, 16, v101
	v_mul_f32_e32 v59, v59, v63
	v_mul_f32_e32 v57, v57, v61
	v_mul_f32_e32 v58, v58, v60
	v_mul_f32_e32 v59, v59, v98
	v_mul_f32_e32 v52, v52, v97
	v_mul_f32_e32 v58, v58, v62
	v_cvt_pk_bf16_f32 v56, v56, v57
	v_cvt_pk_bf16_f32 v57, v58, v59
	v_mul_f32_e32 v59, 0xbfb8aa3b, v52
	v_exp_f32_e32 v59, v59
	v_mul_f32_e32 v53, v53, v97
	v_mul_f32_e32 v61, 0xbfb8aa3b, v53
	v_exp_f32_e32 v61, v61
	v_add_f32_e32 v59, 1.0, v59
	v_rcp_f32_e32 v59, v59
	global_store_dwordx2 v[92:93], v[56:57], off offset:32
	s_waitcnt vmcnt(18)
	v_lshlrev_b32_e32 v56, 16, v102
	v_mul_f32_e32 v54, v54, v97
	v_mul_f32_e32 v55, v55, v97
	v_mul_f32_e32 v52, v52, v59
	v_mul_f32_e32 v52, v52, v56
	v_add_f32_e32 v56, 1.0, v61
	v_mul_f32_e32 v59, 0xbfb8aa3b, v54
	v_mul_f32_e32 v61, 0xbfb8aa3b, v55
	v_rcp_f32_e32 v56, v56
	v_exp_f32_e32 v59, v59
	v_exp_f32_e32 v61, v61
	v_and_b32_e32 v57, 0xffff0000, v102
	v_mul_f32_e32 v53, v53, v56
	v_add_f32_e32 v56, 1.0, v59
	v_add_f32_e32 v59, 1.0, v61
	v_rcp_f32_e32 v59, v59
	v_rcp_f32_e32 v56, v56
	v_and_b32_e32 v60, 0xffff0000, v103
	v_lshlrev_b32_e32 v58, 16, v103
	v_mul_f32_e32 v55, v55, v59
	v_mul_f32_e32 v53, v53, v57
	v_mul_f32_e32 v54, v54, v56
	v_mul_f32_e32 v55, v55, v60
	v_mul_f32_e32 v48, v48, v97
	v_mul_f32_e32 v54, v54, v58
	v_cvt_pk_bf16_f32 v52, v52, v53
	v_cvt_pk_bf16_f32 v53, v54, v55
	v_mul_f32_e32 v55, 0xbfb8aa3b, v48
	v_exp_f32_e32 v55, v55
	v_mul_f32_e32 v49, v49, v97
	v_mul_f32_e32 v57, 0xbfb8aa3b, v49
	v_exp_f32_e32 v57, v57
	v_add_f32_e32 v55, 1.0, v55
	v_rcp_f32_e32 v55, v55
	global_store_dwordx2 v[92:93], v[52:53], off offset:64
	s_waitcnt vmcnt(18)
	v_lshlrev_b32_e32 v52, 16, v104
	v_mul_f32_e32 v50, v50, v97
	v_mul_f32_e32 v48, v48, v55
	v_mul_f32_e32 v48, v48, v52
	v_add_f32_e32 v52, 1.0, v57
	v_mul_f32_e32 v55, 0xbfb8aa3b, v50
	v_rcp_f32_e32 v52, v52
	v_exp_f32_e32 v55, v55
	v_mul_f32_e32 v51, v51, v97
	v_mul_f32_e32 v57, 0xbfb8aa3b, v51
	v_mul_f32_e32 v49, v49, v52
	v_add_f32_e32 v52, 1.0, v55
	v_rcp_f32_e32 v52, v52
	v_exp_f32_e32 v57, v57
	v_and_b32_e32 v53, 0xffff0000, v104
	v_mul_f32_e32 v49, v49, v53
	v_mul_f32_e32 v50, v50, v52
	s_waitcnt vmcnt(17)
	v_fmamk_f32 v52, v106, 0x3a800000, v167
	v_add_f32_e32 v55, 1.0, v57
	v_mul_f32_e32 v53, 0x4b800000, v52
	v_cmp_gt_f32_e32 vcc, s22, v52
	v_rcp_f32_e32 v55, v55
	v_lshlrev_b32_e32 v54, 16, v105
	v_cndmask_b32_e32 v52, v52, v53, vcc
	v_rsq_f32_e32 v52, v52
	v_and_b32_e32 v56, 0xffff0000, v105
	v_mul_f32_e32 v51, v51, v55
	v_cvt_pk_bf16_f32 v48, v48, v49
	v_mul_f32_e32 v50, v50, v54
	v_mul_f32_e32 v51, v51, v56
	v_cvt_pk_bf16_f32 v49, v50, v51
	global_store_dwordx2 v[92:93], v[48:49], off offset:96
	v_mul_f32_e32 v48, 0x45800000, v52
	v_cndmask_b32_e32 v48, v52, v48, vcc
	v_mul_f32_e32 v44, v44, v48
	v_mul_f32_e32 v52, 0xbfb8aa3b, v44
	v_exp_f32_e32 v52, v52
	v_mul_f32_e32 v45, v45, v48
	v_mul_f32_e32 v54, 0xbfb8aa3b, v45
	v_exp_f32_e32 v54, v54
	v_add_f32_e32 v52, 1.0, v52
	v_rcp_f32_e32 v52, v52
	s_waitcnt vmcnt(17)
	v_lshlrev_b32_e32 v49, 16, v94
	v_mul_f32_e32 v46, v46, v48
	v_mul_f32_e32 v47, v47, v48
	v_mul_f32_e32 v44, v44, v52
	v_mul_f32_e32 v44, v44, v49
	v_add_f32_e32 v49, 1.0, v54
	v_mul_f32_e32 v52, 0xbfb8aa3b, v46
	v_mul_f32_e32 v54, 0xbfb8aa3b, v47
	v_rcp_f32_e32 v49, v49
	v_exp_f32_e32 v52, v52
	v_exp_f32_e32 v54, v54
	v_and_b32_e32 v50, 0xffff0000, v94
	v_mul_f32_e32 v45, v45, v49
	v_add_f32_e32 v49, 1.0, v52
	v_add_f32_e32 v52, 1.0, v54
	v_rcp_f32_e32 v52, v52
	v_rcp_f32_e32 v49, v49
	v_and_b32_e32 v53, 0xffff0000, v95
	v_lshlrev_b32_e32 v51, 16, v95
	v_mul_f32_e32 v47, v47, v52
	v_mul_f32_e32 v45, v45, v50
	v_mul_f32_e32 v46, v46, v49
	v_mul_f32_e32 v47, v47, v53
	v_mul_f32_e32 v40, v40, v48
	v_mul_f32_e32 v46, v46, v51
	v_cvt_pk_bf16_f32 v44, v44, v45
	v_cvt_pk_bf16_f32 v45, v46, v47
	v_mul_f32_e32 v47, 0xbfb8aa3b, v40
	v_exp_f32_e32 v47, v47
	v_mul_f32_e32 v41, v41, v48
	v_mul_f32_e32 v50, 0xbfb8aa3b, v41
	v_exp_f32_e32 v50, v50
	v_add_f32_e32 v47, 1.0, v47
	v_rcp_f32_e32 v47, v47
	global_store_dwordx2 v[82:83], v[44:45], off
	s_waitcnt vmcnt(17)
	v_lshlrev_b32_e32 v44, 16, v90
	v_mul_f32_e32 v42, v42, v48
	v_mul_f32_e32 v43, v43, v48
	v_mul_f32_e32 v40, v40, v47
	v_mul_f32_e32 v40, v40, v44
	v_add_f32_e32 v44, 1.0, v50
	v_mul_f32_e32 v47, 0xbfb8aa3b, v42
	v_mul_f32_e32 v50, 0xbfb8aa3b, v43
	v_rcp_f32_e32 v44, v44
	v_exp_f32_e32 v47, v47
	v_exp_f32_e32 v50, v50
	v_and_b32_e32 v45, 0xffff0000, v90
	v_mul_f32_e32 v41, v41, v44
	v_add_f32_e32 v44, 1.0, v47
	v_add_f32_e32 v47, 1.0, v50
	v_rcp_f32_e32 v47, v47
	v_rcp_f32_e32 v44, v44
	v_and_b32_e32 v49, 0xffff0000, v91
	v_lshlrev_b32_e32 v46, 16, v91
	v_mul_f32_e32 v43, v43, v47
	v_mul_f32_e32 v41, v41, v45
	v_mul_f32_e32 v42, v42, v44
	v_mul_f32_e32 v43, v43, v49
	v_mul_f32_e32 v36, v36, v48
	v_mul_f32_e32 v42, v42, v46
	v_cvt_pk_bf16_f32 v40, v40, v41
	v_cvt_pk_bf16_f32 v41, v42, v43
	v_mul_f32_e32 v43, 0xbfb8aa3b, v36
	v_exp_f32_e32 v43, v43
	v_mul_f32_e32 v37, v37, v48
	v_mul_f32_e32 v45, 0xbfb8aa3b, v37
	v_exp_f32_e32 v45, v45
	v_add_f32_e32 v43, 1.0, v43
	v_rcp_f32_e32 v43, v43
	global_store_dwordx2 v[82:83], v[40:41], off offset:32
	s_waitcnt vmcnt(17)
	v_lshlrev_b32_e32 v40, 16, v88
	v_mul_f32_e32 v38, v38, v48
	v_mul_f32_e32 v39, v39, v48
	v_mul_f32_e32 v36, v36, v43
	v_mul_f32_e32 v36, v36, v40
	v_add_f32_e32 v40, 1.0, v45
	v_mul_f32_e32 v43, 0xbfb8aa3b, v38
	v_mul_f32_e32 v45, 0xbfb8aa3b, v39
	v_rcp_f32_e32 v40, v40
	v_exp_f32_e32 v43, v43
	v_exp_f32_e32 v45, v45
	v_and_b32_e32 v41, 0xffff0000, v88
	v_mul_f32_e32 v37, v37, v40
	v_add_f32_e32 v40, 1.0, v43
	v_add_f32_e32 v43, 1.0, v45
	v_rcp_f32_e32 v43, v43
	v_rcp_f32_e32 v40, v40
	v_and_b32_e32 v44, 0xffff0000, v89
	v_lshlrev_b32_e32 v42, 16, v89
	v_mul_f32_e32 v39, v39, v43
	v_mul_f32_e32 v37, v37, v41
	v_mul_f32_e32 v38, v38, v40
	v_mul_f32_e32 v39, v39, v44
	v_mul_f32_e32 v32, v32, v48
	v_mul_f32_e32 v38, v38, v42
	v_cvt_pk_bf16_f32 v36, v36, v37
	v_cvt_pk_bf16_f32 v37, v38, v39
	v_mul_f32_e32 v39, 0xbfb8aa3b, v32
	v_exp_f32_e32 v39, v39
	v_mul_f32_e32 v33, v33, v48
	v_mul_f32_e32 v41, 0xbfb8aa3b, v33
	v_exp_f32_e32 v41, v41
	v_add_f32_e32 v39, 1.0, v39
	v_rcp_f32_e32 v39, v39
	global_store_dwordx2 v[82:83], v[36:37], off offset:64
	s_waitcnt vmcnt(17)
	v_lshlrev_b32_e32 v36, 16, v86
	v_mul_f32_e32 v34, v34, v48
	v_mul_f32_e32 v32, v32, v39
	v_mul_f32_e32 v32, v32, v36
	v_add_f32_e32 v36, 1.0, v41
	v_mul_f32_e32 v39, 0xbfb8aa3b, v34
	v_rcp_f32_e32 v36, v36
	v_exp_f32_e32 v39, v39
	v_mul_f32_e32 v35, v35, v48
	v_mul_f32_e32 v41, 0xbfb8aa3b, v35
	v_mul_f32_e32 v33, v33, v36
	v_add_f32_e32 v36, 1.0, v39
	v_rcp_f32_e32 v36, v36
	v_exp_f32_e32 v41, v41
	v_and_b32_e32 v37, 0xffff0000, v86
	v_mul_f32_e32 v33, v33, v37
	v_mul_f32_e32 v34, v34, v36
	s_waitcnt vmcnt(16)
	v_fmamk_f32 v36, v107, 0x3a800000, v167
	v_add_f32_e32 v39, 1.0, v41
	v_mul_f32_e32 v37, 0x4b800000, v36
	v_cmp_gt_f32_e32 vcc, s22, v36
	v_rcp_f32_e32 v39, v39
	v_lshlrev_b32_e32 v38, 16, v87
	v_cndmask_b32_e32 v36, v36, v37, vcc
	v_rsq_f32_e32 v36, v36
	v_and_b32_e32 v40, 0xffff0000, v87
	v_mul_f32_e32 v35, v35, v39
	v_cvt_pk_bf16_f32 v32, v32, v33
	v_mul_f32_e32 v34, v34, v38
	v_mul_f32_e32 v35, v35, v40
	v_cvt_pk_bf16_f32 v33, v34, v35
	global_store_dwordx2 v[82:83], v[32:33], off offset:96
	v_mul_f32_e32 v32, 0x45800000, v36
	v_cndmask_b32_e32 v32, v36, v32, vcc
	v_mul_f32_e32 v28, v28, v32
	v_mul_f32_e32 v36, 0xbfb8aa3b, v28
	v_exp_f32_e32 v36, v36
	v_mul_f32_e32 v29, v29, v32
	v_mul_f32_e32 v38, 0xbfb8aa3b, v29
	v_exp_f32_e32 v38, v38
	v_add_f32_e32 v36, 1.0, v36
	v_rcp_f32_e32 v36, v36
	s_waitcnt vmcnt(16)
	v_lshlrev_b32_e32 v33, 16, v84
	v_mul_f32_e32 v30, v30, v32
	v_mul_f32_e32 v31, v31, v32
	v_mul_f32_e32 v28, v28, v36
	v_mul_f32_e32 v28, v28, v33
	v_add_f32_e32 v33, 1.0, v38
	v_mul_f32_e32 v36, 0xbfb8aa3b, v30
	v_mul_f32_e32 v38, 0xbfb8aa3b, v31
	v_rcp_f32_e32 v33, v33
	v_exp_f32_e32 v36, v36
	v_exp_f32_e32 v38, v38
	v_and_b32_e32 v34, 0xffff0000, v84
	v_mul_f32_e32 v29, v29, v33
	v_add_f32_e32 v33, 1.0, v36
	v_add_f32_e32 v36, 1.0, v38
	v_rcp_f32_e32 v36, v36
	v_rcp_f32_e32 v33, v33
	v_and_b32_e32 v37, 0xffff0000, v85
	v_lshlrev_b32_e32 v35, 16, v85
	v_mul_f32_e32 v31, v31, v36
	v_mul_f32_e32 v29, v29, v34
	v_mul_f32_e32 v30, v30, v33
	v_mul_f32_e32 v31, v31, v37
	v_mul_f32_e32 v24, v24, v32
	v_mul_f32_e32 v30, v30, v35
	v_cvt_pk_bf16_f32 v28, v28, v29
	v_cvt_pk_bf16_f32 v29, v30, v31
	v_mul_f32_e32 v31, 0xbfb8aa3b, v24
	v_exp_f32_e32 v31, v31
	v_mul_f32_e32 v25, v25, v32
	v_mul_f32_e32 v34, 0xbfb8aa3b, v25
	v_exp_f32_e32 v34, v34
	v_add_f32_e32 v31, 1.0, v31
	v_rcp_f32_e32 v31, v31
	global_store_dwordx2 v[72:73], v[28:29], off
	s_waitcnt vmcnt(16)
	v_lshlrev_b32_e32 v28, 16, v80
	v_mul_f32_e32 v26, v26, v32
	v_mul_f32_e32 v27, v27, v32
	v_mul_f32_e32 v24, v24, v31
	v_mul_f32_e32 v24, v24, v28
	v_add_f32_e32 v28, 1.0, v34
	v_mul_f32_e32 v31, 0xbfb8aa3b, v26
	v_mul_f32_e32 v34, 0xbfb8aa3b, v27
	v_rcp_f32_e32 v28, v28
	v_exp_f32_e32 v31, v31
	v_exp_f32_e32 v34, v34
	v_and_b32_e32 v29, 0xffff0000, v80
	v_mul_f32_e32 v25, v25, v28
	v_add_f32_e32 v28, 1.0, v31
	v_add_f32_e32 v31, 1.0, v34
	v_rcp_f32_e32 v31, v31
	v_rcp_f32_e32 v28, v28
	v_and_b32_e32 v33, 0xffff0000, v81
	v_lshlrev_b32_e32 v30, 16, v81
	v_mul_f32_e32 v27, v27, v31
	v_mul_f32_e32 v25, v25, v29
	v_mul_f32_e32 v26, v26, v28
	v_mul_f32_e32 v27, v27, v33
	v_mul_f32_e32 v20, v20, v32
	v_mul_f32_e32 v26, v26, v30
	v_cvt_pk_bf16_f32 v24, v24, v25
	v_cvt_pk_bf16_f32 v25, v26, v27
	v_mul_f32_e32 v27, 0xbfb8aa3b, v20
	v_exp_f32_e32 v27, v27
	v_mul_f32_e32 v21, v21, v32
	v_mul_f32_e32 v29, 0xbfb8aa3b, v21
	v_exp_f32_e32 v29, v29
	v_add_f32_e32 v27, 1.0, v27
	v_rcp_f32_e32 v27, v27
	global_store_dwordx2 v[72:73], v[24:25], off offset:32
	s_waitcnt vmcnt(16)
	v_lshlrev_b32_e32 v24, 16, v78
	v_mul_f32_e32 v22, v22, v32
	v_mul_f32_e32 v23, v23, v32
	v_mul_f32_e32 v20, v20, v27
	v_mul_f32_e32 v20, v20, v24
	v_add_f32_e32 v24, 1.0, v29
	v_mul_f32_e32 v27, 0xbfb8aa3b, v22
	v_mul_f32_e32 v29, 0xbfb8aa3b, v23
	v_rcp_f32_e32 v24, v24
	v_exp_f32_e32 v27, v27
	v_exp_f32_e32 v29, v29
	v_and_b32_e32 v25, 0xffff0000, v78
	v_mul_f32_e32 v21, v21, v24
	v_add_f32_e32 v24, 1.0, v27
	v_add_f32_e32 v27, 1.0, v29
	v_rcp_f32_e32 v27, v27
	v_rcp_f32_e32 v24, v24
	v_and_b32_e32 v28, 0xffff0000, v79
	v_lshlrev_b32_e32 v26, 16, v79
	v_mul_f32_e32 v23, v23, v27
	v_mul_f32_e32 v21, v21, v25
	v_mul_f32_e32 v22, v22, v24
	v_mul_f32_e32 v23, v23, v28
	v_mul_f32_e32 v16, v16, v32
	v_mul_f32_e32 v22, v22, v26
	v_cvt_pk_bf16_f32 v20, v20, v21
	v_cvt_pk_bf16_f32 v21, v22, v23
	v_mul_f32_e32 v23, 0xbfb8aa3b, v16
	v_exp_f32_e32 v23, v23
	v_mul_f32_e32 v17, v17, v32
	v_mul_f32_e32 v25, 0xbfb8aa3b, v17
	v_exp_f32_e32 v25, v25
	v_add_f32_e32 v23, 1.0, v23
	v_rcp_f32_e32 v23, v23
	global_store_dwordx2 v[72:73], v[20:21], off offset:64
	s_waitcnt vmcnt(16)
	v_lshlrev_b32_e32 v20, 16, v76
	v_mul_f32_e32 v18, v18, v32
	v_mul_f32_e32 v16, v16, v23
	v_mul_f32_e32 v16, v16, v20
	v_add_f32_e32 v20, 1.0, v25
	v_mul_f32_e32 v23, 0xbfb8aa3b, v18
	v_rcp_f32_e32 v20, v20
	v_exp_f32_e32 v23, v23
	v_mul_f32_e32 v19, v19, v32
	v_mul_f32_e32 v25, 0xbfb8aa3b, v19
	v_mul_f32_e32 v17, v17, v20
	v_add_f32_e32 v20, 1.0, v23
	v_rcp_f32_e32 v20, v20
	v_exp_f32_e32 v25, v25
	v_and_b32_e32 v21, 0xffff0000, v76
	v_mul_f32_e32 v17, v17, v21
	v_mul_f32_e32 v18, v18, v20
	s_waitcnt vmcnt(15)
	v_fmamk_f32 v20, v96, 0x3a800000, v167
	v_add_f32_e32 v23, 1.0, v25
	v_mul_f32_e32 v21, 0x4b800000, v20
	v_cmp_gt_f32_e32 vcc, s22, v20
	v_rcp_f32_e32 v23, v23
	v_lshlrev_b32_e32 v22, 16, v77
	v_cndmask_b32_e32 v20, v20, v21, vcc
	v_rsq_f32_e32 v20, v20
	v_and_b32_e32 v24, 0xffff0000, v77
	v_mul_f32_e32 v19, v19, v23
	v_cvt_pk_bf16_f32 v16, v16, v17
	v_mul_f32_e32 v18, v18, v22
	v_mul_f32_e32 v19, v19, v24
	v_cvt_pk_bf16_f32 v17, v18, v19
	global_store_dwordx2 v[72:73], v[16:17], off offset:96
	v_mul_f32_e32 v16, 0x45800000, v20
	v_cndmask_b32_e32 v16, v20, v16, vcc
	v_mul_f32_e32 v12, v12, v16
	v_mul_f32_e32 v20, 0xbfb8aa3b, v12
	v_exp_f32_e32 v20, v20
	v_mul_f32_e32 v13, v13, v16
	v_mul_f32_e32 v22, 0xbfb8aa3b, v13
	v_exp_f32_e32 v22, v22
	v_add_f32_e32 v20, 1.0, v20
	v_rcp_f32_e32 v20, v20
	s_waitcnt vmcnt(15)
	v_lshlrev_b32_e32 v17, 16, v74
	v_mul_f32_e32 v14, v14, v16
	v_mul_f32_e32 v15, v15, v16
	v_mul_f32_e32 v12, v12, v20
	v_mul_f32_e32 v12, v12, v17
	v_add_f32_e32 v17, 1.0, v22
	v_mul_f32_e32 v20, 0xbfb8aa3b, v14
	v_mul_f32_e32 v22, 0xbfb8aa3b, v15
	v_rcp_f32_e32 v17, v17
	v_exp_f32_e32 v20, v20
	v_exp_f32_e32 v22, v22
	v_and_b32_e32 v18, 0xffff0000, v74
	v_mul_f32_e32 v13, v13, v17
	v_add_f32_e32 v17, 1.0, v20
	v_add_f32_e32 v20, 1.0, v22
	v_rcp_f32_e32 v20, v20
	v_rcp_f32_e32 v17, v17
	v_and_b32_e32 v21, 0xffff0000, v75
	v_lshlrev_b32_e32 v19, 16, v75
	v_mul_f32_e32 v15, v15, v20
	v_mul_f32_e32 v13, v13, v18
	v_mul_f32_e32 v14, v14, v17
	v_mul_f32_e32 v15, v15, v21
	v_mul_f32_e32 v8, v8, v16
	v_mul_f32_e32 v14, v14, v19
	v_cvt_pk_bf16_f32 v12, v12, v13
	v_cvt_pk_bf16_f32 v13, v14, v15
	v_mul_f32_e32 v15, 0xbfb8aa3b, v8
	v_exp_f32_e32 v15, v15
	v_mul_f32_e32 v9, v9, v16
	v_mul_f32_e32 v18, 0xbfb8aa3b, v9
	v_exp_f32_e32 v18, v18
	v_add_f32_e32 v15, 1.0, v15
	v_rcp_f32_e32 v15, v15
	global_store_dwordx2 v[64:65], v[12:13], off
	s_waitcnt vmcnt(15)
	v_lshlrev_b32_e32 v12, 16, v70
	v_mul_f32_e32 v10, v10, v16
	v_mul_f32_e32 v11, v11, v16
	v_mul_f32_e32 v8, v8, v15
	v_mul_f32_e32 v8, v8, v12
	v_add_f32_e32 v12, 1.0, v18
	v_mul_f32_e32 v15, 0xbfb8aa3b, v10
	v_mul_f32_e32 v18, 0xbfb8aa3b, v11
	v_rcp_f32_e32 v12, v12
	v_exp_f32_e32 v15, v15
	v_exp_f32_e32 v18, v18
	v_and_b32_e32 v13, 0xffff0000, v70
	v_mul_f32_e32 v9, v9, v12
	v_add_f32_e32 v12, 1.0, v15
	v_add_f32_e32 v15, 1.0, v18
	v_rcp_f32_e32 v15, v15
	v_rcp_f32_e32 v12, v12
	v_and_b32_e32 v17, 0xffff0000, v71
	v_lshlrev_b32_e32 v14, 16, v71
	v_mul_f32_e32 v11, v11, v15
	v_mul_f32_e32 v9, v9, v13
	v_mul_f32_e32 v10, v10, v12
	v_mul_f32_e32 v11, v11, v17
	v_mul_f32_e32 v4, v4, v16
	v_mul_f32_e32 v10, v10, v14
	v_cvt_pk_bf16_f32 v8, v8, v9
	v_cvt_pk_bf16_f32 v9, v10, v11
	v_mul_f32_e32 v11, 0xbfb8aa3b, v4
	v_exp_f32_e32 v11, v11
	v_mul_f32_e32 v5, v5, v16
	v_mul_f32_e32 v13, 0xbfb8aa3b, v5
	v_exp_f32_e32 v13, v13
	v_add_f32_e32 v11, 1.0, v11
	v_rcp_f32_e32 v11, v11
	global_store_dwordx2 v[64:65], v[8:9], off offset:32
	s_waitcnt vmcnt(15)
	v_lshlrev_b32_e32 v8, 16, v68
	v_mul_f32_e32 v6, v6, v16
	v_mul_f32_e32 v7, v7, v16
	v_mul_f32_e32 v4, v4, v11
	v_mul_f32_e32 v4, v4, v8
	v_add_f32_e32 v8, 1.0, v13
	v_mul_f32_e32 v11, 0xbfb8aa3b, v6
	v_mul_f32_e32 v13, 0xbfb8aa3b, v7
	v_rcp_f32_e32 v8, v8
	v_exp_f32_e32 v11, v11
	v_exp_f32_e32 v13, v13
	v_and_b32_e32 v9, 0xffff0000, v68
	v_mul_f32_e32 v5, v5, v8
	v_add_f32_e32 v8, 1.0, v11
	v_add_f32_e32 v11, 1.0, v13
	v_rcp_f32_e32 v11, v11
	v_rcp_f32_e32 v8, v8
	v_and_b32_e32 v12, 0xffff0000, v69
	v_lshlrev_b32_e32 v10, 16, v69
	v_mul_f32_e32 v7, v7, v11
	v_mul_f32_e32 v5, v5, v9
	v_mul_f32_e32 v6, v6, v8
	v_mul_f32_e32 v7, v7, v12
	v_mul_f32_e32 v0, v0, v16
	v_mul_f32_e32 v6, v6, v10
	v_cvt_pk_bf16_f32 v4, v4, v5
	v_cvt_pk_bf16_f32 v5, v6, v7
	v_mul_f32_e32 v7, 0xbfb8aa3b, v0
	v_exp_f32_e32 v7, v7
	v_mul_f32_e32 v1, v1, v16
	v_mul_f32_e32 v9, 0xbfb8aa3b, v1
	v_exp_f32_e32 v9, v9
	v_add_f32_e32 v7, 1.0, v7
	v_rcp_f32_e32 v7, v7
	global_store_dwordx2 v[64:65], v[4:5], off offset:64
	s_waitcnt vmcnt(15)
	v_lshlrev_b32_e32 v4, 16, v66
	v_mul_f32_e32 v2, v2, v16
	v_mul_f32_e32 v3, v3, v16
	v_mul_f32_e32 v0, v0, v7
	v_mul_f32_e32 v0, v0, v4
	v_add_f32_e32 v4, 1.0, v9
	v_mul_f32_e32 v7, 0xbfb8aa3b, v2
	v_mul_f32_e32 v9, 0xbfb8aa3b, v3
	v_rcp_f32_e32 v4, v4
	v_exp_f32_e32 v7, v7
	v_exp_f32_e32 v9, v9
	v_and_b32_e32 v5, 0xffff0000, v66
	v_mul_f32_e32 v1, v1, v4
	v_add_f32_e32 v4, 1.0, v7
	v_add_f32_e32 v7, 1.0, v9
	v_rcp_f32_e32 v4, v4
	v_rcp_f32_e32 v7, v7
	v_lshlrev_b32_e32 v6, 16, v67
	v_and_b32_e32 v8, 0xffff0000, v67
	v_mul_f32_e32 v1, v1, v5
	v_mul_f32_e32 v2, v2, v4
	v_mul_f32_e32 v3, v3, v7
	v_mul_f32_e32 v2, v2, v6
	v_mul_f32_e32 v3, v3, v8
	v_cvt_pk_bf16_f32 v0, v0, v1
	v_cvt_pk_bf16_f32 v1, v2, v3
	global_store_dwordx2 v[64:65], v[0:1], off offset:96
	s_add_i32 s23, s23, s74
	s_cmpk_lt_i32 s23, 0x800
	s_cbranch_scc1 .LBB0_1736

.LBB0_1794:
	s_ashr_i32 s0, s25, 3
	s_lshr_b32 s1, s0, 29
	s_add_i32 s1, s0, s1
	s_and_b32 s18, s1, 0x1fffff8
	s_sub_i32 s0, s0, s18
	s_lshl_b32 s1, s1, 8
	s_lshl_b32 s18, s25, 8
	s_and_b32 s1, s1, 0xfffff800
	s_and_b32 s18, s18, 0x700
	s_or_b32 s20, s1, s18
	s_ashr_i32 s21, s20, 31
	s_lshl_b32 s0, s0, 7
	s_lshl_b64 s[26:27], s[20:21], 12
	s_add_u32 s26, s3, s26
	s_addc_u32 s27, s4, s27
	s_ashr_i32 s1, s0, 31
	v_mov_b32_e32 v36, v220
	s_lshl_b64 s[28:29], s[0:1], 12
	s_add_u32 s28, s5, s28
	v_ashrrev_i32_e32 v26, 2, v36
	v_ashrrev_i32_e32 v27, 31, v26
	s_addc_u32 s29, s6, s29
	v_lshlrev_b64 v[0:1], 12, v[26:27]
	v_lshlrev_b32_e32 v4, 4, v36
	v_lshl_add_u64 v[2:3], s[28:29], 0, v[0:1]
	v_lshl_add_u64 v[0:1], s[26:27], 0, v[0:1]
	v_and_b32_e32 v176, 48, v4
	s_waitcnt vmcnt(9)
	v_lshl_add_u64 v[152:153], v[0:1], 0, v[176:177]
	v_add_co_u32_e32 v28, vcc, s7, v152
	v_lshl_add_u64 v[154:155], v[2:3], 0, v[176:177]
	s_nop 0
	v_addc_co_u32_e32 v29, vcc, 0, v153, vcc
	v_add_co_u32_e32 v30, vcc, s22, v152
	global_load_dwordx4 v[2:5], v[152:153], off
	s_nop 0
	v_addc_co_u32_e32 v31, vcc, 0, v153, vcc
	v_add_co_u32_e32 v32, vcc, s23, v152
	global_load_dwordx4 v[6:9], v[28:29], off
	s_nop 0
	v_addc_co_u32_e32 v33, vcc, 0, v153, vcc
	v_add_co_u32_e32 v34, vcc, s7, v154
	global_load_dwordx4 v[10:13], v[30:31], off
	s_nop 0
	v_addc_co_u32_e32 v35, vcc, 0, v155, vcc
	global_load_dwordx4 v[14:17], v[32:33], off
	global_load_dwordx4 v[18:21], v[154:155], off
	global_load_dwordx4 v[22:25], v[34:35], off
	global_load_dwordx4 v[112:115], v[152:153], off offset:64
	global_load_dwordx4 v[120:123], v[28:29], off offset:64
	global_load_dwordx4 v[124:127], v[30:31], off offset:64
	global_load_dwordx4 v[132:135], v[32:33], off offset:64
	global_load_dwordx4 v[128:131], v[154:155], off offset:64
	global_load_dwordx4 v[136:139], v[34:35], off offset:64
	v_lshrrev_b32_e32 v27, 4, v36
	v_lshrrev_b32_e32 v37, 2, v36
	v_sub_u32_e32 v40, 0, v27
	v_sub_u32_e32 v37, 0, v37
	v_and_b32_e32 v38, 0x3ffff8f, v36
	v_lshlrev_b32_e32 v39, 6, v36
	v_xor_b32_e32 v36, v36, v40
	v_xor_b32_e32 v27, v27, v37
	v_lshlrev_b32_e32 v36, 4, v36
	v_lshlrev_b32_e32 v27, 4, v27
	v_and_b32_e32 v41, 0x1000, v39
	v_and_b32_e32 v36, 48, v36
	v_and_b32_e32 v27, 48, v27
	v_and_b32_e32 v42, 0x3c0, v39
	v_and_b32_e32 v39, 0xffffe3c0, v39
	v_lshl_add_u32 v38, v38, 6, v198
	v_lshl_or_b32 v164, v26, 6, v36
	v_or_b32_e32 v26, v27, v41
	s_mov_b32 s1, -2
	s_mov_b32 s21, s19
	v_mov_b32_e32 v0, 0
	v_mov_b32_e32 v1, v177
	v_or3_b32 v165, v41, v42, v27
	v_add_u32_e32 v166, v27, v39
	v_add_u32_e32 v167, v27, v38
	v_add_u32_e32 v168, v26, v42
	v_lshl_add_u64 v[156:157], v[152:153], 0, s[12:13]
	v_lshl_add_u64 v[158:159], v[152:153], 0, s[14:15]
	v_lshl_add_u64 v[160:161], v[152:153], 0, s[16:17]
	v_lshl_add_u64 v[162:163], v[154:155], 0, s[12:13]
	v_mov_b32_e32 v26, v177
	v_mov_b32_e32 v27, v177
	v_mov_b32_e32 v28, 0
	v_mov_b32_e32 v29, v177
	v_mov_b32_e32 v30, v177
	v_mov_b32_e32 v31, v177
	v_mov_b32_e32 v32, 0
	v_mov_b32_e32 v33, v177
	v_mov_b32_e32 v34, v177
	v_mov_b32_e32 v35, v177
	v_mov_b32_e32 v36, 0
	v_mov_b32_e32 v37, v177
	v_mov_b32_e32 v38, v177
	v_mov_b32_e32 v39, v177
	v_mov_b32_e32 v40, 0
	v_mov_b32_e32 v41, v177
	v_mov_b32_e32 v42, v177
	v_mov_b32_e32 v43, v177
	v_mov_b32_e32 v44, 0
	s_waitcnt vmcnt(11)
	ds_write_b128 v164, v[2:5]
	s_waitcnt vmcnt(10)
	ds_write_b128 v164, v[6:9] offset:4096
	s_waitcnt vmcnt(9)
	ds_write_b128 v164, v[10:13] offset:8192
	s_waitcnt vmcnt(8)
	ds_write_b128 v164, v[14:17] offset:12288
	s_waitcnt vmcnt(7)
	ds_write_b128 v164, v[18:21] offset:32768
	s_waitcnt vmcnt(6)
	ds_write_b128 v164, v[22:25] offset:36864
	v_mov_b32_e32 v2, v177
	v_mov_b32_e32 v3, v177
	v_mov_b32_e32 v4, 0
	v_mov_b32_e32 v5, v177
	v_mov_b32_e32 v6, v177
	v_mov_b32_e32 v7, v177
	v_mov_b32_e32 v8, 0
	v_mov_b32_e32 v9, v177
	v_mov_b32_e32 v10, v177
	v_mov_b32_e32 v11, v177
	v_mov_b32_e32 v12, 0
	v_mov_b32_e32 v13, v177
	v_mov_b32_e32 v14, v177
	v_mov_b32_e32 v15, v177
	v_mov_b32_e32 v16, 0
	v_mov_b32_e32 v17, v177
	v_mov_b32_e32 v18, v177
	v_mov_b32_e32 v19, v177
	v_mov_b32_e32 v20, 0
	v_mov_b32_e32 v21, v177
	v_mov_b32_e32 v22, v177
	v_mov_b32_e32 v23, v177
	v_mov_b32_e32 v24, 0
	v_mov_b32_e32 v25, v177
	v_mov_b32_e32 v45, v177
	v_mov_b32_e32 v46, v177
	v_mov_b32_e32 v47, v177
	v_mov_b32_e32 v48, 0
	v_mov_b32_e32 v49, v177
	v_mov_b32_e32 v50, v177
	v_mov_b32_e32 v51, v177
	v_mov_b32_e32 v52, 0
	v_mov_b32_e32 v53, v177
	v_mov_b32_e32 v54, v177
	v_mov_b32_e32 v55, v177
	v_mov_b32_e32 v56, 0
	v_mov_b32_e32 v57, v177
	v_mov_b32_e32 v58, v177
	v_mov_b32_e32 v59, v177
	v_mov_b32_e32 v60, 0
	v_mov_b32_e32 v61, v177
	v_mov_b32_e32 v62, v177
	v_mov_b32_e32 v63, v177
	v_mov_b32_e32 v64, 0
	v_mov_b32_e32 v65, v177
	v_mov_b32_e32 v66, v177
	v_mov_b32_e32 v67, v177
	v_mov_b32_e32 v68, 0
	v_mov_b32_e32 v69, v177
	v_mov_b32_e32 v70, v177
	v_mov_b32_e32 v71, v177
	v_mov_b32_e32 v72, 0
	v_mov_b32_e32 v73, v177
	v_mov_b32_e32 v74, v177
	v_mov_b32_e32 v75, v177
	v_mov_b32_e32 v76, 0
	v_mov_b32_e32 v77, v177
	v_mov_b32_e32 v78, v177
	v_mov_b32_e32 v79, v177
	v_mov_b32_e32 v80, 0
	v_mov_b32_e32 v81, v177
	v_mov_b32_e32 v82, v177
	v_mov_b32_e32 v83, v177
	v_mov_b32_e32 v84, 0
	v_mov_b32_e32 v85, v177
	v_mov_b32_e32 v86, v177
	v_mov_b32_e32 v87, v177
	v_mov_b32_e32 v88, 0
	v_mov_b32_e32 v89, v177
	v_mov_b32_e32 v90, v177
	v_mov_b32_e32 v91, v177
	v_mov_b32_e32 v92, 0
	v_mov_b32_e32 v93, v177
	v_mov_b32_e32 v94, v177
	v_mov_b32_e32 v95, v177
	v_mov_b32_e32 v96, 0
	v_mov_b32_e32 v97, v177
	v_mov_b32_e32 v98, v177
	v_mov_b32_e32 v99, v177
	v_mov_b32_e32 v100, 0
	v_mov_b32_e32 v101, v177
	v_mov_b32_e32 v102, v177
	v_mov_b32_e32 v103, v177
	v_mov_b32_e32 v104, 0
	v_mov_b32_e32 v105, v177
	v_mov_b32_e32 v106, v177
	v_mov_b32_e32 v107, v177
	v_mov_b32_e32 v108, 0
	v_mov_b32_e32 v109, v177
	v_mov_b32_e32 v110, v177
	v_mov_b32_e32 v111, v177
	v_mov_b32_e32 v116, 0
	v_mov_b32_e32 v117, v177
	v_mov_b32_e32 v118, v177
	v_mov_b32_e32 v119, v177
	v_mov_b32_e32 v140, 0
	v_mov_b32_e32 v141, v177
	v_mov_b32_e32 v142, v177
	v_mov_b32_e32 v143, v177
	v_mov_b32_e32 v144, 0
	v_mov_b32_e32 v145, v177
	v_mov_b32_e32 v146, v177
	v_mov_b32_e32 v147, v177
	v_mov_b32_e32 v148, 0
	v_mov_b32_e32 v149, v177
	v_mov_b32_e32 v150, v177
	v_mov_b32_e32 v151, v177
	s_waitcnt lgkmcnt(0)
	s_barrier
	s_cmpk_lt_u32 s2, 0x100
	s_cbranch_scc1 .Lstag_9
	s_sleep 8
.Lstag_9:
.LBB0_1795:
	s_add_i32 s26, s21, 64
	s_min_u32 s18, s26, 0x7e0
	s_lshl_b32 s18, s18, 1
	v_lshl_add_u64 v[174:175], v[156:157], 0, s[18:19]
	global_load_dwordx4 v[178:181], v[174:175], off
	v_lshl_add_u64 v[174:175], v[158:159], 0, s[18:19]
	v_lshl_add_u64 v[170:171], v[152:153], 0, s[18:19]
	v_lshl_add_u64 v[186:187], v[160:161], 0, s[18:19]
	global_load_dwordx4 v[182:185], v[174:175], off
	v_lshl_add_u64 v[174:175], v[154:155], 0, s[18:19]
	v_lshl_add_u64 v[194:195], v[162:163], 0, s[18:19]
	global_load_dwordx4 v[170:173], v[170:171], off
	ds_read_b128 v[200:203], v168 offset:32768
	global_load_dwordx4 v[186:189], v[186:187], off
	ds_read_b128 v[204:207], v168 offset:33792
	global_load_dwordx4 v[190:193], v[174:175], off
	ds_read_b128 v[208:211], v168 offset:34816
	global_load_dwordx4 v[194:197], v[194:195], off
	ds_read_b128 v[212:215], v168 offset:35840
	ds_read_b128 v[216:219], v166
	ds_read_b128 v[222:225], v166 offset:1024
	ds_read_b128 v[226:229], v166 offset:2048
	ds_read_b128 v[230:233], v166 offset:3072
	ds_read_b128 v[234:237], v166 offset:4096
	ds_read_b128 v[238:241], v166 offset:5120
	ds_read_b128 v[242:245], v166 offset:6144
	ds_read_b128 v[246:249], v166 offset:7168
	s_setprio 1
	s_waitcnt lgkmcnt(7)
	v_mfma_f32_16x16x32_bf16 v[148:151], v[200:203], v[216:219], v[148:151]
	v_mfma_f32_16x16x32_bf16 v[144:147], v[204:207], v[216:219], v[144:147]
	v_mfma_f32_16x16x32_bf16 v[140:143], v[208:211], v[216:219], v[140:143]
	v_mfma_f32_16x16x32_bf16 v[116:119], v[212:215], v[216:219], v[116:119]
	s_waitcnt vmcnt(11)
	ds_write_b128 v164, v[112:115] offset:16384
	s_waitcnt lgkmcnt(7)
	v_mfma_f32_16x16x32_bf16 v[108:111], v[200:203], v[222:225], v[108:111]
	v_mfma_f32_16x16x32_bf16 v[104:107], v[204:207], v[222:225], v[104:107]
	v_mfma_f32_16x16x32_bf16 v[100:103], v[208:211], v[222:225], v[100:103]
	v_mfma_f32_16x16x32_bf16 v[96:99], v[212:215], v[222:225], v[96:99]
	s_waitcnt vmcnt(9)
	ds_write_b128 v164, v[120:123] offset:20480
	s_waitcnt lgkmcnt(7)
	v_mfma_f32_16x16x32_bf16 v[92:95], v[200:203], v[226:229], v[92:95]
	v_mfma_f32_16x16x32_bf16 v[88:91], v[204:207], v[226:229], v[88:91]
	v_mfma_f32_16x16x32_bf16 v[84:87], v[208:211], v[226:229], v[84:87]
	v_mfma_f32_16x16x32_bf16 v[80:83], v[212:215], v[226:229], v[80:83]
	s_waitcnt vmcnt(8)
	ds_write_b128 v164, v[124:127] offset:24576
	s_waitcnt lgkmcnt(7)
	v_mfma_f32_16x16x32_bf16 v[76:79], v[200:203], v[230:233], v[76:79]
	v_mfma_f32_16x16x32_bf16 v[72:75], v[204:207], v[230:233], v[72:75]
	v_mfma_f32_16x16x32_bf16 v[68:71], v[208:211], v[230:233], v[68:71]
	v_mfma_f32_16x16x32_bf16 v[64:67], v[212:215], v[230:233], v[64:67]
	s_waitcnt vmcnt(7)
	ds_write_b128 v164, v[132:135] offset:28672
	s_waitcnt lgkmcnt(7)
	v_mfma_f32_16x16x32_bf16 v[60:63], v[200:203], v[234:237], v[60:63]
	v_mfma_f32_16x16x32_bf16 v[56:59], v[204:207], v[234:237], v[56:59]
	v_mfma_f32_16x16x32_bf16 v[52:55], v[208:211], v[234:237], v[52:55]
	v_mfma_f32_16x16x32_bf16 v[48:51], v[212:215], v[234:237], v[48:51]
	s_waitcnt vmcnt(6)
	ds_write_b128 v164, v[136:139] offset:45056
	s_waitcnt lgkmcnt(7)
	v_mfma_f32_16x16x32_bf16 v[44:47], v[200:203], v[238:241], v[44:47]
	v_mfma_f32_16x16x32_bf16 v[40:43], v[204:207], v[238:241], v[40:43]
	v_mfma_f32_16x16x32_bf16 v[36:39], v[208:211], v[238:241], v[36:39]
	v_mfma_f32_16x16x32_bf16 v[32:35], v[212:215], v[238:241], v[32:35]
	ds_write_b128 v164, v[128:131] offset:40960
	s_waitcnt lgkmcnt(7)
	v_mfma_f32_16x16x32_bf16 v[28:31], v[200:203], v[242:245], v[28:31]
	v_mfma_f32_16x16x32_bf16 v[24:27], v[204:207], v[242:245], v[24:27]
	v_mfma_f32_16x16x32_bf16 v[20:23], v[208:211], v[242:245], v[20:23]
	v_mfma_f32_16x16x32_bf16 v[16:19], v[212:215], v[242:245], v[16:19]
	s_waitcnt lgkmcnt(6)
	v_mfma_f32_16x16x32_bf16 v[12:15], v[200:203], v[246:249], v[12:15]
	v_mfma_f32_16x16x32_bf16 v[8:11], v[204:207], v[246:249], v[8:11]
	v_mfma_f32_16x16x32_bf16 v[4:7], v[208:211], v[246:249], v[4:7]
	v_mfma_f32_16x16x32_bf16 v[0:3], v[212:215], v[246:249], v[0:3]
	s_setprio 0
	s_min_u32 s18, s21, 0x780
	s_lshl_b32 s18, s18, 1
	s_mov_b32 s29, s19
	s_add_i32 s28, s18, 0xc0
	v_lshl_add_u64 v[112:113], v[152:153], 0, s[18:19]
	v_lshl_add_u64 v[120:121], v[154:155], 0, s[18:19]
	v_lshl_add_u64 v[122:123], v[156:157], 0, s[28:29]
	v_lshl_add_u64 v[124:125], v[158:159], 0, s[28:29]
	v_lshl_add_u64 v[132:133], v[160:161], 0, s[28:29]
	v_lshl_add_u64 v[136:137], v[162:163], 0, s[28:29]
	s_waitcnt lgkmcnt(0)
	s_barrier
	global_load_dwordx4 v[112:115], v[112:113], off offset:192
	ds_read_b128 v[200:203], v165 offset:40960
	global_load_dwordx4 v[128:131], v[120:121], off offset:192
	ds_read_b128 v[204:207], v165 offset:41984
	global_load_dwordx4 v[120:123], v[122:123], off
	ds_read_b128 v[208:211], v165 offset:43008
	global_load_dwordx4 v[124:127], v[124:125], off
	ds_read_b128 v[212:215], v165 offset:44032
	global_load_dwordx4 v[132:135], v[132:133], off
	ds_read_b128 v[216:219], v167
	global_load_dwordx4 v[136:139], v[136:137], off
	ds_read_b128 v[222:225], v167 offset:1024
	ds_read_b128 v[226:229], v167 offset:2048
	ds_read_b128 v[230:233], v167 offset:3072
	ds_read_b128 v[234:237], v167 offset:4096
	ds_read_b128 v[238:241], v167 offset:5120
	ds_read_b128 v[242:245], v167 offset:6144
	ds_read_b128 v[246:249], v167 offset:7168
	s_setprio 1
	s_waitcnt lgkmcnt(7)
	v_mfma_f32_16x16x32_bf16 v[148:151], v[200:203], v[216:219], v[148:151]
	v_mfma_f32_16x16x32_bf16 v[144:147], v[204:207], v[216:219], v[144:147]
	v_mfma_f32_16x16x32_bf16 v[140:143], v[208:211], v[216:219], v[140:143]
	v_mfma_f32_16x16x32_bf16 v[116:119], v[212:215], v[216:219], v[116:119]
	s_waitcnt vmcnt(9)
	ds_write_b128 v164, v[170:173]
	s_waitcnt lgkmcnt(7)
	v_mfma_f32_16x16x32_bf16 v[108:111], v[200:203], v[222:225], v[108:111]
	v_mfma_f32_16x16x32_bf16 v[104:107], v[204:207], v[222:225], v[104:107]
	v_mfma_f32_16x16x32_bf16 v[100:103], v[208:211], v[222:225], v[100:103]
	v_mfma_f32_16x16x32_bf16 v[96:99], v[212:215], v[222:225], v[96:99]
	ds_write_b128 v164, v[178:181] offset:4096
	s_waitcnt lgkmcnt(7)
	v_mfma_f32_16x16x32_bf16 v[92:95], v[200:203], v[226:229], v[92:95]
	v_mfma_f32_16x16x32_bf16 v[88:91], v[204:207], v[226:229], v[88:91]
	v_mfma_f32_16x16x32_bf16 v[84:87], v[208:211], v[226:229], v[84:87]
	v_mfma_f32_16x16x32_bf16 v[80:83], v[212:215], v[226:229], v[80:83]
	ds_write_b128 v164, v[182:185] offset:8192
	s_waitcnt lgkmcnt(7)
	v_mfma_f32_16x16x32_bf16 v[76:79], v[200:203], v[230:233], v[76:79]
	v_mfma_f32_16x16x32_bf16 v[72:75], v[204:207], v[230:233], v[72:75]
	v_mfma_f32_16x16x32_bf16 v[68:71], v[208:211], v[230:233], v[68:71]
	v_mfma_f32_16x16x32_bf16 v[64:67], v[212:215], v[230:233], v[64:67]
	s_waitcnt vmcnt(8)
	ds_write_b128 v164, v[186:189] offset:12288
	s_waitcnt lgkmcnt(7)
	v_mfma_f32_16x16x32_bf16 v[60:63], v[200:203], v[234:237], v[60:63]
	v_mfma_f32_16x16x32_bf16 v[56:59], v[204:207], v[234:237], v[56:59]
	v_mfma_f32_16x16x32_bf16 v[52:55], v[208:211], v[234:237], v[52:55]
	v_mfma_f32_16x16x32_bf16 v[48:51], v[212:215], v[234:237], v[48:51]
	s_waitcnt vmcnt(7)
	ds_write_b128 v164, v[190:193] offset:32768
	s_waitcnt lgkmcnt(7)
	v_mfma_f32_16x16x32_bf16 v[44:47], v[200:203], v[238:241], v[44:47]
	v_mfma_f32_16x16x32_bf16 v[40:43], v[204:207], v[238:241], v[40:43]
	v_mfma_f32_16x16x32_bf16 v[36:39], v[208:211], v[238:241], v[36:39]
	v_mfma_f32_16x16x32_bf16 v[32:35], v[212:215], v[238:241], v[32:35]
	s_waitcnt vmcnt(6)
	ds_write_b128 v164, v[194:197] offset:36864
	s_waitcnt lgkmcnt(7)
	v_mfma_f32_16x16x32_bf16 v[28:31], v[200:203], v[242:245], v[28:31]
	v_mfma_f32_16x16x32_bf16 v[24:27], v[204:207], v[242:245], v[24:27]
	v_mfma_f32_16x16x32_bf16 v[20:23], v[208:211], v[242:245], v[20:23]
	v_mfma_f32_16x16x32_bf16 v[16:19], v[212:215], v[242:245], v[16:19]
	s_waitcnt lgkmcnt(6)
	v_mfma_f32_16x16x32_bf16 v[12:15], v[200:203], v[246:249], v[12:15]
	v_mfma_f32_16x16x32_bf16 v[8:11], v[204:207], v[246:249], v[8:11]
	v_mfma_f32_16x16x32_bf16 v[4:7], v[208:211], v[246:249], v[4:7]
	v_mfma_f32_16x16x32_bf16 v[0:3], v[212:215], v[246:249], v[0:3]
	s_setprio 0
	s_add_i32 s1, s1, 2
	s_cmp_lt_u32 s1, 62
	s_mov_b32 s21, s26
	s_waitcnt lgkmcnt(0)
	s_barrier
	s_cbranch_scc1 .LBB0_1795
	s_waitcnt vmcnt(5)
	v_mov_b32_e32 v112, v220
	s_nop 0
	v_and_b32_e32 v114, 0xffffff80, v112
	v_bfe_u32 v176, v112, 4, 2
	v_add_u32_e32 v114, s20, v114
	v_and_b32_e32 v113, 64, v112
	v_and_or_b32 v184, v112, 15, v114
	v_lshlrev_b32_e32 v112, 2, v176
	v_or3_b32 v178, v112, v113, s0
	v_ashrrev_i32_e32 v179, 31, v178
	v_lshlrev_b64 v[216:217], 2, v[178:179]
	v_ashrrev_i32_e32 v185, 31, v184
	v_or_b32_e32 v194, 16, v184
	v_lshl_add_u64 v[182:183], s[70:71], 0, v[216:217]
	v_lshlrev_b64 v[218:219], 12, v[184:185]
	v_ashrrev_i32_e32 v195, 31, v194
	v_or_b32_e32 v190, 32, v184
	v_lshl_add_u64 v[112:113], v[182:183], 0, v[218:219]
	v_lshlrev_b64 v[196:197], 12, v[194:195]
	v_ashrrev_i32_e32 v191, 31, v190
	v_or_b32_e32 v186, 48, v184
	global_load_dwordx4 v[200:203], v[112:113], off
	global_load_dwordx4 v[204:207], v[112:113], off offset:64
	global_load_dwordx4 v[208:211], v[112:113], off offset:128
	global_load_dwordx4 v[212:215], v[112:113], off offset:192
	v_lshl_add_u64 v[112:113], v[182:183], 0, v[196:197]
	v_lshlrev_b64 v[192:193], 12, v[190:191]
	v_ashrrev_i32_e32 v187, 31, v186
	global_load_dwordx4 v[172:175], v[112:113], off
	global_load_dwordx4 v[168:171], v[112:113], off offset:64
	global_load_dwordx4 v[164:167], v[112:113], off offset:128
	global_load_dwordx4 v[160:163], v[112:113], off offset:192
	v_lshl_add_u64 v[112:113], v[182:183], 0, v[192:193]
	v_lshlrev_b64 v[188:189], 12, v[186:187]
	global_load_dwordx4 v[156:159], v[112:113], off
	global_load_dwordx4 v[152:155], v[112:113], off offset:64
	global_load_dwordx4 v[136:139], v[112:113], off offset:128
	global_load_dwordx4 v[132:135], v[112:113], off offset:192
	v_lshl_add_u64 v[112:113], v[182:183], 0, v[188:189]
	global_load_dwordx4 v[128:131], v[112:113], off
	global_load_dwordx4 v[124:127], v[112:113], off offset:64
	global_load_dwordx4 v[120:123], v[112:113], off offset:128
	s_nop 0
	global_load_dwordx4 v[112:115], v[112:113], off offset:192
	v_cmp_eq_u32_e32 vcc, 0, v176
	v_lshlrev_b64 v[222:223], 11, v[184:185]
	v_lshlrev_b64 v[180:181], 1, v[178:179]
	v_lshl_add_u64 v[218:219], s[70:71], 0, v[218:219]
	v_lshl_add_u64 v[224:225], s[8:9], 0, v[222:223]
	v_lshl_add_u64 v[216:217], v[218:219], 0, v[216:217]
	v_lshl_add_u64 v[218:219], v[224:225], 0, v[180:181]
	v_lshl_add_u64 v[222:223], s[72:73], 0, v[222:223]
	v_lshl_add_u64 v[222:223], v[222:223], 0, v[180:181]
	s_waitcnt vmcnt(15)
	v_pk_add_f32 v[148:149], v[148:149], v[200:201]
	s_waitcnt vmcnt(14)
	v_pk_add_f32 v[144:145], v[144:145], v[204:205]
	v_pk_add_f32 v[146:147], v[146:147], v[206:207]
	s_waitcnt vmcnt(13)
	v_pk_add_f32 v[140:141], v[140:141], v[208:209]
	v_mul_f32_e32 v176, v149, v149
	v_mul_f32_e32 v206, v145, v145
	v_pk_add_f32 v[150:151], v[150:151], v[202:203]
	s_waitcnt vmcnt(12)
	v_pk_add_f32 v[116:117], v[116:117], v[212:213]
	v_mul_f32_e32 v212, v141, v141
	v_pk_fma_f32 v[226:227], v[148:149], v[148:149], v[176:177] op_sel_hi:[1,1,0]
	v_pk_fma_f32 v[206:207], v[144:145], v[144:145], v[206:207] op_sel_hi:[1,1,0]
	v_pk_add_f32 v[142:143], v[142:143], v[210:211]
	v_mul_f32_e32 v202, v151, v151
	v_mul_f32_e32 v208, v147, v147
	v_pk_fma_f32 v[212:213], v[140:141], v[140:141], v[212:213] op_sel_hi:[1,1,0]
	v_pk_fma_f32 v[226:227], v[150:151], v[150:151], v[226:227]
	v_pk_fma_f32 v[206:207], v[146:147], v[146:147], v[206:207]
	v_mul_f32_e32 v224, v143, v143
	v_pk_fma_f32 v[212:213], v[142:143], v[142:143], v[212:213]
	v_pk_add_f32 v[202:203], v[202:203], v[226:227] op_sel_hi:[0,1]
	v_pk_add_f32 v[206:207], v[208:209], v[206:207] op_sel_hi:[0,1]
	v_pk_add_f32 v[208:209], v[224:225], v[212:213] op_sel_hi:[0,1]
	v_pk_add_f32 v[202:203], v[202:203], v[206:207]
	v_cvt_pk_bf16_f32 v200, v148, v149
	v_cvt_pk_bf16_f32 v201, v150, v151
	v_cvt_pk_bf16_f32 v204, v144, v145
	v_cvt_pk_bf16_f32 v205, v146, v147
	v_cvt_pk_bf16_f32 v210, v140, v141
	v_cvt_pk_bf16_f32 v211, v142, v143
	s_nop 0
	v_pk_add_f32 v[202:203], v[202:203], v[208:209]
	v_pk_add_f32 v[118:119], v[118:119], v[214:215]
	global_store_dwordx4 v[216:217], v[148:151], off
	global_store_dwordx2 v[218:219], v[200:201], off
	global_store_dwordx4 v[216:217], v[144:147], off offset:64
	s_nop 1
	v_add_co_u32_e64 v144, s[0:1], s24, v222
	s_nop 1
	v_addc_co_u32_e64 v145, s[0:1], 0, v223, s[0:1]
	global_store_dwordx2 v[144:145], v[204:205], off offset:32
	global_store_dwordx4 v[216:217], v[140:143], off offset:128
	global_store_dwordx2 v[144:145], v[210:211], off offset:64
	global_store_dwordx4 v[216:217], v[116:119], off offset:192
	v_cvt_pk_bf16_f32 v140, v116, v117
	v_cvt_pk_bf16_f32 v141, v118, v119
	global_store_dwordx2 v[144:145], v[140:141], off offset:96
	v_mul_f32_e32 v140, v117, v117
	v_pk_fma_f32 v[116:117], v[116:117], v[116:117], v[140:141] op_sel_hi:[1,1,0]
	s_nop 0
	v_pk_fma_f32 v[116:117], v[118:119], v[118:119], v[116:117]
	v_mul_f32_e32 v118, v119, v119
	v_pk_add_f32 v[116:117], v[118:119], v[116:117] op_sel_hi:[0,1]
	v_pk_add_f32 v[116:117], v[202:203], v[116:117]
	s_nop 0
	v_mov_b32_e32 v117, v116
	s_nop 1
	v_permlane32_swap_b32_e32 v116, v117
	v_add_f32_e32 v116, v116, v117
	v_mov_b32_e32 v117, v116
	s_nop 1
	v_permlane16_swap_b32_e32 v116, v117
	s_and_saveexec_b64 s[0:1], vcc
	s_cbranch_execz .LBB0_1798
	v_lshl_add_u64 v[118:119], v[184:185], 2, s[10:11]
	v_add_f32_e32 v116, v116, v117
	global_atomic_add_f32 v[118:119], v116, off

.LBB0_1867:
	s_min_u32 s24, s22, 0xe0
	s_lshl_b32 s6, s24, 2
	v_lshl_add_u64 v[94:95], v[70:71], 0, s[6:7]
	v_lshl_add_u64 v[96:97], v[72:73], 0, s[6:7]
	s_lshl_b32 s6, s24, 1
	v_lshl_add_u64 v[102:103], v[66:67], 0, s[6:7]
	v_lshl_add_u64 v[104:105], v[68:69], 0, s[6:7]
	global_load_dwordx4 v[78:81], v[94:95], off offset:16 nt
	global_load_dwordx4 v[82:85], v[94:95], off nt
	global_load_dwordx4 v[86:89], v[96:97], off offset:16 nt
	global_load_dwordx4 v[90:93], v[96:97], off nt
	global_load_dwordx4 v[98:101], v[104:105], off
	s_and_b32 s6, s23, 0x80
	global_load_dwordx4 v[94:97], v[102:103], off
	v_add_u32_e32 v77, s6, v74
	v_or_b32_e32 v102, s6, v76
	v_lshl_or_b32 v77, v77, 6, v75
	v_lshl_or_b32 v130, v102, 6, v75
	ds_read_b128 v[102:105], v77
	ds_read_b128 v[106:109], v77 offset:1024
	ds_read_b128 v[110:113], v130 offset:16384
	ds_read_b128 v[114:117], v130 offset:17408
	ds_read_b128 v[118:121], v77 offset:2048
	ds_read_b128 v[122:125], v77 offset:3072
	ds_read_b128 v[126:129], v130 offset:18432
	ds_read_b128 v[130:133], v130 offset:19456
	s_setprio 1
	s_waitcnt lgkmcnt(5)
	v_mfma_f32_16x16x32_bf16 v[52:55], v[110:113], v[102:105], v[52:55]
	s_waitcnt lgkmcnt(4)
	v_mfma_f32_16x16x32_bf16 v[48:51], v[114:117], v[102:105], v[48:51]
	s_waitcnt lgkmcnt(1)
	v_mfma_f32_16x16x32_bf16 v[40:43], v[126:129], v[102:105], v[40:43]
	s_waitcnt lgkmcnt(0)
	v_mfma_f32_16x16x32_bf16 v[20:23], v[130:133], v[102:105], v[20:23]
	v_mfma_f32_16x16x32_bf16 v[44:47], v[110:113], v[106:109], v[44:47]
	v_mfma_f32_16x16x32_bf16 v[36:39], v[114:117], v[106:109], v[36:39]
	v_mfma_f32_16x16x32_bf16 v[28:31], v[126:129], v[106:109], v[28:31]
	v_mfma_f32_16x16x32_bf16 v[16:19], v[130:133], v[106:109], v[16:19]
	v_mfma_f32_16x16x32_bf16 v[32:35], v[110:113], v[118:121], v[32:35]
	v_mfma_f32_16x16x32_bf16 v[24:27], v[114:117], v[118:121], v[24:27]
	v_mfma_f32_16x16x32_bf16 v[12:15], v[126:129], v[118:121], v[12:15]
	v_mfma_f32_16x16x32_bf16 v[8:11], v[130:133], v[118:121], v[8:11]
	v_mfma_f32_16x16x32_bf16 v[60:63], v[110:113], v[122:125], v[60:63]
	v_mfma_f32_16x16x32_bf16 v[56:59], v[114:117], v[122:125], v[56:59]
	v_mfma_f32_16x16x32_bf16 v[4:7], v[126:129], v[122:125], v[4:7]
	v_mfma_f32_16x16x32_bf16 v[0:3], v[130:133], v[122:125], v[0:3]
	s_setprio 0
	s_waitcnt vmcnt(4)
	v_and_b32_sdwa v102, v84, v155 dst_sel:DWORD dst_unused:UNUSED_PAD src0_sel:WORD_1 src1_sel:DWORD
	v_and_b32_sdwa v103, v82, v155 dst_sel:DWORD dst_unused:UNUSED_PAD src0_sel:WORD_1 src1_sel:DWORD
	v_add3_u32 v84, v84, v102, s17
	v_and_b32_sdwa v102, v85, v155 dst_sel:DWORD dst_unused:UNUSED_PAD src0_sel:WORD_1 src1_sel:DWORD
	v_add3_u32 v82, v82, v103, s17
	v_and_b32_sdwa v103, v83, v155 dst_sel:DWORD dst_unused:UNUSED_PAD src0_sel:WORD_1 src1_sel:DWORD
	v_add3_u32 v85, v85, v102, s17
	v_add3_u32 v83, v83, v103, s17
	v_and_b32_e32 v85, 0xffff0000, v85
	v_and_b32_e32 v102, 0xffff0000, v83
	v_or_b32_sdwa v83, v85, v84 dst_sel:DWORD dst_unused:UNUSED_PAD src0_sel:DWORD src1_sel:WORD_1
	v_and_b32_sdwa v85, v78, v155 dst_sel:DWORD dst_unused:UNUSED_PAD src0_sel:WORD_1 src1_sel:DWORD
	v_and_b32_sdwa v84, v80, v155 dst_sel:DWORD dst_unused:UNUSED_PAD src0_sel:WORD_1 src1_sel:DWORD
	v_add3_u32 v78, v78, v85, s17
	v_and_b32_sdwa v85, v79, v155 dst_sel:DWORD dst_unused:UNUSED_PAD src0_sel:WORD_1 src1_sel:DWORD
	v_add3_u32 v80, v80, v84, s17
	v_and_b32_sdwa v84, v81, v155 dst_sel:DWORD dst_unused:UNUSED_PAD src0_sel:WORD_1 src1_sel:DWORD
	v_add3_u32 v79, v79, v85, s17
	v_add3_u32 v81, v81, v84, s17
	v_and_b32_e32 v79, 0xffff0000, v79
	v_and_b32_e32 v81, 0xffff0000, v81
	v_or_b32_sdwa v84, v79, v78 dst_sel:DWORD dst_unused:UNUSED_PAD src0_sel:DWORD src1_sel:WORD_1
	s_waitcnt vmcnt(2)
	v_and_b32_sdwa v79, v90, v155 dst_sel:DWORD dst_unused:UNUSED_PAD src0_sel:WORD_1 src1_sel:DWORD
	v_or_b32_sdwa v85, v81, v80 dst_sel:DWORD dst_unused:UNUSED_PAD src0_sel:DWORD src1_sel:WORD_1
	v_add3_u32 v80, v90, v79, s17
	v_and_b32_sdwa v79, v93, v155 dst_sel:DWORD dst_unused:UNUSED_PAD src0_sel:WORD_1 src1_sel:DWORD
	v_and_b32_sdwa v81, v91, v155 dst_sel:DWORD dst_unused:UNUSED_PAD src0_sel:WORD_1 src1_sel:DWORD
	s_xor_b32 s6, s6, 0x80
	v_and_b32_sdwa v78, v92, v155 dst_sel:DWORD dst_unused:UNUSED_PAD src0_sel:WORD_1 src1_sel:DWORD
	v_add3_u32 v79, v93, v79, s17
	v_add3_u32 v81, v91, v81, s17
	v_add_u32_e32 v77, s6, v64
	v_add3_u32 v78, v92, v78, s17
	v_and_b32_e32 v79, 0xffff0000, v79
	v_and_b32_e32 v81, 0xffff0000, v81
	v_lshl_or_b32 v77, v77, 6, v65
	v_or_b32_sdwa v82, v102, v82 dst_sel:DWORD dst_unused:UNUSED_PAD src0_sel:DWORD src1_sel:WORD_1
	v_or_b32_sdwa v79, v79, v78 dst_sel:DWORD dst_unused:UNUSED_PAD src0_sel:DWORD src1_sel:WORD_1
	v_or_b32_sdwa v78, v81, v80 dst_sel:DWORD dst_unused:UNUSED_PAD src0_sel:DWORD src1_sel:WORD_1
	v_and_b32_sdwa v81, v86, v155 dst_sel:DWORD dst_unused:UNUSED_PAD src0_sel:WORD_1 src1_sel:DWORD
	ds_write_b128 v77, v[82:85]
	v_add3_u32 v82, v86, v81, s17
	v_and_b32_sdwa v81, v89, v155 dst_sel:DWORD dst_unused:UNUSED_PAD src0_sel:WORD_1 src1_sel:DWORD
	v_and_b32_sdwa v83, v87, v155 dst_sel:DWORD dst_unused:UNUSED_PAD src0_sel:WORD_1 src1_sel:DWORD
	v_and_b32_sdwa v80, v88, v155 dst_sel:DWORD dst_unused:UNUSED_PAD src0_sel:WORD_1 src1_sel:DWORD
	v_add3_u32 v81, v89, v81, s17
	v_add3_u32 v83, v87, v83, s17
	v_add3_u32 v80, v88, v80, s17
	v_and_b32_e32 v81, 0xffff0000, v81
	v_and_b32_e32 v83, 0xffff0000, v83
	s_addk_i32 s23, 0x80
	s_add_i32 s22, s22, 32
	v_or_b32_sdwa v81, v81, v80 dst_sel:DWORD dst_unused:UNUSED_PAD src0_sel:DWORD src1_sel:WORD_1
	v_or_b32_sdwa v80, v83, v82 dst_sel:DWORD dst_unused:UNUSED_PAD src0_sel:DWORD src1_sel:WORD_1
	s_cmpk_lg_i32 s23, 0x400
	ds_write_b128 v77, v[78:81] offset:4096
	s_waitcnt vmcnt(0)
	ds_write_b128 v77, v[94:97] offset:16384
	ds_write_b128 v77, v[98:101] offset:20480
	s_waitcnt lgkmcnt(0)
	s_barrier
	s_cbranch_scc1 .LBB0_1867
	s_lshl_b64 s[22:23], s[10:11], 11
	v_mov_b32_e32 v106, v220
	s_add_u32 s22, s13, s22
	s_addc_u32 s23, s14, s23
	v_ashrrev_i32_e32 v102, 2, v106
	s_lshl_b64 s[24:25], s[8:9], 11
	v_add_u32_e32 v104, 64, v102
	s_add_u32 s24, s15, s24
	v_ashrrev_i32_e32 v105, 31, v104
	s_addc_u32 s25, s16, s25
	v_lshlrev_b64 v[64:65], 11, v[104:105]
	v_min_i32_e32 v66, 0x7f, v102
	v_lshlrev_b32_e32 v67, 4, v106
	v_lshl_add_u64 v[64:65], s[24:25], 0, v[64:65]
	v_and_b32_e32 v144, 48, v67
	v_ashrrev_i32_e32 v67, 31, v66
	v_ashrrev_i32_e32 v103, 31, v102
	v_min_i32_e32 v68, 0x7f, v104
	v_lshl_add_u64 v[148:149], v[64:65], 0, v[144:145]
	v_lshlrev_b64 v[64:65], 11, v[66:67]
	v_lshlrev_b64 v[70:71], 11, v[102:103]
	v_lshl_add_u64 v[64:65], s[22:23], 0, v[64:65]
	v_ashrrev_i32_e32 v69, 31, v68
	v_lshl_add_u64 v[70:71], s[24:25], 0, v[70:71]
	v_lshl_add_u64 v[150:151], v[64:65], 0, v[144:145]
	v_lshlrev_b64 v[64:65], 11, v[68:69]
	v_lshl_add_u64 v[146:147], v[70:71], 0, v[144:145]
	v_lshl_add_u64 v[64:65], s[22:23], 0, v[64:65]
	global_load_dwordx4 v[86:89], v[150:151], off
	global_load_dwordx4 v[90:93], v[146:147], off
	v_lshl_add_u64 v[152:153], v[64:65], 0, v[144:145]
	global_load_dwordx4 v[94:97], v[148:149], off
	global_load_dwordx4 v[98:101], v[152:153], off
	global_load_dwordx4 v[124:127], v[146:147], off offset:64
	global_load_dwordx4 v[128:131], v[150:151], off offset:64
	global_load_dwordx4 v[132:135], v[148:149], off offset:64
	global_load_dwordx4 v[136:139], v[152:153], off offset:64
	v_lshrrev_b32_e32 v103, 4, v106
	v_lshrrev_b32_e32 v105, 2, v106
	v_sub_u32_e32 v110, 0, v103
	v_and_b32_e32 v107, 15, v106
	v_lshrrev_b32_e32 v108, 1, v106
	v_lshlrev_b32_e32 v109, 6, v106
	v_sub_u32_e32 v105, 0, v105
	v_xor_b32_e32 v106, v106, v110
	v_and_or_b32 v107, v108, s19, v107
	v_xor_b32_e32 v103, v103, v105
	v_lshlrev_b32_e32 v105, 4, v106
	v_lshlrev_b32_e32 v156, 6, v107
	v_lshlrev_b32_e32 v103, 4, v103
	v_and_b32_e32 v105, 48, v105
	v_mov_b32_e32 v64, 0
	v_and_b32_e32 v144, 0x13c0, v109
	v_add_u32_e32 v106, 0x2000, v156
	v_and_b32_e32 v157, 48, v103
	v_lshl_or_b32 v158, v102, 6, v105
	s_mov_b32 s11, 0
	s_mov_b32 s9, -2
	v_mov_b32_e32 v65, v64
	v_mov_b32_e32 v66, v64
	v_mov_b32_e32 v67, v64
	v_mov_b32_e32 v68, v64
	v_mov_b32_e32 v69, v64
	v_mov_b32_e32 v70, v64
	v_mov_b32_e32 v71, v64
	v_mov_b32_e32 v72, v64
	v_mov_b32_e32 v73, v64
	v_mov_b32_e32 v74, v64
	v_mov_b32_e32 v75, v64
	v_mov_b32_e32 v76, v64
	v_mov_b32_e32 v77, v64
	v_mov_b32_e32 v78, v64
	v_mov_b32_e32 v79, v64
	v_mov_b32_e32 v80, v64
	v_mov_b32_e32 v81, v64
	v_mov_b32_e32 v82, v64
	v_mov_b32_e32 v83, v64
	v_mov_b32_e32 v84, v64
	v_mov_b32_e32 v85, v64
	v_lshl_or_b32 v159, v104, 6, v105
	v_or_b32_e32 v160, v157, v144
	v_add_u32_e32 v161, v157, v106
	v_mov_b32_e32 v102, v64
	v_mov_b32_e32 v103, v64
	v_mov_b32_e32 v104, v64
	v_mov_b32_e32 v105, v64
	v_mov_b32_e32 v106, v64
	v_mov_b32_e32 v107, v64
	v_mov_b32_e32 v108, v64
	v_mov_b32_e32 v109, v64
	v_mov_b32_e32 v110, v64
	v_mov_b32_e32 v111, v64
	v_mov_b32_e32 v112, v64
	s_waitcnt vmcnt(6)
	ds_write_b128 v158, v[90:93] offset:16384
	ds_write_b128 v158, v[86:89]
	s_waitcnt vmcnt(5)
	ds_write_b128 v159, v[94:97] offset:16384
	s_waitcnt vmcnt(4)
	ds_write_b128 v159, v[98:101]
	v_mov_b32_e32 v86, v64
	v_mov_b32_e32 v87, v64
	v_mov_b32_e32 v88, v64
	v_mov_b32_e32 v89, v64
	v_mov_b32_e32 v90, v64
	v_mov_b32_e32 v91, v64
	v_mov_b32_e32 v92, v64
	v_mov_b32_e32 v93, v64
	v_mov_b32_e32 v94, v64
	v_mov_b32_e32 v95, v64
	v_mov_b32_e32 v96, v64
	v_mov_b32_e32 v97, v64
	v_mov_b32_e32 v98, v64
	v_mov_b32_e32 v99, v64
	v_mov_b32_e32 v100, v64
	v_mov_b32_e32 v101, v64
	v_mov_b32_e32 v113, v64
	v_mov_b32_e32 v114, v64
	v_mov_b32_e32 v115, v64
	v_mov_b32_e32 v116, v64
	v_mov_b32_e32 v117, v64
	v_mov_b32_e32 v118, v64
	v_mov_b32_e32 v119, v64
	v_mov_b32_e32 v120, v64
	v_mov_b32_e32 v121, v64
	v_mov_b32_e32 v122, v64
	v_mov_b32_e32 v123, v64
	v_mov_b32_e32 v140, v64
	v_mov_b32_e32 v141, v64
	v_mov_b32_e32 v142, v64
	v_mov_b32_e32 v143, v64
	s_waitcnt lgkmcnt(0)
	s_barrier
	s_cmpk_lt_u32 s2, 0x100
	s_cbranch_scc1 .Lstag_10
	s_sleep 8
.Lstag_10:
.LBB0_1869:
	s_add_i32 s22, s11, 64
	s_min_u32 s6, s22, 0x3e0
	s_lshl_b32 s6, s6, 1
	v_lshl_add_u64 v[162:163], v[150:151], 0, s[6:7]
	v_lshl_add_u64 v[166:167], v[152:153], 0, s[6:7]
	v_lshl_add_u64 v[170:171], v[146:147], 0, s[6:7]
	v_lshl_add_u64 v[174:175], v[148:149], 0, s[6:7]
	global_load_dwordx4 v[162:165], v[162:163], off
	v_add_u32_e32 v198, v157, v156
	global_load_dwordx4 v[166:169], v[166:167], off
	v_add_u32_e32 v206, v157, v144
	global_load_dwordx4 v[170:173], v[170:171], off
	ds_read_b128 v[178:181], v198
	global_load_dwordx4 v[174:177], v[174:175], off
	ds_read_b128 v[182:185], v198 offset:1024
	ds_read_b128 v[186:189], v206 offset:16384
	ds_read_b128 v[190:193], v206 offset:17408
	ds_read_b128 v[194:197], v198 offset:2048
	ds_read_b128 v[198:201], v198 offset:3072
	ds_read_b128 v[202:205], v206 offset:18432
	ds_read_b128 v[206:209], v206 offset:19456
	s_setprio 1
	s_waitcnt lgkmcnt(5)
	v_mfma_f32_16x16x32_bf16 v[140:143], v[186:189], v[178:181], v[140:143]
	s_waitcnt lgkmcnt(4)
	v_mfma_f32_16x16x32_bf16 v[120:123], v[190:193], v[178:181], v[120:123]
	s_waitcnt lgkmcnt(1)
	v_mfma_f32_16x16x32_bf16 v[116:119], v[202:205], v[178:181], v[116:119]
	s_waitcnt lgkmcnt(0)
	v_mfma_f32_16x16x32_bf16 v[112:115], v[206:209], v[178:181], v[112:115]
	v_mfma_f32_16x16x32_bf16 v[108:111], v[186:189], v[182:185], v[108:111]
	v_mfma_f32_16x16x32_bf16 v[104:107], v[190:193], v[182:185], v[104:107]
	v_mfma_f32_16x16x32_bf16 v[100:103], v[202:205], v[182:185], v[100:103]
	v_mfma_f32_16x16x32_bf16 v[96:99], v[206:209], v[182:185], v[96:99]
	v_mfma_f32_16x16x32_bf16 v[92:95], v[186:189], v[194:197], v[92:95]
	v_mfma_f32_16x16x32_bf16 v[88:91], v[190:193], v[194:197], v[88:91]
	v_mfma_f32_16x16x32_bf16 v[84:87], v[202:205], v[194:197], v[84:87]
	v_mfma_f32_16x16x32_bf16 v[80:83], v[206:209], v[194:197], v[80:83]
	v_mfma_f32_16x16x32_bf16 v[76:79], v[186:189], v[198:201], v[76:79]
	v_mfma_f32_16x16x32_bf16 v[72:75], v[190:193], v[198:201], v[72:75]
	v_mfma_f32_16x16x32_bf16 v[68:71], v[202:205], v[198:201], v[68:71]
	v_mfma_f32_16x16x32_bf16 v[64:67], v[206:209], v[198:201], v[64:67]
	s_setprio 0
	s_min_u32 s6, s11, 0x380
	s_lshl_b32 s6, s6, 1
	s_waitcnt vmcnt(5)
	ds_write_b128 v158, v[124:127] offset:24576
	s_waitcnt vmcnt(4)
	ds_write_b128 v158, v[132:135] offset:28672
	v_lshl_add_u64 v[124:125], v[150:151], 0, s[6:7]
	v_lshl_add_u64 v[126:127], v[152:153], 0, s[6:7]
	v_lshl_add_u64 v[132:133], v[146:147], 0, s[6:7]
	v_lshl_add_u64 v[134:135], v[148:149], 0, s[6:7]
	ds_write_b128 v158, v[128:131] offset:8192
	s_waitcnt vmcnt(4)
	ds_write_b128 v158, v[136:139] offset:12288
	s_waitcnt lgkmcnt(0)
	s_barrier
	global_load_dwordx4 v[128:131], v[124:125], off offset:192
	global_load_dwordx4 v[136:139], v[126:127], off offset:192
	ds_read_b128 v[178:181], v161
	global_load_dwordx4 v[124:127], v[132:133], off offset:192
	ds_read_b128 v[182:185], v160 offset:24576
	global_load_dwordx4 v[132:135], v[134:135], off offset:192
	ds_read_b128 v[186:189], v161 offset:1024
	ds_read_b128 v[190:193], v160 offset:25600
	ds_read_b128 v[194:197], v161 offset:2048
	ds_read_b128 v[198:201], v160 offset:26624
	ds_read_b128 v[202:205], v161 offset:3072
	ds_read_b128 v[206:209], v160 offset:27648
	s_setprio 1
	s_waitcnt lgkmcnt(6)
	v_mfma_f32_16x16x32_bf16 v[140:143], v[182:185], v[178:181], v[140:143]
	s_waitcnt lgkmcnt(4)
	v_mfma_f32_16x16x32_bf16 v[120:123], v[190:193], v[178:181], v[120:123]
	s_waitcnt lgkmcnt(2)
	v_mfma_f32_16x16x32_bf16 v[116:119], v[198:201], v[178:181], v[116:119]
	s_waitcnt lgkmcnt(0)
	v_mfma_f32_16x16x32_bf16 v[112:115], v[206:209], v[178:181], v[112:115]
	v_mfma_f32_16x16x32_bf16 v[108:111], v[182:185], v[186:189], v[108:111]
	v_mfma_f32_16x16x32_bf16 v[104:107], v[190:193], v[186:189], v[104:107]
	v_mfma_f32_16x16x32_bf16 v[100:103], v[198:201], v[186:189], v[100:103]
	v_mfma_f32_16x16x32_bf16 v[96:99], v[206:209], v[186:189], v[96:99]
	v_mfma_f32_16x16x32_bf16 v[92:95], v[182:185], v[194:197], v[92:95]
	v_mfma_f32_16x16x32_bf16 v[88:91], v[190:193], v[194:197], v[88:91]
	v_mfma_f32_16x16x32_bf16 v[84:87], v[198:201], v[194:197], v[84:87]
	v_mfma_f32_16x16x32_bf16 v[80:83], v[206:209], v[194:197], v[80:83]
	v_mfma_f32_16x16x32_bf16 v[76:79], v[182:185], v[202:205], v[76:79]
	v_mfma_f32_16x16x32_bf16 v[72:75], v[190:193], v[202:205], v[72:75]
	v_mfma_f32_16x16x32_bf16 v[68:71], v[198:201], v[202:205], v[68:71]
	v_mfma_f32_16x16x32_bf16 v[64:67], v[206:209], v[202:205], v[64:67]
	s_setprio 0
	s_add_i32 s9, s9, 2
	s_cmp_lt_u32 s9, 30
	s_mov_b32 s11, s22
	s_waitcnt vmcnt(7)
	ds_write_b128 v158, v[162:165]
	s_waitcnt vmcnt(6)
	ds_write_b128 v159, v[166:169]
	s_waitcnt vmcnt(5)
	ds_write_b128 v158, v[170:173] offset:16384
	s_waitcnt vmcnt(4)
	ds_write_b128 v159, v[174:177] offset:16384
	s_waitcnt lgkmcnt(0)
	s_barrier
	s_cbranch_scc1 .LBB0_1869
	s_waitcnt vmcnt(3)
	v_mov_b32_e32 v128, v220
	s_waitcnt vmcnt(1)
	v_ashrrev_i32_e32 v124, 1, v128
	v_and_b32_e32 v124, 0xffffffc0, v124
	v_add_u32_e32 v124, s10, v124
	v_and_or_b32 v124, v128, 15, v124
	v_ashrrev_i32_e32 v125, 31, v124
	v_lshl_add_u64 v[126:127], v[124:125], 2, s[0:1]
	global_load_dword v144, v[126:127], off
	v_and_b32_e32 v126, 64, v128
	v_lshrrev_b32_e32 v127, 2, v128
	v_or_b32_e32 v128, 16, v124
	v_ashrrev_i32_e32 v129, 31, v128
	v_lshl_add_u64 v[136:137], v[128:129], 2, s[0:1]
	global_load_dword v156, v[136:137], off
	v_or_b32_e32 v130, 32, v124
	v_ashrrev_i32_e32 v131, 31, v130
	v_lshlrev_b64 v[152:153], 12, v[128:129]
	v_lshl_add_u64 v[128:129], v[130:131], 2, s[0:1]
	global_load_dword v157, v[128:129], off
	s_waitcnt vmcnt(3)
	v_or_b32_e32 v132, 48, v124
	v_ashrrev_i32_e32 v133, 31, v132
	v_lshlrev_b64 v[150:151], 12, v[130:131]
	v_lshl_add_u64 v[130:131], v[132:133], 2, s[0:1]
	v_and_b32_e32 v127, 12, v127
	v_or3_b32 v126, v126, v127, s8
	v_ashrrev_i32_e32 v127, 31, v126
	v_lshlrev_b64 v[134:135], 2, v[126:127]
	v_lshl_add_u64 v[138:139], s[70:71], 0, v[134:135]
	v_lshlrev_b64 v[124:125], 12, v[124:125]
	v_lshlrev_b64 v[146:147], 12, v[132:133]
	v_lshl_add_u64 v[126:127], v[138:139], 0, v[124:125]
	v_lshl_add_u64 v[132:133], v[138:139], 0, v[152:153]
	v_lshl_add_u64 v[136:137], v[138:139], 0, v[150:151]
	v_lshl_add_u64 v[148:149], v[138:139], 0, v[146:147]
	v_lshl_add_u64 v[124:125], s[70:71], 0, v[124:125]
	v_lshl_add_u64 v[124:125], v[124:125], 0, v[134:135]
	global_load_dwordx4 v[160:163], v[148:149], off offset:128
	global_load_dwordx4 v[164:167], v[136:137], off
	global_load_dwordx4 v[168:171], v[136:137], off offset:64
	global_load_dwordx4 v[172:175], v[136:137], off offset:128
	global_load_dwordx4 v[176:179], v[132:133], off
	global_load_dwordx4 v[180:183], v[132:133], off offset:128
	global_load_dwordx4 v[184:187], v[132:133], off offset:192
	global_load_dwordx4 v[188:191], v[126:127], off
	global_load_dwordx4 v[192:195], v[126:127], off offset:64
	global_load_dwordx4 v[196:199], v[126:127], off offset:128
	global_load_dwordx4 v[200:203], v[126:127], off offset:192
	s_waitcnt vmcnt(13)
	v_fmamk_f32 v128, v144, 0x3a800000, v154
	global_load_dword v144, v[130:131], off
	v_mul_f32_e32 v129, 0x4b800000, v128
	v_cmp_gt_f32_e32 vcc, s20, v128
	s_waitcnt vmcnt(0)
	v_fmamk_f32 v144, v144, 0x3a800000, v154
	v_cndmask_b32_e32 v128, v128, v129, vcc
	v_rsq_f32_e32 v128, v128
	s_nop 0
	v_mul_f32_e32 v129, 0x45800000, v128
	v_cndmask_b32_e32 v138, v128, v129, vcc
	v_mul_f32_e32 v128, v140, v138
	v_mul_f32_e32 v129, v141, v138
	v_mul_f32_e32 v130, v142, v138
	v_mul_f32_e32 v131, v143, v138
	v_mul_f32_e32 v119, v119, v138
	v_mul_f32_e32 v139, v112, v138
	v_mul_f32_e32 v112, 0xbfb8aa3b, v128
	v_mul_f32_e32 v128, 0xbfb8aa3b, v129
	v_mul_f32_e32 v129, 0xbfb8aa3b, v130
	v_mul_f32_e32 v130, 0xbfb8aa3b, v131
	v_mul_f32_e32 v119, 0xbfb8aa3b, v119
	v_exp_f32_e32 v130, v130
	v_exp_f32_e32 v119, v119
	v_mul_f32_e32 v120, v120, v138
	v_mul_f32_e32 v121, v121, v138
	v_mul_f32_e32 v122, v122, v138
	v_mul_f32_e32 v123, v123, v138
	v_mul_f32_e32 v116, v116, v138
	v_mul_f32_e32 v117, v117, v138
	v_mul_f32_e32 v118, v118, v138
	v_add_f32_e32 v130, 1.0, v130
	v_mul_f32_e32 v113, v113, v138
	v_mul_f32_e32 v114, v114, v138
	v_mul_f32_e32 v115, v115, v138
	v_fmamk_f32 v138, v156, 0x3a800000, v154
	v_add_f32_e32 v142, 1.0, v119
	v_rcp_f32_e32 v119, v130
	v_mul_f32_e32 v130, 0xbfb8aa3b, v139
	v_mul_f32_e32 v139, 0x4b800000, v138
	v_cmp_gt_f32_e32 vcc, s20, v138
	v_mul_f32_e32 v117, 0xbfb8aa3b, v117
	v_mul_f32_e32 v118, 0xbfb8aa3b, v118
	v_cndmask_b32_e32 v138, v138, v139, vcc
	v_exp_f32_e32 v129, v129
	v_exp_f32_e32 v117, v117
	v_rsq_f32_e32 v138, v138
	v_exp_f32_e32 v118, v118
	v_mul_f32_e32 v116, 0xbfb8aa3b, v116
	v_exp_f32_e32 v112, v112
	v_exp_f32_e32 v116, v116
	v_add_f32_e32 v129, 1.0, v129
	v_add_f32_e32 v140, 1.0, v117
	v_mul_f32_e32 v139, 0x45800000, v138
	v_add_f32_e32 v141, 1.0, v118
	v_rcp_f32_e32 v118, v129
	v_rcp_f32_e32 v129, v140
	v_cndmask_b32_e32 v140, v138, v139, vcc
	v_mul_f32_e32 v104, v104, v140
	v_add_f32_e32 v112, 1.0, v112
	v_mul_f32_e32 v104, 0xbfb8aa3b, v104
	v_add_f32_e32 v131, 1.0, v116
	v_rcp_f32_e32 v116, v112
	v_rcp_f32_e32 v112, v141
	v_mul_f32_e32 v108, v108, v140
	v_mul_f32_e32 v109, v109, v140
	v_mul_f32_e32 v110, v110, v140
	v_mul_f32_e32 v111, v111, v140
	v_exp_f32_e32 v141, v104
	v_mul_f32_e32 v104, v105, v140
	v_mul_f32_e32 v106, v106, v140
	v_mul_f32_e32 v107, v107, v140
	v_mul_f32_e32 v100, v100, v140
	v_mul_f32_e32 v101, v101, v140
	v_mul_f32_e32 v102, v102, v140
	v_mul_f32_e32 v103, v103, v140
	v_mul_f32_e32 v96, v96, v140
	v_mul_f32_e32 v97, v97, v140
	v_mul_f32_e32 v98, v98, v140
	v_mul_f32_e32 v99, v99, v140
	v_fmamk_f32 v140, v157, 0x3a800000, v154
	global_load_dwordx4 v[156:159], v[148:149], off
	v_exp_f32_e32 v128, v128
	v_mul_f32_e32 v113, 0xbfb8aa3b, v113
	v_lshl_add_u64 v[138:139], s[70:71], 0, v[152:153]
	v_mul_f32_e32 v104, 0xbfb8aa3b, v104
	v_add_f32_e32 v128, 1.0, v128
	v_rcp_f32_e32 v117, v128
	v_rcp_f32_e32 v128, v131
	v_exp_f32_e32 v131, v113
	v_rcp_f32_e32 v113, v142
	v_exp_f32_e32 v142, v104
	v_lshl_add_u64 v[104:105], v[138:139], 0, v[134:135]
	v_add_f32_e32 v138, 1.0, v141
	v_mul_f32_e32 v141, 0x4b800000, v140
	v_cmp_gt_f32_e32 vcc, s20, v140
	v_add_f32_e32 v139, 1.0, v142
	v_mul_f32_e32 v120, 0xbfb8aa3b, v120
	v_cndmask_b32_e32 v140, v140, v141, vcc
	v_rsq_f32_e32 v140, v140
	v_mul_f32_e32 v121, 0xbfb8aa3b, v121
	v_mul_f32_e32 v122, 0xbfb8aa3b, v122
	v_mul_f32_e32 v123, 0xbfb8aa3b, v123
	v_mul_f32_e32 v141, 0x45800000, v140
	v_cndmask_b32_e32 v152, v140, v141, vcc
	v_mul_f32_e32 v84, v84, v152
	v_mul_f32_e32 v88, v88, v152
	v_mul_f32_e32 v84, 0xbfb8aa3b, v84
	v_mul_f32_e32 v85, v85, v152
	v_mul_f32_e32 v88, 0xbfb8aa3b, v88
	v_exp_f32_e32 v84, v84
	v_mul_f32_e32 v85, 0xbfb8aa3b, v85
	v_exp_f32_e32 v142, v88
	v_exp_f32_e32 v85, v85
	v_mul_f32_e32 v88, v89, v152
	v_lshl_add_u64 v[140:141], s[70:71], 0, v[150:151]
	v_mul_f32_e32 v88, 0xbfb8aa3b, v88
	v_add_f32_e32 v84, 1.0, v84
	v_mul_f32_e32 v92, v92, v152
	v_mul_f32_e32 v93, v93, v152
	v_mul_f32_e32 v94, v94, v152
	v_mul_f32_e32 v95, v95, v152
	v_exp_f32_e32 v143, v88
	v_lshl_add_u64 v[88:89], v[140:141], 0, v[134:135]
	v_add_f32_e32 v140, 1.0, v142
	v_mul_f32_e32 v90, v90, v152
	v_mul_f32_e32 v91, v91, v152
	v_rcp_f32_e32 v142, v84
	v_add_f32_e32 v84, 1.0, v85
	v_mul_f32_e32 v85, v86, v152
	v_mul_f32_e32 v86, v87, v152
	v_mul_f32_e32 v80, v80, v152
	v_mul_f32_e32 v81, v81, v152
	v_mul_f32_e32 v82, v82, v152
	v_mul_f32_e32 v83, v83, v152
	v_mul_f32_e32 v152, 0x4b800000, v144
	v_cmp_gt_f32_e32 vcc, s20, v144
	v_mul_f32_e32 v85, 0xbfb8aa3b, v85
	v_exp_f32_e32 v85, v85
	v_cndmask_b32_e32 v144, v144, v152, vcc
	v_rsq_f32_e32 v144, v144
	v_mul_f32_e32 v86, 0xbfb8aa3b, v86
	v_exp_f32_e32 v86, v86
	v_add_f32_e32 v141, 1.0, v143
	v_mul_f32_e32 v152, 0x45800000, v144
	v_cndmask_b32_e32 v144, v144, v152, vcc
	v_mul_f32_e32 v76, v76, v144
	v_mul_f32_e32 v76, 0xbfb8aa3b, v76
	v_mul_f32_e32 v77, v77, v144
	v_exp_f32_e32 v76, v76
	v_mul_f32_e32 v77, 0xbfb8aa3b, v77
	v_exp_f32_e32 v77, v77
	v_rcp_f32_e32 v143, v84
	v_add_f32_e32 v76, 1.0, v76
	v_rcp_f32_e32 v152, v76
	v_add_f32_e32 v76, 1.0, v77
	v_mul_f32_e32 v77, v78, v144
	v_mul_f32_e32 v77, 0xbfb8aa3b, v77
	v_mul_f32_e32 v78, v79, v144
	v_exp_f32_e32 v77, v77
	v_mul_f32_e32 v78, 0xbfb8aa3b, v78
	v_exp_f32_e32 v79, v78
	v_rcp_f32_e32 v153, v76
	v_add_f32_e32 v76, 1.0, v77
	v_rcp_f32_e32 v78, v76
	v_add_f32_e32 v76, 1.0, v79
	v_rcp_f32_e32 v79, v76
	v_add_f32_e32 v84, 1.0, v85
	v_rcp_f32_e32 v150, v84
	v_add_f32_e32 v84, 1.0, v86
	v_lshl_add_u64 v[76:77], s[70:71], 0, v[146:147]
	v_rcp_f32_e32 v151, v84
	global_load_dwordx4 v[84:87], v[148:149], off offset:64
	v_lshl_add_u64 v[76:77], v[76:77], 0, v[134:135]
	global_load_dwordx4 v[146:149], v[148:149], off offset:192
	s_waitcnt vmcnt(2)
	v_pk_fma_f32 v[60:61], v[60:61], v[152:153], v[156:157]
	global_load_dwordx4 v[134:137], v[136:137], off offset:192
	v_pk_fma_f32 v[62:63], v[62:63], v[78:79], v[158:159]
	global_load_dwordx4 v[156:159], v[132:133], off offset:64
	v_mul_f32_e32 v72, v72, v144
	v_mul_f32_e32 v73, v73, v144
	v_mul_f32_e32 v74, v74, v144
	v_mul_f32_e32 v75, v75, v144
	v_mul_f32_e32 v68, v68, v144
	v_mul_f32_e32 v69, v69, v144
	v_mul_f32_e32 v70, v70, v144
	v_mul_f32_e32 v71, v71, v144
	v_mul_f32_e32 v64, v64, v144
	v_mul_f32_e32 v65, v65, v144
	v_mul_f32_e32 v66, v66, v144
	v_mul_f32_e32 v67, v67, v144
	v_mul_f32_e32 v114, 0xbfb8aa3b, v114
	v_mul_f32_e32 v115, 0xbfb8aa3b, v115
	v_mul_f32_e32 v108, 0xbfb8aa3b, v108
	v_mul_f32_e32 v109, 0xbfb8aa3b, v109
	v_mul_f32_e32 v110, 0xbfb8aa3b, v110
	v_mul_f32_e32 v111, 0xbfb8aa3b, v111
	v_mul_f32_e32 v106, 0xbfb8aa3b, v106
	v_mul_f32_e32 v107, 0xbfb8aa3b, v107
	v_mul_f32_e32 v100, 0xbfb8aa3b, v100
	v_mul_f32_e32 v101, 0xbfb8aa3b, v101
	v_mul_f32_e32 v102, 0xbfb8aa3b, v102
	v_mul_f32_e32 v103, 0xbfb8aa3b, v103
	v_mul_f32_e32 v96, 0xbfb8aa3b, v96
	v_mul_f32_e32 v97, 0xbfb8aa3b, v97
	v_mul_f32_e32 v98, 0xbfb8aa3b, v98
	v_mul_f32_e32 v99, 0xbfb8aa3b, v99
	v_mul_f32_e32 v92, 0xbfb8aa3b, v92
	v_mul_f32_e32 v93, 0xbfb8aa3b, v93
	v_mul_f32_e32 v94, 0xbfb8aa3b, v94
	v_mul_f32_e32 v95, 0xbfb8aa3b, v95
	v_mul_f32_e32 v90, 0xbfb8aa3b, v90
	v_mul_f32_e32 v91, 0xbfb8aa3b, v91
	v_mul_f32_e32 v80, 0xbfb8aa3b, v80
	v_mul_f32_e32 v81, 0xbfb8aa3b, v81
	v_mul_f32_e32 v82, 0xbfb8aa3b, v82
	v_mul_f32_e32 v83, 0xbfb8aa3b, v83
	v_mul_f32_e32 v72, 0xbfb8aa3b, v72
	v_mul_f32_e32 v73, 0xbfb8aa3b, v73
	v_mul_f32_e32 v74, 0xbfb8aa3b, v74
	v_mul_f32_e32 v75, 0xbfb8aa3b, v75
	v_mul_f32_e32 v68, 0xbfb8aa3b, v68
	v_mul_f32_e32 v69, 0xbfb8aa3b, v69
	v_mul_f32_e32 v70, 0xbfb8aa3b, v70
	v_mul_f32_e32 v71, 0xbfb8aa3b, v71
	v_mul_f32_e32 v64, 0xbfb8aa3b, v64
	v_mul_f32_e32 v65, 0xbfb8aa3b, v65
	v_mul_f32_e32 v66, 0xbfb8aa3b, v66
	v_mul_f32_e32 v67, 0xbfb8aa3b, v67
	v_exp_f32_e32 v120, v120
	v_exp_f32_e32 v121, v121
	v_exp_f32_e32 v122, v122
	v_exp_f32_e32 v123, v123
	v_exp_f32_e32 v130, v130
	v_exp_f32_e32 v114, v114
	v_exp_f32_e32 v115, v115
	v_exp_f32_e32 v108, v108
	v_exp_f32_e32 v109, v109
	v_exp_f32_e32 v110, v110
	v_exp_f32_e32 v111, v111
	v_exp_f32_e32 v106, v106
	v_exp_f32_e32 v107, v107
	v_exp_f32_e32 v100, v100
	v_exp_f32_e32 v101, v101
	v_exp_f32_e32 v102, v102
	v_exp_f32_e32 v103, v103
	v_exp_f32_e32 v96, v96
	v_exp_f32_e32 v97, v97
	v_exp_f32_e32 v98, v98
	v_exp_f32_e32 v99, v99
	v_exp_f32_e32 v92, v92
	v_exp_f32_e32 v93, v93
	v_exp_f32_e32 v94, v94
	v_exp_f32_e32 v95, v95
	v_exp_f32_e32 v90, v90
	v_exp_f32_e32 v91, v91
	v_exp_f32_e32 v80, v80
	v_exp_f32_e32 v81, v81
	v_exp_f32_e32 v82, v82
	v_exp_f32_e32 v83, v83
	v_exp_f32_e32 v72, v72
	v_exp_f32_e32 v73, v73
	v_exp_f32_e32 v74, v74
	v_exp_f32_e32 v75, v75
	v_exp_f32_e32 v68, v68
	v_exp_f32_e32 v69, v69
	v_exp_f32_e32 v70, v70
	v_exp_f32_e32 v71, v71
	v_exp_f32_e32 v64, v64
	v_exp_f32_e32 v65, v65
	v_exp_f32_e32 v66, v66
	v_exp_f32_e32 v67, v67
	v_add_f32_e32 v120, 1.0, v120
	v_add_f32_e32 v121, 1.0, v121
	v_add_f32_e32 v122, 1.0, v122
	v_add_f32_e32 v123, 1.0, v123
	v_add_f32_e32 v130, 1.0, v130
	v_add_f32_e32 v131, 1.0, v131
	v_add_f32_e32 v114, 1.0, v114
	v_add_f32_e32 v115, 1.0, v115
	v_add_f32_e32 v108, 1.0, v108
	v_add_f32_e32 v109, 1.0, v109
	v_add_f32_e32 v110, 1.0, v110
	v_add_f32_e32 v111, 1.0, v111
	v_add_f32_e32 v106, 1.0, v106
	v_add_f32_e32 v107, 1.0, v107
	v_add_f32_e32 v100, 1.0, v100
	v_add_f32_e32 v101, 1.0, v101
	v_add_f32_e32 v102, 1.0, v102
	v_add_f32_e32 v103, 1.0, v103
	v_add_f32_e32 v96, 1.0, v96
	v_add_f32_e32 v97, 1.0, v97
	v_add_f32_e32 v98, 1.0, v98
	v_add_f32_e32 v99, 1.0, v99
	v_add_f32_e32 v92, 1.0, v92
	v_add_f32_e32 v93, 1.0, v93
	v_add_f32_e32 v94, 1.0, v94
	v_add_f32_e32 v95, 1.0, v95
	v_add_f32_e32 v90, 1.0, v90
	v_add_f32_e32 v91, 1.0, v91
	v_add_f32_e32 v80, 1.0, v80
	v_add_f32_e32 v81, 1.0, v81
	v_add_f32_e32 v82, 1.0, v82
	v_add_f32_e32 v83, 1.0, v83
	v_add_f32_e32 v72, 1.0, v72
	v_add_f32_e32 v73, 1.0, v73
	v_add_f32_e32 v74, 1.0, v74
	v_add_f32_e32 v75, 1.0, v75
	v_add_f32_e32 v68, 1.0, v68
	v_add_f32_e32 v69, 1.0, v69
	v_add_f32_e32 v70, 1.0, v70
	v_add_f32_e32 v71, 1.0, v71
	v_add_f32_e32 v64, 1.0, v64
	v_add_f32_e32 v65, 1.0, v65
	v_add_f32_e32 v66, 1.0, v66
	v_add_f32_e32 v67, 1.0, v67
	v_rcp_f32_e32 v120, v120
	v_rcp_f32_e32 v121, v121
	v_rcp_f32_e32 v122, v122
	v_rcp_f32_e32 v123, v123
	v_rcp_f32_e32 v130, v130
	v_rcp_f32_e32 v131, v131
	v_rcp_f32_e32 v114, v114
	v_rcp_f32_e32 v115, v115
	v_rcp_f32_e32 v108, v108
	v_rcp_f32_e32 v109, v109
	v_rcp_f32_e32 v110, v110
	v_rcp_f32_e32 v111, v111
	v_rcp_f32_e32 v138, v138
	v_rcp_f32_e32 v139, v139
	v_rcp_f32_e32 v106, v106
	v_rcp_f32_e32 v107, v107
	v_rcp_f32_e32 v100, v100
	v_rcp_f32_e32 v101, v101
	v_rcp_f32_e32 v102, v102
	v_rcp_f32_e32 v103, v103
	v_rcp_f32_e32 v96, v96
	v_rcp_f32_e32 v97, v97
	v_rcp_f32_e32 v98, v98
	v_rcp_f32_e32 v99, v99
	v_rcp_f32_e32 v92, v92
	v_rcp_f32_e32 v93, v93
	v_rcp_f32_e32 v94, v94
	v_rcp_f32_e32 v95, v95
	v_rcp_f32_e32 v140, v140
	v_rcp_f32_e32 v141, v141
	v_rcp_f32_e32 v90, v90
	v_rcp_f32_e32 v91, v91
	v_rcp_f32_e32 v80, v80
	v_rcp_f32_e32 v81, v81
	v_rcp_f32_e32 v82, v82
	v_rcp_f32_e32 v83, v83
	v_rcp_f32_e32 v72, v72
	v_rcp_f32_e32 v73, v73
	v_rcp_f32_e32 v74, v74
	v_rcp_f32_e32 v75, v75
	v_rcp_f32_e32 v68, v68
	v_rcp_f32_e32 v69, v69
	v_rcp_f32_e32 v70, v70
	v_rcp_f32_e32 v71, v71
	v_rcp_f32_e32 v64, v64
	v_rcp_f32_e32 v65, v65
	v_rcp_f32_e32 v66, v66
	v_rcp_f32_e32 v67, v67
	s_waitcnt vmcnt(3)
	v_pk_fma_f32 v[56:57], v[56:57], v[72:73], v[84:85]
	v_pk_fma_f32 v[58:59], v[58:59], v[74:75], v[86:87]
	v_pk_fma_f32 v[4:5], v[4:5], v[68:69], v[160:161]
	v_pk_fma_f32 v[6:7], v[6:7], v[70:71], v[162:163]
	s_waitcnt vmcnt(2)
	v_pk_fma_f32 v[0:1], v[0:1], v[64:65], v[146:147]
	v_pk_fma_f32 v[2:3], v[2:3], v[66:67], v[148:149]
	v_pk_fma_f32 v[32:33], v[32:33], v[92:93], v[164:165]
	v_pk_fma_f32 v[34:35], v[34:35], v[94:95], v[166:167]
	v_pk_fma_f32 v[24:25], v[24:25], v[140:141], v[168:169]
	v_pk_fma_f32 v[26:27], v[26:27], v[90:91], v[170:171]
	v_pk_fma_f32 v[12:13], v[12:13], v[142:143], v[172:173]
	v_pk_fma_f32 v[14:15], v[14:15], v[150:151], v[174:175]
	s_waitcnt vmcnt(1)
	v_pk_fma_f32 v[8:9], v[8:9], v[80:81], v[134:135]
	v_pk_fma_f32 v[10:11], v[10:11], v[82:83], v[136:137]
	v_pk_fma_f32 v[44:45], v[44:45], v[108:109], v[176:177]
	v_pk_fma_f32 v[46:47], v[46:47], v[110:111], v[178:179]
	s_waitcnt vmcnt(0)
	v_pk_fma_f32 v[36:37], v[36:37], v[138:139], v[156:157]
	v_pk_fma_f32 v[38:39], v[38:39], v[106:107], v[158:159]
	v_pk_fma_f32 v[28:29], v[28:29], v[100:101], v[180:181]
	v_pk_fma_f32 v[30:31], v[30:31], v[102:103], v[182:183]
	v_pk_fma_f32 v[16:17], v[16:17], v[96:97], v[184:185]
	v_pk_fma_f32 v[18:19], v[18:19], v[98:99], v[186:187]
	v_pk_fma_f32 v[52:53], v[52:53], v[116:117], v[188:189]
	v_pk_fma_f32 v[54:55], v[54:55], v[118:119], v[190:191]
	v_pk_fma_f32 v[48:49], v[48:49], v[120:121], v[192:193]
	v_pk_fma_f32 v[50:51], v[50:51], v[122:123], v[194:195]
	v_pk_fma_f32 v[40:41], v[40:41], v[128:129], v[196:197]
	v_pk_fma_f32 v[42:43], v[42:43], v[112:113], v[198:199]
	v_pk_fma_f32 v[20:21], v[20:21], v[130:131], v[200:201]
	v_pk_fma_f32 v[22:23], v[22:23], v[114:115], v[202:203]
	s_add_i32 s21, s21, s74
	s_cmpk_lt_i32 s21, 0x800
	global_store_dwordx4 v[124:125], v[52:55], off
	global_store_dwordx4 v[124:125], v[48:51], off offset:64
	global_store_dwordx4 v[124:125], v[40:43], off offset:128
	global_store_dwordx4 v[124:125], v[20:23], off offset:192
	global_store_dwordx4 v[104:105], v[44:47], off
	global_store_dwordx4 v[104:105], v[36:39], off offset:64
	global_store_dwordx4 v[104:105], v[28:31], off offset:128
	global_store_dwordx4 v[104:105], v[16:19], off offset:192
	global_store_dwordx4 v[88:89], v[32:35], off
	global_store_dwordx4 v[88:89], v[24:27], off offset:64
	global_store_dwordx4 v[88:89], v[12:15], off offset:128
	global_store_dwordx4 v[88:89], v[8:11], off offset:192
	global_store_dwordx4 v[76:77], v[60:63], off
	global_store_dwordx4 v[76:77], v[56:59], off offset:64
	global_store_dwordx4 v[76:77], v[4:7], off offset:128
	global_store_dwordx4 v[76:77], v[0:3], off offset:192
	s_cbranch_scc1 .LBB0_1866
